# half-offset single barrier per load-segment/MFMA-block pair (leading half barrier after its MFMA block, trailing half after its load segment, loop body duplicated per half, trailing MFMA blocks at pri
# speedup vs baseline: 1.0907x; 1.0008x over previous
; #define PG8_STAGE(bufoff, gbase, voff) do { _Pragma("unroll") for (int _i = 0; _i < 2; ++_i) \
;         __builtin_amdgcn_global_load_lds((const unsigned*)((const char*)(gbase) + (voff)[_i]), (PG8_LAS unsigned*)(lds + (bufoff) + ldsw + _i * 8192), 16, 0, 0); } while (0)
; #define PG8_WAIT_V(n) asm volatile("s_waitcnt vmcnt(" #n ")" ::: "memory")
; #define PG8_BAR __builtin_amdgcn_s_barrier()
;     ...
;     for (int i = 0; i < 2; ++i) { int R, C; stage_rc(tid * 16 + i * 8192, R, C); const int Rb = Epi::PERM ? ((R & ~31) + perm32(R & 31)) : R;
;         const int Ra = Epi::PERMROW ? ((R & ~63) + 4 * (R & 15) + ((R >> 4) & 3)) : R;
;         voffA[i] = (unsigned)(Ra * K + C) * 2u; voffB[i] = (unsigned)(Rb * K + C) * 2u; }
;     ...
;     const char* cA = (const char*)g.A + (size_t)cur.pm * tstep; const char* cB = (const char*)g.Bt + (size_t)cur.pn * tstep;
;     S.a_ready(cur);
;     if constexpr (SP2) {
;         PG8_STAGE(PG8_SB(0, 0), cB, voffB); PG8_STAGE(PG8_SB(0, 1), cB + hstep, voffB); PG8_STAGE(PG8_SA(0, 0), cA, voffA); PG8_STAGE(PG8_SA(0, 1), cA + hstep, voffA);
;         if (wr == 1) PG8_BAR;
;         PG8_WAIT_V(2); PG8_BAR;
;         PG8_STAGE(PG8_SB(1, 0), cB + kstep, voffB); PG8_STAGE(PG8_SA(1, 0), cA + kstep, voffA); PG8_STAGE(PG8_SB(1, 1), cB + hstep + kstep, voffB);
;         PG8_WAIT_V(6); PG8_BAR;
;     } else {
;         PG8_STAGE(PG8_SB(0, 0), cB, voffB); PG8_STAGE(PG8_SA(0, 0), cA, voffA); PG8_STAGE(PG8_SB(0, 1), cB + hstep, voffB); PG8_STAGE(PG8_SA(0, 1), cA + hstep, voffA);
;         if (wr == 1) PG8_BAR;
.LBB0_222:
	v_ashrrev_i32_e32 v5, 31, v3
	v_lshrrev_b32_e32 v5, 26, v5
	v_add_u32_e32 v5, v3, v5
	v_ashrrev_i32_e32 v13, 6, v5
	v_bfe_i32 v5, v3, 27, 1
	v_lshlrev_b32_e32 v4, 4, v3
	v_lshrrev_b32_e32 v5, 22, v5
	v_add_u32_e32 v5, v4, v5
	v_and_b32_e32 v5, 0xfffffc00, v5
	v_sub_u32_e32 v5, v4, v5
	v_lshrrev_b32_e32 v6, 4, v5
	v_bitop3_b32 v6, v6, v5, 32 bitop3:0x6c
	v_ashrrev_i32_e32 v5, 31, v5
	v_lshrrev_b32_e32 v5, 26, v5
	v_add_u32_e32 v5, v6, v5
	s_add_u32 s51, s10, 0x18000000
	v_ashrrev_i32_e32 v14, 6, v5
	s_addc_u32 s84, s11, 0
	s_lshl_b64 s[4:5], s[44:45], 24
	v_lshlrev_b32_e32 v7, 3, v13
	v_mul_i32_i24_e32 v8, 64, v14
	s_add_u32 s2, s10, s4
	v_and_b32_e32 v7, -16, v7
	v_sub_u32_e32 v6, v6, v8
	s_addc_u32 s4, s11, s5
	v_add_u32_e32 v5, v14, v7
	v_lshlrev_b32_e32 v7, 5, v13
	v_ashrrev_i16_sdwa v6, v235, sext(v6) dst_sel:DWORD dst_unused:UNUSED_PAD src0_sel:DWORD src1_sel:BYTE_0
	s_add_u32 s85, s2, 0x4e00000
	v_and_b32_e32 v7, 32, v7
	v_bfe_i32 v15, v6, 0, 16
	s_addc_u32 s86, s4, 0
	v_and_b32_e32 v9, 3, v14
	s_mov_b32 s4, 0xfffe0
	v_add_lshl_u32 v7, v7, v15, 1
	v_add_u32_e32 v4, 0x2000, v4
	v_lshlrev_b32_e32 v6, 1, v5
	v_lshrrev_b32_e32 v8, 2, v5
	v_and_or_b32 v9, v5, s4, v9
	v_lshl_add_u32 v130, v5, 12, v7
	v_ashrrev_i32_e32 v5, 31, v4
	v_lshrrev_b32_e32 v5, 22, v5
	v_add_u32_e32 v5, v4, v5
	v_ashrrev_i32_e32 v16, 10, v5
	v_mul_i32_i24_e32 v5, 0x400, v16
	v_sub_u32_e32 v4, v4, v5
	v_and_b32_e32 v6, 24, v6
	v_and_b32_e32 v8, 4, v8
	v_lshrrev_b32_e32 v5, 4, v4
	v_or3_b32 v6, v9, v8, v6
	v_bitop3_b32 v4, v5, v4, 32 bitop3:0x6c
	v_lshl_add_u32 v182, v6, 12, v7
	v_ashrrev_i32_e32 v6, 31, v4
	v_lshrrev_b32_e32 v6, 26, v6
	v_lshlrev_b32_e32 v5, 3, v16
	v_add_u32_e32 v6, v4, v6
	v_and_b32_e32 v5, -16, v5
	v_ashrrev_i32_e32 v17, 6, v6
	v_add_u32_e32 v5, v17, v5
	v_and_b32_e32 v6, 0xc0, v6
	v_and_b32_e32 v8, 3, v17
	s_ashr_i32 s77, s76, 31
	s_ashr_i32 s75, s74, 31
	s_ashr_i32 s2, s0, 8
	v_sub_u32_e32 v4, v4, v6
	v_and_or_b32 v8, v5, s4, v8
	s_lshl_b32 s87, s6, 10
	s_lshl_b64 s[4:5], s[76:77], 20
	s_lshl_b64 s[18:19], s[74:75], 20
	v_ashrrev_i16_sdwa v4, v235, sext(v4) dst_sel:DWORD dst_unused:UNUSED_PAD src0_sel:DWORD src1_sel:BYTE_0
	s_add_u32 s80, s85, s18
	v_lshlrev_b32_e32 v7, 5, v16
	s_waitcnt vmcnt(0)
	v_bfe_i32 v18, v4, 0, 16
	v_lshlrev_b32_e32 v4, 1, v5
	v_lshrrev_b32_e32 v6, 2, v5
	s_addc_u32 s81, s86, s19
	s_add_i32 s75, s87, 0
	v_and_b32_e32 v7, 32, v7
	v_and_b32_e32 v4, 24, v4
	v_and_b32_e32 v6, 4, v6
	s_add_i32 m0, s75, 0x10000
	v_or3_b32 v4, v8, v6, v4
	v_add_lshl_u32 v6, v7, v18, 1
	global_load_lds_dwordx4 v182, s[80:81]
	s_add_i32 m0, s75, 0x12000
	v_lshl_add_u32 v134, v4, 12, v6
	s_add_u32 s18, s80, 0x80000
	global_load_lds_dwordx4 v134, s[80:81]
	s_addc_u32 s19, s81, 0
	s_add_i32 m0, s75, 0x14000
	v_lshl_add_u32 v132, v5, 12, v6
	global_load_lds_dwordx4 v182, s[18:19]
	s_add_i32 m0, s75, 0x16000
	s_add_u32 s78, s51, s4
	s_addc_u32 s79, s84, s5
	s_add_i32 s88, s75, 0x2000
	global_load_lds_dwordx4 v134, s[18:19]
	s_mov_b32 m0, s75
	s_add_u32 s4, s78, 0x80000
	global_load_lds_dwordx4 v130, s[78:79]
	s_mov_b32 m0, s88
	s_addc_u32 s5, s79, 0
	s_add_i32 s89, s75, 0x4000
	global_load_lds_dwordx4 v132, s[78:79]
	s_mov_b32 m0, s89
	s_add_i32 s90, s75, 0x6000
	global_load_lds_dwordx4 v130, s[4:5]
	s_mov_b32 m0, s90
	v_mov_b32_e32 v135, v183
	global_load_lds_dwordx4 v132, s[4:5]
	v_mov_b32_e32 v131, v183
	v_mov_b32_e32 v133, v183
	s_cmp_eq_u32 s2, 1
	v_lshl_add_u64 v[10:11], s[80:81], 0, v[182:183]
	v_lshl_add_u64 v[8:9], s[80:81], 0, v[134:135]
	v_lshl_add_u64 v[4:5], s[78:79], 0, v[130:131]
	s_cselect_b64 s[60:61], -1, 0
	s_cmp_lg_u32 s2, 1
	v_lshl_add_u64 v[6:7], s[78:79], 0, v[132:133]
	s_cbranch_scc1 .LBB0_224
	s_setprio 0

;     __host__ __device__ bool next(int i, Unit& u) const { const long L = (long)i * G + c; if (L >= lim) return false; unit_of((int)L, u); return true; }
;     __device__ __forceinline__ bool next(int i, Unit& v) const { if (i != 0) return false; v = u; return true; }
; #define PG8_STAGE(bufoff, gbase, voff) do { _Pragma("unroll") for (int _i = 0; _i < 2; ++_i) \
;         __builtin_amdgcn_global_load_lds((const unsigned*)((const char*)(gbase) + (voff)[_i]), (PG8_LAS unsigned*)(lds + (bufoff) + ldsw + _i * 8192), 16, 0, 0); } while (0)
; #define PG8_LDA(dst, b, h) do { _Pragma("unroll") for (int m = 0; m < 4; ++m) _Pragma("unroll") for (int k = 0; k < 2; ++k) dst[m][k] = *(const PG8_LAS bf16x8*)(lds + PG8_SA(b, h) + aoff + m * 2048 + k * 1024); } while (0)
;     ...
;         const bool has_next = S.next(ui + 1, nxt);
;         if constexpr (TP == 3) { if (ui > 0) tp_acc += __builtin_amdgcn_s_memrealtime() - tp3; }
;         const char* nA = has_next ? (const char*)g.A + (size_t)nxt.pm * tstep : cA; const char* nB = has_next ? (const char*)g.Bt + (size_t)nxt.pn * tstep : cB;
;         for (int t = 0; t < nt * KREP; t += 2) {
;             const bool last = (t == nt * KREP - 2);
;             const int t1w = KREP > 1 ? ((t + 1) & (nt - 1)) : t + 1, t2w = KREP > 1 ? ((t + 2) & (nt - 1)) : t + 2;
;             const char* a1 = cA + (size_t)t1w * kstep;
;             const char* a2 = last ? nA : cA + (size_t)t2w * kstep; const char* b2 = last ? nB : cB + (size_t)t2w * kstep;
;             const char* a3 = a2 + kstep; const char* b3 = b2 + kstep;
;             if (last && has_next) S.a_ready(nxt);
;             const int relax = __builtin_amdgcn_readfirstlane((MK_RELAXW && t == 0 && ui > 0) ? 1 : 0);
;             if constexpr (SP2) {
;             PG8_LDB(B0, 0, 0); PG8_LDB(B1, 0, 1); PG8_SCHED; PG8_LDA(At, 0, 0); PG8_STAGE(PG8_SA(1, 1), a1 + hstep, voffA);
;             PG8_WAIT_V_SEL(relax);
;             PG8_WAIT_L(0); PG8_BAR; PG8_MMA(0, 0, At, B0); PG8_MMA(0, 1, At, B1); PG8_BAR; PG8_SCHED;
;     ...
; #pragma unroll
;         for (int a = 0; a < 2; ++a)
; #pragma unroll
;             for (int b = 0; b < 2; ++b)
; #pragma unroll
;                 for (int m = 0; m < 4; ++m)
; #pragma unroll
;                     for (int n = 0; n < 2; ++n) acc[a][b][m][n] = (f32x4){0.f, 0.f, 0.f, 0.f};
;         cur = nxt; cA = nA; cB = nB; ++ui;
.LBB0_233:
	s_ashr_i32 s69, s68, 31
	s_lshl_b64 s[0:1], s[68:69], 20
	s_add_u32 s70, s51, s0
	s_addc_u32 s71, s84, s1
	s_and_b64 s[0:1], s[6:7], exec
	s_cselect_b32 s19, s71, s79
	s_cselect_b32 s20, s70, s78
	s_ashr_i32 s67, s66, 31
	s_lshl_b64 s[0:1], s[66:67], 20
	s_add_u32 s72, s85, s0
	s_addc_u32 s73, s86, s1
	s_and_b64 s[0:1], s[6:7], exec
	s_cselect_b32 s24, s73, s81
	s_cselect_b32 s31, s72, s80
	s_add_u32 s78, s78, 0x80080
	s_addc_u32 s79, s79, 0
	s_add_u32 s33, s80, 0x100
	v_mov_b64_e32 v[2:3], 0
	v_mov_b64_e32 v[4:5], 0
	v_mov_b64_e32 v[6:7], 0
	v_mov_b64_e32 v[8:9], 0
	v_mov_b64_e32 v[10:11], 0
	v_mov_b64_e32 v[12:13], 0
	v_mov_b64_e32 v[14:15], 0
	v_mov_b64_e32 v[16:17], 0
	v_mov_b64_e32 v[18:19], 0
	v_mov_b64_e32 v[20:21], 0
	v_mov_b64_e32 v[22:23], 0
	v_mov_b64_e32 v[24:25], 0
	v_mov_b64_e32 v[26:27], 0
	v_mov_b64_e32 v[28:29], 0
	v_mov_b64_e32 v[30:31], 0
	v_mov_b64_e32 v[32:33], 0
	v_mov_b64_e32 v[34:35], 0
	v_mov_b64_e32 v[36:37], 0
	v_mov_b64_e32 v[38:39], 0
	v_mov_b64_e32 v[40:41], 0
	v_mov_b64_e32 v[42:43], 0
	v_mov_b64_e32 v[44:45], 0
	v_mov_b64_e32 v[46:47], 0
	v_mov_b64_e32 v[48:49], 0
	v_mov_b64_e32 v[50:51], 0
	v_mov_b64_e32 v[52:53], 0
	v_mov_b64_e32 v[54:55], 0
	v_mov_b64_e32 v[56:57], 0
	v_mov_b64_e32 v[58:59], 0
	v_mov_b64_e32 v[60:61], 0
	v_mov_b64_e32 v[62:63], 0
	v_mov_b64_e32 v[64:65], 0
	v_mov_b64_e32 v[66:67], 0
	v_mov_b64_e32 v[68:69], 0
	v_mov_b64_e32 v[70:71], 0
	v_mov_b64_e32 v[72:73], 0
	v_mov_b64_e32 v[74:75], 0
	v_mov_b64_e32 v[76:77], 0
	v_mov_b64_e32 v[78:79], 0
	v_mov_b64_e32 v[80:81], 0
	v_mov_b64_e32 v[82:83], 0
	v_mov_b64_e32 v[84:85], 0
	v_mov_b64_e32 v[86:87], 0
	v_mov_b64_e32 v[88:89], 0
	v_mov_b64_e32 v[90:91], 0
	v_mov_b64_e32 v[92:93], 0
	v_mov_b64_e32 v[94:95], 0
	v_mov_b64_e32 v[96:97], 0
	v_mov_b64_e32 v[98:99], 0
	v_mov_b64_e32 v[100:101], 0
	v_mov_b64_e32 v[102:103], 0
	v_mov_b64_e32 v[104:105], 0
	v_mov_b64_e32 v[106:107], 0
	v_mov_b64_e32 v[108:109], 0
	v_mov_b64_e32 v[110:111], 0
	v_mov_b64_e32 v[112:113], 0
	v_mov_b64_e32 v[114:115], 0
	v_mov_b64_e32 v[116:117], 0
	v_mov_b64_e32 v[118:119], 0
	v_mov_b64_e32 v[120:121], 0
	v_mov_b64_e32 v[122:123], 0
	v_mov_b64_e32 v[124:125], 0
	v_mov_b64_e32 v[126:127], 0
	v_mov_b64_e32 v[128:129], 0
	s_addc_u32 s35, s81, 0
	s_mov_b32 s37, -2
	s_waitcnt lgkmcnt(0)
	v_add_u32_e32 v168, 0x10000, v181
	s_cmp_lg_u32 s64, 0
	s_cbranch_scc0 .Lhob_gi_Thead
.LBB0_234:
	s_add_u32 s0, s78, 0xfff80080
	s_addc_u32 s1, s79, -1
	s_add_i32 s40, 0, 0x10000
	s_cmp_eq_u32 s37, 28
	s_cselect_b32 s83, s19, s1
	s_cselect_b32 s82, s20, s0
	s_cselect_b32 s81, s24, s35
	s_cselect_b32 s80, s31, s33
	s_add_i32 s41, 0, 0x14000
	ds_read_b128 v[142:145], v168
	ds_read_b128 v[146:149], v168 offset:1024
	ds_read_b128 v[150:153], v168 offset:2048
	ds_read_b128 v[154:157], v168 offset:3072
	ds_read_b128 v[158:161], v168 offset:16384
	ds_read_b128 v[162:165], v168 offset:17408
	ds_read_b128 v[174:177], v168 offset:18432
	ds_read_b128 v[188:191], v168 offset:19456
	s_add_i32 m0, s75, 0xc000
	ds_read_b128 v[198:201], v196
	ds_read_b128 v[202:205], v196 offset:1024
	ds_read_b128 v[206:209], v196 offset:2048
	ds_read_b128 v[210:213], v196 offset:3072
	ds_read_b128 v[214:217], v196 offset:4096
	ds_read_b128 v[218:221], v196 offset:5120
	ds_read_b128 v[222:225], v196 offset:6144
	ds_read_b128 v[226:229], v196 offset:7168
	global_load_lds_dwordx4 v138, s[78:79]
	s_add_i32 m0, s75, 0xe000
	s_nop 0
	global_load_lds_dwordx4 v140, s[78:79]
	s_waitcnt vmcnt(8)
	s_waitcnt lgkmcnt(0)
	s_setprio 1
	v_mfma_f32_16x16x32_bf16 v[126:129], v[142:145], v[198:201], v[126:129]
	v_mfma_f32_16x16x32_bf16 v[126:129], v[146:149], v[202:205], v[126:129]
	v_mfma_f32_16x16x32_bf16 v[122:125], v[142:145], v[206:209], v[122:125]
	v_mfma_f32_16x16x32_bf16 v[122:125], v[146:149], v[210:213], v[122:125]
	v_mfma_f32_16x16x32_bf16 v[118:121], v[142:145], v[214:217], v[118:121]
	v_mfma_f32_16x16x32_bf16 v[118:121], v[146:149], v[218:221], v[118:121]
	v_mfma_f32_16x16x32_bf16 v[114:117], v[142:145], v[222:225], v[114:117]
	v_mfma_f32_16x16x32_bf16 v[114:117], v[146:149], v[226:229], v[114:117]
	v_mfma_f32_16x16x32_bf16 v[98:101], v[150:153], v[222:225], v[98:101]
	v_mfma_f32_16x16x32_bf16 v[98:101], v[154:157], v[226:229], v[98:101]
	v_mfma_f32_16x16x32_bf16 v[102:105], v[150:153], v[214:217], v[102:105]
	v_mfma_f32_16x16x32_bf16 v[102:105], v[154:157], v[218:221], v[102:105]
	v_mfma_f32_16x16x32_bf16 v[106:109], v[150:153], v[206:209], v[106:109]
	v_mfma_f32_16x16x32_bf16 v[106:109], v[154:157], v[210:213], v[106:109]
	v_mfma_f32_16x16x32_bf16 v[110:113], v[150:153], v[198:201], v[110:113]
	v_mfma_f32_16x16x32_bf16 v[110:113], v[154:157], v[202:205], v[110:113]
	v_mfma_f32_16x16x32_bf16 v[82:85], v[158:161], v[198:201], v[82:85]
	v_mfma_f32_16x16x32_bf16 v[82:85], v[162:165], v[202:205], v[82:85]
	v_mfma_f32_16x16x32_bf16 v[70:73], v[158:161], v[206:209], v[70:73]
	v_mfma_f32_16x16x32_bf16 v[70:73], v[162:165], v[210:213], v[70:73]
	v_mfma_f32_16x16x32_bf16 v[66:69], v[158:161], v[214:217], v[66:69]
	v_mfma_f32_16x16x32_bf16 v[66:69], v[162:165], v[218:221], v[66:69]
	v_mfma_f32_16x16x32_bf16 v[58:61], v[158:161], v[222:225], v[58:61]
	v_mfma_f32_16x16x32_bf16 v[58:61], v[162:165], v[226:229], v[58:61]
	v_mfma_f32_16x16x32_bf16 v[18:21], v[174:177], v[222:225], v[18:21]
	v_mfma_f32_16x16x32_bf16 v[18:21], v[188:191], v[226:229], v[18:21]
	v_mfma_f32_16x16x32_bf16 v[22:25], v[174:177], v[214:217], v[22:25]
	v_mfma_f32_16x16x32_bf16 v[22:25], v[188:191], v[218:221], v[22:25]
	v_mfma_f32_16x16x32_bf16 v[26:29], v[174:177], v[206:209], v[26:29]
	v_mfma_f32_16x16x32_bf16 v[26:29], v[188:191], v[210:213], v[26:29]
	v_mfma_f32_16x16x32_bf16 v[30:33], v[174:177], v[198:201], v[30:33]
	v_mfma_f32_16x16x32_bf16 v[30:33], v[188:191], v[202:205], v[30:33]
	s_setprio 0
	s_barrier
; #define PG8_STAGE(bufoff, gbase, voff) do { _Pragma("unroll") for (int _i = 0; _i < 2; ++_i) \
;         __builtin_amdgcn_global_load_lds((const unsigned*)((const char*)(gbase) + (voff)[_i]), (PG8_LAS unsigned*)(lds + (bufoff) + ldsw + _i * 8192), 16, 0, 0); } while (0)
; #define PG8_LDA(dst, b, h) do { _Pragma("unroll") for (int m = 0; m < 4; ++m) _Pragma("unroll") for (int k = 0; k < 2; ++k) dst[m][k] = *(const PG8_LAS bf16x8*)(lds + PG8_SA(b, h) + aoff + m * 2048 + k * 1024); } while (0)
; #define PG8_LDB(dst, b, h) do { _Pragma("unroll") for (int n = 0; n < 2; ++n) _Pragma("unroll") for (int k = 0; k < 2; ++k) dst[n][k] = *(const PG8_LAS bf16x8*)(lds + PG8_SB(b, h) + boff + n * 2048 + k * 1024); } while (0)
; #define PG8_WAIT_V(n) asm volatile("s_waitcnt vmcnt(" #n ")" ::: "memory")
; #define PG8_WAIT_L(n) asm volatile("s_waitcnt lgkmcnt(" #n ")" ::: "memory")
; #define PG8_WAIT_V_SEL(sel) asm volatile("s_cmp_eq_u32 %0, 0\n\ts_cbranch_scc1 .Lw8_%=\n\ts_waitcnt vmcnt(22)\n\ts_branch .Lwd_%=\n.Lw8_%=:\n\ts_waitcnt vmcnt(8)\n.Lwd_%=:" :: "s"(sel) : "memory", "scc")
; #define PG8_BAR __builtin_amdgcn_s_barrier()
; #define PG8_SCHED __builtin_amdgcn_sched_barrier(0)
;     ...
;             PG8_WAIT_L(0); PG8_BAR; PG8_MMA(0, 0, At, B0); PG8_MMA(0, 1, At, B1); PG8_BAR; PG8_SCHED;
;             PG8_LDA(At, 0, 1); PG8_STAGE(PG8_SB(0, 0), b2, voffB); PG8_STAGE(PG8_SB(0, 1), b2 + hstep, voffB); PG8_STAGE(PG8_SA(0, 0), a2, voffA);
;             PG8_WAIT_V_SEL(relax);
;             PG8_WAIT_L(0); PG8_BAR; PG8_MMA(1, 0, At, B0); PG8_MMA(1, 1, At, B1); PG8_BAR; PG8_SCHED;
;             PG8_LDB(B0, 1, 0); PG8_LDB(B1, 1, 1); PG8_SCHED; PG8_LDA(At, 1, 0); PG8_STAGE(PG8_SA(0, 1), a2 + hstep, voffA);
;             PG8_WAIT_V(8); PG8_WAIT_L(0); PG8_BAR; PG8_MMA(0, 0, At, B0); PG8_MMA(0, 1, At, B1); PG8_BAR; PG8_SCHED;
	s_add_i32 s0, s40, s87
	s_mov_b32 m0, s0
	ds_read_b128 v[198:201], v196 offset:16384
	ds_read_b128 v[202:205], v196 offset:17408
	ds_read_b128 v[206:209], v196 offset:18432
	ds_read_b128 v[210:213], v196 offset:19456
	ds_read_b128 v[214:217], v196 offset:20480
	ds_read_b128 v[218:221], v196 offset:21504
	ds_read_b128 v[222:225], v196 offset:22528
	ds_read_b128 v[226:229], v196 offset:23552
	global_load_lds_dwordx4 v182, s[80:81]
	s_add_i32 m0, s0, 0x2000
	s_add_u32 s0, s80, 0x80000
	s_addc_u32 s1, s81, 0
	s_add_i32 s40, s41, s87
	global_load_lds_dwordx4 v134, s[80:81]
	s_mov_b32 m0, s40
	s_nop 0
	global_load_lds_dwordx4 v182, s[0:1]
	s_add_i32 m0, s40, 0x2000
	s_nop 0
	global_load_lds_dwordx4 v134, s[0:1]
	s_mov_b32 m0, s75
	s_nop 0
	global_load_lds_dwordx4 v130, s[82:83]
	s_mov_b32 m0, s88
	s_nop 0
	global_load_lds_dwordx4 v132, s[82:83]
	s_waitcnt vmcnt(8)
	s_waitcnt lgkmcnt(0)
	s_setprio 1
	v_mfma_f32_16x16x32_bf16 v[94:97], v[142:145], v[198:201], v[94:97]
	v_mfma_f32_16x16x32_bf16 v[94:97], v[146:149], v[202:205], v[94:97]
	v_mfma_f32_16x16x32_bf16 v[90:93], v[142:145], v[206:209], v[90:93]
	v_mfma_f32_16x16x32_bf16 v[90:93], v[146:149], v[210:213], v[90:93]
	v_mfma_f32_16x16x32_bf16 v[86:89], v[142:145], v[214:217], v[86:89]
	v_mfma_f32_16x16x32_bf16 v[86:89], v[146:149], v[218:221], v[86:89]
	v_mfma_f32_16x16x32_bf16 v[78:81], v[142:145], v[222:225], v[78:81]
	v_mfma_f32_16x16x32_bf16 v[78:81], v[146:149], v[226:229], v[78:81]
	v_mfma_f32_16x16x32_bf16 v[50:53], v[150:153], v[222:225], v[50:53]
	v_mfma_f32_16x16x32_bf16 v[50:53], v[154:157], v[226:229], v[50:53]
	v_mfma_f32_16x16x32_bf16 v[54:57], v[150:153], v[214:217], v[54:57]
	v_mfma_f32_16x16x32_bf16 v[54:57], v[154:157], v[218:221], v[54:57]
	v_mfma_f32_16x16x32_bf16 v[62:65], v[150:153], v[206:209], v[62:65]
	v_mfma_f32_16x16x32_bf16 v[62:65], v[154:157], v[210:213], v[62:65]
	v_mfma_f32_16x16x32_bf16 v[74:77], v[150:153], v[198:201], v[74:77]
	v_mfma_f32_16x16x32_bf16 v[74:77], v[154:157], v[202:205], v[74:77]
	v_mfma_f32_16x16x32_bf16 v[46:49], v[158:161], v[198:201], v[46:49]
	v_mfma_f32_16x16x32_bf16 v[46:49], v[162:165], v[202:205], v[46:49]
	v_mfma_f32_16x16x32_bf16 v[42:45], v[158:161], v[206:209], v[42:45]
	v_mfma_f32_16x16x32_bf16 v[42:45], v[162:165], v[210:213], v[42:45]
	v_mfma_f32_16x16x32_bf16 v[38:41], v[158:161], v[214:217], v[38:41]
	v_mfma_f32_16x16x32_bf16 v[38:41], v[162:165], v[218:221], v[38:41]
	v_mfma_f32_16x16x32_bf16 v[34:37], v[158:161], v[222:225], v[34:37]
	v_mfma_f32_16x16x32_bf16 v[34:37], v[162:165], v[226:229], v[34:37]
	v_mfma_f32_16x16x32_bf16 v[2:5], v[174:177], v[222:225], v[2:5]
	v_mfma_f32_16x16x32_bf16 v[2:5], v[188:191], v[226:229], v[2:5]
	v_mfma_f32_16x16x32_bf16 v[6:9], v[174:177], v[214:217], v[6:9]
	v_mfma_f32_16x16x32_bf16 v[6:9], v[188:191], v[218:221], v[6:9]
	v_mfma_f32_16x16x32_bf16 v[10:13], v[174:177], v[206:209], v[10:13]
	v_mfma_f32_16x16x32_bf16 v[10:13], v[188:191], v[210:213], v[10:13]
	v_mfma_f32_16x16x32_bf16 v[14:17], v[174:177], v[198:201], v[14:17]
	v_mfma_f32_16x16x32_bf16 v[14:17], v[188:191], v[202:205], v[14:17]
	s_setprio 0
	s_barrier
	s_add_i32 s40, 0, 0x18000
	s_add_i32 s41, 0, 0x1c000
	ds_read_b128 v[142:145], v168 offset:32768
	ds_read_b128 v[146:149], v168 offset:33792
	ds_read_b128 v[150:153], v168 offset:34816
	ds_read_b128 v[154:157], v168 offset:35840
	ds_read_b128 v[158:161], v168 offset:49152
	ds_read_b128 v[162:165], v168 offset:50176
	ds_read_b128 v[174:177], v168 offset:51200
	ds_read_b128 v[188:191], v168 offset:52224
	s_add_u32 s0, s82, 0x80000
	s_addc_u32 s1, s83, 0
	s_mov_b32 m0, s89
	ds_read_b128 v[198:201], v196 offset:32768
	ds_read_b128 v[202:205], v196 offset:33792
	ds_read_b128 v[206:209], v196 offset:34816
	ds_read_b128 v[210:213], v196 offset:35840
	ds_read_b128 v[214:217], v196 offset:36864
	ds_read_b128 v[218:221], v196 offset:37888
	ds_read_b128 v[222:225], v196 offset:38912
	ds_read_b128 v[226:229], v196 offset:39936
	global_load_lds_dwordx4 v130, s[0:1]
	s_mov_b32 m0, s90
	s_nop 0
	global_load_lds_dwordx4 v132, s[0:1]
	s_waitcnt vmcnt(8)
	s_waitcnt lgkmcnt(0)
	s_setprio 1
	v_mfma_f32_16x16x32_bf16 v[126:129], v[142:145], v[198:201], v[126:129]
	v_mfma_f32_16x16x32_bf16 v[126:129], v[146:149], v[202:205], v[126:129]
	v_mfma_f32_16x16x32_bf16 v[122:125], v[142:145], v[206:209], v[122:125]
	v_mfma_f32_16x16x32_bf16 v[122:125], v[146:149], v[210:213], v[122:125]
	v_mfma_f32_16x16x32_bf16 v[118:121], v[142:145], v[214:217], v[118:121]
	v_mfma_f32_16x16x32_bf16 v[118:121], v[146:149], v[218:221], v[118:121]
	v_mfma_f32_16x16x32_bf16 v[114:117], v[142:145], v[222:225], v[114:117]
	v_mfma_f32_16x16x32_bf16 v[114:117], v[146:149], v[226:229], v[114:117]
	v_mfma_f32_16x16x32_bf16 v[98:101], v[150:153], v[222:225], v[98:101]
	v_mfma_f32_16x16x32_bf16 v[98:101], v[154:157], v[226:229], v[98:101]
	v_mfma_f32_16x16x32_bf16 v[102:105], v[150:153], v[214:217], v[102:105]
	v_mfma_f32_16x16x32_bf16 v[102:105], v[154:157], v[218:221], v[102:105]
	v_mfma_f32_16x16x32_bf16 v[106:109], v[150:153], v[206:209], v[106:109]
	v_mfma_f32_16x16x32_bf16 v[106:109], v[154:157], v[210:213], v[106:109]
	v_mfma_f32_16x16x32_bf16 v[110:113], v[150:153], v[198:201], v[110:113]
	v_mfma_f32_16x16x32_bf16 v[110:113], v[154:157], v[202:205], v[110:113]
	v_mfma_f32_16x16x32_bf16 v[82:85], v[158:161], v[198:201], v[82:85]
	v_mfma_f32_16x16x32_bf16 v[82:85], v[162:165], v[202:205], v[82:85]
	v_mfma_f32_16x16x32_bf16 v[70:73], v[158:161], v[206:209], v[70:73]
	v_mfma_f32_16x16x32_bf16 v[70:73], v[162:165], v[210:213], v[70:73]
	v_mfma_f32_16x16x32_bf16 v[66:69], v[158:161], v[214:217], v[66:69]
	v_mfma_f32_16x16x32_bf16 v[66:69], v[162:165], v[218:221], v[66:69]
	v_mfma_f32_16x16x32_bf16 v[58:61], v[158:161], v[222:225], v[58:61]
	v_mfma_f32_16x16x32_bf16 v[58:61], v[162:165], v[226:229], v[58:61]
	v_mfma_f32_16x16x32_bf16 v[18:21], v[174:177], v[222:225], v[18:21]
	v_mfma_f32_16x16x32_bf16 v[18:21], v[188:191], v[226:229], v[18:21]
	v_mfma_f32_16x16x32_bf16 v[22:25], v[174:177], v[214:217], v[22:25]
	v_mfma_f32_16x16x32_bf16 v[22:25], v[188:191], v[218:221], v[22:25]
	v_mfma_f32_16x16x32_bf16 v[26:29], v[174:177], v[206:209], v[26:29]
	v_mfma_f32_16x16x32_bf16 v[26:29], v[188:191], v[210:213], v[26:29]
	v_mfma_f32_16x16x32_bf16 v[30:33], v[174:177], v[198:201], v[30:33]
	v_mfma_f32_16x16x32_bf16 v[30:33], v[188:191], v[202:205], v[30:33]
	s_setprio 0
	s_barrier
; #define PG8_STAGE(bufoff, gbase, voff) do { _Pragma("unroll") for (int _i = 0; _i < 2; ++_i) \
;         __builtin_amdgcn_global_load_lds((const unsigned*)((const char*)(gbase) + (voff)[_i]), (PG8_LAS unsigned*)(lds + (bufoff) + ldsw + _i * 8192), 16, 0, 0); } while (0)
; #define PG8_LDA(dst, b, h) do { _Pragma("unroll") for (int m = 0; m < 4; ++m) _Pragma("unroll") for (int k = 0; k < 2; ++k) dst[m][k] = *(const PG8_LAS bf16x8*)(lds + PG8_SA(b, h) + aoff + m * 2048 + k * 1024); } while (0)
; #define PG8_LDB(dst, b, h) do { _Pragma("unroll") for (int n = 0; n < 2; ++n) _Pragma("unroll") for (int k = 0; k < 2; ++k) dst[n][k] = *(const PG8_LAS bf16x8*)(lds + PG8_SB(b, h) + boff + n * 2048 + k * 1024); } while (0)
; #define PG8_WAIT_V(n) asm volatile("s_waitcnt vmcnt(" #n ")" ::: "memory")
; #define PG8_WAIT_L(n) asm volatile("s_waitcnt lgkmcnt(" #n ")" ::: "memory")
; #define PG8_WAIT_V_SEL(sel) asm volatile("s_cmp_eq_u32 %0, 0\n\ts_cbranch_scc1 .Lw8_%=\n\ts_waitcnt vmcnt(22)\n\ts_branch .Lwd_%=\n.Lw8_%=:\n\ts_waitcnt vmcnt(8)\n.Lwd_%=:" :: "s"(sel) : "memory", "scc")
; #define PG8_BAR __builtin_amdgcn_s_barrier()
; #define PG8_SCHED __builtin_amdgcn_sched_barrier(0)
;     ...
;             PG8_LDB(B0, 0, 0); PG8_LDB(B1, 0, 1); PG8_SCHED; PG8_LDA(At, 0, 0); PG8_STAGE(PG8_SA(1, 1), a1 + hstep, voffA);
;             PG8_WAIT_V_SEL(relax);
;             PG8_WAIT_L(0); PG8_BAR; PG8_MMA(0, 0, At, B0); PG8_MMA(0, 1, At, B1); PG8_BAR; PG8_SCHED;
;     ...
;             PG8_LDA(At, 1, 1); PG8_STAGE(PG8_SB(1, 0), b3, voffB); PG8_STAGE(PG8_SB(1, 1), b3 + hstep, voffB); PG8_STAGE(PG8_SA(1, 0), a3, voffA);
;             PG8_WAIT_V(8); PG8_WAIT_L(0); PG8_BAR; PG8_MMA(1, 0, At, B0); PG8_MMA(1, 1, At, B1); PG8_BAR; PG8_SCHED;
	s_add_i32 s0, s40, s87
	s_mov_b32 m0, s0
	ds_read_b128 v[198:201], v196 offset:49152
	ds_read_b128 v[202:205], v196 offset:50176
	ds_read_b128 v[206:209], v196 offset:51200
	ds_read_b128 v[210:213], v196 offset:52224
	ds_read_b128 v[214:217], v196 offset:53248
	ds_read_b128 v[218:221], v196 offset:54272
	ds_read_b128 v[222:225], v196 offset:55296
	ds_read_b128 v[226:229], v196 offset:56320
	s_add_u32 s100, s80, 0x80
	s_addc_u32 s101, s81, 0
	global_load_lds_dwordx4 v182, s[100:101]
	s_add_i32 m0, s0, 0x2000
	s_add_u32 s0, s80, 0x80080
	s_addc_u32 s1, s81, 0
	s_add_i32 s40, s41, s87
	global_load_lds_dwordx4 v134, s[100:101]
	s_mov_b32 m0, s40
	s_nop 0
	global_load_lds_dwordx4 v182, s[0:1]
	s_add_i32 m0, s40, 0x2000
	s_nop 0
	global_load_lds_dwordx4 v134, s[0:1]
	s_mov_b32 m0, s94
	s_nop 0
	s_add_u32 s100, s82, 0x80
	s_addc_u32 s101, s83, 0
	global_load_lds_dwordx4 v130, s[100:101]
	s_mov_b32 m0, s95
	s_nop 0
	global_load_lds_dwordx4 v132, s[100:101]
	s_waitcnt vmcnt(8)
	s_waitcnt lgkmcnt(0)
	s_setprio 1
	v_mfma_f32_16x16x32_bf16 v[94:97], v[142:145], v[198:201], v[94:97]
	v_mfma_f32_16x16x32_bf16 v[94:97], v[146:149], v[202:205], v[94:97]
	v_mfma_f32_16x16x32_bf16 v[90:93], v[142:145], v[206:209], v[90:93]
	v_mfma_f32_16x16x32_bf16 v[90:93], v[146:149], v[210:213], v[90:93]
	v_mfma_f32_16x16x32_bf16 v[86:89], v[142:145], v[214:217], v[86:89]
	v_mfma_f32_16x16x32_bf16 v[86:89], v[146:149], v[218:221], v[86:89]
	v_mfma_f32_16x16x32_bf16 v[78:81], v[142:145], v[222:225], v[78:81]
	v_mfma_f32_16x16x32_bf16 v[78:81], v[146:149], v[226:229], v[78:81]
	v_mfma_f32_16x16x32_bf16 v[50:53], v[150:153], v[222:225], v[50:53]
	v_mfma_f32_16x16x32_bf16 v[50:53], v[154:157], v[226:229], v[50:53]
	v_mfma_f32_16x16x32_bf16 v[54:57], v[150:153], v[214:217], v[54:57]
	v_mfma_f32_16x16x32_bf16 v[54:57], v[154:157], v[218:221], v[54:57]
	v_mfma_f32_16x16x32_bf16 v[62:65], v[150:153], v[206:209], v[62:65]
	v_mfma_f32_16x16x32_bf16 v[62:65], v[154:157], v[210:213], v[62:65]
	v_mfma_f32_16x16x32_bf16 v[74:77], v[150:153], v[198:201], v[74:77]
	v_mfma_f32_16x16x32_bf16 v[74:77], v[154:157], v[202:205], v[74:77]
	v_mfma_f32_16x16x32_bf16 v[46:49], v[158:161], v[198:201], v[46:49]
	v_mfma_f32_16x16x32_bf16 v[46:49], v[162:165], v[202:205], v[46:49]
	v_mfma_f32_16x16x32_bf16 v[42:45], v[158:161], v[206:209], v[42:45]
	v_mfma_f32_16x16x32_bf16 v[42:45], v[162:165], v[210:213], v[42:45]
	v_mfma_f32_16x16x32_bf16 v[38:41], v[158:161], v[214:217], v[38:41]
	v_mfma_f32_16x16x32_bf16 v[38:41], v[162:165], v[218:221], v[38:41]
	v_mfma_f32_16x16x32_bf16 v[34:37], v[158:161], v[222:225], v[34:37]
	v_mfma_f32_16x16x32_bf16 v[34:37], v[162:165], v[226:229], v[34:37]
	v_mfma_f32_16x16x32_bf16 v[2:5], v[174:177], v[222:225], v[2:5]
	v_mfma_f32_16x16x32_bf16 v[2:5], v[188:191], v[226:229], v[2:5]
	v_mfma_f32_16x16x32_bf16 v[6:9], v[174:177], v[214:217], v[6:9]
	v_mfma_f32_16x16x32_bf16 v[6:9], v[188:191], v[218:221], v[6:9]
	v_mfma_f32_16x16x32_bf16 v[10:13], v[174:177], v[206:209], v[10:13]
	v_mfma_f32_16x16x32_bf16 v[10:13], v[188:191], v[210:213], v[10:13]
	v_mfma_f32_16x16x32_bf16 v[14:17], v[174:177], v[198:201], v[14:17]
	v_mfma_f32_16x16x32_bf16 v[14:17], v[188:191], v[202:205], v[14:17]
	s_setprio 0
	s_barrier
	s_add_i32 s37, s37, 2
	s_add_u32 s78, s78, 0x100
	s_addc_u32 s79, s79, 0
	s_add_u32 s33, s33, 0x100
	s_addc_u32 s35, s35, 0
	s_cmp_gt_u32 s37, 29
	s_cbranch_scc0 .LBB0_234
	s_branch .Lhob_gi_exit
.Lhob_gi_Thead:
	s_add_u32 s0, s78, 0xfff80080
	s_addc_u32 s1, s79, -1
	s_add_i32 s40, 0, 0x10000
	s_cmp_eq_u32 s37, 28
	s_cselect_b32 s83, s19, s1
	s_cselect_b32 s82, s20, s0
	s_cselect_b32 s81, s24, s35
	s_cselect_b32 s80, s31, s33
	s_add_i32 s41, 0, 0x14000
	ds_read_b128 v[142:145], v168
	ds_read_b128 v[146:149], v168 offset:1024
	ds_read_b128 v[150:153], v168 offset:2048
	ds_read_b128 v[154:157], v168 offset:3072
	ds_read_b128 v[158:161], v168 offset:16384
	ds_read_b128 v[162:165], v168 offset:17408
	ds_read_b128 v[174:177], v168 offset:18432
	ds_read_b128 v[188:191], v168 offset:19456
	s_add_i32 m0, s75, 0xc000
	ds_read_b128 v[198:201], v196
	ds_read_b128 v[202:205], v196 offset:1024
	ds_read_b128 v[206:209], v196 offset:2048
	ds_read_b128 v[210:213], v196 offset:3072
	ds_read_b128 v[214:217], v196 offset:4096
	ds_read_b128 v[218:221], v196 offset:5120
	ds_read_b128 v[222:225], v196 offset:6144
	ds_read_b128 v[226:229], v196 offset:7168
	global_load_lds_dwordx4 v138, s[78:79]
	s_add_i32 m0, s75, 0xe000
	s_nop 0
	global_load_lds_dwordx4 v140, s[78:79]
	s_waitcnt vmcnt(8)
	s_waitcnt lgkmcnt(0)
	s_barrier
; #define PG8_STAGE(bufoff, gbase, voff) do { _Pragma("unroll") for (int _i = 0; _i < 2; ++_i) \
;         __builtin_amdgcn_global_load_lds((const unsigned*)((const char*)(gbase) + (voff)[_i]), (PG8_LAS unsigned*)(lds + (bufoff) + ldsw + _i * 8192), 16, 0, 0); } while (0)
; #define PG8_LDA(dst, b, h) do { _Pragma("unroll") for (int m = 0; m < 4; ++m) _Pragma("unroll") for (int k = 0; k < 2; ++k) dst[m][k] = *(const PG8_LAS bf16x8*)(lds + PG8_SA(b, h) + aoff + m * 2048 + k * 1024); } while (0)
; #define PG8_LDB(dst, b, h) do { _Pragma("unroll") for (int n = 0; n < 2; ++n) _Pragma("unroll") for (int k = 0; k < 2; ++k) dst[n][k] = *(const PG8_LAS bf16x8*)(lds + PG8_SB(b, h) + boff + n * 2048 + k * 1024); } while (0)
; #define PG8_WAIT_V(n) asm volatile("s_waitcnt vmcnt(" #n ")" ::: "memory")
; #define PG8_WAIT_L(n) asm volatile("s_waitcnt lgkmcnt(" #n ")" ::: "memory")
; #define PG8_WAIT_V_SEL(sel) asm volatile("s_cmp_eq_u32 %0, 0\n\ts_cbranch_scc1 .Lw8_%=\n\ts_waitcnt vmcnt(22)\n\ts_branch .Lwd_%=\n.Lw8_%=:\n\ts_waitcnt vmcnt(8)\n.Lwd_%=:" :: "s"(sel) : "memory", "scc")
; #define PG8_BAR __builtin_amdgcn_s_barrier()
; #define PG8_SCHED __builtin_amdgcn_sched_barrier(0)
;     ...
;             PG8_LDB(B0, 0, 0); PG8_LDB(B1, 0, 1); PG8_SCHED; PG8_LDA(At, 0, 0); PG8_STAGE(PG8_SA(1, 1), a1 + hstep, voffA);
;             PG8_WAIT_V_SEL(relax);
;             PG8_WAIT_L(0); PG8_BAR; PG8_MMA(0, 0, At, B0); PG8_MMA(0, 1, At, B1); PG8_BAR; PG8_SCHED;
;             PG8_LDA(At, 0, 1); PG8_STAGE(PG8_SB(0, 0), b2, voffB); PG8_STAGE(PG8_SB(0, 1), b2 + hstep, voffB); PG8_STAGE(PG8_SA(0, 0), a2, voffA);
;             PG8_WAIT_V_SEL(relax);
;             PG8_WAIT_L(0); PG8_BAR; PG8_MMA(1, 0, At, B0); PG8_MMA(1, 1, At, B1); PG8_BAR; PG8_SCHED;
;             PG8_LDB(B0, 1, 0); PG8_LDB(B1, 1, 1); PG8_SCHED; PG8_LDA(At, 1, 0); PG8_STAGE(PG8_SA(0, 1), a2 + hstep, voffA);
;             PG8_WAIT_V(8); PG8_WAIT_L(0); PG8_BAR; PG8_MMA(0, 0, At, B0); PG8_MMA(0, 1, At, B1); PG8_BAR; PG8_SCHED;
	s_setprio 2
	v_mfma_f32_16x16x32_bf16 v[126:129], v[142:145], v[198:201], v[126:129]
	v_mfma_f32_16x16x32_bf16 v[126:129], v[146:149], v[202:205], v[126:129]
	v_mfma_f32_16x16x32_bf16 v[122:125], v[142:145], v[206:209], v[122:125]
	v_mfma_f32_16x16x32_bf16 v[122:125], v[146:149], v[210:213], v[122:125]
	v_mfma_f32_16x16x32_bf16 v[118:121], v[142:145], v[214:217], v[118:121]
	v_mfma_f32_16x16x32_bf16 v[118:121], v[146:149], v[218:221], v[118:121]
	v_mfma_f32_16x16x32_bf16 v[114:117], v[142:145], v[222:225], v[114:117]
	v_mfma_f32_16x16x32_bf16 v[114:117], v[146:149], v[226:229], v[114:117]
	v_mfma_f32_16x16x32_bf16 v[98:101], v[150:153], v[222:225], v[98:101]
	v_mfma_f32_16x16x32_bf16 v[98:101], v[154:157], v[226:229], v[98:101]
	v_mfma_f32_16x16x32_bf16 v[102:105], v[150:153], v[214:217], v[102:105]
	v_mfma_f32_16x16x32_bf16 v[102:105], v[154:157], v[218:221], v[102:105]
	v_mfma_f32_16x16x32_bf16 v[106:109], v[150:153], v[206:209], v[106:109]
	v_mfma_f32_16x16x32_bf16 v[106:109], v[154:157], v[210:213], v[106:109]
	v_mfma_f32_16x16x32_bf16 v[110:113], v[150:153], v[198:201], v[110:113]
	v_mfma_f32_16x16x32_bf16 v[110:113], v[154:157], v[202:205], v[110:113]
	v_mfma_f32_16x16x32_bf16 v[82:85], v[158:161], v[198:201], v[82:85]
	v_mfma_f32_16x16x32_bf16 v[82:85], v[162:165], v[202:205], v[82:85]
	v_mfma_f32_16x16x32_bf16 v[70:73], v[158:161], v[206:209], v[70:73]
	v_mfma_f32_16x16x32_bf16 v[70:73], v[162:165], v[210:213], v[70:73]
	v_mfma_f32_16x16x32_bf16 v[66:69], v[158:161], v[214:217], v[66:69]
	v_mfma_f32_16x16x32_bf16 v[66:69], v[162:165], v[218:221], v[66:69]
	v_mfma_f32_16x16x32_bf16 v[58:61], v[158:161], v[222:225], v[58:61]
	v_mfma_f32_16x16x32_bf16 v[58:61], v[162:165], v[226:229], v[58:61]
	v_mfma_f32_16x16x32_bf16 v[18:21], v[174:177], v[222:225], v[18:21]
	v_mfma_f32_16x16x32_bf16 v[18:21], v[188:191], v[226:229], v[18:21]
	v_mfma_f32_16x16x32_bf16 v[22:25], v[174:177], v[214:217], v[22:25]
	v_mfma_f32_16x16x32_bf16 v[22:25], v[188:191], v[218:221], v[22:25]
	v_mfma_f32_16x16x32_bf16 v[26:29], v[174:177], v[206:209], v[26:29]
	v_mfma_f32_16x16x32_bf16 v[26:29], v[188:191], v[210:213], v[26:29]
	v_mfma_f32_16x16x32_bf16 v[30:33], v[174:177], v[198:201], v[30:33]
	v_mfma_f32_16x16x32_bf16 v[30:33], v[188:191], v[202:205], v[30:33]
	s_setprio 0
	s_add_i32 s0, s40, s87
	s_mov_b32 m0, s0
	ds_read_b128 v[198:201], v196 offset:16384
	ds_read_b128 v[202:205], v196 offset:17408
	ds_read_b128 v[206:209], v196 offset:18432
	ds_read_b128 v[210:213], v196 offset:19456
	ds_read_b128 v[214:217], v196 offset:20480
	ds_read_b128 v[218:221], v196 offset:21504
	ds_read_b128 v[222:225], v196 offset:22528
	ds_read_b128 v[226:229], v196 offset:23552
	global_load_lds_dwordx4 v182, s[80:81]
	s_add_i32 m0, s0, 0x2000
	s_add_u32 s0, s80, 0x80000
	s_addc_u32 s1, s81, 0
	s_add_i32 s40, s41, s87
	global_load_lds_dwordx4 v134, s[80:81]
	s_mov_b32 m0, s40
	s_nop 0
	global_load_lds_dwordx4 v182, s[0:1]
	s_add_i32 m0, s40, 0x2000
	s_nop 0
	global_load_lds_dwordx4 v134, s[0:1]
	s_mov_b32 m0, s75
	s_nop 0
	global_load_lds_dwordx4 v130, s[82:83]
	s_mov_b32 m0, s88
	s_nop 0
	global_load_lds_dwordx4 v132, s[82:83]
	s_waitcnt vmcnt(8)
	s_waitcnt lgkmcnt(0)
	s_barrier
	s_setprio 2
	v_mfma_f32_16x16x32_bf16 v[94:97], v[142:145], v[198:201], v[94:97]
	v_mfma_f32_16x16x32_bf16 v[94:97], v[146:149], v[202:205], v[94:97]
	v_mfma_f32_16x16x32_bf16 v[90:93], v[142:145], v[206:209], v[90:93]
	v_mfma_f32_16x16x32_bf16 v[90:93], v[146:149], v[210:213], v[90:93]
	v_mfma_f32_16x16x32_bf16 v[86:89], v[142:145], v[214:217], v[86:89]
	v_mfma_f32_16x16x32_bf16 v[86:89], v[146:149], v[218:221], v[86:89]
	v_mfma_f32_16x16x32_bf16 v[78:81], v[142:145], v[222:225], v[78:81]
	v_mfma_f32_16x16x32_bf16 v[78:81], v[146:149], v[226:229], v[78:81]
	v_mfma_f32_16x16x32_bf16 v[50:53], v[150:153], v[222:225], v[50:53]
	v_mfma_f32_16x16x32_bf16 v[50:53], v[154:157], v[226:229], v[50:53]
	v_mfma_f32_16x16x32_bf16 v[54:57], v[150:153], v[214:217], v[54:57]
	v_mfma_f32_16x16x32_bf16 v[54:57], v[154:157], v[218:221], v[54:57]
	v_mfma_f32_16x16x32_bf16 v[62:65], v[150:153], v[206:209], v[62:65]
	v_mfma_f32_16x16x32_bf16 v[62:65], v[154:157], v[210:213], v[62:65]
	v_mfma_f32_16x16x32_bf16 v[74:77], v[150:153], v[198:201], v[74:77]
	v_mfma_f32_16x16x32_bf16 v[74:77], v[154:157], v[202:205], v[74:77]
	v_mfma_f32_16x16x32_bf16 v[46:49], v[158:161], v[198:201], v[46:49]
	v_mfma_f32_16x16x32_bf16 v[46:49], v[162:165], v[202:205], v[46:49]
	v_mfma_f32_16x16x32_bf16 v[42:45], v[158:161], v[206:209], v[42:45]
	v_mfma_f32_16x16x32_bf16 v[42:45], v[162:165], v[210:213], v[42:45]
	v_mfma_f32_16x16x32_bf16 v[38:41], v[158:161], v[214:217], v[38:41]
	v_mfma_f32_16x16x32_bf16 v[38:41], v[162:165], v[218:221], v[38:41]
	v_mfma_f32_16x16x32_bf16 v[34:37], v[158:161], v[222:225], v[34:37]
	v_mfma_f32_16x16x32_bf16 v[34:37], v[162:165], v[226:229], v[34:37]
	v_mfma_f32_16x16x32_bf16 v[2:5], v[174:177], v[222:225], v[2:5]
	v_mfma_f32_16x16x32_bf16 v[2:5], v[188:191], v[226:229], v[2:5]
	v_mfma_f32_16x16x32_bf16 v[6:9], v[174:177], v[214:217], v[6:9]
	v_mfma_f32_16x16x32_bf16 v[6:9], v[188:191], v[218:221], v[6:9]
	v_mfma_f32_16x16x32_bf16 v[10:13], v[174:177], v[206:209], v[10:13]
	v_mfma_f32_16x16x32_bf16 v[10:13], v[188:191], v[210:213], v[10:13]
	v_mfma_f32_16x16x32_bf16 v[14:17], v[174:177], v[198:201], v[14:17]
	v_mfma_f32_16x16x32_bf16 v[14:17], v[188:191], v[202:205], v[14:17]
	s_setprio 0
	s_add_i32 s40, 0, 0x18000
	s_add_i32 s41, 0, 0x1c000
	ds_read_b128 v[142:145], v168 offset:32768
	ds_read_b128 v[146:149], v168 offset:33792
	ds_read_b128 v[150:153], v168 offset:34816
	ds_read_b128 v[154:157], v168 offset:35840
	ds_read_b128 v[158:161], v168 offset:49152
	ds_read_b128 v[162:165], v168 offset:50176
	ds_read_b128 v[174:177], v168 offset:51200
	ds_read_b128 v[188:191], v168 offset:52224
	s_add_u32 s0, s82, 0x80000
	s_addc_u32 s1, s83, 0
	s_mov_b32 m0, s89
	ds_read_b128 v[198:201], v196 offset:32768
	ds_read_b128 v[202:205], v196 offset:33792
	ds_read_b128 v[206:209], v196 offset:34816
	ds_read_b128 v[210:213], v196 offset:35840
	ds_read_b128 v[214:217], v196 offset:36864
	ds_read_b128 v[218:221], v196 offset:37888
	ds_read_b128 v[222:225], v196 offset:38912
	ds_read_b128 v[226:229], v196 offset:39936
	global_load_lds_dwordx4 v130, s[0:1]
	s_mov_b32 m0, s90
	s_nop 0
	global_load_lds_dwordx4 v132, s[0:1]
	s_waitcnt vmcnt(8)
	s_waitcnt lgkmcnt(0)
	s_barrier
; #define PG8_STAGE(bufoff, gbase, voff) do { _Pragma("unroll") for (int _i = 0; _i < 2; ++_i) \
;         __builtin_amdgcn_global_load_lds((const unsigned*)((const char*)(gbase) + (voff)[_i]), (PG8_LAS unsigned*)(lds + (bufoff) + ldsw + _i * 8192), 16, 0, 0); } while (0)
; #define PG8_LDA(dst, b, h) do { _Pragma("unroll") for (int m = 0; m < 4; ++m) _Pragma("unroll") for (int k = 0; k < 2; ++k) dst[m][k] = *(const PG8_LAS bf16x8*)(lds + PG8_SA(b, h) + aoff + m * 2048 + k * 1024); } while (0)
; #define PG8_LDB(dst, b, h) do { _Pragma("unroll") for (int n = 0; n < 2; ++n) _Pragma("unroll") for (int k = 0; k < 2; ++k) dst[n][k] = *(const PG8_LAS bf16x8*)(lds + PG8_SB(b, h) + boff + n * 2048 + k * 1024); } while (0)
; #define PG8_WAIT_V(n) asm volatile("s_waitcnt vmcnt(" #n ")" ::: "memory")
; #define PG8_WAIT_L(n) asm volatile("s_waitcnt lgkmcnt(" #n ")" ::: "memory")
; #define PG8_BAR __builtin_amdgcn_s_barrier()
; #define PG8_SCHED __builtin_amdgcn_sched_barrier(0)
;     ...
;             PG8_LDB(B0, 1, 0); PG8_LDB(B1, 1, 1); PG8_SCHED; PG8_LDA(At, 1, 0); PG8_STAGE(PG8_SA(0, 1), a2 + hstep, voffA);
;             PG8_WAIT_V(8); PG8_WAIT_L(0); PG8_BAR; PG8_MMA(0, 0, At, B0); PG8_MMA(0, 1, At, B1); PG8_BAR; PG8_SCHED;
;             PG8_LDA(At, 1, 1); PG8_STAGE(PG8_SB(1, 0), b3, voffB); PG8_STAGE(PG8_SB(1, 1), b3 + hstep, voffB); PG8_STAGE(PG8_SA(1, 0), a3, voffA);
;             PG8_WAIT_V(8); PG8_WAIT_L(0); PG8_BAR; PG8_MMA(1, 0, At, B0); PG8_MMA(1, 1, At, B1); PG8_BAR; PG8_SCHED;
;     ...
;         if constexpr (ALIGN_EPI) { if (wr == 0) PG8_BAR; }
	s_setprio 2
	v_mfma_f32_16x16x32_bf16 v[126:129], v[142:145], v[198:201], v[126:129]
	v_mfma_f32_16x16x32_bf16 v[126:129], v[146:149], v[202:205], v[126:129]
	v_mfma_f32_16x16x32_bf16 v[122:125], v[142:145], v[206:209], v[122:125]
	v_mfma_f32_16x16x32_bf16 v[122:125], v[146:149], v[210:213], v[122:125]
	v_mfma_f32_16x16x32_bf16 v[118:121], v[142:145], v[214:217], v[118:121]
	v_mfma_f32_16x16x32_bf16 v[118:121], v[146:149], v[218:221], v[118:121]
	v_mfma_f32_16x16x32_bf16 v[114:117], v[142:145], v[222:225], v[114:117]
	v_mfma_f32_16x16x32_bf16 v[114:117], v[146:149], v[226:229], v[114:117]
	v_mfma_f32_16x16x32_bf16 v[98:101], v[150:153], v[222:225], v[98:101]
	v_mfma_f32_16x16x32_bf16 v[98:101], v[154:157], v[226:229], v[98:101]
	v_mfma_f32_16x16x32_bf16 v[102:105], v[150:153], v[214:217], v[102:105]
	v_mfma_f32_16x16x32_bf16 v[102:105], v[154:157], v[218:221], v[102:105]
	v_mfma_f32_16x16x32_bf16 v[106:109], v[150:153], v[206:209], v[106:109]
	v_mfma_f32_16x16x32_bf16 v[106:109], v[154:157], v[210:213], v[106:109]
	v_mfma_f32_16x16x32_bf16 v[110:113], v[150:153], v[198:201], v[110:113]
	v_mfma_f32_16x16x32_bf16 v[110:113], v[154:157], v[202:205], v[110:113]
	v_mfma_f32_16x16x32_bf16 v[82:85], v[158:161], v[198:201], v[82:85]
	v_mfma_f32_16x16x32_bf16 v[82:85], v[162:165], v[202:205], v[82:85]
	v_mfma_f32_16x16x32_bf16 v[70:73], v[158:161], v[206:209], v[70:73]
	v_mfma_f32_16x16x32_bf16 v[70:73], v[162:165], v[210:213], v[70:73]
	v_mfma_f32_16x16x32_bf16 v[66:69], v[158:161], v[214:217], v[66:69]
	v_mfma_f32_16x16x32_bf16 v[66:69], v[162:165], v[218:221], v[66:69]
	v_mfma_f32_16x16x32_bf16 v[58:61], v[158:161], v[222:225], v[58:61]
	v_mfma_f32_16x16x32_bf16 v[58:61], v[162:165], v[226:229], v[58:61]
	v_mfma_f32_16x16x32_bf16 v[18:21], v[174:177], v[222:225], v[18:21]
	v_mfma_f32_16x16x32_bf16 v[18:21], v[188:191], v[226:229], v[18:21]
	v_mfma_f32_16x16x32_bf16 v[22:25], v[174:177], v[214:217], v[22:25]
	v_mfma_f32_16x16x32_bf16 v[22:25], v[188:191], v[218:221], v[22:25]
	v_mfma_f32_16x16x32_bf16 v[26:29], v[174:177], v[206:209], v[26:29]
	v_mfma_f32_16x16x32_bf16 v[26:29], v[188:191], v[210:213], v[26:29]
	v_mfma_f32_16x16x32_bf16 v[30:33], v[174:177], v[198:201], v[30:33]
	v_mfma_f32_16x16x32_bf16 v[30:33], v[188:191], v[202:205], v[30:33]
	s_setprio 0
	s_add_i32 s0, s40, s87
	s_mov_b32 m0, s0
	ds_read_b128 v[198:201], v196 offset:49152
	ds_read_b128 v[202:205], v196 offset:50176
	ds_read_b128 v[206:209], v196 offset:51200
	ds_read_b128 v[210:213], v196 offset:52224
	ds_read_b128 v[214:217], v196 offset:53248
	ds_read_b128 v[218:221], v196 offset:54272
	ds_read_b128 v[222:225], v196 offset:55296
	ds_read_b128 v[226:229], v196 offset:56320
	s_add_u32 s100, s80, 0x80
	s_addc_u32 s101, s81, 0
	global_load_lds_dwordx4 v182, s[100:101]
	s_add_i32 m0, s0, 0x2000
	s_add_u32 s0, s80, 0x80080
	s_addc_u32 s1, s81, 0
	s_add_i32 s40, s41, s87
	global_load_lds_dwordx4 v134, s[100:101]
	s_mov_b32 m0, s40
	s_nop 0
	global_load_lds_dwordx4 v182, s[0:1]
	s_add_i32 m0, s40, 0x2000
	s_nop 0
	global_load_lds_dwordx4 v134, s[0:1]
	s_mov_b32 m0, s94
	s_nop 0
	s_add_u32 s100, s82, 0x80
	s_addc_u32 s101, s83, 0
	global_load_lds_dwordx4 v130, s[100:101]
	s_mov_b32 m0, s95
	s_nop 0
	global_load_lds_dwordx4 v132, s[100:101]
	s_waitcnt vmcnt(8)
	s_waitcnt lgkmcnt(0)
	s_barrier
	s_setprio 2
	v_mfma_f32_16x16x32_bf16 v[94:97], v[142:145], v[198:201], v[94:97]
	v_mfma_f32_16x16x32_bf16 v[94:97], v[146:149], v[202:205], v[94:97]
	v_mfma_f32_16x16x32_bf16 v[90:93], v[142:145], v[206:209], v[90:93]
	v_mfma_f32_16x16x32_bf16 v[90:93], v[146:149], v[210:213], v[90:93]
	v_mfma_f32_16x16x32_bf16 v[86:89], v[142:145], v[214:217], v[86:89]
	v_mfma_f32_16x16x32_bf16 v[86:89], v[146:149], v[218:221], v[86:89]
	v_mfma_f32_16x16x32_bf16 v[78:81], v[142:145], v[222:225], v[78:81]
	v_mfma_f32_16x16x32_bf16 v[78:81], v[146:149], v[226:229], v[78:81]
	v_mfma_f32_16x16x32_bf16 v[50:53], v[150:153], v[222:225], v[50:53]
	v_mfma_f32_16x16x32_bf16 v[50:53], v[154:157], v[226:229], v[50:53]
	v_mfma_f32_16x16x32_bf16 v[54:57], v[150:153], v[214:217], v[54:57]
	v_mfma_f32_16x16x32_bf16 v[54:57], v[154:157], v[218:221], v[54:57]
	v_mfma_f32_16x16x32_bf16 v[62:65], v[150:153], v[206:209], v[62:65]
	v_mfma_f32_16x16x32_bf16 v[62:65], v[154:157], v[210:213], v[62:65]
	v_mfma_f32_16x16x32_bf16 v[74:77], v[150:153], v[198:201], v[74:77]
	v_mfma_f32_16x16x32_bf16 v[74:77], v[154:157], v[202:205], v[74:77]
	v_mfma_f32_16x16x32_bf16 v[46:49], v[158:161], v[198:201], v[46:49]
	v_mfma_f32_16x16x32_bf16 v[46:49], v[162:165], v[202:205], v[46:49]
	v_mfma_f32_16x16x32_bf16 v[42:45], v[158:161], v[206:209], v[42:45]
	v_mfma_f32_16x16x32_bf16 v[42:45], v[162:165], v[210:213], v[42:45]
	v_mfma_f32_16x16x32_bf16 v[38:41], v[158:161], v[214:217], v[38:41]
	v_mfma_f32_16x16x32_bf16 v[38:41], v[162:165], v[218:221], v[38:41]
	v_mfma_f32_16x16x32_bf16 v[34:37], v[158:161], v[222:225], v[34:37]
	v_mfma_f32_16x16x32_bf16 v[34:37], v[162:165], v[226:229], v[34:37]
	v_mfma_f32_16x16x32_bf16 v[2:5], v[174:177], v[222:225], v[2:5]
	v_mfma_f32_16x16x32_bf16 v[2:5], v[188:191], v[226:229], v[2:5]
	v_mfma_f32_16x16x32_bf16 v[6:9], v[174:177], v[214:217], v[6:9]
	v_mfma_f32_16x16x32_bf16 v[6:9], v[188:191], v[218:221], v[6:9]
	v_mfma_f32_16x16x32_bf16 v[10:13], v[174:177], v[206:209], v[10:13]
	v_mfma_f32_16x16x32_bf16 v[10:13], v[188:191], v[210:213], v[10:13]
	v_mfma_f32_16x16x32_bf16 v[14:17], v[174:177], v[198:201], v[14:17]
	v_mfma_f32_16x16x32_bf16 v[14:17], v[188:191], v[202:205], v[14:17]
	s_setprio 0
	s_add_i32 s37, s37, 2
	s_add_u32 s78, s78, 0x100
	s_addc_u32 s79, s79, 0
	s_add_u32 s33, s33, 0x100
	s_addc_u32 s35, s35, 0
	s_cmp_gt_u32 s37, 29
	s_cbranch_scc0 .Lhob_gi_Thead
	s_branch .Lhob_gi_exit
.Lhob_gi_exit:
	s_and_b64 vcc, exec, s[64:65]
	s_cbranch_vccz .LBB0_237
	s_setprio 0

; #define PG8_BAR __builtin_amdgcn_s_barrier()
;     ...
;         cur = nxt; cA = nA; cB = nB; ++ui;
;         if constexpr (ALIGN_EPI) { if (wr == 1) PG8_BAR; }
.LBB0_247:
	s_setprio 0
	s_branch .LBB0_225

; #define PG8_STAGE(bufoff, gbase, voff) do { _Pragma("unroll") for (int _i = 0; _i < 2; ++_i) \
;         __builtin_amdgcn_global_load_lds((const unsigned*)((const char*)(gbase) + (voff)[_i]), (PG8_LAS unsigned*)(lds + (bufoff) + ldsw + _i * 8192), 16, 0, 0); } while (0)
; #define PG8_BAR __builtin_amdgcn_s_barrier()
;     ...
;     for (int i = 0; i < 2; ++i) { int R, C; stage_rc(tid * 16 + i * 8192, R, C); const int Rb = Epi::PERM ? ((R & ~31) + perm32(R & 31)) : R;
;         const int Ra = Epi::PERMROW ? ((R & ~63) + 4 * (R & 15) + ((R >> 4) & 3)) : R;
;         voffA[i] = (unsigned)(Ra * K + C) * 2u; voffB[i] = (unsigned)(Rb * K + C) * 2u; }
;     ...
;         PG8_STAGE(PG8_SB(0, 0), cB, voffB); PG8_STAGE(PG8_SB(0, 1), cB + hstep, voffB); PG8_STAGE(PG8_SA(0, 0), cA, voffA); PG8_STAGE(PG8_SA(0, 1), cA + hstep, voffA);
;         if (wr == 1) PG8_BAR;
.LBB0_529:
	v_ashrrev_i32_e32 v3, 31, v11
	v_lshrrev_b32_e32 v3, 26, v3
	v_add_u32_e32 v3, v11, v3
	v_ashrrev_i32_e32 v12, 6, v3
	v_bfe_i32 v3, v11, 27, 1
	v_lshlrev_b32_e32 v2, 4, v11
	v_lshrrev_b32_e32 v3, 22, v3
	v_add_u32_e32 v3, v2, v3
	v_and_b32_e32 v3, 0xfffffc00, v3
	v_sub_u32_e32 v3, v2, v3
	v_lshrrev_b32_e32 v4, 4, v3
	v_bitop3_b32 v4, v4, v3, 32 bitop3:0x6c
	v_ashrrev_i32_e32 v3, 31, v3
	v_lshrrev_b32_e32 v3, 26, v3
	v_add_u32_e32 v3, v4, v3
	v_ashrrev_i32_e32 v13, 6, v3
	v_lshlrev_b32_e32 v5, 3, v12
	v_mul_i32_i24_e32 v6, 64, v13
	v_and_b32_e32 v5, -16, v5
	v_sub_u32_e32 v4, v4, v6
	v_add_u32_e32 v3, v13, v5
	v_lshlrev_b32_e32 v5, 5, v12
	v_ashrrev_i16_sdwa v4, v235, sext(v4) dst_sel:DWORD dst_unused:UNUSED_PAD src0_sel:DWORD src1_sel:BYTE_0
	v_and_b32_e32 v5, 32, v5
	v_bfe_i32 v14, v4, 0, 16
	v_and_b32_e32 v7, 3, v13
	s_mov_b32 s1, 0xfffe0
	v_add_lshl_u32 v5, v5, v14, 1
	v_add_u32_e32 v2, 0x2000, v2
	v_lshlrev_b32_e32 v4, 1, v3
	v_lshrrev_b32_e32 v6, 2, v3
	v_and_or_b32 v7, v3, s1, v7
	v_lshl_add_u32 v174, v3, 12, v5
	v_ashrrev_i32_e32 v3, 31, v2
	v_lshrrev_b32_e32 v3, 22, v3
	v_add_u32_e32 v3, v2, v3
	v_ashrrev_i32_e32 v15, 10, v3
	v_mul_i32_i24_e32 v3, 0x400, v15
	v_sub_u32_e32 v2, v2, v3
	v_and_b32_e32 v4, 24, v4
	v_and_b32_e32 v6, 4, v6
	v_lshrrev_b32_e32 v3, 4, v2
	v_or3_b32 v4, v7, v6, v4
	v_bitop3_b32 v2, v3, v2, 32 bitop3:0x6c
	v_lshl_add_u32 v182, v4, 12, v5
	v_ashrrev_i32_e32 v4, 31, v2
	v_lshrrev_b32_e32 v4, 26, v4
	v_lshlrev_b32_e32 v3, 3, v15
	v_add_u32_e32 v4, v2, v4
	v_writelane_b32 v255, s37, 35
	v_and_b32_e32 v3, -16, v3
	v_ashrrev_i32_e32 v16, 6, v4
	v_writelane_b32 v255, s35, 36
	v_add_u32_e32 v3, v16, v3
	v_and_b32_e32 v6, 3, v16
	v_writelane_b32 v255, s51, 37
	v_and_or_b32 v6, v3, s1, v6
	s_ashr_i32 s1, s0, 8
	s_lshl_b32 s30, s3, 10
	s_mov_b32 s4, s82
	s_add_u32 s31, s12, 0x18000000
	v_writelane_b32 v255, s4, 33
	s_addc_u32 s33, s13, 0
	v_and_b32_e32 v4, 0xc0, v4
	v_writelane_b32 v255, s5, 34
	s_lshl_b32 s4, s82, 23
	s_add_u32 s4, s12, s4
	s_addc_u32 s5, s13, 0
	s_add_u32 s35, s4, 0x6e00000
	s_addc_u32 s37, s5, 0
	s_ashr_i32 s81, s80, 31
	s_ashr_i32 s79, s78, 31
	v_sub_u32_e32 v2, v2, v4
	s_lshl_b64 s[4:5], s[80:81], 20
	s_lshl_b64 s[6:7], s[78:79], 20
	v_ashrrev_i16_sdwa v2, v235, sext(v2) dst_sel:DWORD dst_unused:UNUSED_PAD src0_sel:DWORD src1_sel:BYTE_0
	s_add_u32 s84, s35, s6
	v_lshlrev_b32_e32 v5, 5, v15
	v_bfe_i32 v17, v2, 0, 16
	v_lshlrev_b32_e32 v2, 1, v3
	v_lshrrev_b32_e32 v4, 2, v3
	s_addc_u32 s85, s37, s7
	s_add_i32 s44, s30, 0
	v_and_b32_e32 v5, 32, v5
	v_and_b32_e32 v2, 24, v2
	v_and_b32_e32 v4, 4, v4
	s_add_i32 m0, s44, 0x10000
	v_or3_b32 v2, v6, v4, v2
	v_add_lshl_u32 v4, v5, v17, 1
	global_load_lds_dwordx4 v182, s[84:85]
	s_add_i32 m0, s44, 0x12000
	v_lshl_add_u32 v178, v2, 12, v4
	s_add_u32 s6, s84, 0x80000
	global_load_lds_dwordx4 v178, s[84:85]
	s_addc_u32 s7, s85, 0
	s_add_i32 m0, s44, 0x14000
	v_lshl_add_u32 v176, v3, 12, v4
	global_load_lds_dwordx4 v182, s[6:7]
	s_add_i32 m0, s44, 0x16000
	s_add_u32 s82, s31, s4
	s_addc_u32 s83, s33, s5
	s_add_i32 s45, s44, 0x2000
	global_load_lds_dwordx4 v178, s[6:7]
	s_mov_b32 m0, s44
	s_add_u32 s4, s82, 0x80000
	global_load_lds_dwordx4 v174, s[82:83]
	s_mov_b32 m0, s45
	s_addc_u32 s5, s83, 0
	s_add_i32 s46, s44, 0x4000
	global_load_lds_dwordx4 v176, s[82:83]
	s_mov_b32 m0, s46
	s_add_i32 s47, s44, 0x6000
	global_load_lds_dwordx4 v174, s[4:5]
	s_mov_b32 m0, s47
	v_mov_b32_e32 v179, v183
	global_load_lds_dwordx4 v176, s[4:5]
	v_mov_b32_e32 v175, v183
	v_mov_b32_e32 v177, v183
	s_cmp_eq_u32 s1, 1
	v_lshl_add_u64 v[8:9], s[84:85], 0, v[182:183]
	v_lshl_add_u64 v[6:7], s[84:85], 0, v[178:179]
	v_lshl_add_u64 v[2:3], s[82:83], 0, v[174:175]
	s_cselect_b64 s[60:61], -1, 0
	s_cmp_lg_u32 s1, 1
	v_lshl_add_u64 v[4:5], s[82:83], 0, v[176:177]
	s_cbranch_scc1 .LBB0_531
	s_setprio 0

; #define PG8_STAGE(bufoff, gbase, voff) do { _Pragma("unroll") for (int _i = 0; _i < 2; ++_i) \
;         __builtin_amdgcn_global_load_lds((const unsigned*)((const char*)(gbase) + (voff)[_i]), (PG8_LAS unsigned*)(lds + (bufoff) + ldsw + _i * 8192), 16, 0, 0); } while (0)
; #define PG8_LDA(dst, b, h) do { _Pragma("unroll") for (int m = 0; m < 4; ++m) _Pragma("unroll") for (int k = 0; k < 2; ++k) dst[m][k] = *(const PG8_LAS bf16x8*)(lds + PG8_SA(b, h) + aoff + m * 2048 + k * 1024); } while (0)
; #define PG8_LDB(dst, b, h) do { _Pragma("unroll") for (int n = 0; n < 2; ++n) _Pragma("unroll") for (int k = 0; k < 2; ++k) dst[n][k] = *(const PG8_LAS bf16x8*)(lds + PG8_SB(b, h) + boff + n * 2048 + k * 1024); } while (0)
; #define PG8_WAIT_L(n) asm volatile("s_waitcnt lgkmcnt(" #n ")" ::: "memory")
; #define PG8_WAIT_V_SEL(sel) asm volatile("s_cmp_eq_u32 %0, 0\n\ts_cbranch_scc1 .Lw8_%=\n\ts_waitcnt vmcnt(22)\n\ts_branch .Lwd_%=\n.Lw8_%=:\n\ts_waitcnt vmcnt(8)\n.Lwd_%=:" :: "s"(sel) : "memory", "scc")
; #define PG8_BAR __builtin_amdgcn_s_barrier()
; #define PG8_SCHED __builtin_amdgcn_sched_barrier(0)
;     ...
;         for (int t = 0; t < nt * KREP; t += 2) {
;             const bool last = (t == nt * KREP - 2);
;             const int t1w = KREP > 1 ? ((t + 1) & (nt - 1)) : t + 1, t2w = KREP > 1 ? ((t + 2) & (nt - 1)) : t + 2;
;             const char* a1 = cA + (size_t)t1w * kstep;
;             const char* a2 = last ? nA : cA + (size_t)t2w * kstep; const char* b2 = last ? nB : cB + (size_t)t2w * kstep;
;             const char* a3 = a2 + kstep; const char* b3 = b2 + kstep;
;             if (last && has_next) S.a_ready(nxt);
;             const int relax = __builtin_amdgcn_readfirstlane((MK_RELAXW && t == 0 && ui > 0) ? 1 : 0);
;             if constexpr (SP2) {
;             PG8_LDB(B0, 0, 0); PG8_LDB(B1, 0, 1); PG8_SCHED; PG8_LDA(At, 0, 0); PG8_STAGE(PG8_SA(1, 1), a1 + hstep, voffA);
;             PG8_WAIT_V_SEL(relax);
;             PG8_WAIT_L(0); PG8_BAR; PG8_MMA(0, 0, At, B0); PG8_MMA(0, 1, At, B1); PG8_BAR; PG8_SCHED;
;     ...
; #pragma unroll
;         for (int a = 0; a < 2; ++a)
; #pragma unroll
;             for (int b = 0; b < 2; ++b)
; #pragma unroll
;                 for (int m = 0; m < 4; ++m)
; #pragma unroll
;                     for (int n = 0; n < 2; ++n) acc[a][b][m][n] = (f32x4){0.f, 0.f, 0.f, 0.f};
;         cur = nxt; cA = nA; cB = nB; ++ui;
.LBB0_540:
	s_ashr_i32 s73, s72, 31
	s_lshl_b64 s[0:1], s[72:73], 20
	s_add_u32 s74, s31, s0
	s_addc_u32 s75, s33, s1
	s_and_b64 s[0:1], s[6:7], exec
	s_cselect_b32 s40, s75, s83
	s_cselect_b32 s41, s74, s82
	s_ashr_i32 s71, s70, 31
	s_lshl_b64 s[0:1], s[70:71], 20
	s_add_u32 s76, s35, s0
	s_addc_u32 s77, s37, s1
	s_and_b64 s[0:1], s[6:7], exec
	s_cselect_b32 s57, s77, s85
	s_cselect_b32 s58, s76, s84
	s_add_u32 s82, s82, 0x80080
	s_addc_u32 s83, s83, 0
	s_add_u32 s59, s84, 0x100
	v_mov_b64_e32 v[2:3], 0
	v_mov_b64_e32 v[4:5], 0
	v_mov_b64_e32 v[6:7], 0
	v_mov_b64_e32 v[8:9], 0
	v_mov_b64_e32 v[10:11], 0
	v_mov_b64_e32 v[12:13], 0
	v_mov_b64_e32 v[14:15], 0
	v_mov_b64_e32 v[16:17], 0
	v_mov_b64_e32 v[18:19], 0
	v_mov_b64_e32 v[20:21], 0
	v_mov_b64_e32 v[22:23], 0
	v_mov_b64_e32 v[24:25], 0
	v_mov_b64_e32 v[26:27], 0
	v_mov_b64_e32 v[28:29], 0
	v_mov_b64_e32 v[30:31], 0
	v_mov_b64_e32 v[32:33], 0
	v_mov_b64_e32 v[34:35], 0
	v_mov_b64_e32 v[36:37], 0
	v_mov_b64_e32 v[38:39], 0
	v_mov_b64_e32 v[40:41], 0
	v_mov_b64_e32 v[42:43], 0
	v_mov_b64_e32 v[44:45], 0
	v_mov_b64_e32 v[46:47], 0
	v_mov_b64_e32 v[48:49], 0
	v_mov_b64_e32 v[50:51], 0
	v_mov_b64_e32 v[52:53], 0
	v_mov_b64_e32 v[54:55], 0
	v_mov_b64_e32 v[56:57], 0
	v_mov_b64_e32 v[58:59], 0
	v_mov_b64_e32 v[60:61], 0
	v_mov_b64_e32 v[62:63], 0
	v_mov_b64_e32 v[64:65], 0
	v_mov_b64_e32 v[66:67], 0
	v_mov_b64_e32 v[68:69], 0
	v_mov_b64_e32 v[70:71], 0
	v_mov_b64_e32 v[72:73], 0
	v_mov_b64_e32 v[74:75], 0
	v_mov_b64_e32 v[76:77], 0
	v_mov_b64_e32 v[78:79], 0
	v_mov_b64_e32 v[80:81], 0
	v_mov_b64_e32 v[82:83], 0
	v_mov_b64_e32 v[84:85], 0
	v_mov_b64_e32 v[86:87], 0
	v_mov_b64_e32 v[88:89], 0
	v_mov_b64_e32 v[106:107], 0
	v_mov_b64_e32 v[108:109], 0
	v_mov_b64_e32 v[110:111], 0
	v_mov_b64_e32 v[112:113], 0
	v_mov_b64_e32 v[114:115], 0
	v_mov_b64_e32 v[116:117], 0
	v_mov_b64_e32 v[118:119], 0
	v_mov_b64_e32 v[120:121], 0
	v_mov_b64_e32 v[122:123], 0
	v_mov_b64_e32 v[124:125], 0
	v_mov_b64_e32 v[126:127], 0
	v_mov_b64_e32 v[128:129], 0
	v_mov_b64_e32 v[130:131], 0
	v_mov_b64_e32 v[132:133], 0
	v_mov_b64_e32 v[134:135], 0
	v_mov_b64_e32 v[136:137], 0
	v_mov_b64_e32 v[138:139], 0
	v_mov_b64_e32 v[140:141], 0
	v_mov_b64_e32 v[142:143], 0
	v_mov_b64_e32 v[144:145], 0
	s_addc_u32 s71, s85, 0
	s_mov_b32 s73, -2
	s_waitcnt lgkmcnt(0)
	v_add_u32_e32 v210, 0x10000, v227
	s_cmp_lg_u32 s68, 0
	s_cbranch_scc0 .Lhob_go_Thead
.LBB0_541:
	s_add_u32 s0, s82, 0xfff80080
	s_addc_u32 s1, s83, -1
	s_add_i32 s79, 0, 0x10000
	s_cmp_eq_u32 s73, 28
	s_cselect_b32 s87, s40, s1
	s_cselect_b32 s86, s41, s0
	s_cselect_b32 s85, s57, s71
	s_cselect_b32 s84, s58, s59
	s_add_i32 s81, 0, 0x14000
	ds_read_b128 v[90:93], v210
	ds_read_b128 v[94:97], v210 offset:1024
	ds_read_b128 v[98:101], v210 offset:2048
	ds_read_b128 v[102:105], v210 offset:3072
	ds_read_b128 v[146:149], v210 offset:16384
	ds_read_b128 v[150:153], v210 offset:17408
	ds_read_b128 v[154:157], v210 offset:18432
	ds_read_b128 v[158:161], v210 offset:19456
	s_add_i32 m0, s44, 0xc000
	ds_read_b128 v[162:165], v230
	ds_read_b128 v[166:169], v230 offset:1024
	ds_read_b128 v[184:187], v230 offset:2048
	ds_read_b128 v[190:193], v230 offset:3072
	ds_read_b128 v[194:197], v230 offset:4096
	ds_read_b128 v[198:201], v230 offset:5120
	ds_read_b128 v[202:205], v230 offset:6144
	ds_read_b128 v[206:209], v230 offset:7168
	global_load_lds_dwordx4 v180, s[82:83]
	s_add_i32 m0, s44, 0xe000
	s_nop 0
	global_load_lds_dwordx4 v188, s[82:83]
	s_waitcnt vmcnt(8)
	s_waitcnt lgkmcnt(0)
	s_setprio 1
	v_mfma_f32_16x16x32_bf16 v[142:145], v[90:93], v[162:165], v[142:145]
	v_mfma_f32_16x16x32_bf16 v[142:145], v[94:97], v[166:169], v[142:145]
	v_mfma_f32_16x16x32_bf16 v[126:129], v[90:93], v[184:187], v[126:129]
	v_mfma_f32_16x16x32_bf16 v[126:129], v[94:97], v[190:193], v[126:129]
	v_mfma_f32_16x16x32_bf16 v[110:113], v[90:93], v[194:197], v[110:113]
	v_mfma_f32_16x16x32_bf16 v[110:113], v[94:97], v[198:201], v[110:113]
	v_mfma_f32_16x16x32_bf16 v[78:81], v[90:93], v[202:205], v[78:81]
	v_mfma_f32_16x16x32_bf16 v[78:81], v[94:97], v[206:209], v[78:81]
	v_mfma_f32_16x16x32_bf16 v[74:77], v[98:101], v[202:205], v[74:77]
	v_mfma_f32_16x16x32_bf16 v[74:77], v[102:105], v[206:209], v[74:77]
	v_mfma_f32_16x16x32_bf16 v[106:109], v[98:101], v[194:197], v[106:109]
	v_mfma_f32_16x16x32_bf16 v[106:109], v[102:105], v[198:201], v[106:109]
	v_mfma_f32_16x16x32_bf16 v[122:125], v[98:101], v[184:187], v[122:125]
	v_mfma_f32_16x16x32_bf16 v[122:125], v[102:105], v[190:193], v[122:125]
	v_mfma_f32_16x16x32_bf16 v[138:141], v[98:101], v[162:165], v[138:141]
	v_mfma_f32_16x16x32_bf16 v[138:141], v[102:105], v[166:169], v[138:141]
	v_mfma_f32_16x16x32_bf16 v[134:137], v[146:149], v[162:165], v[134:137]
	v_mfma_f32_16x16x32_bf16 v[134:137], v[150:153], v[166:169], v[134:137]
	v_mfma_f32_16x16x32_bf16 v[118:121], v[146:149], v[184:187], v[118:121]
	v_mfma_f32_16x16x32_bf16 v[118:121], v[150:153], v[190:193], v[118:121]
	v_mfma_f32_16x16x32_bf16 v[86:89], v[146:149], v[194:197], v[86:89]
	v_mfma_f32_16x16x32_bf16 v[86:89], v[150:153], v[198:201], v[86:89]
	v_mfma_f32_16x16x32_bf16 v[70:73], v[146:149], v[202:205], v[70:73]
	v_mfma_f32_16x16x32_bf16 v[70:73], v[150:153], v[206:209], v[70:73]
	v_mfma_f32_16x16x32_bf16 v[66:69], v[154:157], v[202:205], v[66:69]
	v_mfma_f32_16x16x32_bf16 v[66:69], v[158:161], v[206:209], v[66:69]
	v_mfma_f32_16x16x32_bf16 v[82:85], v[154:157], v[194:197], v[82:85]
	v_mfma_f32_16x16x32_bf16 v[82:85], v[158:161], v[198:201], v[82:85]
	v_mfma_f32_16x16x32_bf16 v[114:117], v[154:157], v[184:187], v[114:117]
	v_mfma_f32_16x16x32_bf16 v[114:117], v[158:161], v[190:193], v[114:117]
	v_mfma_f32_16x16x32_bf16 v[130:133], v[154:157], v[162:165], v[130:133]
	v_mfma_f32_16x16x32_bf16 v[130:133], v[158:161], v[166:169], v[130:133]
	s_setprio 0
	s_barrier
; #define PG8_STAGE(bufoff, gbase, voff) do { _Pragma("unroll") for (int _i = 0; _i < 2; ++_i) \
;         __builtin_amdgcn_global_load_lds((const unsigned*)((const char*)(gbase) + (voff)[_i]), (PG8_LAS unsigned*)(lds + (bufoff) + ldsw + _i * 8192), 16, 0, 0); } while (0)
; #define PG8_LDA(dst, b, h) do { _Pragma("unroll") for (int m = 0; m < 4; ++m) _Pragma("unroll") for (int k = 0; k < 2; ++k) dst[m][k] = *(const PG8_LAS bf16x8*)(lds + PG8_SA(b, h) + aoff + m * 2048 + k * 1024); } while (0)
; #define PG8_LDB(dst, b, h) do { _Pragma("unroll") for (int n = 0; n < 2; ++n) _Pragma("unroll") for (int k = 0; k < 2; ++k) dst[n][k] = *(const PG8_LAS bf16x8*)(lds + PG8_SB(b, h) + boff + n * 2048 + k * 1024); } while (0)
; #define PG8_WAIT_V(n) asm volatile("s_waitcnt vmcnt(" #n ")" ::: "memory")
; #define PG8_WAIT_L(n) asm volatile("s_waitcnt lgkmcnt(" #n ")" ::: "memory")
; #define PG8_WAIT_V_SEL(sel) asm volatile("s_cmp_eq_u32 %0, 0\n\ts_cbranch_scc1 .Lw8_%=\n\ts_waitcnt vmcnt(22)\n\ts_branch .Lwd_%=\n.Lw8_%=:\n\ts_waitcnt vmcnt(8)\n.Lwd_%=:" :: "s"(sel) : "memory", "scc")
; #define PG8_BAR __builtin_amdgcn_s_barrier()
; #define PG8_SCHED __builtin_amdgcn_sched_barrier(0)
;     ...
;             PG8_LDA(At, 0, 1); PG8_STAGE(PG8_SB(0, 0), b2, voffB); PG8_STAGE(PG8_SB(0, 1), b2 + hstep, voffB); PG8_STAGE(PG8_SA(0, 0), a2, voffA);
;             PG8_WAIT_V_SEL(relax);
;             PG8_WAIT_L(0); PG8_BAR; PG8_MMA(1, 0, At, B0); PG8_MMA(1, 1, At, B1); PG8_BAR; PG8_SCHED;
;             PG8_LDB(B0, 1, 0); PG8_LDB(B1, 1, 1); PG8_SCHED; PG8_LDA(At, 1, 0); PG8_STAGE(PG8_SA(0, 1), a2 + hstep, voffA);
;             PG8_WAIT_V(8); PG8_WAIT_L(0); PG8_BAR; PG8_MMA(0, 0, At, B0); PG8_MMA(0, 1, At, B1); PG8_BAR; PG8_SCHED;
	s_add_i32 s0, s79, s30
	s_mov_b32 m0, s0
	ds_read_b128 v[162:165], v230 offset:16384
	ds_read_b128 v[166:169], v230 offset:17408
	ds_read_b128 v[184:187], v230 offset:18432
	ds_read_b128 v[190:193], v230 offset:19456
	ds_read_b128 v[194:197], v230 offset:20480
	ds_read_b128 v[198:201], v230 offset:21504
	ds_read_b128 v[202:205], v230 offset:22528
	ds_read_b128 v[206:209], v230 offset:23552
	global_load_lds_dwordx4 v182, s[84:85]
	s_add_i32 m0, s0, 0x2000
	s_add_u32 s0, s84, 0x80000
	s_addc_u32 s1, s85, 0
	s_add_i32 s79, s81, s30
	global_load_lds_dwordx4 v178, s[84:85]
	s_mov_b32 m0, s79
	s_nop 0
	global_load_lds_dwordx4 v182, s[0:1]
	s_add_i32 m0, s79, 0x2000
	s_nop 0
	global_load_lds_dwordx4 v178, s[0:1]
	s_mov_b32 m0, s44
	s_nop 0
	global_load_lds_dwordx4 v174, s[86:87]
	s_mov_b32 m0, s45
	s_nop 0
	global_load_lds_dwordx4 v176, s[86:87]
	s_waitcnt vmcnt(8)
	s_waitcnt lgkmcnt(0)
	s_setprio 1
	v_mfma_f32_16x16x32_bf16 v[62:65], v[90:93], v[162:165], v[62:65]
	v_mfma_f32_16x16x32_bf16 v[62:65], v[94:97], v[166:169], v[62:65]
	v_mfma_f32_16x16x32_bf16 v[46:49], v[90:93], v[184:187], v[46:49]
	v_mfma_f32_16x16x32_bf16 v[46:49], v[94:97], v[190:193], v[46:49]
	v_mfma_f32_16x16x32_bf16 v[30:33], v[90:93], v[194:197], v[30:33]
	v_mfma_f32_16x16x32_bf16 v[30:33], v[94:97], v[198:201], v[30:33]
	v_mfma_f32_16x16x32_bf16 v[14:17], v[90:93], v[202:205], v[14:17]
	v_mfma_f32_16x16x32_bf16 v[14:17], v[94:97], v[206:209], v[14:17]
	v_mfma_f32_16x16x32_bf16 v[10:13], v[98:101], v[202:205], v[10:13]
	v_mfma_f32_16x16x32_bf16 v[10:13], v[102:105], v[206:209], v[10:13]
	v_mfma_f32_16x16x32_bf16 v[26:29], v[98:101], v[194:197], v[26:29]
	v_mfma_f32_16x16x32_bf16 v[26:29], v[102:105], v[198:201], v[26:29]
	v_mfma_f32_16x16x32_bf16 v[42:45], v[98:101], v[184:187], v[42:45]
	v_mfma_f32_16x16x32_bf16 v[42:45], v[102:105], v[190:193], v[42:45]
	v_mfma_f32_16x16x32_bf16 v[58:61], v[98:101], v[162:165], v[58:61]
	v_mfma_f32_16x16x32_bf16 v[58:61], v[102:105], v[166:169], v[58:61]
	v_mfma_f32_16x16x32_bf16 v[54:57], v[146:149], v[162:165], v[54:57]
	v_mfma_f32_16x16x32_bf16 v[54:57], v[150:153], v[166:169], v[54:57]
	v_mfma_f32_16x16x32_bf16 v[38:41], v[146:149], v[184:187], v[38:41]
	v_mfma_f32_16x16x32_bf16 v[38:41], v[150:153], v[190:193], v[38:41]
	v_mfma_f32_16x16x32_bf16 v[22:25], v[146:149], v[194:197], v[22:25]
	v_mfma_f32_16x16x32_bf16 v[22:25], v[150:153], v[198:201], v[22:25]
	v_mfma_f32_16x16x32_bf16 v[6:9], v[146:149], v[202:205], v[6:9]
	v_mfma_f32_16x16x32_bf16 v[6:9], v[150:153], v[206:209], v[6:9]
	v_mfma_f32_16x16x32_bf16 v[2:5], v[154:157], v[202:205], v[2:5]
	v_mfma_f32_16x16x32_bf16 v[2:5], v[158:161], v[206:209], v[2:5]
	v_mfma_f32_16x16x32_bf16 v[18:21], v[154:157], v[194:197], v[18:21]
	v_mfma_f32_16x16x32_bf16 v[18:21], v[158:161], v[198:201], v[18:21]
	v_mfma_f32_16x16x32_bf16 v[34:37], v[154:157], v[184:187], v[34:37]
	v_mfma_f32_16x16x32_bf16 v[34:37], v[158:161], v[190:193], v[34:37]
	v_mfma_f32_16x16x32_bf16 v[50:53], v[154:157], v[162:165], v[50:53]
	v_mfma_f32_16x16x32_bf16 v[50:53], v[158:161], v[166:169], v[50:53]
	s_setprio 0
	s_barrier
	s_add_i32 s79, 0, 0x18000
	s_add_i32 s81, 0, 0x1c000
	ds_read_b128 v[90:93], v210 offset:32768
	ds_read_b128 v[94:97], v210 offset:33792
	ds_read_b128 v[98:101], v210 offset:34816
	ds_read_b128 v[102:105], v210 offset:35840
	ds_read_b128 v[146:149], v210 offset:49152
	ds_read_b128 v[150:153], v210 offset:50176
	ds_read_b128 v[154:157], v210 offset:51200
	ds_read_b128 v[158:161], v210 offset:52224
	s_add_u32 s0, s86, 0x80000
	s_addc_u32 s1, s87, 0
	s_mov_b32 m0, s46
	ds_read_b128 v[162:165], v230 offset:32768
	ds_read_b128 v[166:169], v230 offset:33792
	ds_read_b128 v[184:187], v230 offset:34816
	ds_read_b128 v[190:193], v230 offset:35840
	ds_read_b128 v[194:197], v230 offset:36864
	ds_read_b128 v[198:201], v230 offset:37888
	ds_read_b128 v[202:205], v230 offset:38912
	ds_read_b128 v[206:209], v230 offset:39936
	global_load_lds_dwordx4 v174, s[0:1]
	s_mov_b32 m0, s47
	s_nop 0
	global_load_lds_dwordx4 v176, s[0:1]
	s_waitcnt vmcnt(8)
	s_waitcnt lgkmcnt(0)
	s_setprio 1
	v_mfma_f32_16x16x32_bf16 v[142:145], v[90:93], v[162:165], v[142:145]
	v_mfma_f32_16x16x32_bf16 v[142:145], v[94:97], v[166:169], v[142:145]
	v_mfma_f32_16x16x32_bf16 v[126:129], v[90:93], v[184:187], v[126:129]
	v_mfma_f32_16x16x32_bf16 v[126:129], v[94:97], v[190:193], v[126:129]
	v_mfma_f32_16x16x32_bf16 v[110:113], v[90:93], v[194:197], v[110:113]
	v_mfma_f32_16x16x32_bf16 v[110:113], v[94:97], v[198:201], v[110:113]
	v_mfma_f32_16x16x32_bf16 v[78:81], v[90:93], v[202:205], v[78:81]
	v_mfma_f32_16x16x32_bf16 v[78:81], v[94:97], v[206:209], v[78:81]
	v_mfma_f32_16x16x32_bf16 v[74:77], v[98:101], v[202:205], v[74:77]
	v_mfma_f32_16x16x32_bf16 v[74:77], v[102:105], v[206:209], v[74:77]
	v_mfma_f32_16x16x32_bf16 v[106:109], v[98:101], v[194:197], v[106:109]
	v_mfma_f32_16x16x32_bf16 v[106:109], v[102:105], v[198:201], v[106:109]
	v_mfma_f32_16x16x32_bf16 v[122:125], v[98:101], v[184:187], v[122:125]
	v_mfma_f32_16x16x32_bf16 v[122:125], v[102:105], v[190:193], v[122:125]
	v_mfma_f32_16x16x32_bf16 v[138:141], v[98:101], v[162:165], v[138:141]
	v_mfma_f32_16x16x32_bf16 v[138:141], v[102:105], v[166:169], v[138:141]
	v_mfma_f32_16x16x32_bf16 v[134:137], v[146:149], v[162:165], v[134:137]
	v_mfma_f32_16x16x32_bf16 v[134:137], v[150:153], v[166:169], v[134:137]
	v_mfma_f32_16x16x32_bf16 v[118:121], v[146:149], v[184:187], v[118:121]
	v_mfma_f32_16x16x32_bf16 v[118:121], v[150:153], v[190:193], v[118:121]
	v_mfma_f32_16x16x32_bf16 v[86:89], v[146:149], v[194:197], v[86:89]
	v_mfma_f32_16x16x32_bf16 v[86:89], v[150:153], v[198:201], v[86:89]
	v_mfma_f32_16x16x32_bf16 v[70:73], v[146:149], v[202:205], v[70:73]
	v_mfma_f32_16x16x32_bf16 v[70:73], v[150:153], v[206:209], v[70:73]
	v_mfma_f32_16x16x32_bf16 v[66:69], v[154:157], v[202:205], v[66:69]
	v_mfma_f32_16x16x32_bf16 v[66:69], v[158:161], v[206:209], v[66:69]
	v_mfma_f32_16x16x32_bf16 v[82:85], v[154:157], v[194:197], v[82:85]
	v_mfma_f32_16x16x32_bf16 v[82:85], v[158:161], v[198:201], v[82:85]
	v_mfma_f32_16x16x32_bf16 v[114:117], v[154:157], v[184:187], v[114:117]
	v_mfma_f32_16x16x32_bf16 v[114:117], v[158:161], v[190:193], v[114:117]
	v_mfma_f32_16x16x32_bf16 v[130:133], v[154:157], v[162:165], v[130:133]
	v_mfma_f32_16x16x32_bf16 v[130:133], v[158:161], v[166:169], v[130:133]
	s_setprio 0
	s_barrier
; #define PG8_STAGE(bufoff, gbase, voff) do { _Pragma("unroll") for (int _i = 0; _i < 2; ++_i) \
;         __builtin_amdgcn_global_load_lds((const unsigned*)((const char*)(gbase) + (voff)[_i]), (PG8_LAS unsigned*)(lds + (bufoff) + ldsw + _i * 8192), 16, 0, 0); } while (0)
; #define PG8_LDA(dst, b, h) do { _Pragma("unroll") for (int m = 0; m < 4; ++m) _Pragma("unroll") for (int k = 0; k < 2; ++k) dst[m][k] = *(const PG8_LAS bf16x8*)(lds + PG8_SA(b, h) + aoff + m * 2048 + k * 1024); } while (0)
; #define PG8_LDB(dst, b, h) do { _Pragma("unroll") for (int n = 0; n < 2; ++n) _Pragma("unroll") for (int k = 0; k < 2; ++k) dst[n][k] = *(const PG8_LAS bf16x8*)(lds + PG8_SB(b, h) + boff + n * 2048 + k * 1024); } while (0)
; #define PG8_WAIT_V(n) asm volatile("s_waitcnt vmcnt(" #n ")" ::: "memory")
; #define PG8_WAIT_L(n) asm volatile("s_waitcnt lgkmcnt(" #n ")" ::: "memory")
; #define PG8_WAIT_V_SEL(sel) asm volatile("s_cmp_eq_u32 %0, 0\n\ts_cbranch_scc1 .Lw8_%=\n\ts_waitcnt vmcnt(22)\n\ts_branch .Lwd_%=\n.Lw8_%=:\n\ts_waitcnt vmcnt(8)\n.Lwd_%=:" :: "s"(sel) : "memory", "scc")
; #define PG8_BAR __builtin_amdgcn_s_barrier()
; #define PG8_SCHED __builtin_amdgcn_sched_barrier(0)
;     ...
;             PG8_LDB(B0, 0, 0); PG8_LDB(B1, 0, 1); PG8_SCHED; PG8_LDA(At, 0, 0); PG8_STAGE(PG8_SA(1, 1), a1 + hstep, voffA);
;             PG8_WAIT_V_SEL(relax);
;             PG8_WAIT_L(0); PG8_BAR; PG8_MMA(0, 0, At, B0); PG8_MMA(0, 1, At, B1); PG8_BAR; PG8_SCHED;
;             PG8_LDA(At, 0, 1); PG8_STAGE(PG8_SB(0, 0), b2, voffB); PG8_STAGE(PG8_SB(0, 1), b2 + hstep, voffB); PG8_STAGE(PG8_SA(0, 0), a2, voffA);
;             PG8_WAIT_V_SEL(relax);
;             PG8_WAIT_L(0); PG8_BAR; PG8_MMA(1, 0, At, B0); PG8_MMA(1, 1, At, B1); PG8_BAR; PG8_SCHED;
;             PG8_LDB(B0, 1, 0); PG8_LDB(B1, 1, 1); PG8_SCHED; PG8_LDA(At, 1, 0); PG8_STAGE(PG8_SA(0, 1), a2 + hstep, voffA);
;             PG8_WAIT_V(8); PG8_WAIT_L(0); PG8_BAR; PG8_MMA(0, 0, At, B0); PG8_MMA(0, 1, At, B1); PG8_BAR; PG8_SCHED;
;             PG8_LDA(At, 1, 1); PG8_STAGE(PG8_SB(1, 0), b3, voffB); PG8_STAGE(PG8_SB(1, 1), b3 + hstep, voffB); PG8_STAGE(PG8_SA(1, 0), a3, voffA);
;             PG8_WAIT_V(8); PG8_WAIT_L(0); PG8_BAR; PG8_MMA(1, 0, At, B0); PG8_MMA(1, 1, At, B1); PG8_BAR; PG8_SCHED;
	s_add_i32 s0, s79, s30
	s_mov_b32 m0, s0
	ds_read_b128 v[162:165], v230 offset:49152
	ds_read_b128 v[166:169], v230 offset:50176
	ds_read_b128 v[184:187], v230 offset:51200
	ds_read_b128 v[190:193], v230 offset:52224
	ds_read_b128 v[194:197], v230 offset:53248
	ds_read_b128 v[198:201], v230 offset:54272
	ds_read_b128 v[202:205], v230 offset:55296
	ds_read_b128 v[206:209], v230 offset:56320
	s_add_u32 s100, s84, 0x80
	s_addc_u32 s101, s85, 0
	global_load_lds_dwordx4 v182, s[100:101]
	s_add_i32 m0, s0, 0x2000
	s_add_u32 s0, s84, 0x80080
	s_addc_u32 s1, s85, 0
	s_add_i32 s79, s81, s30
	global_load_lds_dwordx4 v178, s[100:101]
	s_mov_b32 m0, s79
	s_nop 0
	global_load_lds_dwordx4 v182, s[0:1]
	s_add_i32 m0, s79, 0x2000
	s_nop 0
	global_load_lds_dwordx4 v178, s[0:1]
	s_mov_b32 m0, s49
	s_nop 0
	s_add_u32 s100, s86, 0x80
	s_addc_u32 s101, s87, 0
	global_load_lds_dwordx4 v174, s[100:101]
	s_mov_b32 m0, s50
	s_nop 0
	global_load_lds_dwordx4 v176, s[100:101]
	s_waitcnt vmcnt(8)
	s_waitcnt lgkmcnt(0)
	s_setprio 1
	v_mfma_f32_16x16x32_bf16 v[62:65], v[90:93], v[162:165], v[62:65]
	v_mfma_f32_16x16x32_bf16 v[62:65], v[94:97], v[166:169], v[62:65]
	v_mfma_f32_16x16x32_bf16 v[46:49], v[90:93], v[184:187], v[46:49]
	v_mfma_f32_16x16x32_bf16 v[46:49], v[94:97], v[190:193], v[46:49]
	v_mfma_f32_16x16x32_bf16 v[30:33], v[90:93], v[194:197], v[30:33]
	v_mfma_f32_16x16x32_bf16 v[30:33], v[94:97], v[198:201], v[30:33]
	v_mfma_f32_16x16x32_bf16 v[14:17], v[90:93], v[202:205], v[14:17]
	v_mfma_f32_16x16x32_bf16 v[14:17], v[94:97], v[206:209], v[14:17]
	v_mfma_f32_16x16x32_bf16 v[10:13], v[98:101], v[202:205], v[10:13]
	v_mfma_f32_16x16x32_bf16 v[10:13], v[102:105], v[206:209], v[10:13]
	v_mfma_f32_16x16x32_bf16 v[26:29], v[98:101], v[194:197], v[26:29]
	v_mfma_f32_16x16x32_bf16 v[26:29], v[102:105], v[198:201], v[26:29]
	v_mfma_f32_16x16x32_bf16 v[42:45], v[98:101], v[184:187], v[42:45]
	v_mfma_f32_16x16x32_bf16 v[42:45], v[102:105], v[190:193], v[42:45]
	v_mfma_f32_16x16x32_bf16 v[58:61], v[98:101], v[162:165], v[58:61]
	v_mfma_f32_16x16x32_bf16 v[58:61], v[102:105], v[166:169], v[58:61]
	v_mfma_f32_16x16x32_bf16 v[54:57], v[146:149], v[162:165], v[54:57]
	v_mfma_f32_16x16x32_bf16 v[54:57], v[150:153], v[166:169], v[54:57]
	v_mfma_f32_16x16x32_bf16 v[38:41], v[146:149], v[184:187], v[38:41]
	v_mfma_f32_16x16x32_bf16 v[38:41], v[150:153], v[190:193], v[38:41]
	v_mfma_f32_16x16x32_bf16 v[22:25], v[146:149], v[194:197], v[22:25]
	v_mfma_f32_16x16x32_bf16 v[22:25], v[150:153], v[198:201], v[22:25]
	v_mfma_f32_16x16x32_bf16 v[6:9], v[146:149], v[202:205], v[6:9]
	v_mfma_f32_16x16x32_bf16 v[6:9], v[150:153], v[206:209], v[6:9]
	v_mfma_f32_16x16x32_bf16 v[2:5], v[154:157], v[202:205], v[2:5]
	v_mfma_f32_16x16x32_bf16 v[2:5], v[158:161], v[206:209], v[2:5]
	v_mfma_f32_16x16x32_bf16 v[18:21], v[154:157], v[194:197], v[18:21]
	v_mfma_f32_16x16x32_bf16 v[18:21], v[158:161], v[198:201], v[18:21]
	v_mfma_f32_16x16x32_bf16 v[34:37], v[154:157], v[184:187], v[34:37]
	v_mfma_f32_16x16x32_bf16 v[34:37], v[158:161], v[190:193], v[34:37]
	v_mfma_f32_16x16x32_bf16 v[50:53], v[154:157], v[162:165], v[50:53]
	v_mfma_f32_16x16x32_bf16 v[50:53], v[158:161], v[166:169], v[50:53]
	s_setprio 0
	s_barrier
	s_add_i32 s73, s73, 2
	s_add_u32 s82, s82, 0x100
	s_addc_u32 s83, s83, 0
	s_add_u32 s59, s59, 0x100
	s_addc_u32 s71, s71, 0
	s_cmp_gt_u32 s73, 29
	s_cbranch_scc0 .LBB0_541
	s_branch .Lhob_go_exit
.Lhob_go_Thead:
	s_add_u32 s0, s82, 0xfff80080
	s_addc_u32 s1, s83, -1
	s_add_i32 s79, 0, 0x10000
	s_cmp_eq_u32 s73, 28
	s_cselect_b32 s87, s40, s1
	s_cselect_b32 s86, s41, s0
	s_cselect_b32 s85, s57, s71
	s_cselect_b32 s84, s58, s59
	s_add_i32 s81, 0, 0x14000
	ds_read_b128 v[90:93], v210
	ds_read_b128 v[94:97], v210 offset:1024
	ds_read_b128 v[98:101], v210 offset:2048
	ds_read_b128 v[102:105], v210 offset:3072
	ds_read_b128 v[146:149], v210 offset:16384
	ds_read_b128 v[150:153], v210 offset:17408
	ds_read_b128 v[154:157], v210 offset:18432
	ds_read_b128 v[158:161], v210 offset:19456
	s_add_i32 m0, s44, 0xc000
	ds_read_b128 v[162:165], v230
	ds_read_b128 v[166:169], v230 offset:1024
	ds_read_b128 v[184:187], v230 offset:2048
	ds_read_b128 v[190:193], v230 offset:3072
	ds_read_b128 v[194:197], v230 offset:4096
	ds_read_b128 v[198:201], v230 offset:5120
	ds_read_b128 v[202:205], v230 offset:6144
	ds_read_b128 v[206:209], v230 offset:7168
	global_load_lds_dwordx4 v180, s[82:83]
	s_add_i32 m0, s44, 0xe000
	s_nop 0
	global_load_lds_dwordx4 v188, s[82:83]
	s_waitcnt vmcnt(8)
	s_waitcnt lgkmcnt(0)
	s_barrier
; #define PG8_STAGE(bufoff, gbase, voff) do { _Pragma("unroll") for (int _i = 0; _i < 2; ++_i) \
;         __builtin_amdgcn_global_load_lds((const unsigned*)((const char*)(gbase) + (voff)[_i]), (PG8_LAS unsigned*)(lds + (bufoff) + ldsw + _i * 8192), 16, 0, 0); } while (0)
; #define PG8_LDA(dst, b, h) do { _Pragma("unroll") for (int m = 0; m < 4; ++m) _Pragma("unroll") for (int k = 0; k < 2; ++k) dst[m][k] = *(const PG8_LAS bf16x8*)(lds + PG8_SA(b, h) + aoff + m * 2048 + k * 1024); } while (0)
; #define PG8_LDB(dst, b, h) do { _Pragma("unroll") for (int n = 0; n < 2; ++n) _Pragma("unroll") for (int k = 0; k < 2; ++k) dst[n][k] = *(const PG8_LAS bf16x8*)(lds + PG8_SB(b, h) + boff + n * 2048 + k * 1024); } while (0)
; #define PG8_WAIT_V(n) asm volatile("s_waitcnt vmcnt(" #n ")" ::: "memory")
; #define PG8_WAIT_L(n) asm volatile("s_waitcnt lgkmcnt(" #n ")" ::: "memory")
; #define PG8_WAIT_V_SEL(sel) asm volatile("s_cmp_eq_u32 %0, 0\n\ts_cbranch_scc1 .Lw8_%=\n\ts_waitcnt vmcnt(22)\n\ts_branch .Lwd_%=\n.Lw8_%=:\n\ts_waitcnt vmcnt(8)\n.Lwd_%=:" :: "s"(sel) : "memory", "scc")
; #define PG8_BAR __builtin_amdgcn_s_barrier()
; #define PG8_SCHED __builtin_amdgcn_sched_barrier(0)
;     ...
;             PG8_WAIT_L(0); PG8_BAR; PG8_MMA(0, 0, At, B0); PG8_MMA(0, 1, At, B1); PG8_BAR; PG8_SCHED;
;             PG8_LDA(At, 0, 1); PG8_STAGE(PG8_SB(0, 0), b2, voffB); PG8_STAGE(PG8_SB(0, 1), b2 + hstep, voffB); PG8_STAGE(PG8_SA(0, 0), a2, voffA);
;             PG8_WAIT_V_SEL(relax);
;             PG8_WAIT_L(0); PG8_BAR; PG8_MMA(1, 0, At, B0); PG8_MMA(1, 1, At, B1); PG8_BAR; PG8_SCHED;
;             PG8_LDB(B0, 1, 0); PG8_LDB(B1, 1, 1); PG8_SCHED; PG8_LDA(At, 1, 0); PG8_STAGE(PG8_SA(0, 1), a2 + hstep, voffA);
;             PG8_WAIT_V(8); PG8_WAIT_L(0); PG8_BAR; PG8_MMA(0, 0, At, B0); PG8_MMA(0, 1, At, B1); PG8_BAR; PG8_SCHED;
	s_setprio 2
	v_mfma_f32_16x16x32_bf16 v[142:145], v[90:93], v[162:165], v[142:145]
	v_mfma_f32_16x16x32_bf16 v[142:145], v[94:97], v[166:169], v[142:145]
	v_mfma_f32_16x16x32_bf16 v[126:129], v[90:93], v[184:187], v[126:129]
	v_mfma_f32_16x16x32_bf16 v[126:129], v[94:97], v[190:193], v[126:129]
	v_mfma_f32_16x16x32_bf16 v[110:113], v[90:93], v[194:197], v[110:113]
	v_mfma_f32_16x16x32_bf16 v[110:113], v[94:97], v[198:201], v[110:113]
	v_mfma_f32_16x16x32_bf16 v[78:81], v[90:93], v[202:205], v[78:81]
	v_mfma_f32_16x16x32_bf16 v[78:81], v[94:97], v[206:209], v[78:81]
	v_mfma_f32_16x16x32_bf16 v[74:77], v[98:101], v[202:205], v[74:77]
	v_mfma_f32_16x16x32_bf16 v[74:77], v[102:105], v[206:209], v[74:77]
	v_mfma_f32_16x16x32_bf16 v[106:109], v[98:101], v[194:197], v[106:109]
	v_mfma_f32_16x16x32_bf16 v[106:109], v[102:105], v[198:201], v[106:109]
	v_mfma_f32_16x16x32_bf16 v[122:125], v[98:101], v[184:187], v[122:125]
	v_mfma_f32_16x16x32_bf16 v[122:125], v[102:105], v[190:193], v[122:125]
	v_mfma_f32_16x16x32_bf16 v[138:141], v[98:101], v[162:165], v[138:141]
	v_mfma_f32_16x16x32_bf16 v[138:141], v[102:105], v[166:169], v[138:141]
	v_mfma_f32_16x16x32_bf16 v[134:137], v[146:149], v[162:165], v[134:137]
	v_mfma_f32_16x16x32_bf16 v[134:137], v[150:153], v[166:169], v[134:137]
	v_mfma_f32_16x16x32_bf16 v[118:121], v[146:149], v[184:187], v[118:121]
	v_mfma_f32_16x16x32_bf16 v[118:121], v[150:153], v[190:193], v[118:121]
	v_mfma_f32_16x16x32_bf16 v[86:89], v[146:149], v[194:197], v[86:89]
	v_mfma_f32_16x16x32_bf16 v[86:89], v[150:153], v[198:201], v[86:89]
	v_mfma_f32_16x16x32_bf16 v[70:73], v[146:149], v[202:205], v[70:73]
	v_mfma_f32_16x16x32_bf16 v[70:73], v[150:153], v[206:209], v[70:73]
	v_mfma_f32_16x16x32_bf16 v[66:69], v[154:157], v[202:205], v[66:69]
	v_mfma_f32_16x16x32_bf16 v[66:69], v[158:161], v[206:209], v[66:69]
	v_mfma_f32_16x16x32_bf16 v[82:85], v[154:157], v[194:197], v[82:85]
	v_mfma_f32_16x16x32_bf16 v[82:85], v[158:161], v[198:201], v[82:85]
	v_mfma_f32_16x16x32_bf16 v[114:117], v[154:157], v[184:187], v[114:117]
	v_mfma_f32_16x16x32_bf16 v[114:117], v[158:161], v[190:193], v[114:117]
	v_mfma_f32_16x16x32_bf16 v[130:133], v[154:157], v[162:165], v[130:133]
	v_mfma_f32_16x16x32_bf16 v[130:133], v[158:161], v[166:169], v[130:133]
	s_setprio 0
	s_add_i32 s0, s79, s30
	s_mov_b32 m0, s0
	ds_read_b128 v[162:165], v230 offset:16384
	ds_read_b128 v[166:169], v230 offset:17408
	ds_read_b128 v[184:187], v230 offset:18432
	ds_read_b128 v[190:193], v230 offset:19456
	ds_read_b128 v[194:197], v230 offset:20480
	ds_read_b128 v[198:201], v230 offset:21504
	ds_read_b128 v[202:205], v230 offset:22528
	ds_read_b128 v[206:209], v230 offset:23552
	global_load_lds_dwordx4 v182, s[84:85]
	s_add_i32 m0, s0, 0x2000
	s_add_u32 s0, s84, 0x80000
	s_addc_u32 s1, s85, 0
	s_add_i32 s79, s81, s30
	global_load_lds_dwordx4 v178, s[84:85]
	s_mov_b32 m0, s79
	s_nop 0
	global_load_lds_dwordx4 v182, s[0:1]
	s_add_i32 m0, s79, 0x2000
	s_nop 0
	global_load_lds_dwordx4 v178, s[0:1]
	s_mov_b32 m0, s44
	s_nop 0
	global_load_lds_dwordx4 v174, s[86:87]
	s_mov_b32 m0, s45
	s_nop 0
	global_load_lds_dwordx4 v176, s[86:87]
	s_waitcnt vmcnt(8)
	s_waitcnt lgkmcnt(0)
	s_barrier
	s_setprio 2
	v_mfma_f32_16x16x32_bf16 v[62:65], v[90:93], v[162:165], v[62:65]
	v_mfma_f32_16x16x32_bf16 v[62:65], v[94:97], v[166:169], v[62:65]
	v_mfma_f32_16x16x32_bf16 v[46:49], v[90:93], v[184:187], v[46:49]
	v_mfma_f32_16x16x32_bf16 v[46:49], v[94:97], v[190:193], v[46:49]
	v_mfma_f32_16x16x32_bf16 v[30:33], v[90:93], v[194:197], v[30:33]
	v_mfma_f32_16x16x32_bf16 v[30:33], v[94:97], v[198:201], v[30:33]
	v_mfma_f32_16x16x32_bf16 v[14:17], v[90:93], v[202:205], v[14:17]
	v_mfma_f32_16x16x32_bf16 v[14:17], v[94:97], v[206:209], v[14:17]
	v_mfma_f32_16x16x32_bf16 v[10:13], v[98:101], v[202:205], v[10:13]
	v_mfma_f32_16x16x32_bf16 v[10:13], v[102:105], v[206:209], v[10:13]
	v_mfma_f32_16x16x32_bf16 v[26:29], v[98:101], v[194:197], v[26:29]
	v_mfma_f32_16x16x32_bf16 v[26:29], v[102:105], v[198:201], v[26:29]
	v_mfma_f32_16x16x32_bf16 v[42:45], v[98:101], v[184:187], v[42:45]
	v_mfma_f32_16x16x32_bf16 v[42:45], v[102:105], v[190:193], v[42:45]
	v_mfma_f32_16x16x32_bf16 v[58:61], v[98:101], v[162:165], v[58:61]
	v_mfma_f32_16x16x32_bf16 v[58:61], v[102:105], v[166:169], v[58:61]
	v_mfma_f32_16x16x32_bf16 v[54:57], v[146:149], v[162:165], v[54:57]
	v_mfma_f32_16x16x32_bf16 v[54:57], v[150:153], v[166:169], v[54:57]
	v_mfma_f32_16x16x32_bf16 v[38:41], v[146:149], v[184:187], v[38:41]
	v_mfma_f32_16x16x32_bf16 v[38:41], v[150:153], v[190:193], v[38:41]
	v_mfma_f32_16x16x32_bf16 v[22:25], v[146:149], v[194:197], v[22:25]
	v_mfma_f32_16x16x32_bf16 v[22:25], v[150:153], v[198:201], v[22:25]
	v_mfma_f32_16x16x32_bf16 v[6:9], v[146:149], v[202:205], v[6:9]
	v_mfma_f32_16x16x32_bf16 v[6:9], v[150:153], v[206:209], v[6:9]
	v_mfma_f32_16x16x32_bf16 v[2:5], v[154:157], v[202:205], v[2:5]
	v_mfma_f32_16x16x32_bf16 v[2:5], v[158:161], v[206:209], v[2:5]
	v_mfma_f32_16x16x32_bf16 v[18:21], v[154:157], v[194:197], v[18:21]
	v_mfma_f32_16x16x32_bf16 v[18:21], v[158:161], v[198:201], v[18:21]
	v_mfma_f32_16x16x32_bf16 v[34:37], v[154:157], v[184:187], v[34:37]
	v_mfma_f32_16x16x32_bf16 v[34:37], v[158:161], v[190:193], v[34:37]
	v_mfma_f32_16x16x32_bf16 v[50:53], v[154:157], v[162:165], v[50:53]
	v_mfma_f32_16x16x32_bf16 v[50:53], v[158:161], v[166:169], v[50:53]
	s_setprio 0
	s_add_i32 s79, 0, 0x18000
	s_add_i32 s81, 0, 0x1c000
	ds_read_b128 v[90:93], v210 offset:32768
	ds_read_b128 v[94:97], v210 offset:33792
	ds_read_b128 v[98:101], v210 offset:34816
	ds_read_b128 v[102:105], v210 offset:35840
	ds_read_b128 v[146:149], v210 offset:49152
	ds_read_b128 v[150:153], v210 offset:50176
	ds_read_b128 v[154:157], v210 offset:51200
	ds_read_b128 v[158:161], v210 offset:52224
	s_add_u32 s0, s86, 0x80000
	s_addc_u32 s1, s87, 0
	s_mov_b32 m0, s46
	ds_read_b128 v[162:165], v230 offset:32768
	ds_read_b128 v[166:169], v230 offset:33792
	ds_read_b128 v[184:187], v230 offset:34816
	ds_read_b128 v[190:193], v230 offset:35840
	ds_read_b128 v[194:197], v230 offset:36864
	ds_read_b128 v[198:201], v230 offset:37888
	ds_read_b128 v[202:205], v230 offset:38912
	ds_read_b128 v[206:209], v230 offset:39936
	global_load_lds_dwordx4 v174, s[0:1]
	s_mov_b32 m0, s47
	s_nop 0
	global_load_lds_dwordx4 v176, s[0:1]
	s_waitcnt vmcnt(8)
	s_waitcnt lgkmcnt(0)
	s_barrier
; #define PG8_STAGE(bufoff, gbase, voff) do { _Pragma("unroll") for (int _i = 0; _i < 2; ++_i) \
;         __builtin_amdgcn_global_load_lds((const unsigned*)((const char*)(gbase) + (voff)[_i]), (PG8_LAS unsigned*)(lds + (bufoff) + ldsw + _i * 8192), 16, 0, 0); } while (0)
; #define PG8_LDA(dst, b, h) do { _Pragma("unroll") for (int m = 0; m < 4; ++m) _Pragma("unroll") for (int k = 0; k < 2; ++k) dst[m][k] = *(const PG8_LAS bf16x8*)(lds + PG8_SA(b, h) + aoff + m * 2048 + k * 1024); } while (0)
; #define PG8_WAIT_V(n) asm volatile("s_waitcnt vmcnt(" #n ")" ::: "memory")
; #define PG8_WAIT_L(n) asm volatile("s_waitcnt lgkmcnt(" #n ")" ::: "memory")
; #define PG8_BAR __builtin_amdgcn_s_barrier()
; #define PG8_SCHED __builtin_amdgcn_sched_barrier(0)
;     ...
;             PG8_WAIT_V(8); PG8_WAIT_L(0); PG8_BAR; PG8_MMA(0, 0, At, B0); PG8_MMA(0, 1, At, B1); PG8_BAR; PG8_SCHED;
;             PG8_LDA(At, 1, 1); PG8_STAGE(PG8_SB(1, 0), b3, voffB); PG8_STAGE(PG8_SB(1, 1), b3 + hstep, voffB); PG8_STAGE(PG8_SA(1, 0), a3, voffA);
;             PG8_WAIT_V(8); PG8_WAIT_L(0); PG8_BAR; PG8_MMA(1, 0, At, B0); PG8_MMA(1, 1, At, B1); PG8_BAR; PG8_SCHED;
;     ...
;         if constexpr (ALIGN_EPI) { if (wr == 0) PG8_BAR; }
	s_setprio 2
	v_mfma_f32_16x16x32_bf16 v[142:145], v[90:93], v[162:165], v[142:145]
	v_mfma_f32_16x16x32_bf16 v[142:145], v[94:97], v[166:169], v[142:145]
	v_mfma_f32_16x16x32_bf16 v[126:129], v[90:93], v[184:187], v[126:129]
	v_mfma_f32_16x16x32_bf16 v[126:129], v[94:97], v[190:193], v[126:129]
	v_mfma_f32_16x16x32_bf16 v[110:113], v[90:93], v[194:197], v[110:113]
	v_mfma_f32_16x16x32_bf16 v[110:113], v[94:97], v[198:201], v[110:113]
	v_mfma_f32_16x16x32_bf16 v[78:81], v[90:93], v[202:205], v[78:81]
	v_mfma_f32_16x16x32_bf16 v[78:81], v[94:97], v[206:209], v[78:81]
	v_mfma_f32_16x16x32_bf16 v[74:77], v[98:101], v[202:205], v[74:77]
	v_mfma_f32_16x16x32_bf16 v[74:77], v[102:105], v[206:209], v[74:77]
	v_mfma_f32_16x16x32_bf16 v[106:109], v[98:101], v[194:197], v[106:109]
	v_mfma_f32_16x16x32_bf16 v[106:109], v[102:105], v[198:201], v[106:109]
	v_mfma_f32_16x16x32_bf16 v[122:125], v[98:101], v[184:187], v[122:125]
	v_mfma_f32_16x16x32_bf16 v[122:125], v[102:105], v[190:193], v[122:125]
	v_mfma_f32_16x16x32_bf16 v[138:141], v[98:101], v[162:165], v[138:141]
	v_mfma_f32_16x16x32_bf16 v[138:141], v[102:105], v[166:169], v[138:141]
	v_mfma_f32_16x16x32_bf16 v[134:137], v[146:149], v[162:165], v[134:137]
	v_mfma_f32_16x16x32_bf16 v[134:137], v[150:153], v[166:169], v[134:137]
	v_mfma_f32_16x16x32_bf16 v[118:121], v[146:149], v[184:187], v[118:121]
	v_mfma_f32_16x16x32_bf16 v[118:121], v[150:153], v[190:193], v[118:121]
	v_mfma_f32_16x16x32_bf16 v[86:89], v[146:149], v[194:197], v[86:89]
	v_mfma_f32_16x16x32_bf16 v[86:89], v[150:153], v[198:201], v[86:89]
	v_mfma_f32_16x16x32_bf16 v[70:73], v[146:149], v[202:205], v[70:73]
	v_mfma_f32_16x16x32_bf16 v[70:73], v[150:153], v[206:209], v[70:73]
	v_mfma_f32_16x16x32_bf16 v[66:69], v[154:157], v[202:205], v[66:69]
	v_mfma_f32_16x16x32_bf16 v[66:69], v[158:161], v[206:209], v[66:69]
	v_mfma_f32_16x16x32_bf16 v[82:85], v[154:157], v[194:197], v[82:85]
	v_mfma_f32_16x16x32_bf16 v[82:85], v[158:161], v[198:201], v[82:85]
	v_mfma_f32_16x16x32_bf16 v[114:117], v[154:157], v[184:187], v[114:117]
	v_mfma_f32_16x16x32_bf16 v[114:117], v[158:161], v[190:193], v[114:117]
	v_mfma_f32_16x16x32_bf16 v[130:133], v[154:157], v[162:165], v[130:133]
	v_mfma_f32_16x16x32_bf16 v[130:133], v[158:161], v[166:169], v[130:133]
	s_setprio 0
	s_add_i32 s0, s79, s30
	s_mov_b32 m0, s0
	ds_read_b128 v[162:165], v230 offset:49152
	ds_read_b128 v[166:169], v230 offset:50176
	ds_read_b128 v[184:187], v230 offset:51200
	ds_read_b128 v[190:193], v230 offset:52224
	ds_read_b128 v[194:197], v230 offset:53248
	ds_read_b128 v[198:201], v230 offset:54272
	ds_read_b128 v[202:205], v230 offset:55296
	ds_read_b128 v[206:209], v230 offset:56320
	s_add_u32 s100, s84, 0x80
	s_addc_u32 s101, s85, 0
	global_load_lds_dwordx4 v182, s[100:101]
	s_add_i32 m0, s0, 0x2000
	s_add_u32 s0, s84, 0x80080
	s_addc_u32 s1, s85, 0
	s_add_i32 s79, s81, s30
	global_load_lds_dwordx4 v178, s[100:101]
	s_mov_b32 m0, s79
	s_nop 0
	global_load_lds_dwordx4 v182, s[0:1]
	s_add_i32 m0, s79, 0x2000
	s_nop 0
	global_load_lds_dwordx4 v178, s[0:1]
	s_mov_b32 m0, s49
	s_nop 0
	s_add_u32 s100, s86, 0x80
	s_addc_u32 s101, s87, 0
	global_load_lds_dwordx4 v174, s[100:101]
	s_mov_b32 m0, s50
	s_nop 0
	global_load_lds_dwordx4 v176, s[100:101]
	s_waitcnt vmcnt(8)
	s_waitcnt lgkmcnt(0)
	s_barrier
	s_setprio 2
	v_mfma_f32_16x16x32_bf16 v[62:65], v[90:93], v[162:165], v[62:65]
	v_mfma_f32_16x16x32_bf16 v[62:65], v[94:97], v[166:169], v[62:65]
	v_mfma_f32_16x16x32_bf16 v[46:49], v[90:93], v[184:187], v[46:49]
	v_mfma_f32_16x16x32_bf16 v[46:49], v[94:97], v[190:193], v[46:49]
	v_mfma_f32_16x16x32_bf16 v[30:33], v[90:93], v[194:197], v[30:33]
	v_mfma_f32_16x16x32_bf16 v[30:33], v[94:97], v[198:201], v[30:33]
	v_mfma_f32_16x16x32_bf16 v[14:17], v[90:93], v[202:205], v[14:17]
	v_mfma_f32_16x16x32_bf16 v[14:17], v[94:97], v[206:209], v[14:17]
	v_mfma_f32_16x16x32_bf16 v[10:13], v[98:101], v[202:205], v[10:13]
	v_mfma_f32_16x16x32_bf16 v[10:13], v[102:105], v[206:209], v[10:13]
	v_mfma_f32_16x16x32_bf16 v[26:29], v[98:101], v[194:197], v[26:29]
	v_mfma_f32_16x16x32_bf16 v[26:29], v[102:105], v[198:201], v[26:29]
	v_mfma_f32_16x16x32_bf16 v[42:45], v[98:101], v[184:187], v[42:45]
	v_mfma_f32_16x16x32_bf16 v[42:45], v[102:105], v[190:193], v[42:45]
	v_mfma_f32_16x16x32_bf16 v[58:61], v[98:101], v[162:165], v[58:61]
	v_mfma_f32_16x16x32_bf16 v[58:61], v[102:105], v[166:169], v[58:61]
	v_mfma_f32_16x16x32_bf16 v[54:57], v[146:149], v[162:165], v[54:57]
	v_mfma_f32_16x16x32_bf16 v[54:57], v[150:153], v[166:169], v[54:57]
	v_mfma_f32_16x16x32_bf16 v[38:41], v[146:149], v[184:187], v[38:41]
	v_mfma_f32_16x16x32_bf16 v[38:41], v[150:153], v[190:193], v[38:41]
	v_mfma_f32_16x16x32_bf16 v[22:25], v[146:149], v[194:197], v[22:25]
	v_mfma_f32_16x16x32_bf16 v[22:25], v[150:153], v[198:201], v[22:25]
	v_mfma_f32_16x16x32_bf16 v[6:9], v[146:149], v[202:205], v[6:9]
	v_mfma_f32_16x16x32_bf16 v[6:9], v[150:153], v[206:209], v[6:9]
	v_mfma_f32_16x16x32_bf16 v[2:5], v[154:157], v[202:205], v[2:5]
	v_mfma_f32_16x16x32_bf16 v[2:5], v[158:161], v[206:209], v[2:5]
	v_mfma_f32_16x16x32_bf16 v[18:21], v[154:157], v[194:197], v[18:21]
	v_mfma_f32_16x16x32_bf16 v[18:21], v[158:161], v[198:201], v[18:21]
	v_mfma_f32_16x16x32_bf16 v[34:37], v[154:157], v[184:187], v[34:37]
	v_mfma_f32_16x16x32_bf16 v[34:37], v[158:161], v[190:193], v[34:37]
	v_mfma_f32_16x16x32_bf16 v[50:53], v[154:157], v[162:165], v[50:53]
	v_mfma_f32_16x16x32_bf16 v[50:53], v[158:161], v[166:169], v[50:53]
	s_setprio 0
	s_add_i32 s73, s73, 2
	s_add_u32 s82, s82, 0x100
	s_addc_u32 s83, s83, 0
	s_add_u32 s59, s59, 0x100
	s_addc_u32 s71, s71, 0
	s_cmp_gt_u32 s73, 29
	s_cbranch_scc0 .Lhob_go_Thead
	s_branch .Lhob_go_exit
.Lhob_go_exit:
	s_and_b64 vcc, exec, s[68:69]
	s_cbranch_vccz .LBB0_544
	s_setprio 0

; #define PG8_STAGE(bufoff, gbase, voff) do { _Pragma("unroll") for (int _i = 0; _i < 2; ++_i) \
;         __builtin_amdgcn_global_load_lds((const unsigned*)((const char*)(gbase) + (voff)[_i]), (PG8_LAS unsigned*)(lds + (bufoff) + ldsw + _i * 8192), 16, 0, 0); } while (0)
; #define PG8_BAR __builtin_amdgcn_s_barrier()
;     ...
;     for (int i = 0; i < 2; ++i) { int R, C; stage_rc(tid * 16 + i * 8192, R, C); const int Rb = Epi::PERM ? ((R & ~31) + perm32(R & 31)) : R;
;         const int Ra = Epi::PERMROW ? ((R & ~63) + 4 * (R & 15) + ((R >> 4) & 3)) : R;
;         voffA[i] = (unsigned)(Ra * K + C) * 2u; voffB[i] = (unsigned)(Rb * K + C) * 2u; }
;     ...
;         PG8_STAGE(PG8_SB(0, 0), cB, voffB); PG8_STAGE(PG8_SB(0, 1), cB + hstep, voffB); PG8_STAGE(PG8_SA(0, 0), cA, voffA); PG8_STAGE(PG8_SA(0, 1), cA + hstep, voffA);
;         if (wr == 1) PG8_BAR;
.LBB0_588:
	v_ashrrev_i32_e32 v3, 31, v10
	v_lshrrev_b32_e32 v3, 26, v3
	v_add_u32_e32 v3, v10, v3
	v_ashrrev_i32_e32 v12, 6, v3
	v_bfe_i32 v3, v10, 27, 1
	v_lshlrev_b32_e32 v2, 4, v10
	v_lshrrev_b32_e32 v3, 22, v3
	v_add_u32_e32 v3, v2, v3
	v_and_b32_e32 v3, 0xfffffc00, v3
	v_sub_u32_e32 v3, v2, v3
	v_lshrrev_b32_e32 v4, 4, v3
	v_bitop3_b32 v4, v4, v3, 32 bitop3:0x6c
	v_ashrrev_i32_e32 v3, 31, v3
	v_lshrrev_b32_e32 v3, 26, v3
	v_add_u32_e32 v3, v4, v3
	v_ashrrev_i32_e32 v13, 6, v3
	v_lshlrev_b32_e32 v5, 3, v12
	v_mul_i32_i24_e32 v6, 64, v13
	v_and_b32_e32 v5, -16, v5
	v_sub_u32_e32 v4, v4, v6
	v_add_u32_e32 v3, v13, v5
	v_lshlrev_b32_e32 v5, 5, v12
	v_ashrrev_i16_sdwa v4, v235, sext(v4) dst_sel:DWORD dst_unused:UNUSED_PAD src0_sel:DWORD src1_sel:BYTE_0
	v_and_b32_e32 v5, 32, v5
	v_bfe_i32 v14, v4, 0, 16
	v_and_b32_e32 v7, 3, v13
	s_mov_b32 s15, 0xfffe0
	v_add_lshl_u32 v5, v5, v14, 1
	v_add_u32_e32 v2, 0x2000, v2
	v_lshlrev_b32_e32 v4, 1, v3
	v_lshrrev_b32_e32 v6, 2, v3
	v_and_or_b32 v7, v3, s15, v7
	v_lshl_add_u32 v130, v3, 12, v5
	v_ashrrev_i32_e32 v3, 31, v2
	v_lshrrev_b32_e32 v3, 22, v3
	v_add_u32_e32 v3, v2, v3
	v_ashrrev_i32_e32 v15, 10, v3
	v_mul_i32_i24_e32 v3, 0x400, v15
	v_sub_u32_e32 v2, v2, v3
	v_and_b32_e32 v4, 24, v4
	v_and_b32_e32 v6, 4, v6
	v_lshrrev_b32_e32 v3, 4, v2
	v_or3_b32 v4, v7, v6, v4
	v_bitop3_b32 v2, v3, v2, 32 bitop3:0x6c
	v_lshl_add_u32 v132, v4, 12, v5
	v_ashrrev_i32_e32 v4, 31, v2
	v_lshrrev_b32_e32 v4, 26, v4
	v_add_u32_e32 v4, v2, v4
	v_lshlrev_b32_e32 v3, 3, v15
	v_ashrrev_i32_e32 v16, 6, v4
	v_and_b32_e32 v4, 0xc0, v4
	v_and_b32_e32 v3, -16, v3
	v_sub_u32_e32 v2, v2, v4
	s_ashr_i32 s40, s0, 8
	v_add_u32_e32 v3, v16, v3
	v_ashrrev_i16_sdwa v2, v235, sext(v2) dst_sel:DWORD dst_unused:UNUSED_PAD src0_sel:DWORD src1_sel:BYTE_0
	v_and_b32_e32 v6, 3, v16
	s_lshl_b32 s20, s1, 10
	s_mul_i32 s24, s86, 0x1900000
	v_lshlrev_b32_e32 v5, 5, v15
	v_bfe_i32 v17, v2, 0, 16
	v_lshlrev_b32_e32 v2, 1, v3
	v_lshrrev_b32_e32 v4, 2, v3
	v_and_or_b32 v6, v3, s15, v6
	s_mul_hi_u32 s15, s86, 0x1900000
	s_add_u32 s24, s4, s24
	v_and_b32_e32 v5, 32, v5
	v_and_b32_e32 v2, 24, v2
	v_and_b32_e32 v4, 4, v4
	s_addc_u32 s15, s5, s15
	v_or3_b32 v2, v6, v4, v2
	v_add_lshl_u32 v4, v5, v17, 1
	s_add_u32 s24, s24, 0xc00000
	v_lshl_add_u32 v136, v2, 12, v4
	s_addc_u32 s30, s15, 0
	v_mov_b32_e32 v2, s14
	s_add_u32 s31, s4, 0x18000000
	v_readfirstlane_b32 s26, v2
	s_addc_u32 s33, s5, 0
	s_ashr_i32 s73, s72, 31
	s_bfe_i64 s[14:15], s[26:27], 0x80000
	s_lshl_b64 s[44:45], s[72:73], 20
	s_lshl_b64 s[14:15], s[14:15], 20
	s_add_u32 s76, s24, s14
	s_addc_u32 s77, s30, s15
	s_add_i32 s35, s20, 0
	s_add_i32 m0, s35, 0x10000
	v_lshl_add_u32 v134, v3, 12, v4
	global_load_lds_dwordx4 v132, s[76:77]
	s_add_i32 m0, s35, 0x12000
	s_add_u32 s14, s76, 0x80000
	global_load_lds_dwordx4 v136, s[76:77]
	s_addc_u32 s15, s77, 0
	s_add_i32 m0, s35, 0x14000
	v_mov_b32_e32 v133, v183
	global_load_lds_dwordx4 v132, s[14:15]
	s_add_i32 m0, s35, 0x16000
	s_add_u32 s74, s31, s44
	s_addc_u32 s75, s33, s45
	s_add_i32 s37, s35, 0x2000
	global_load_lds_dwordx4 v136, s[14:15]
	s_mov_b32 m0, s35
	s_add_u32 s14, s74, 0x80000
	global_load_lds_dwordx4 v130, s[74:75]
	s_mov_b32 m0, s37
	s_addc_u32 s15, s75, 0
	s_add_i32 s43, s35, 0x4000
	global_load_lds_dwordx4 v134, s[74:75]
	s_mov_b32 m0, s43
	s_add_i32 s44, s35, 0x6000
	global_load_lds_dwordx4 v130, s[14:15]
	s_mov_b32 m0, s44
	v_mov_b32_e32 v137, v183
	global_load_lds_dwordx4 v134, s[14:15]
	v_mov_b32_e32 v131, v183
	v_mov_b32_e32 v135, v183
	s_cmp_eq_u32 s40, 1
	s_mov_b32 s85, s51
	v_lshl_add_u64 v[8:9], s[76:77], 0, v[132:133]
	v_lshl_add_u64 v[6:7], s[76:77], 0, v[136:137]
	v_lshl_add_u64 v[2:3], s[74:75], 0, v[130:131]
	s_cselect_b64 s[14:15], -1, 0
	s_cmp_lg_u32 s40, 1
	v_lshl_add_u64 v[4:5], s[74:75], 0, v[134:135]
	s_cbranch_scc1 .LBB0_590
	s_setprio 0

; #define PG8_STAGE(bufoff, gbase, voff) do { _Pragma("unroll") for (int _i = 0; _i < 2; ++_i) \
;         __builtin_amdgcn_global_load_lds((const unsigned*)((const char*)(gbase) + (voff)[_i]), (PG8_LAS unsigned*)(lds + (bufoff) + ldsw + _i * 8192), 16, 0, 0); } while (0)
; #define PG8_LDA(dst, b, h) do { _Pragma("unroll") for (int m = 0; m < 4; ++m) _Pragma("unroll") for (int k = 0; k < 2; ++k) dst[m][k] = *(const PG8_LAS bf16x8*)(lds + PG8_SA(b, h) + aoff + m * 2048 + k * 1024); } while (0)
; #define PG8_LDB(dst, b, h) do { _Pragma("unroll") for (int n = 0; n < 2; ++n) _Pragma("unroll") for (int k = 0; k < 2; ++k) dst[n][k] = *(const PG8_LAS bf16x8*)(lds + PG8_SB(b, h) + boff + n * 2048 + k * 1024); } while (0)
; #define PG8_WAIT_L(n) asm volatile("s_waitcnt lgkmcnt(" #n ")" ::: "memory")
; #define PG8_WAIT_V_SEL(sel) asm volatile("s_cmp_eq_u32 %0, 0\n\ts_cbranch_scc1 .Lw8_%=\n\ts_waitcnt vmcnt(22)\n\ts_branch .Lwd_%=\n.Lw8_%=:\n\ts_waitcnt vmcnt(8)\n.Lwd_%=:" :: "s"(sel) : "memory", "scc")
; #define PG8_BAR __builtin_amdgcn_s_barrier()
; #define PG8_SCHED __builtin_amdgcn_sched_barrier(0)
;     ...
;         for (int t = 0; t < nt * KREP; t += 2) {
;             const bool last = (t == nt * KREP - 2);
;             const int t1w = KREP > 1 ? ((t + 1) & (nt - 1)) : t + 1, t2w = KREP > 1 ? ((t + 2) & (nt - 1)) : t + 2;
;             const char* a1 = cA + (size_t)t1w * kstep;
;             const char* a2 = last ? nA : cA + (size_t)t2w * kstep; const char* b2 = last ? nB : cB + (size_t)t2w * kstep;
;             const char* a3 = a2 + kstep; const char* b3 = b2 + kstep;
;             if (last && has_next) S.a_ready(nxt);
;             const int relax = __builtin_amdgcn_readfirstlane((MK_RELAXW && t == 0 && ui > 0) ? 1 : 0);
;             if constexpr (SP2) {
;             PG8_LDB(B0, 0, 0); PG8_LDB(B1, 0, 1); PG8_SCHED; PG8_LDA(At, 0, 0); PG8_STAGE(PG8_SA(1, 1), a1 + hstep, voffA);
;             PG8_WAIT_V_SEL(relax);
;             PG8_WAIT_L(0); PG8_BAR; PG8_MMA(0, 0, At, B0); PG8_MMA(0, 1, At, B1); PG8_BAR; PG8_SCHED;
;     ...
; #pragma unroll
;         for (int a = 0; a < 2; ++a)
; #pragma unroll
;             for (int b = 0; b < 2; ++b)
; #pragma unroll
;                 for (int m = 0; m < 4; ++m)
; #pragma unroll
;                     for (int n = 0; n < 2; ++n) acc[a][b][m][n] = (f32x4){0.f, 0.f, 0.f, 0.f};
;         cur = nxt; cA = nA; cB = nB; ++ui;
.LBB0_595:
	s_ashr_i32 s67, s66, 31
	s_lshl_b64 s[0:1], s[66:67], 20
	s_add_u32 s68, s31, s0
	s_addc_u32 s69, s33, s1
	s_and_b64 s[0:1], s[2:3], exec
	s_cselect_b32 s40, s69, s75
	s_cselect_b32 s41, s68, s74
	s_ashr_i32 s65, s64, 31
	s_lshl_b64 s[0:1], s[64:65], 20
	s_add_u32 s70, s24, s0
	s_addc_u32 s71, s30, s1
	s_and_b64 s[0:1], s[2:3], exec
	s_cselect_b32 s65, s71, s77
	s_cselect_b32 s73, s70, s76
	s_add_u32 s74, s74, 0x80080
	s_addc_u32 s75, s75, 0
	s_add_u32 s80, s76, 0x100
	v_mov_b64_e32 v[2:3], 0
	v_mov_b64_e32 v[4:5], 0
	v_mov_b64_e32 v[6:7], 0
	v_mov_b64_e32 v[8:9], 0
	v_mov_b64_e32 v[10:11], 0
	v_mov_b64_e32 v[12:13], 0
	v_mov_b64_e32 v[14:15], 0
	v_mov_b64_e32 v[16:17], 0
	v_mov_b64_e32 v[18:19], 0
	v_mov_b64_e32 v[20:21], 0
	v_mov_b64_e32 v[22:23], 0
	v_mov_b64_e32 v[24:25], 0
	v_mov_b64_e32 v[26:27], 0
	v_mov_b64_e32 v[28:29], 0
	v_mov_b64_e32 v[30:31], 0
	v_mov_b64_e32 v[32:33], 0
	v_mov_b64_e32 v[34:35], 0
	v_mov_b64_e32 v[36:37], 0
	v_mov_b64_e32 v[38:39], 0
	v_mov_b64_e32 v[40:41], 0
	v_mov_b64_e32 v[42:43], 0
	v_mov_b64_e32 v[44:45], 0
	v_mov_b64_e32 v[46:47], 0
	v_mov_b64_e32 v[48:49], 0
	v_mov_b64_e32 v[50:51], 0
	v_mov_b64_e32 v[52:53], 0
	v_mov_b64_e32 v[54:55], 0
	v_mov_b64_e32 v[56:57], 0
	v_mov_b64_e32 v[58:59], 0
	v_mov_b64_e32 v[60:61], 0
	v_mov_b64_e32 v[62:63], 0
	v_mov_b64_e32 v[64:65], 0
	v_mov_b64_e32 v[66:67], 0
	v_mov_b64_e32 v[68:69], 0
	v_mov_b64_e32 v[70:71], 0
	v_mov_b64_e32 v[72:73], 0
	v_mov_b64_e32 v[74:75], 0
	v_mov_b64_e32 v[76:77], 0
	v_mov_b64_e32 v[78:79], 0
	v_mov_b64_e32 v[80:81], 0
	v_mov_b64_e32 v[82:83], 0
	v_mov_b64_e32 v[84:85], 0
	v_mov_b64_e32 v[86:87], 0
	v_mov_b64_e32 v[88:89], 0
	v_mov_b64_e32 v[90:91], 0
	v_mov_b64_e32 v[92:93], 0
	v_mov_b64_e32 v[94:95], 0
	v_mov_b64_e32 v[96:97], 0
	v_mov_b64_e32 v[98:99], 0
	v_mov_b64_e32 v[100:101], 0
	v_mov_b64_e32 v[102:103], 0
	v_mov_b64_e32 v[104:105], 0
	v_mov_b64_e32 v[106:107], 0
	v_mov_b64_e32 v[108:109], 0
	v_mov_b64_e32 v[110:111], 0
	v_mov_b64_e32 v[112:113], 0
	v_mov_b64_e32 v[114:115], 0
	v_mov_b64_e32 v[116:117], 0
	v_mov_b64_e32 v[118:119], 0
	v_mov_b64_e32 v[120:121], 0
	v_mov_b64_e32 v[122:123], 0
	v_mov_b64_e32 v[124:125], 0
	v_mov_b64_e32 v[126:127], 0
	v_mov_b64_e32 v[128:129], 0
	s_addc_u32 s81, s77, 0
	s_mov_b32 s82, -2
	v_add_u32_e32 v180, 0x10000, v146
	s_cmp_lg_u32 s62, 0
	s_cbranch_scc0 .Lhob_qkv_Thead
.LBB0_596:
	s_add_u32 s0, s74, 0xfff80080
	s_addc_u32 s1, s75, -1
	s_add_i32 s83, 0, 0x10000
	s_cmp_eq_u32 s82, 28
	s_cselect_b32 s79, s40, s1
	s_cselect_b32 s78, s41, s0
	s_cselect_b32 s77, s65, s81
	s_cselect_b32 s76, s73, s80
	s_add_i32 s84, 0, 0x14000
	ds_read_b128 v[150:153], v180
	ds_read_b128 v[154:157], v180 offset:1024
	ds_read_b128 v[158:161], v180 offset:2048
	ds_read_b128 v[162:165], v180 offset:3072
	ds_read_b128 v[166:169], v180 offset:16384
	ds_read_b128 v[172:175], v180 offset:17408
	ds_read_b128 v[176:179], v180 offset:18432
	ds_read_b128 v[188:191], v180 offset:19456
	s_add_i32 m0, s35, 0xc000
	ds_read_b128 v[192:195], v148
	ds_read_b128 v[196:199], v148 offset:1024
	ds_read_b128 v[200:203], v148 offset:2048
	ds_read_b128 v[204:207], v148 offset:3072
	ds_read_b128 v[208:211], v148 offset:4096
	ds_read_b128 v[212:215], v148 offset:5120
	ds_read_b128 v[216:219], v148 offset:6144
	ds_read_b128 v[220:223], v148 offset:7168
	global_load_lds_dwordx4 v140, s[74:75]
	s_add_i32 m0, s35, 0xe000
	s_nop 0
	global_load_lds_dwordx4 v142, s[74:75]
	s_waitcnt vmcnt(8)
	s_waitcnt lgkmcnt(0)
	s_setprio 1
	v_mfma_f32_16x16x32_bf16 v[126:129], v[150:153], v[192:195], v[126:129]
	v_mfma_f32_16x16x32_bf16 v[126:129], v[154:157], v[196:199], v[126:129]
	v_mfma_f32_16x16x32_bf16 v[122:125], v[150:153], v[200:203], v[122:125]
	v_mfma_f32_16x16x32_bf16 v[122:125], v[154:157], v[204:207], v[122:125]
	v_mfma_f32_16x16x32_bf16 v[118:121], v[150:153], v[208:211], v[118:121]
	v_mfma_f32_16x16x32_bf16 v[118:121], v[154:157], v[212:215], v[118:121]
	v_mfma_f32_16x16x32_bf16 v[114:117], v[150:153], v[216:219], v[114:117]
	v_mfma_f32_16x16x32_bf16 v[114:117], v[154:157], v[220:223], v[114:117]
	v_mfma_f32_16x16x32_bf16 v[98:101], v[158:161], v[216:219], v[98:101]
	v_mfma_f32_16x16x32_bf16 v[98:101], v[162:165], v[220:223], v[98:101]
	v_mfma_f32_16x16x32_bf16 v[102:105], v[158:161], v[208:211], v[102:105]
	v_mfma_f32_16x16x32_bf16 v[102:105], v[162:165], v[212:215], v[102:105]
	v_mfma_f32_16x16x32_bf16 v[106:109], v[158:161], v[200:203], v[106:109]
	v_mfma_f32_16x16x32_bf16 v[106:109], v[162:165], v[204:207], v[106:109]
	v_mfma_f32_16x16x32_bf16 v[110:113], v[158:161], v[192:195], v[110:113]
	v_mfma_f32_16x16x32_bf16 v[110:113], v[162:165], v[196:199], v[110:113]
	v_mfma_f32_16x16x32_bf16 v[70:73], v[166:169], v[192:195], v[70:73]
	v_mfma_f32_16x16x32_bf16 v[70:73], v[172:175], v[196:199], v[70:73]
	v_mfma_f32_16x16x32_bf16 v[66:69], v[166:169], v[200:203], v[66:69]
	v_mfma_f32_16x16x32_bf16 v[66:69], v[172:175], v[204:207], v[66:69]
	v_mfma_f32_16x16x32_bf16 v[58:61], v[166:169], v[208:211], v[58:61]
	v_mfma_f32_16x16x32_bf16 v[58:61], v[172:175], v[212:215], v[58:61]
	v_mfma_f32_16x16x32_bf16 v[46:49], v[166:169], v[216:219], v[46:49]
	v_mfma_f32_16x16x32_bf16 v[46:49], v[172:175], v[220:223], v[46:49]
	v_mfma_f32_16x16x32_bf16 v[34:37], v[176:179], v[216:219], v[34:37]
	v_mfma_f32_16x16x32_bf16 v[34:37], v[188:191], v[220:223], v[34:37]
	v_mfma_f32_16x16x32_bf16 v[38:41], v[176:179], v[208:211], v[38:41]
	v_mfma_f32_16x16x32_bf16 v[38:41], v[188:191], v[212:215], v[38:41]
	v_mfma_f32_16x16x32_bf16 v[42:45], v[176:179], v[200:203], v[42:45]
	v_mfma_f32_16x16x32_bf16 v[42:45], v[188:191], v[204:207], v[42:45]
	v_mfma_f32_16x16x32_bf16 v[50:53], v[176:179], v[192:195], v[50:53]
	v_mfma_f32_16x16x32_bf16 v[50:53], v[188:191], v[196:199], v[50:53]
	s_setprio 0
	s_barrier
; #define PG8_STAGE(bufoff, gbase, voff) do { _Pragma("unroll") for (int _i = 0; _i < 2; ++_i) \
;         __builtin_amdgcn_global_load_lds((const unsigned*)((const char*)(gbase) + (voff)[_i]), (PG8_LAS unsigned*)(lds + (bufoff) + ldsw + _i * 8192), 16, 0, 0); } while (0)
; #define PG8_LDA(dst, b, h) do { _Pragma("unroll") for (int m = 0; m < 4; ++m) _Pragma("unroll") for (int k = 0; k < 2; ++k) dst[m][k] = *(const PG8_LAS bf16x8*)(lds + PG8_SA(b, h) + aoff + m * 2048 + k * 1024); } while (0)
; #define PG8_LDB(dst, b, h) do { _Pragma("unroll") for (int n = 0; n < 2; ++n) _Pragma("unroll") for (int k = 0; k < 2; ++k) dst[n][k] = *(const PG8_LAS bf16x8*)(lds + PG8_SB(b, h) + boff + n * 2048 + k * 1024); } while (0)
; #define PG8_WAIT_V(n) asm volatile("s_waitcnt vmcnt(" #n ")" ::: "memory")
; #define PG8_WAIT_L(n) asm volatile("s_waitcnt lgkmcnt(" #n ")" ::: "memory")
; #define PG8_WAIT_V_SEL(sel) asm volatile("s_cmp_eq_u32 %0, 0\n\ts_cbranch_scc1 .Lw8_%=\n\ts_waitcnt vmcnt(22)\n\ts_branch .Lwd_%=\n.Lw8_%=:\n\ts_waitcnt vmcnt(8)\n.Lwd_%=:" :: "s"(sel) : "memory", "scc")
; #define PG8_BAR __builtin_amdgcn_s_barrier()
; #define PG8_SCHED __builtin_amdgcn_sched_barrier(0)
;     ...
;             PG8_LDA(At, 0, 1); PG8_STAGE(PG8_SB(0, 0), b2, voffB); PG8_STAGE(PG8_SB(0, 1), b2 + hstep, voffB); PG8_STAGE(PG8_SA(0, 0), a2, voffA);
;             PG8_WAIT_V_SEL(relax);
;             PG8_WAIT_L(0); PG8_BAR; PG8_MMA(1, 0, At, B0); PG8_MMA(1, 1, At, B1); PG8_BAR; PG8_SCHED;
;             PG8_LDB(B0, 1, 0); PG8_LDB(B1, 1, 1); PG8_SCHED; PG8_LDA(At, 1, 0); PG8_STAGE(PG8_SA(0, 1), a2 + hstep, voffA);
;             PG8_WAIT_V(8); PG8_WAIT_L(0); PG8_BAR; PG8_MMA(0, 0, At, B0); PG8_MMA(0, 1, At, B1); PG8_BAR; PG8_SCHED;
	s_add_i32 s0, s83, s20
	s_mov_b32 m0, s0
	ds_read_b128 v[192:195], v148 offset:16384
	ds_read_b128 v[196:199], v148 offset:17408
	ds_read_b128 v[200:203], v148 offset:18432
	ds_read_b128 v[204:207], v148 offset:19456
	ds_read_b128 v[208:211], v148 offset:20480
	ds_read_b128 v[212:215], v148 offset:21504
	ds_read_b128 v[216:219], v148 offset:22528
	ds_read_b128 v[220:223], v148 offset:23552
	global_load_lds_dwordx4 v132, s[76:77]
	s_add_i32 m0, s0, 0x2000
	s_add_u32 s0, s76, 0x80000
	s_addc_u32 s1, s77, 0
	s_add_i32 s83, s84, s20
	global_load_lds_dwordx4 v136, s[76:77]
	s_mov_b32 m0, s83
	s_nop 0
	global_load_lds_dwordx4 v132, s[0:1]
	s_add_i32 m0, s83, 0x2000
	s_nop 0
	global_load_lds_dwordx4 v136, s[0:1]
	s_mov_b32 m0, s35
	s_nop 0
	global_load_lds_dwordx4 v130, s[78:79]
	s_mov_b32 m0, s37
	s_nop 0
	global_load_lds_dwordx4 v134, s[78:79]
	s_waitcnt vmcnt(8)
	s_waitcnt lgkmcnt(0)
	s_setprio 1
	v_mfma_f32_16x16x32_bf16 v[94:97], v[150:153], v[192:195], v[94:97]
	v_mfma_f32_16x16x32_bf16 v[94:97], v[154:157], v[196:199], v[94:97]
	v_mfma_f32_16x16x32_bf16 v[90:93], v[150:153], v[200:203], v[90:93]
	v_mfma_f32_16x16x32_bf16 v[90:93], v[154:157], v[204:207], v[90:93]
	v_mfma_f32_16x16x32_bf16 v[86:89], v[150:153], v[208:211], v[86:89]
	v_mfma_f32_16x16x32_bf16 v[86:89], v[154:157], v[212:215], v[86:89]
	v_mfma_f32_16x16x32_bf16 v[82:85], v[150:153], v[216:219], v[82:85]
	v_mfma_f32_16x16x32_bf16 v[82:85], v[154:157], v[220:223], v[82:85]
	v_mfma_f32_16x16x32_bf16 v[54:57], v[158:161], v[216:219], v[54:57]
	v_mfma_f32_16x16x32_bf16 v[54:57], v[162:165], v[220:223], v[54:57]
	v_mfma_f32_16x16x32_bf16 v[62:65], v[158:161], v[208:211], v[62:65]
	v_mfma_f32_16x16x32_bf16 v[62:65], v[162:165], v[212:215], v[62:65]
	v_mfma_f32_16x16x32_bf16 v[74:77], v[158:161], v[200:203], v[74:77]
	v_mfma_f32_16x16x32_bf16 v[74:77], v[162:165], v[204:207], v[74:77]
	v_mfma_f32_16x16x32_bf16 v[78:81], v[158:161], v[192:195], v[78:81]
	v_mfma_f32_16x16x32_bf16 v[78:81], v[162:165], v[196:199], v[78:81]
	v_mfma_f32_16x16x32_bf16 v[30:33], v[166:169], v[192:195], v[30:33]
	v_mfma_f32_16x16x32_bf16 v[30:33], v[172:175], v[196:199], v[30:33]
	v_mfma_f32_16x16x32_bf16 v[26:29], v[166:169], v[200:203], v[26:29]
	v_mfma_f32_16x16x32_bf16 v[26:29], v[172:175], v[204:207], v[26:29]
	v_mfma_f32_16x16x32_bf16 v[22:25], v[166:169], v[208:211], v[22:25]
	v_mfma_f32_16x16x32_bf16 v[22:25], v[172:175], v[212:215], v[22:25]
	v_mfma_f32_16x16x32_bf16 v[18:21], v[166:169], v[216:219], v[18:21]
	v_mfma_f32_16x16x32_bf16 v[18:21], v[172:175], v[220:223], v[18:21]
	v_mfma_f32_16x16x32_bf16 v[2:5], v[176:179], v[216:219], v[2:5]
	v_mfma_f32_16x16x32_bf16 v[2:5], v[188:191], v[220:223], v[2:5]
	v_mfma_f32_16x16x32_bf16 v[6:9], v[176:179], v[208:211], v[6:9]
	v_mfma_f32_16x16x32_bf16 v[6:9], v[188:191], v[212:215], v[6:9]
	v_mfma_f32_16x16x32_bf16 v[10:13], v[176:179], v[200:203], v[10:13]
	v_mfma_f32_16x16x32_bf16 v[10:13], v[188:191], v[204:207], v[10:13]
	v_mfma_f32_16x16x32_bf16 v[14:17], v[176:179], v[192:195], v[14:17]
	v_mfma_f32_16x16x32_bf16 v[14:17], v[188:191], v[196:199], v[14:17]
	s_setprio 0
	s_barrier
	s_add_i32 s83, 0, 0x18000
	s_add_i32 s84, 0, 0x1c000
	ds_read_b128 v[150:153], v180 offset:32768
	ds_read_b128 v[154:157], v180 offset:33792
	ds_read_b128 v[158:161], v180 offset:34816
	ds_read_b128 v[162:165], v180 offset:35840
	ds_read_b128 v[166:169], v180 offset:49152
	ds_read_b128 v[172:175], v180 offset:50176
	ds_read_b128 v[176:179], v180 offset:51200
	ds_read_b128 v[188:191], v180 offset:52224
	s_add_u32 s0, s78, 0x80000
	s_addc_u32 s1, s79, 0
	s_mov_b32 m0, s43
	ds_read_b128 v[192:195], v148 offset:32768
	ds_read_b128 v[196:199], v148 offset:33792
	ds_read_b128 v[200:203], v148 offset:34816
	ds_read_b128 v[204:207], v148 offset:35840
	ds_read_b128 v[208:211], v148 offset:36864
	ds_read_b128 v[212:215], v148 offset:37888
	ds_read_b128 v[216:219], v148 offset:38912
	ds_read_b128 v[220:223], v148 offset:39936
	global_load_lds_dwordx4 v130, s[0:1]
	s_mov_b32 m0, s44
	s_nop 0
	global_load_lds_dwordx4 v134, s[0:1]
	s_waitcnt vmcnt(8)
	s_waitcnt lgkmcnt(0)
	s_setprio 1
	v_mfma_f32_16x16x32_bf16 v[126:129], v[150:153], v[192:195], v[126:129]
	v_mfma_f32_16x16x32_bf16 v[126:129], v[154:157], v[196:199], v[126:129]
	v_mfma_f32_16x16x32_bf16 v[122:125], v[150:153], v[200:203], v[122:125]
	v_mfma_f32_16x16x32_bf16 v[122:125], v[154:157], v[204:207], v[122:125]
	v_mfma_f32_16x16x32_bf16 v[118:121], v[150:153], v[208:211], v[118:121]
	v_mfma_f32_16x16x32_bf16 v[118:121], v[154:157], v[212:215], v[118:121]
	v_mfma_f32_16x16x32_bf16 v[114:117], v[150:153], v[216:219], v[114:117]
	v_mfma_f32_16x16x32_bf16 v[114:117], v[154:157], v[220:223], v[114:117]
	v_mfma_f32_16x16x32_bf16 v[98:101], v[158:161], v[216:219], v[98:101]
	v_mfma_f32_16x16x32_bf16 v[98:101], v[162:165], v[220:223], v[98:101]
	v_mfma_f32_16x16x32_bf16 v[102:105], v[158:161], v[208:211], v[102:105]
	v_mfma_f32_16x16x32_bf16 v[102:105], v[162:165], v[212:215], v[102:105]
	v_mfma_f32_16x16x32_bf16 v[106:109], v[158:161], v[200:203], v[106:109]
	v_mfma_f32_16x16x32_bf16 v[106:109], v[162:165], v[204:207], v[106:109]
	v_mfma_f32_16x16x32_bf16 v[110:113], v[158:161], v[192:195], v[110:113]
	v_mfma_f32_16x16x32_bf16 v[110:113], v[162:165], v[196:199], v[110:113]
	v_mfma_f32_16x16x32_bf16 v[70:73], v[166:169], v[192:195], v[70:73]
	v_mfma_f32_16x16x32_bf16 v[70:73], v[172:175], v[196:199], v[70:73]
	v_mfma_f32_16x16x32_bf16 v[66:69], v[166:169], v[200:203], v[66:69]
	v_mfma_f32_16x16x32_bf16 v[66:69], v[172:175], v[204:207], v[66:69]
	v_mfma_f32_16x16x32_bf16 v[58:61], v[166:169], v[208:211], v[58:61]
	v_mfma_f32_16x16x32_bf16 v[58:61], v[172:175], v[212:215], v[58:61]
	v_mfma_f32_16x16x32_bf16 v[46:49], v[166:169], v[216:219], v[46:49]
	v_mfma_f32_16x16x32_bf16 v[46:49], v[172:175], v[220:223], v[46:49]
	v_mfma_f32_16x16x32_bf16 v[34:37], v[176:179], v[216:219], v[34:37]
	v_mfma_f32_16x16x32_bf16 v[34:37], v[188:191], v[220:223], v[34:37]
	v_mfma_f32_16x16x32_bf16 v[38:41], v[176:179], v[208:211], v[38:41]
	v_mfma_f32_16x16x32_bf16 v[38:41], v[188:191], v[212:215], v[38:41]
	v_mfma_f32_16x16x32_bf16 v[42:45], v[176:179], v[200:203], v[42:45]
	v_mfma_f32_16x16x32_bf16 v[42:45], v[188:191], v[204:207], v[42:45]
	v_mfma_f32_16x16x32_bf16 v[50:53], v[176:179], v[192:195], v[50:53]
	v_mfma_f32_16x16x32_bf16 v[50:53], v[188:191], v[196:199], v[50:53]
	s_setprio 0
	s_barrier
; #define PG8_STAGE(bufoff, gbase, voff) do { _Pragma("unroll") for (int _i = 0; _i < 2; ++_i) \
;         __builtin_amdgcn_global_load_lds((const unsigned*)((const char*)(gbase) + (voff)[_i]), (PG8_LAS unsigned*)(lds + (bufoff) + ldsw + _i * 8192), 16, 0, 0); } while (0)
; #define PG8_LDA(dst, b, h) do { _Pragma("unroll") for (int m = 0; m < 4; ++m) _Pragma("unroll") for (int k = 0; k < 2; ++k) dst[m][k] = *(const PG8_LAS bf16x8*)(lds + PG8_SA(b, h) + aoff + m * 2048 + k * 1024); } while (0)
; #define PG8_LDB(dst, b, h) do { _Pragma("unroll") for (int n = 0; n < 2; ++n) _Pragma("unroll") for (int k = 0; k < 2; ++k) dst[n][k] = *(const PG8_LAS bf16x8*)(lds + PG8_SB(b, h) + boff + n * 2048 + k * 1024); } while (0)
; #define PG8_WAIT_V(n) asm volatile("s_waitcnt vmcnt(" #n ")" ::: "memory")
; #define PG8_WAIT_L(n) asm volatile("s_waitcnt lgkmcnt(" #n ")" ::: "memory")
; #define PG8_WAIT_V_SEL(sel) asm volatile("s_cmp_eq_u32 %0, 0\n\ts_cbranch_scc1 .Lw8_%=\n\ts_waitcnt vmcnt(22)\n\ts_branch .Lwd_%=\n.Lw8_%=:\n\ts_waitcnt vmcnt(8)\n.Lwd_%=:" :: "s"(sel) : "memory", "scc")
; #define PG8_BAR __builtin_amdgcn_s_barrier()
; #define PG8_SCHED __builtin_amdgcn_sched_barrier(0)
;     ...
;             PG8_LDB(B0, 0, 0); PG8_LDB(B1, 0, 1); PG8_SCHED; PG8_LDA(At, 0, 0); PG8_STAGE(PG8_SA(1, 1), a1 + hstep, voffA);
;             PG8_WAIT_V_SEL(relax);
;             PG8_WAIT_L(0); PG8_BAR; PG8_MMA(0, 0, At, B0); PG8_MMA(0, 1, At, B1); PG8_BAR; PG8_SCHED;
;             PG8_LDA(At, 0, 1); PG8_STAGE(PG8_SB(0, 0), b2, voffB); PG8_STAGE(PG8_SB(0, 1), b2 + hstep, voffB); PG8_STAGE(PG8_SA(0, 0), a2, voffA);
;             PG8_WAIT_V_SEL(relax);
;             PG8_WAIT_L(0); PG8_BAR; PG8_MMA(1, 0, At, B0); PG8_MMA(1, 1, At, B1); PG8_BAR; PG8_SCHED;
;             PG8_LDB(B0, 1, 0); PG8_LDB(B1, 1, 1); PG8_SCHED; PG8_LDA(At, 1, 0); PG8_STAGE(PG8_SA(0, 1), a2 + hstep, voffA);
;             PG8_WAIT_V(8); PG8_WAIT_L(0); PG8_BAR; PG8_MMA(0, 0, At, B0); PG8_MMA(0, 1, At, B1); PG8_BAR; PG8_SCHED;
;             PG8_LDA(At, 1, 1); PG8_STAGE(PG8_SB(1, 0), b3, voffB); PG8_STAGE(PG8_SB(1, 1), b3 + hstep, voffB); PG8_STAGE(PG8_SA(1, 0), a3, voffA);
;             PG8_WAIT_V(8); PG8_WAIT_L(0); PG8_BAR; PG8_MMA(1, 0, At, B0); PG8_MMA(1, 1, At, B1); PG8_BAR; PG8_SCHED;
	s_add_i32 s0, s83, s20
	s_mov_b32 m0, s0
	ds_read_b128 v[192:195], v148 offset:49152
	ds_read_b128 v[196:199], v148 offset:50176
	ds_read_b128 v[200:203], v148 offset:51200
	ds_read_b128 v[204:207], v148 offset:52224
	ds_read_b128 v[208:211], v148 offset:53248
	ds_read_b128 v[212:215], v148 offset:54272
	ds_read_b128 v[216:219], v148 offset:55296
	ds_read_b128 v[220:223], v148 offset:56320
	s_add_u32 s100, s76, 0x80
	s_addc_u32 s101, s77, 0
	global_load_lds_dwordx4 v132, s[100:101]
	s_add_i32 m0, s0, 0x2000
	s_add_u32 s0, s76, 0x80080
	s_addc_u32 s1, s77, 0
	s_add_i32 s76, s84, s20
	global_load_lds_dwordx4 v136, s[100:101]
	s_mov_b32 m0, s76
	s_nop 0
	global_load_lds_dwordx4 v132, s[0:1]
	s_add_i32 m0, s76, 0x2000
	s_nop 0
	global_load_lds_dwordx4 v136, s[0:1]
	s_mov_b32 m0, s48
	s_nop 0
	s_add_u32 s100, s78, 0x80
	s_addc_u32 s101, s79, 0
	global_load_lds_dwordx4 v130, s[100:101]
	s_mov_b32 m0, s49
	s_nop 0
	global_load_lds_dwordx4 v134, s[100:101]
	s_waitcnt vmcnt(8)
	s_waitcnt lgkmcnt(0)
	s_setprio 1
	v_mfma_f32_16x16x32_bf16 v[94:97], v[150:153], v[192:195], v[94:97]
	v_mfma_f32_16x16x32_bf16 v[94:97], v[154:157], v[196:199], v[94:97]
	v_mfma_f32_16x16x32_bf16 v[90:93], v[150:153], v[200:203], v[90:93]
	v_mfma_f32_16x16x32_bf16 v[90:93], v[154:157], v[204:207], v[90:93]
	v_mfma_f32_16x16x32_bf16 v[86:89], v[150:153], v[208:211], v[86:89]
	v_mfma_f32_16x16x32_bf16 v[86:89], v[154:157], v[212:215], v[86:89]
	v_mfma_f32_16x16x32_bf16 v[82:85], v[150:153], v[216:219], v[82:85]
	v_mfma_f32_16x16x32_bf16 v[82:85], v[154:157], v[220:223], v[82:85]
	v_mfma_f32_16x16x32_bf16 v[54:57], v[158:161], v[216:219], v[54:57]
	v_mfma_f32_16x16x32_bf16 v[54:57], v[162:165], v[220:223], v[54:57]
	v_mfma_f32_16x16x32_bf16 v[62:65], v[158:161], v[208:211], v[62:65]
	v_mfma_f32_16x16x32_bf16 v[62:65], v[162:165], v[212:215], v[62:65]
	v_mfma_f32_16x16x32_bf16 v[74:77], v[158:161], v[200:203], v[74:77]
	v_mfma_f32_16x16x32_bf16 v[74:77], v[162:165], v[204:207], v[74:77]
	v_mfma_f32_16x16x32_bf16 v[78:81], v[158:161], v[192:195], v[78:81]
	v_mfma_f32_16x16x32_bf16 v[78:81], v[162:165], v[196:199], v[78:81]
	v_mfma_f32_16x16x32_bf16 v[30:33], v[166:169], v[192:195], v[30:33]
	v_mfma_f32_16x16x32_bf16 v[30:33], v[172:175], v[196:199], v[30:33]
	v_mfma_f32_16x16x32_bf16 v[26:29], v[166:169], v[200:203], v[26:29]
	v_mfma_f32_16x16x32_bf16 v[26:29], v[172:175], v[204:207], v[26:29]
	v_mfma_f32_16x16x32_bf16 v[22:25], v[166:169], v[208:211], v[22:25]
	v_mfma_f32_16x16x32_bf16 v[22:25], v[172:175], v[212:215], v[22:25]
	v_mfma_f32_16x16x32_bf16 v[18:21], v[166:169], v[216:219], v[18:21]
	v_mfma_f32_16x16x32_bf16 v[18:21], v[172:175], v[220:223], v[18:21]
	v_mfma_f32_16x16x32_bf16 v[2:5], v[176:179], v[216:219], v[2:5]
	v_mfma_f32_16x16x32_bf16 v[2:5], v[188:191], v[220:223], v[2:5]
	v_mfma_f32_16x16x32_bf16 v[6:9], v[176:179], v[208:211], v[6:9]
	v_mfma_f32_16x16x32_bf16 v[6:9], v[188:191], v[212:215], v[6:9]
	v_mfma_f32_16x16x32_bf16 v[10:13], v[176:179], v[200:203], v[10:13]
	v_mfma_f32_16x16x32_bf16 v[10:13], v[188:191], v[204:207], v[10:13]
	v_mfma_f32_16x16x32_bf16 v[14:17], v[176:179], v[192:195], v[14:17]
	v_mfma_f32_16x16x32_bf16 v[14:17], v[188:191], v[196:199], v[14:17]
	s_setprio 0
	s_barrier
	s_add_i32 s82, s82, 2
	s_add_u32 s74, s74, 0x100
	s_addc_u32 s75, s75, 0
	s_add_u32 s80, s80, 0x100
	s_addc_u32 s81, s81, 0
	s_cmp_gt_u32 s82, 29
	s_cbranch_scc0 .LBB0_596
	s_branch .Lhob_qkv_exit
.Lhob_qkv_Thead:
	s_add_u32 s0, s74, 0xfff80080
	s_addc_u32 s1, s75, -1
	s_add_i32 s83, 0, 0x10000
	s_cmp_eq_u32 s82, 28
	s_cselect_b32 s79, s40, s1
	s_cselect_b32 s78, s41, s0
	s_cselect_b32 s77, s65, s81
	s_cselect_b32 s76, s73, s80
	s_add_i32 s84, 0, 0x14000
	ds_read_b128 v[150:153], v180
	ds_read_b128 v[154:157], v180 offset:1024
	ds_read_b128 v[158:161], v180 offset:2048
	ds_read_b128 v[162:165], v180 offset:3072
	ds_read_b128 v[166:169], v180 offset:16384
	ds_read_b128 v[172:175], v180 offset:17408
	ds_read_b128 v[176:179], v180 offset:18432
	ds_read_b128 v[188:191], v180 offset:19456
	s_add_i32 m0, s35, 0xc000
	ds_read_b128 v[192:195], v148
	ds_read_b128 v[196:199], v148 offset:1024
	ds_read_b128 v[200:203], v148 offset:2048
	ds_read_b128 v[204:207], v148 offset:3072
	ds_read_b128 v[208:211], v148 offset:4096
	ds_read_b128 v[212:215], v148 offset:5120
	ds_read_b128 v[216:219], v148 offset:6144
	ds_read_b128 v[220:223], v148 offset:7168
	global_load_lds_dwordx4 v140, s[74:75]
	s_add_i32 m0, s35, 0xe000
	s_nop 0
	global_load_lds_dwordx4 v142, s[74:75]
	s_waitcnt vmcnt(8)
	s_waitcnt lgkmcnt(0)
	s_barrier
; #define PG8_STAGE(bufoff, gbase, voff) do { _Pragma("unroll") for (int _i = 0; _i < 2; ++_i) \
;         __builtin_amdgcn_global_load_lds((const unsigned*)((const char*)(gbase) + (voff)[_i]), (PG8_LAS unsigned*)(lds + (bufoff) + ldsw + _i * 8192), 16, 0, 0); } while (0)
; #define PG8_LDA(dst, b, h) do { _Pragma("unroll") for (int m = 0; m < 4; ++m) _Pragma("unroll") for (int k = 0; k < 2; ++k) dst[m][k] = *(const PG8_LAS bf16x8*)(lds + PG8_SA(b, h) + aoff + m * 2048 + k * 1024); } while (0)
; #define PG8_LDB(dst, b, h) do { _Pragma("unroll") for (int n = 0; n < 2; ++n) _Pragma("unroll") for (int k = 0; k < 2; ++k) dst[n][k] = *(const PG8_LAS bf16x8*)(lds + PG8_SB(b, h) + boff + n * 2048 + k * 1024); } while (0)
; #define PG8_WAIT_V(n) asm volatile("s_waitcnt vmcnt(" #n ")" ::: "memory")
; #define PG8_WAIT_L(n) asm volatile("s_waitcnt lgkmcnt(" #n ")" ::: "memory")
; #define PG8_WAIT_V_SEL(sel) asm volatile("s_cmp_eq_u32 %0, 0\n\ts_cbranch_scc1 .Lw8_%=\n\ts_waitcnt vmcnt(22)\n\ts_branch .Lwd_%=\n.Lw8_%=:\n\ts_waitcnt vmcnt(8)\n.Lwd_%=:" :: "s"(sel) : "memory", "scc")
; #define PG8_BAR __builtin_amdgcn_s_barrier()
; #define PG8_SCHED __builtin_amdgcn_sched_barrier(0)
;     ...
;             PG8_WAIT_L(0); PG8_BAR; PG8_MMA(0, 0, At, B0); PG8_MMA(0, 1, At, B1); PG8_BAR; PG8_SCHED;
;             PG8_LDA(At, 0, 1); PG8_STAGE(PG8_SB(0, 0), b2, voffB); PG8_STAGE(PG8_SB(0, 1), b2 + hstep, voffB); PG8_STAGE(PG8_SA(0, 0), a2, voffA);
;             PG8_WAIT_V_SEL(relax);
;             PG8_WAIT_L(0); PG8_BAR; PG8_MMA(1, 0, At, B0); PG8_MMA(1, 1, At, B1); PG8_BAR; PG8_SCHED;
;             PG8_LDB(B0, 1, 0); PG8_LDB(B1, 1, 1); PG8_SCHED; PG8_LDA(At, 1, 0); PG8_STAGE(PG8_SA(0, 1), a2 + hstep, voffA);
;             PG8_WAIT_V(8); PG8_WAIT_L(0); PG8_BAR; PG8_MMA(0, 0, At, B0); PG8_MMA(0, 1, At, B1); PG8_BAR; PG8_SCHED;
	s_setprio 2
	v_mfma_f32_16x16x32_bf16 v[126:129], v[150:153], v[192:195], v[126:129]
	v_mfma_f32_16x16x32_bf16 v[126:129], v[154:157], v[196:199], v[126:129]
	v_mfma_f32_16x16x32_bf16 v[122:125], v[150:153], v[200:203], v[122:125]
	v_mfma_f32_16x16x32_bf16 v[122:125], v[154:157], v[204:207], v[122:125]
	v_mfma_f32_16x16x32_bf16 v[118:121], v[150:153], v[208:211], v[118:121]
	v_mfma_f32_16x16x32_bf16 v[118:121], v[154:157], v[212:215], v[118:121]
	v_mfma_f32_16x16x32_bf16 v[114:117], v[150:153], v[216:219], v[114:117]
	v_mfma_f32_16x16x32_bf16 v[114:117], v[154:157], v[220:223], v[114:117]
	v_mfma_f32_16x16x32_bf16 v[98:101], v[158:161], v[216:219], v[98:101]
	v_mfma_f32_16x16x32_bf16 v[98:101], v[162:165], v[220:223], v[98:101]
	v_mfma_f32_16x16x32_bf16 v[102:105], v[158:161], v[208:211], v[102:105]
	v_mfma_f32_16x16x32_bf16 v[102:105], v[162:165], v[212:215], v[102:105]
	v_mfma_f32_16x16x32_bf16 v[106:109], v[158:161], v[200:203], v[106:109]
	v_mfma_f32_16x16x32_bf16 v[106:109], v[162:165], v[204:207], v[106:109]
	v_mfma_f32_16x16x32_bf16 v[110:113], v[158:161], v[192:195], v[110:113]
	v_mfma_f32_16x16x32_bf16 v[110:113], v[162:165], v[196:199], v[110:113]
	v_mfma_f32_16x16x32_bf16 v[70:73], v[166:169], v[192:195], v[70:73]
	v_mfma_f32_16x16x32_bf16 v[70:73], v[172:175], v[196:199], v[70:73]
	v_mfma_f32_16x16x32_bf16 v[66:69], v[166:169], v[200:203], v[66:69]
	v_mfma_f32_16x16x32_bf16 v[66:69], v[172:175], v[204:207], v[66:69]
	v_mfma_f32_16x16x32_bf16 v[58:61], v[166:169], v[208:211], v[58:61]
	v_mfma_f32_16x16x32_bf16 v[58:61], v[172:175], v[212:215], v[58:61]
	v_mfma_f32_16x16x32_bf16 v[46:49], v[166:169], v[216:219], v[46:49]
	v_mfma_f32_16x16x32_bf16 v[46:49], v[172:175], v[220:223], v[46:49]
	v_mfma_f32_16x16x32_bf16 v[34:37], v[176:179], v[216:219], v[34:37]
	v_mfma_f32_16x16x32_bf16 v[34:37], v[188:191], v[220:223], v[34:37]
	v_mfma_f32_16x16x32_bf16 v[38:41], v[176:179], v[208:211], v[38:41]
	v_mfma_f32_16x16x32_bf16 v[38:41], v[188:191], v[212:215], v[38:41]
	v_mfma_f32_16x16x32_bf16 v[42:45], v[176:179], v[200:203], v[42:45]
	v_mfma_f32_16x16x32_bf16 v[42:45], v[188:191], v[204:207], v[42:45]
	v_mfma_f32_16x16x32_bf16 v[50:53], v[176:179], v[192:195], v[50:53]
	v_mfma_f32_16x16x32_bf16 v[50:53], v[188:191], v[196:199], v[50:53]
	s_setprio 0
	s_add_i32 s0, s83, s20
	s_mov_b32 m0, s0
	ds_read_b128 v[192:195], v148 offset:16384
	ds_read_b128 v[196:199], v148 offset:17408
	ds_read_b128 v[200:203], v148 offset:18432
	ds_read_b128 v[204:207], v148 offset:19456
	ds_read_b128 v[208:211], v148 offset:20480
	ds_read_b128 v[212:215], v148 offset:21504
	ds_read_b128 v[216:219], v148 offset:22528
	ds_read_b128 v[220:223], v148 offset:23552
	global_load_lds_dwordx4 v132, s[76:77]
	s_add_i32 m0, s0, 0x2000
	s_add_u32 s0, s76, 0x80000
	s_addc_u32 s1, s77, 0
	s_add_i32 s83, s84, s20
	global_load_lds_dwordx4 v136, s[76:77]
	s_mov_b32 m0, s83
	s_nop 0
	global_load_lds_dwordx4 v132, s[0:1]
	s_add_i32 m0, s83, 0x2000
	s_nop 0
	global_load_lds_dwordx4 v136, s[0:1]
	s_mov_b32 m0, s35
	s_nop 0
	global_load_lds_dwordx4 v130, s[78:79]
	s_mov_b32 m0, s37
	s_nop 0
	global_load_lds_dwordx4 v134, s[78:79]
	s_waitcnt vmcnt(8)
	s_waitcnt lgkmcnt(0)
	s_barrier
	s_setprio 2
	v_mfma_f32_16x16x32_bf16 v[94:97], v[150:153], v[192:195], v[94:97]
	v_mfma_f32_16x16x32_bf16 v[94:97], v[154:157], v[196:199], v[94:97]
	v_mfma_f32_16x16x32_bf16 v[90:93], v[150:153], v[200:203], v[90:93]
	v_mfma_f32_16x16x32_bf16 v[90:93], v[154:157], v[204:207], v[90:93]
	v_mfma_f32_16x16x32_bf16 v[86:89], v[150:153], v[208:211], v[86:89]
	v_mfma_f32_16x16x32_bf16 v[86:89], v[154:157], v[212:215], v[86:89]
	v_mfma_f32_16x16x32_bf16 v[82:85], v[150:153], v[216:219], v[82:85]
	v_mfma_f32_16x16x32_bf16 v[82:85], v[154:157], v[220:223], v[82:85]
	v_mfma_f32_16x16x32_bf16 v[54:57], v[158:161], v[216:219], v[54:57]
	v_mfma_f32_16x16x32_bf16 v[54:57], v[162:165], v[220:223], v[54:57]
	v_mfma_f32_16x16x32_bf16 v[62:65], v[158:161], v[208:211], v[62:65]
	v_mfma_f32_16x16x32_bf16 v[62:65], v[162:165], v[212:215], v[62:65]
	v_mfma_f32_16x16x32_bf16 v[74:77], v[158:161], v[200:203], v[74:77]
	v_mfma_f32_16x16x32_bf16 v[74:77], v[162:165], v[204:207], v[74:77]
	v_mfma_f32_16x16x32_bf16 v[78:81], v[158:161], v[192:195], v[78:81]
	v_mfma_f32_16x16x32_bf16 v[78:81], v[162:165], v[196:199], v[78:81]
	v_mfma_f32_16x16x32_bf16 v[30:33], v[166:169], v[192:195], v[30:33]
	v_mfma_f32_16x16x32_bf16 v[30:33], v[172:175], v[196:199], v[30:33]
	v_mfma_f32_16x16x32_bf16 v[26:29], v[166:169], v[200:203], v[26:29]
	v_mfma_f32_16x16x32_bf16 v[26:29], v[172:175], v[204:207], v[26:29]
	v_mfma_f32_16x16x32_bf16 v[22:25], v[166:169], v[208:211], v[22:25]
	v_mfma_f32_16x16x32_bf16 v[22:25], v[172:175], v[212:215], v[22:25]
	v_mfma_f32_16x16x32_bf16 v[18:21], v[166:169], v[216:219], v[18:21]
	v_mfma_f32_16x16x32_bf16 v[18:21], v[172:175], v[220:223], v[18:21]
	v_mfma_f32_16x16x32_bf16 v[2:5], v[176:179], v[216:219], v[2:5]
	v_mfma_f32_16x16x32_bf16 v[2:5], v[188:191], v[220:223], v[2:5]
	v_mfma_f32_16x16x32_bf16 v[6:9], v[176:179], v[208:211], v[6:9]
	v_mfma_f32_16x16x32_bf16 v[6:9], v[188:191], v[212:215], v[6:9]
	v_mfma_f32_16x16x32_bf16 v[10:13], v[176:179], v[200:203], v[10:13]
	v_mfma_f32_16x16x32_bf16 v[10:13], v[188:191], v[204:207], v[10:13]
	v_mfma_f32_16x16x32_bf16 v[14:17], v[176:179], v[192:195], v[14:17]
	v_mfma_f32_16x16x32_bf16 v[14:17], v[188:191], v[196:199], v[14:17]
	s_setprio 0
	s_add_i32 s83, 0, 0x18000
	s_add_i32 s84, 0, 0x1c000
	ds_read_b128 v[150:153], v180 offset:32768
	ds_read_b128 v[154:157], v180 offset:33792
	ds_read_b128 v[158:161], v180 offset:34816
	ds_read_b128 v[162:165], v180 offset:35840
	ds_read_b128 v[166:169], v180 offset:49152
	ds_read_b128 v[172:175], v180 offset:50176
	ds_read_b128 v[176:179], v180 offset:51200
	ds_read_b128 v[188:191], v180 offset:52224
	s_add_u32 s0, s78, 0x80000
	s_addc_u32 s1, s79, 0
	s_mov_b32 m0, s43
	ds_read_b128 v[192:195], v148 offset:32768
	ds_read_b128 v[196:199], v148 offset:33792
	ds_read_b128 v[200:203], v148 offset:34816
	ds_read_b128 v[204:207], v148 offset:35840
	ds_read_b128 v[208:211], v148 offset:36864
	ds_read_b128 v[212:215], v148 offset:37888
	ds_read_b128 v[216:219], v148 offset:38912
	ds_read_b128 v[220:223], v148 offset:39936
	global_load_lds_dwordx4 v130, s[0:1]
	s_mov_b32 m0, s44
	s_nop 0
	global_load_lds_dwordx4 v134, s[0:1]
	s_waitcnt vmcnt(8)
	s_waitcnt lgkmcnt(0)
	s_barrier
; #define PG8_STAGE(bufoff, gbase, voff) do { _Pragma("unroll") for (int _i = 0; _i < 2; ++_i) \
;         __builtin_amdgcn_global_load_lds((const unsigned*)((const char*)(gbase) + (voff)[_i]), (PG8_LAS unsigned*)(lds + (bufoff) + ldsw + _i * 8192), 16, 0, 0); } while (0)
; #define PG8_LDA(dst, b, h) do { _Pragma("unroll") for (int m = 0; m < 4; ++m) _Pragma("unroll") for (int k = 0; k < 2; ++k) dst[m][k] = *(const PG8_LAS bf16x8*)(lds + PG8_SA(b, h) + aoff + m * 2048 + k * 1024); } while (0)
; #define PG8_WAIT_V(n) asm volatile("s_waitcnt vmcnt(" #n ")" ::: "memory")
; #define PG8_WAIT_L(n) asm volatile("s_waitcnt lgkmcnt(" #n ")" ::: "memory")
; #define PG8_BAR __builtin_amdgcn_s_barrier()
; #define PG8_SCHED __builtin_amdgcn_sched_barrier(0)
;     ...
;             PG8_WAIT_V(8); PG8_WAIT_L(0); PG8_BAR; PG8_MMA(0, 0, At, B0); PG8_MMA(0, 1, At, B1); PG8_BAR; PG8_SCHED;
;             PG8_LDA(At, 1, 1); PG8_STAGE(PG8_SB(1, 0), b3, voffB); PG8_STAGE(PG8_SB(1, 1), b3 + hstep, voffB); PG8_STAGE(PG8_SA(1, 0), a3, voffA);
;             PG8_WAIT_V(8); PG8_WAIT_L(0); PG8_BAR; PG8_MMA(1, 0, At, B0); PG8_MMA(1, 1, At, B1); PG8_BAR; PG8_SCHED;
;     ...
;         if constexpr (ALIGN_EPI) { if (wr == 0) PG8_BAR; }
	s_setprio 2
	v_mfma_f32_16x16x32_bf16 v[126:129], v[150:153], v[192:195], v[126:129]
	v_mfma_f32_16x16x32_bf16 v[126:129], v[154:157], v[196:199], v[126:129]
	v_mfma_f32_16x16x32_bf16 v[122:125], v[150:153], v[200:203], v[122:125]
	v_mfma_f32_16x16x32_bf16 v[122:125], v[154:157], v[204:207], v[122:125]
	v_mfma_f32_16x16x32_bf16 v[118:121], v[150:153], v[208:211], v[118:121]
	v_mfma_f32_16x16x32_bf16 v[118:121], v[154:157], v[212:215], v[118:121]
	v_mfma_f32_16x16x32_bf16 v[114:117], v[150:153], v[216:219], v[114:117]
	v_mfma_f32_16x16x32_bf16 v[114:117], v[154:157], v[220:223], v[114:117]
	v_mfma_f32_16x16x32_bf16 v[98:101], v[158:161], v[216:219], v[98:101]
	v_mfma_f32_16x16x32_bf16 v[98:101], v[162:165], v[220:223], v[98:101]
	v_mfma_f32_16x16x32_bf16 v[102:105], v[158:161], v[208:211], v[102:105]
	v_mfma_f32_16x16x32_bf16 v[102:105], v[162:165], v[212:215], v[102:105]
	v_mfma_f32_16x16x32_bf16 v[106:109], v[158:161], v[200:203], v[106:109]
	v_mfma_f32_16x16x32_bf16 v[106:109], v[162:165], v[204:207], v[106:109]
	v_mfma_f32_16x16x32_bf16 v[110:113], v[158:161], v[192:195], v[110:113]
	v_mfma_f32_16x16x32_bf16 v[110:113], v[162:165], v[196:199], v[110:113]
	v_mfma_f32_16x16x32_bf16 v[70:73], v[166:169], v[192:195], v[70:73]
	v_mfma_f32_16x16x32_bf16 v[70:73], v[172:175], v[196:199], v[70:73]
	v_mfma_f32_16x16x32_bf16 v[66:69], v[166:169], v[200:203], v[66:69]
	v_mfma_f32_16x16x32_bf16 v[66:69], v[172:175], v[204:207], v[66:69]
	v_mfma_f32_16x16x32_bf16 v[58:61], v[166:169], v[208:211], v[58:61]
	v_mfma_f32_16x16x32_bf16 v[58:61], v[172:175], v[212:215], v[58:61]
	v_mfma_f32_16x16x32_bf16 v[46:49], v[166:169], v[216:219], v[46:49]
	v_mfma_f32_16x16x32_bf16 v[46:49], v[172:175], v[220:223], v[46:49]
	v_mfma_f32_16x16x32_bf16 v[34:37], v[176:179], v[216:219], v[34:37]
	v_mfma_f32_16x16x32_bf16 v[34:37], v[188:191], v[220:223], v[34:37]
	v_mfma_f32_16x16x32_bf16 v[38:41], v[176:179], v[208:211], v[38:41]
	v_mfma_f32_16x16x32_bf16 v[38:41], v[188:191], v[212:215], v[38:41]
	v_mfma_f32_16x16x32_bf16 v[42:45], v[176:179], v[200:203], v[42:45]
	v_mfma_f32_16x16x32_bf16 v[42:45], v[188:191], v[204:207], v[42:45]
	v_mfma_f32_16x16x32_bf16 v[50:53], v[176:179], v[192:195], v[50:53]
	v_mfma_f32_16x16x32_bf16 v[50:53], v[188:191], v[196:199], v[50:53]
	s_setprio 0
	s_add_i32 s0, s83, s20
	s_mov_b32 m0, s0
	ds_read_b128 v[192:195], v148 offset:49152
	ds_read_b128 v[196:199], v148 offset:50176
	ds_read_b128 v[200:203], v148 offset:51200
	ds_read_b128 v[204:207], v148 offset:52224
	ds_read_b128 v[208:211], v148 offset:53248
	ds_read_b128 v[212:215], v148 offset:54272
	ds_read_b128 v[216:219], v148 offset:55296
	ds_read_b128 v[220:223], v148 offset:56320
	s_add_u32 s100, s76, 0x80
	s_addc_u32 s101, s77, 0
	global_load_lds_dwordx4 v132, s[100:101]
	s_add_i32 m0, s0, 0x2000
	s_add_u32 s0, s76, 0x80080
	s_addc_u32 s1, s77, 0
	s_add_i32 s76, s84, s20
	global_load_lds_dwordx4 v136, s[100:101]
	s_mov_b32 m0, s76
	s_nop 0
	global_load_lds_dwordx4 v132, s[0:1]
	s_add_i32 m0, s76, 0x2000
	s_nop 0
	global_load_lds_dwordx4 v136, s[0:1]
	s_mov_b32 m0, s48
	s_nop 0
	s_add_u32 s100, s78, 0x80
	s_addc_u32 s101, s79, 0
	global_load_lds_dwordx4 v130, s[100:101]
	s_mov_b32 m0, s49
	s_nop 0
	global_load_lds_dwordx4 v134, s[100:101]
	s_waitcnt vmcnt(8)
	s_waitcnt lgkmcnt(0)
	s_barrier
	s_setprio 2
	v_mfma_f32_16x16x32_bf16 v[94:97], v[150:153], v[192:195], v[94:97]
	v_mfma_f32_16x16x32_bf16 v[94:97], v[154:157], v[196:199], v[94:97]
	v_mfma_f32_16x16x32_bf16 v[90:93], v[150:153], v[200:203], v[90:93]
	v_mfma_f32_16x16x32_bf16 v[90:93], v[154:157], v[204:207], v[90:93]
	v_mfma_f32_16x16x32_bf16 v[86:89], v[150:153], v[208:211], v[86:89]
	v_mfma_f32_16x16x32_bf16 v[86:89], v[154:157], v[212:215], v[86:89]
	v_mfma_f32_16x16x32_bf16 v[82:85], v[150:153], v[216:219], v[82:85]
	v_mfma_f32_16x16x32_bf16 v[82:85], v[154:157], v[220:223], v[82:85]
	v_mfma_f32_16x16x32_bf16 v[54:57], v[158:161], v[216:219], v[54:57]
	v_mfma_f32_16x16x32_bf16 v[54:57], v[162:165], v[220:223], v[54:57]
	v_mfma_f32_16x16x32_bf16 v[62:65], v[158:161], v[208:211], v[62:65]
	v_mfma_f32_16x16x32_bf16 v[62:65], v[162:165], v[212:215], v[62:65]
	v_mfma_f32_16x16x32_bf16 v[74:77], v[158:161], v[200:203], v[74:77]
	v_mfma_f32_16x16x32_bf16 v[74:77], v[162:165], v[204:207], v[74:77]
	v_mfma_f32_16x16x32_bf16 v[78:81], v[158:161], v[192:195], v[78:81]
	v_mfma_f32_16x16x32_bf16 v[78:81], v[162:165], v[196:199], v[78:81]
	v_mfma_f32_16x16x32_bf16 v[30:33], v[166:169], v[192:195], v[30:33]
	v_mfma_f32_16x16x32_bf16 v[30:33], v[172:175], v[196:199], v[30:33]
	v_mfma_f32_16x16x32_bf16 v[26:29], v[166:169], v[200:203], v[26:29]
	v_mfma_f32_16x16x32_bf16 v[26:29], v[172:175], v[204:207], v[26:29]
	v_mfma_f32_16x16x32_bf16 v[22:25], v[166:169], v[208:211], v[22:25]
	v_mfma_f32_16x16x32_bf16 v[22:25], v[172:175], v[212:215], v[22:25]
	v_mfma_f32_16x16x32_bf16 v[18:21], v[166:169], v[216:219], v[18:21]
	v_mfma_f32_16x16x32_bf16 v[18:21], v[172:175], v[220:223], v[18:21]
	v_mfma_f32_16x16x32_bf16 v[2:5], v[176:179], v[216:219], v[2:5]
	v_mfma_f32_16x16x32_bf16 v[2:5], v[188:191], v[220:223], v[2:5]
	v_mfma_f32_16x16x32_bf16 v[6:9], v[176:179], v[208:211], v[6:9]
	v_mfma_f32_16x16x32_bf16 v[6:9], v[188:191], v[212:215], v[6:9]
	v_mfma_f32_16x16x32_bf16 v[10:13], v[176:179], v[200:203], v[10:13]
	v_mfma_f32_16x16x32_bf16 v[10:13], v[188:191], v[204:207], v[10:13]
	v_mfma_f32_16x16x32_bf16 v[14:17], v[176:179], v[192:195], v[14:17]
	v_mfma_f32_16x16x32_bf16 v[14:17], v[188:191], v[196:199], v[14:17]
	s_setprio 0
	s_add_i32 s82, s82, 2
	s_add_u32 s74, s74, 0x100
	s_addc_u32 s75, s75, 0
	s_add_u32 s80, s80, 0x100
	s_addc_u32 s81, s81, 0
	s_cmp_gt_u32 s82, 29
	s_cbranch_scc0 .Lhob_qkv_Thead
	s_branch .Lhob_qkv_exit
.Lhob_qkv_exit:
	s_and_b64 vcc, exec, s[62:63]
	s_cbranch_vccz .LBB0_599
	s_setprio 0

; #define PG8_STAGE(bufoff, gbase, voff) do { _Pragma("unroll") for (int _i = 0; _i < 2; ++_i) \
;         __builtin_amdgcn_global_load_lds((const unsigned*)((const char*)(gbase) + (voff)[_i]), (PG8_LAS unsigned*)(lds + (bufoff) + ldsw + _i * 8192), 16, 0, 0); } while (0)
; #define PG8_BAR __builtin_amdgcn_s_barrier()
;     ...
;     for (int i = 0; i < 2; ++i) { int R, C; stage_rc(tid * 16 + i * 8192, R, C); const int Rb = Epi::PERM ? ((R & ~31) + perm32(R & 31)) : R;
;         const int Ra = Epi::PERMROW ? ((R & ~63) + 4 * (R & 15) + ((R >> 4) & 3)) : R;
;         voffA[i] = (unsigned)(Ra * K + C) * 2u; voffB[i] = (unsigned)(Rb * K + C) * 2u; }
;     ...
;         PG8_STAGE(PG8_SB(0, 0), cB, voffB); PG8_STAGE(PG8_SB(0, 1), cB + hstep, voffB); PG8_STAGE(PG8_SA(0, 0), cA, voffA); PG8_STAGE(PG8_SA(0, 1), cA + hstep, voffA);
;         if (wr == 1) PG8_BAR;
.LBB0_1158:
	v_ashrrev_i32_e32 v3, 31, v11
	v_lshrrev_b32_e32 v3, 26, v3
	v_add_u32_e32 v3, v11, v3
	v_ashrrev_i32_e32 v12, 6, v3
	v_bfe_i32 v3, v11, 27, 1
	v_lshlrev_b32_e32 v2, 4, v11
	v_lshrrev_b32_e32 v3, 22, v3
	v_add_u32_e32 v3, v2, v3
	v_and_b32_e32 v3, 0xfffffc00, v3
	v_sub_u32_e32 v3, v2, v3
	v_lshrrev_b32_e32 v4, 4, v3
	v_bitop3_b32 v4, v4, v3, 32 bitop3:0x6c
	v_ashrrev_i32_e32 v3, 31, v3
	v_lshrrev_b32_e32 v3, 26, v3
	v_add_u32_e32 v3, v4, v3
	v_ashrrev_i32_e32 v13, 6, v3
	v_lshlrev_b32_e32 v5, 3, v12
	v_mul_i32_i24_e32 v6, 64, v13
	v_and_b32_e32 v5, -16, v5
	v_sub_u32_e32 v4, v4, v6
	v_add_u32_e32 v3, v13, v5
	v_lshlrev_b32_e32 v5, 5, v12
	v_ashrrev_i16_sdwa v4, v235, sext(v4) dst_sel:DWORD dst_unused:UNUSED_PAD src0_sel:DWORD src1_sel:BYTE_0
	v_and_b32_e32 v5, 32, v5
	v_bfe_i32 v14, v4, 0, 16
	v_and_b32_e32 v7, 3, v13
	s_mov_b32 s1, 0xfffe0
	v_add_lshl_u32 v5, v5, v14, 1
	v_add_u32_e32 v2, 0x2000, v2
	v_lshlrev_b32_e32 v4, 1, v3
	v_lshrrev_b32_e32 v6, 2, v3
	v_and_or_b32 v7, v3, s1, v7
	v_lshl_add_u32 v172, v3, 12, v5
	v_ashrrev_i32_e32 v3, 31, v2
	v_lshrrev_b32_e32 v3, 22, v3
	v_add_u32_e32 v3, v2, v3
	v_ashrrev_i32_e32 v15, 10, v3
	v_mul_i32_i24_e32 v3, 0x400, v15
	v_sub_u32_e32 v2, v2, v3
	v_and_b32_e32 v4, 24, v4
	v_and_b32_e32 v6, 4, v6
	v_lshrrev_b32_e32 v3, 4, v2
	v_or3_b32 v4, v7, v6, v4
	v_bitop3_b32 v2, v3, v2, 32 bitop3:0x6c
	v_lshl_add_u32 v182, v4, 12, v5
	v_ashrrev_i32_e32 v4, 31, v2
	v_lshrrev_b32_e32 v4, 26, v4
	v_lshlrev_b32_e32 v3, 3, v15
	v_add_u32_e32 v4, v2, v4
	v_and_b32_e32 v3, -16, v3
	v_ashrrev_i32_e32 v16, 6, v4
	v_add_u32_e32 v3, v16, v3
	v_and_b32_e32 v6, 3, v16
	v_and_or_b32 v6, v3, s1, v6
	s_ashr_i32 s1, s0, 8
	s_lshl_b32 s33, s19, 10
	s_add_u32 s35, s8, 0x18000000
	s_addc_u32 s37, s9, 0
	s_lshl_b32 s2, s82, 23
	s_add_u32 s2, s8, s2
	s_addc_u32 s3, s9, 0
	s_add_u32 s43, s2, 0x3e00000
	v_and_b32_e32 v4, 0xc0, v4
	s_addc_u32 s44, s3, 0
	s_ashr_i32 s77, s76, 31
	s_ashr_i32 s75, s74, 31
	v_sub_u32_e32 v2, v2, v4
	s_lshl_b64 s[2:3], s[76:77], 20
	s_lshl_b64 s[4:5], s[74:75], 20
	v_ashrrev_i16_sdwa v2, v235, sext(v2) dst_sel:DWORD dst_unused:UNUSED_PAD src0_sel:DWORD src1_sel:BYTE_0
	s_add_u32 s80, s43, s4
	v_lshlrev_b32_e32 v5, 5, v15
	v_bfe_i32 v17, v2, 0, 16
	v_lshlrev_b32_e32 v2, 1, v3
	v_lshrrev_b32_e32 v4, 2, v3
	s_addc_u32 s81, s44, s5
	s_add_i32 s45, s33, 0
	v_and_b32_e32 v5, 32, v5
	v_and_b32_e32 v2, 24, v2
	v_and_b32_e32 v4, 4, v4
	s_add_i32 m0, s45, 0x10000
	v_or3_b32 v2, v6, v4, v2
	v_add_lshl_u32 v4, v5, v17, 1
	global_load_lds_dwordx4 v182, s[80:81]
	s_add_i32 m0, s45, 0x12000
	v_lshl_add_u32 v176, v2, 12, v4
	s_add_u32 s4, s80, 0x80000
	global_load_lds_dwordx4 v176, s[80:81]
	s_addc_u32 s5, s81, 0
	s_add_i32 m0, s45, 0x14000
	v_lshl_add_u32 v174, v3, 12, v4
	global_load_lds_dwordx4 v182, s[4:5]
	s_add_i32 m0, s45, 0x16000
	s_add_u32 s78, s35, s2
	s_addc_u32 s79, s37, s3
	s_add_i32 s46, s45, 0x2000
	global_load_lds_dwordx4 v176, s[4:5]
	s_mov_b32 m0, s45
	s_add_u32 s2, s78, 0x80000
	global_load_lds_dwordx4 v172, s[78:79]
	s_mov_b32 m0, s46
	s_addc_u32 s3, s79, 0
	s_add_i32 s47, s45, 0x4000
	global_load_lds_dwordx4 v174, s[78:79]
	s_mov_b32 m0, s47
	s_add_i32 s48, s45, 0x6000
	global_load_lds_dwordx4 v172, s[2:3]
	s_mov_b32 m0, s48
	v_mov_b32_e32 v177, v183
	global_load_lds_dwordx4 v174, s[2:3]
	v_mov_b32_e32 v173, v183
	v_mov_b32_e32 v175, v183
	s_cmp_eq_u32 s1, 1
	s_mov_b32 s87, s51
	v_lshl_add_u64 v[8:9], s[80:81], 0, v[182:183]
	v_lshl_add_u64 v[6:7], s[80:81], 0, v[176:177]
	v_lshl_add_u64 v[2:3], s[78:79], 0, v[172:173]
	s_cselect_b64 s[12:13], -1, 0
	s_cmp_lg_u32 s1, 1
	v_lshl_add_u64 v[4:5], s[78:79], 0, v[174:175]
	s_cbranch_scc1 .LBB0_1160
	s_setprio 0

; #define PG8_STAGE(bufoff, gbase, voff) do { _Pragma("unroll") for (int _i = 0; _i < 2; ++_i) \
;         __builtin_amdgcn_global_load_lds((const unsigned*)((const char*)(gbase) + (voff)[_i]), (PG8_LAS unsigned*)(lds + (bufoff) + ldsw + _i * 8192), 16, 0, 0); } while (0)
; #define PG8_LDA(dst, b, h) do { _Pragma("unroll") for (int m = 0; m < 4; ++m) _Pragma("unroll") for (int k = 0; k < 2; ++k) dst[m][k] = *(const PG8_LAS bf16x8*)(lds + PG8_SA(b, h) + aoff + m * 2048 + k * 1024); } while (0)
; #define PG8_LDB(dst, b, h) do { _Pragma("unroll") for (int n = 0; n < 2; ++n) _Pragma("unroll") for (int k = 0; k < 2; ++k) dst[n][k] = *(const PG8_LAS bf16x8*)(lds + PG8_SB(b, h) + boff + n * 2048 + k * 1024); } while (0)
; #define PG8_WAIT_L(n) asm volatile("s_waitcnt lgkmcnt(" #n ")" ::: "memory")
; #define PG8_WAIT_V_SEL(sel) asm volatile("s_cmp_eq_u32 %0, 0\n\ts_cbranch_scc1 .Lw8_%=\n\ts_waitcnt vmcnt(22)\n\ts_branch .Lwd_%=\n.Lw8_%=:\n\ts_waitcnt vmcnt(8)\n.Lwd_%=:" :: "s"(sel) : "memory", "scc")
; #define PG8_BAR __builtin_amdgcn_s_barrier()
; #define PG8_SCHED __builtin_amdgcn_sched_barrier(0)
;     ...
;         for (int t = 0; t < nt * KREP; t += 2) {
;             const bool last = (t == nt * KREP - 2);
;             const int t1w = KREP > 1 ? ((t + 1) & (nt - 1)) : t + 1, t2w = KREP > 1 ? ((t + 2) & (nt - 1)) : t + 2;
;             const char* a1 = cA + (size_t)t1w * kstep;
;             const char* a2 = last ? nA : cA + (size_t)t2w * kstep; const char* b2 = last ? nB : cB + (size_t)t2w * kstep;
;             const char* a3 = a2 + kstep; const char* b3 = b2 + kstep;
;             if (last && has_next) S.a_ready(nxt);
;             const int relax = __builtin_amdgcn_readfirstlane((MK_RELAXW && t == 0 && ui > 0) ? 1 : 0);
;             if constexpr (SP2) {
;             PG8_LDB(B0, 0, 0); PG8_LDB(B1, 0, 1); PG8_SCHED; PG8_LDA(At, 0, 0); PG8_STAGE(PG8_SA(1, 1), a1 + hstep, voffA);
;             PG8_WAIT_V_SEL(relax);
;             PG8_WAIT_L(0); PG8_BAR; PG8_MMA(0, 0, At, B0); PG8_MMA(0, 1, At, B1); PG8_BAR; PG8_SCHED;
;     ...
; #pragma unroll
;         for (int a = 0; a < 2; ++a)
; #pragma unroll
;             for (int b = 0; b < 2; ++b)
; #pragma unroll
;                 for (int m = 0; m < 4; ++m)
; #pragma unroll
;                     for (int n = 0; n < 2; ++n) acc[a][b][m][n] = (f32x4){0.f, 0.f, 0.f, 0.f};
;         cur = nxt; cA = nA; cB = nB; ++ui;
.LBB0_1169:
	s_ashr_i32 s69, s68, 31
	s_lshl_b64 s[0:1], s[68:69], 20
	s_add_u32 s70, s35, s0
	s_addc_u32 s71, s37, s1
	s_and_b64 s[0:1], s[4:5], exec
	s_cselect_b32 s40, s71, s79
	s_cselect_b32 s41, s70, s78
	s_ashr_i32 s67, s66, 31
	s_lshl_b64 s[0:1], s[66:67], 20
	s_add_u32 s72, s43, s0
	s_addc_u32 s73, s44, s1
	s_and_b64 s[0:1], s[4:5], exec
	s_cselect_b32 s67, s73, s81
	s_cselect_b32 s69, s72, s80
	s_add_u32 s78, s78, 0x80080
	s_addc_u32 s79, s79, 0
	s_add_u32 s75, s80, 0x100
	v_mov_b64_e32 v[2:3], 0
	v_mov_b64_e32 v[4:5], 0
	v_mov_b64_e32 v[6:7], 0
	v_mov_b64_e32 v[8:9], 0
	v_mov_b64_e32 v[10:11], 0
	v_mov_b64_e32 v[12:13], 0
	v_mov_b64_e32 v[14:15], 0
	v_mov_b64_e32 v[16:17], 0
	v_mov_b64_e32 v[18:19], 0
	v_mov_b64_e32 v[20:21], 0
	v_mov_b64_e32 v[22:23], 0
	v_mov_b64_e32 v[24:25], 0
	v_mov_b64_e32 v[26:27], 0
	v_mov_b64_e32 v[28:29], 0
	v_mov_b64_e32 v[30:31], 0
	v_mov_b64_e32 v[32:33], 0
	v_mov_b64_e32 v[34:35], 0
	v_mov_b64_e32 v[36:37], 0
	v_mov_b64_e32 v[38:39], 0
	v_mov_b64_e32 v[40:41], 0
	v_mov_b64_e32 v[42:43], 0
	v_mov_b64_e32 v[44:45], 0
	v_mov_b64_e32 v[46:47], 0
	v_mov_b64_e32 v[48:49], 0
	v_mov_b64_e32 v[50:51], 0
	v_mov_b64_e32 v[52:53], 0
	v_mov_b64_e32 v[54:55], 0
	v_mov_b64_e32 v[56:57], 0
	v_mov_b64_e32 v[58:59], 0
	v_mov_b64_e32 v[60:61], 0
	v_mov_b64_e32 v[62:63], 0
	v_mov_b64_e32 v[64:65], 0
	v_mov_b64_e32 v[66:67], 0
	v_mov_b64_e32 v[68:69], 0
	v_mov_b64_e32 v[70:71], 0
	v_mov_b64_e32 v[72:73], 0
	v_mov_b64_e32 v[74:75], 0
	v_mov_b64_e32 v[76:77], 0
	v_mov_b64_e32 v[78:79], 0
	v_mov_b64_e32 v[80:81], 0
	v_mov_b64_e32 v[82:83], 0
	v_mov_b64_e32 v[84:85], 0
	v_mov_b64_e32 v[86:87], 0
	v_mov_b64_e32 v[88:89], 0
	v_mov_b64_e32 v[106:107], 0
	v_mov_b64_e32 v[108:109], 0
	v_mov_b64_e32 v[110:111], 0
	v_mov_b64_e32 v[112:113], 0
	v_mov_b64_e32 v[114:115], 0
	v_mov_b64_e32 v[116:117], 0
	v_mov_b64_e32 v[118:119], 0
	v_mov_b64_e32 v[120:121], 0
	v_mov_b64_e32 v[122:123], 0
	v_mov_b64_e32 v[124:125], 0
	v_mov_b64_e32 v[126:127], 0
	v_mov_b64_e32 v[128:129], 0
	v_mov_b64_e32 v[130:131], 0
	v_mov_b64_e32 v[132:133], 0
	v_mov_b64_e32 v[134:135], 0
	v_mov_b64_e32 v[136:137], 0
	v_mov_b64_e32 v[138:139], 0
	v_mov_b64_e32 v[140:141], 0
	v_mov_b64_e32 v[142:143], 0
	v_mov_b64_e32 v[144:145], 0
	s_addc_u32 s77, s81, 0
	s_mov_b32 s84, -2
	s_waitcnt lgkmcnt(0)
	v_add_u32_e32 v184, 0x10000, v224
	s_cmp_lg_u32 s64, 0
	s_cbranch_scc0 .Lhob_wo_Thead
.LBB0_1170:
	s_add_u32 s0, s78, 0xfff80080
	s_addc_u32 s1, s79, -1
	s_add_i32 s85, 0, 0x10000
	s_cmp_eq_u32 s84, 28
	s_cselect_b32 s83, s40, s1
	s_cselect_b32 s82, s41, s0
	s_cselect_b32 s81, s67, s77
	s_cselect_b32 s80, s69, s75
	s_add_i32 s86, 0, 0x14000
	ds_read_b128 v[90:93], v184
	ds_read_b128 v[94:97], v184 offset:1024
	ds_read_b128 v[98:101], v184 offset:2048
	ds_read_b128 v[102:105], v184 offset:3072
	ds_read_b128 v[146:149], v184 offset:16384
	ds_read_b128 v[150:153], v184 offset:17408
	ds_read_b128 v[154:157], v184 offset:18432
	ds_read_b128 v[158:161], v184 offset:19456
	s_add_i32 m0, s45, 0xc000
	ds_read_b128 v[162:165], v227
	ds_read_b128 v[166:169], v227 offset:1024
	ds_read_b128 v[188:191], v227 offset:2048
	ds_read_b128 v[192:195], v227 offset:3072
	ds_read_b128 v[196:199], v227 offset:4096
	ds_read_b128 v[200:203], v227 offset:5120
	ds_read_b128 v[204:207], v227 offset:6144
	ds_read_b128 v[208:211], v227 offset:7168
	global_load_lds_dwordx4 v178, s[78:79]
	s_add_i32 m0, s45, 0xe000
	s_nop 0
	global_load_lds_dwordx4 v180, s[78:79]
	s_waitcnt vmcnt(8)
	s_waitcnt lgkmcnt(0)
	s_setprio 1
	v_mfma_f32_16x16x32_bf16 v[142:145], v[90:93], v[162:165], v[142:145]
	v_mfma_f32_16x16x32_bf16 v[142:145], v[94:97], v[166:169], v[142:145]
	v_mfma_f32_16x16x32_bf16 v[126:129], v[90:93], v[188:191], v[126:129]
	v_mfma_f32_16x16x32_bf16 v[126:129], v[94:97], v[192:195], v[126:129]
	v_mfma_f32_16x16x32_bf16 v[110:113], v[90:93], v[196:199], v[110:113]
	v_mfma_f32_16x16x32_bf16 v[110:113], v[94:97], v[200:203], v[110:113]
	v_mfma_f32_16x16x32_bf16 v[78:81], v[90:93], v[204:207], v[78:81]
	v_mfma_f32_16x16x32_bf16 v[78:81], v[94:97], v[208:211], v[78:81]
	v_mfma_f32_16x16x32_bf16 v[74:77], v[98:101], v[204:207], v[74:77]
	v_mfma_f32_16x16x32_bf16 v[74:77], v[102:105], v[208:211], v[74:77]
	v_mfma_f32_16x16x32_bf16 v[106:109], v[98:101], v[196:199], v[106:109]
	v_mfma_f32_16x16x32_bf16 v[106:109], v[102:105], v[200:203], v[106:109]
	v_mfma_f32_16x16x32_bf16 v[122:125], v[98:101], v[188:191], v[122:125]
	v_mfma_f32_16x16x32_bf16 v[122:125], v[102:105], v[192:195], v[122:125]
	v_mfma_f32_16x16x32_bf16 v[138:141], v[98:101], v[162:165], v[138:141]
	v_mfma_f32_16x16x32_bf16 v[138:141], v[102:105], v[166:169], v[138:141]
	v_mfma_f32_16x16x32_bf16 v[134:137], v[146:149], v[162:165], v[134:137]
	v_mfma_f32_16x16x32_bf16 v[134:137], v[150:153], v[166:169], v[134:137]
	v_mfma_f32_16x16x32_bf16 v[118:121], v[146:149], v[188:191], v[118:121]
	v_mfma_f32_16x16x32_bf16 v[118:121], v[150:153], v[192:195], v[118:121]
	v_mfma_f32_16x16x32_bf16 v[86:89], v[146:149], v[196:199], v[86:89]
	v_mfma_f32_16x16x32_bf16 v[86:89], v[150:153], v[200:203], v[86:89]
	v_mfma_f32_16x16x32_bf16 v[70:73], v[146:149], v[204:207], v[70:73]
	v_mfma_f32_16x16x32_bf16 v[70:73], v[150:153], v[208:211], v[70:73]
	v_mfma_f32_16x16x32_bf16 v[66:69], v[154:157], v[204:207], v[66:69]
	v_mfma_f32_16x16x32_bf16 v[66:69], v[158:161], v[208:211], v[66:69]
	v_mfma_f32_16x16x32_bf16 v[82:85], v[154:157], v[196:199], v[82:85]
	v_mfma_f32_16x16x32_bf16 v[82:85], v[158:161], v[200:203], v[82:85]
	v_mfma_f32_16x16x32_bf16 v[114:117], v[154:157], v[188:191], v[114:117]
	v_mfma_f32_16x16x32_bf16 v[114:117], v[158:161], v[192:195], v[114:117]
	v_mfma_f32_16x16x32_bf16 v[130:133], v[154:157], v[162:165], v[130:133]
	v_mfma_f32_16x16x32_bf16 v[130:133], v[158:161], v[166:169], v[130:133]
	s_setprio 0
	s_barrier
; #define PG8_STAGE(bufoff, gbase, voff) do { _Pragma("unroll") for (int _i = 0; _i < 2; ++_i) \
;         __builtin_amdgcn_global_load_lds((const unsigned*)((const char*)(gbase) + (voff)[_i]), (PG8_LAS unsigned*)(lds + (bufoff) + ldsw + _i * 8192), 16, 0, 0); } while (0)
; #define PG8_LDA(dst, b, h) do { _Pragma("unroll") for (int m = 0; m < 4; ++m) _Pragma("unroll") for (int k = 0; k < 2; ++k) dst[m][k] = *(const PG8_LAS bf16x8*)(lds + PG8_SA(b, h) + aoff + m * 2048 + k * 1024); } while (0)
; #define PG8_LDB(dst, b, h) do { _Pragma("unroll") for (int n = 0; n < 2; ++n) _Pragma("unroll") for (int k = 0; k < 2; ++k) dst[n][k] = *(const PG8_LAS bf16x8*)(lds + PG8_SB(b, h) + boff + n * 2048 + k * 1024); } while (0)
; #define PG8_WAIT_V(n) asm volatile("s_waitcnt vmcnt(" #n ")" ::: "memory")
; #define PG8_WAIT_L(n) asm volatile("s_waitcnt lgkmcnt(" #n ")" ::: "memory")
; #define PG8_WAIT_V_SEL(sel) asm volatile("s_cmp_eq_u32 %0, 0\n\ts_cbranch_scc1 .Lw8_%=\n\ts_waitcnt vmcnt(22)\n\ts_branch .Lwd_%=\n.Lw8_%=:\n\ts_waitcnt vmcnt(8)\n.Lwd_%=:" :: "s"(sel) : "memory", "scc")
; #define PG8_BAR __builtin_amdgcn_s_barrier()
; #define PG8_SCHED __builtin_amdgcn_sched_barrier(0)
;     ...
;             PG8_LDA(At, 0, 1); PG8_STAGE(PG8_SB(0, 0), b2, voffB); PG8_STAGE(PG8_SB(0, 1), b2 + hstep, voffB); PG8_STAGE(PG8_SA(0, 0), a2, voffA);
;             PG8_WAIT_V_SEL(relax);
;             PG8_WAIT_L(0); PG8_BAR; PG8_MMA(1, 0, At, B0); PG8_MMA(1, 1, At, B1); PG8_BAR; PG8_SCHED;
;             PG8_LDB(B0, 1, 0); PG8_LDB(B1, 1, 1); PG8_SCHED; PG8_LDA(At, 1, 0); PG8_STAGE(PG8_SA(0, 1), a2 + hstep, voffA);
;             PG8_WAIT_V(8); PG8_WAIT_L(0); PG8_BAR; PG8_MMA(0, 0, At, B0); PG8_MMA(0, 1, At, B1); PG8_BAR; PG8_SCHED;
	s_add_i32 s0, s85, s33
	s_mov_b32 m0, s0
	ds_read_b128 v[162:165], v227 offset:16384
	ds_read_b128 v[166:169], v227 offset:17408
	ds_read_b128 v[188:191], v227 offset:18432
	ds_read_b128 v[192:195], v227 offset:19456
	ds_read_b128 v[196:199], v227 offset:20480
	ds_read_b128 v[200:203], v227 offset:21504
	ds_read_b128 v[204:207], v227 offset:22528
	ds_read_b128 v[208:211], v227 offset:23552
	global_load_lds_dwordx4 v182, s[80:81]
	s_add_i32 m0, s0, 0x2000
	s_add_u32 s0, s80, 0x80000
	s_addc_u32 s1, s81, 0
	s_add_i32 s85, s86, s33
	global_load_lds_dwordx4 v176, s[80:81]
	s_mov_b32 m0, s85
	s_nop 0
	global_load_lds_dwordx4 v182, s[0:1]
	s_add_i32 m0, s85, 0x2000
	s_nop 0
	global_load_lds_dwordx4 v176, s[0:1]
	s_mov_b32 m0, s45
	s_nop 0
	global_load_lds_dwordx4 v172, s[82:83]
	s_mov_b32 m0, s46
	s_nop 0
	global_load_lds_dwordx4 v174, s[82:83]
	s_waitcnt vmcnt(8)
	s_waitcnt lgkmcnt(0)
	s_setprio 1
	v_mfma_f32_16x16x32_bf16 v[62:65], v[90:93], v[162:165], v[62:65]
	v_mfma_f32_16x16x32_bf16 v[62:65], v[94:97], v[166:169], v[62:65]
	v_mfma_f32_16x16x32_bf16 v[46:49], v[90:93], v[188:191], v[46:49]
	v_mfma_f32_16x16x32_bf16 v[46:49], v[94:97], v[192:195], v[46:49]
	v_mfma_f32_16x16x32_bf16 v[30:33], v[90:93], v[196:199], v[30:33]
	v_mfma_f32_16x16x32_bf16 v[30:33], v[94:97], v[200:203], v[30:33]
	v_mfma_f32_16x16x32_bf16 v[14:17], v[90:93], v[204:207], v[14:17]
	v_mfma_f32_16x16x32_bf16 v[14:17], v[94:97], v[208:211], v[14:17]
	v_mfma_f32_16x16x32_bf16 v[10:13], v[98:101], v[204:207], v[10:13]
	v_mfma_f32_16x16x32_bf16 v[10:13], v[102:105], v[208:211], v[10:13]
	v_mfma_f32_16x16x32_bf16 v[26:29], v[98:101], v[196:199], v[26:29]
	v_mfma_f32_16x16x32_bf16 v[26:29], v[102:105], v[200:203], v[26:29]
	v_mfma_f32_16x16x32_bf16 v[42:45], v[98:101], v[188:191], v[42:45]
	v_mfma_f32_16x16x32_bf16 v[42:45], v[102:105], v[192:195], v[42:45]
	v_mfma_f32_16x16x32_bf16 v[58:61], v[98:101], v[162:165], v[58:61]
	v_mfma_f32_16x16x32_bf16 v[58:61], v[102:105], v[166:169], v[58:61]
	v_mfma_f32_16x16x32_bf16 v[54:57], v[146:149], v[162:165], v[54:57]
	v_mfma_f32_16x16x32_bf16 v[54:57], v[150:153], v[166:169], v[54:57]
	v_mfma_f32_16x16x32_bf16 v[38:41], v[146:149], v[188:191], v[38:41]
	v_mfma_f32_16x16x32_bf16 v[38:41], v[150:153], v[192:195], v[38:41]
	v_mfma_f32_16x16x32_bf16 v[22:25], v[146:149], v[196:199], v[22:25]
	v_mfma_f32_16x16x32_bf16 v[22:25], v[150:153], v[200:203], v[22:25]
	v_mfma_f32_16x16x32_bf16 v[6:9], v[146:149], v[204:207], v[6:9]
	v_mfma_f32_16x16x32_bf16 v[6:9], v[150:153], v[208:211], v[6:9]
	v_mfma_f32_16x16x32_bf16 v[2:5], v[154:157], v[204:207], v[2:5]
	v_mfma_f32_16x16x32_bf16 v[2:5], v[158:161], v[208:211], v[2:5]
	v_mfma_f32_16x16x32_bf16 v[18:21], v[154:157], v[196:199], v[18:21]
	v_mfma_f32_16x16x32_bf16 v[18:21], v[158:161], v[200:203], v[18:21]
	v_mfma_f32_16x16x32_bf16 v[34:37], v[154:157], v[188:191], v[34:37]
	v_mfma_f32_16x16x32_bf16 v[34:37], v[158:161], v[192:195], v[34:37]
	v_mfma_f32_16x16x32_bf16 v[50:53], v[154:157], v[162:165], v[50:53]
	v_mfma_f32_16x16x32_bf16 v[50:53], v[158:161], v[166:169], v[50:53]
	s_setprio 0
	s_barrier
	s_add_i32 s85, 0, 0x18000
	s_add_i32 s86, 0, 0x1c000
	ds_read_b128 v[90:93], v184 offset:32768
	ds_read_b128 v[94:97], v184 offset:33792
	ds_read_b128 v[98:101], v184 offset:34816
	ds_read_b128 v[102:105], v184 offset:35840
	ds_read_b128 v[146:149], v184 offset:49152
	ds_read_b128 v[150:153], v184 offset:50176
	ds_read_b128 v[154:157], v184 offset:51200
	ds_read_b128 v[158:161], v184 offset:52224
	s_add_u32 s0, s82, 0x80000
	s_addc_u32 s1, s83, 0
	s_mov_b32 m0, s47
	ds_read_b128 v[162:165], v227 offset:32768
	ds_read_b128 v[166:169], v227 offset:33792
	ds_read_b128 v[188:191], v227 offset:34816
	ds_read_b128 v[192:195], v227 offset:35840
	ds_read_b128 v[196:199], v227 offset:36864
	ds_read_b128 v[200:203], v227 offset:37888
	ds_read_b128 v[204:207], v227 offset:38912
	ds_read_b128 v[208:211], v227 offset:39936
	global_load_lds_dwordx4 v172, s[0:1]
	s_mov_b32 m0, s48
	s_nop 0
	global_load_lds_dwordx4 v174, s[0:1]
	s_waitcnt vmcnt(8)
	s_waitcnt lgkmcnt(0)
	s_setprio 1
	v_mfma_f32_16x16x32_bf16 v[142:145], v[90:93], v[162:165], v[142:145]
	v_mfma_f32_16x16x32_bf16 v[142:145], v[94:97], v[166:169], v[142:145]
	v_mfma_f32_16x16x32_bf16 v[126:129], v[90:93], v[188:191], v[126:129]
	v_mfma_f32_16x16x32_bf16 v[126:129], v[94:97], v[192:195], v[126:129]
	v_mfma_f32_16x16x32_bf16 v[110:113], v[90:93], v[196:199], v[110:113]
	v_mfma_f32_16x16x32_bf16 v[110:113], v[94:97], v[200:203], v[110:113]
	v_mfma_f32_16x16x32_bf16 v[78:81], v[90:93], v[204:207], v[78:81]
	v_mfma_f32_16x16x32_bf16 v[78:81], v[94:97], v[208:211], v[78:81]
	v_mfma_f32_16x16x32_bf16 v[74:77], v[98:101], v[204:207], v[74:77]
	v_mfma_f32_16x16x32_bf16 v[74:77], v[102:105], v[208:211], v[74:77]
	v_mfma_f32_16x16x32_bf16 v[106:109], v[98:101], v[196:199], v[106:109]
	v_mfma_f32_16x16x32_bf16 v[106:109], v[102:105], v[200:203], v[106:109]
	v_mfma_f32_16x16x32_bf16 v[122:125], v[98:101], v[188:191], v[122:125]
	v_mfma_f32_16x16x32_bf16 v[122:125], v[102:105], v[192:195], v[122:125]
	v_mfma_f32_16x16x32_bf16 v[138:141], v[98:101], v[162:165], v[138:141]
	v_mfma_f32_16x16x32_bf16 v[138:141], v[102:105], v[166:169], v[138:141]
	v_mfma_f32_16x16x32_bf16 v[134:137], v[146:149], v[162:165], v[134:137]
	v_mfma_f32_16x16x32_bf16 v[134:137], v[150:153], v[166:169], v[134:137]
	v_mfma_f32_16x16x32_bf16 v[118:121], v[146:149], v[188:191], v[118:121]
	v_mfma_f32_16x16x32_bf16 v[118:121], v[150:153], v[192:195], v[118:121]
	v_mfma_f32_16x16x32_bf16 v[86:89], v[146:149], v[196:199], v[86:89]
	v_mfma_f32_16x16x32_bf16 v[86:89], v[150:153], v[200:203], v[86:89]
	v_mfma_f32_16x16x32_bf16 v[70:73], v[146:149], v[204:207], v[70:73]
	v_mfma_f32_16x16x32_bf16 v[70:73], v[150:153], v[208:211], v[70:73]
	v_mfma_f32_16x16x32_bf16 v[66:69], v[154:157], v[204:207], v[66:69]
	v_mfma_f32_16x16x32_bf16 v[66:69], v[158:161], v[208:211], v[66:69]
	v_mfma_f32_16x16x32_bf16 v[82:85], v[154:157], v[196:199], v[82:85]
	v_mfma_f32_16x16x32_bf16 v[82:85], v[158:161], v[200:203], v[82:85]
	v_mfma_f32_16x16x32_bf16 v[114:117], v[154:157], v[188:191], v[114:117]
	v_mfma_f32_16x16x32_bf16 v[114:117], v[158:161], v[192:195], v[114:117]
	v_mfma_f32_16x16x32_bf16 v[130:133], v[154:157], v[162:165], v[130:133]
	v_mfma_f32_16x16x32_bf16 v[130:133], v[158:161], v[166:169], v[130:133]
	s_setprio 0
	s_barrier
; #define PG8_STAGE(bufoff, gbase, voff) do { _Pragma("unroll") for (int _i = 0; _i < 2; ++_i) \
;         __builtin_amdgcn_global_load_lds((const unsigned*)((const char*)(gbase) + (voff)[_i]), (PG8_LAS unsigned*)(lds + (bufoff) + ldsw + _i * 8192), 16, 0, 0); } while (0)
; #define PG8_LDA(dst, b, h) do { _Pragma("unroll") for (int m = 0; m < 4; ++m) _Pragma("unroll") for (int k = 0; k < 2; ++k) dst[m][k] = *(const PG8_LAS bf16x8*)(lds + PG8_SA(b, h) + aoff + m * 2048 + k * 1024); } while (0)
; #define PG8_LDB(dst, b, h) do { _Pragma("unroll") for (int n = 0; n < 2; ++n) _Pragma("unroll") for (int k = 0; k < 2; ++k) dst[n][k] = *(const PG8_LAS bf16x8*)(lds + PG8_SB(b, h) + boff + n * 2048 + k * 1024); } while (0)
; #define PG8_WAIT_V(n) asm volatile("s_waitcnt vmcnt(" #n ")" ::: "memory")
; #define PG8_WAIT_L(n) asm volatile("s_waitcnt lgkmcnt(" #n ")" ::: "memory")
; #define PG8_WAIT_V_SEL(sel) asm volatile("s_cmp_eq_u32 %0, 0\n\ts_cbranch_scc1 .Lw8_%=\n\ts_waitcnt vmcnt(22)\n\ts_branch .Lwd_%=\n.Lw8_%=:\n\ts_waitcnt vmcnt(8)\n.Lwd_%=:" :: "s"(sel) : "memory", "scc")
; #define PG8_BAR __builtin_amdgcn_s_barrier()
; #define PG8_SCHED __builtin_amdgcn_sched_barrier(0)
;     ...
;             PG8_LDB(B0, 0, 0); PG8_LDB(B1, 0, 1); PG8_SCHED; PG8_LDA(At, 0, 0); PG8_STAGE(PG8_SA(1, 1), a1 + hstep, voffA);
;             PG8_WAIT_V_SEL(relax);
;             PG8_WAIT_L(0); PG8_BAR; PG8_MMA(0, 0, At, B0); PG8_MMA(0, 1, At, B1); PG8_BAR; PG8_SCHED;
;             PG8_LDA(At, 0, 1); PG8_STAGE(PG8_SB(0, 0), b2, voffB); PG8_STAGE(PG8_SB(0, 1), b2 + hstep, voffB); PG8_STAGE(PG8_SA(0, 0), a2, voffA);
;             PG8_WAIT_V_SEL(relax);
;             PG8_WAIT_L(0); PG8_BAR; PG8_MMA(1, 0, At, B0); PG8_MMA(1, 1, At, B1); PG8_BAR; PG8_SCHED;
;             PG8_LDB(B0, 1, 0); PG8_LDB(B1, 1, 1); PG8_SCHED; PG8_LDA(At, 1, 0); PG8_STAGE(PG8_SA(0, 1), a2 + hstep, voffA);
;             PG8_WAIT_V(8); PG8_WAIT_L(0); PG8_BAR; PG8_MMA(0, 0, At, B0); PG8_MMA(0, 1, At, B1); PG8_BAR; PG8_SCHED;
;             PG8_LDA(At, 1, 1); PG8_STAGE(PG8_SB(1, 0), b3, voffB); PG8_STAGE(PG8_SB(1, 1), b3 + hstep, voffB); PG8_STAGE(PG8_SA(1, 0), a3, voffA);
;             PG8_WAIT_V(8); PG8_WAIT_L(0); PG8_BAR; PG8_MMA(1, 0, At, B0); PG8_MMA(1, 1, At, B1); PG8_BAR; PG8_SCHED;
	s_add_i32 s0, s85, s33
	s_mov_b32 m0, s0
	ds_read_b128 v[162:165], v227 offset:49152
	ds_read_b128 v[166:169], v227 offset:50176
	ds_read_b128 v[188:191], v227 offset:51200
	ds_read_b128 v[192:195], v227 offset:52224
	ds_read_b128 v[196:199], v227 offset:53248
	ds_read_b128 v[200:203], v227 offset:54272
	ds_read_b128 v[204:207], v227 offset:55296
	ds_read_b128 v[208:211], v227 offset:56320
	s_add_u32 s100, s80, 0x80
	s_addc_u32 s101, s81, 0
	global_load_lds_dwordx4 v182, s[100:101]
	s_add_i32 m0, s0, 0x2000
	s_add_u32 s0, s80, 0x80080
	s_addc_u32 s1, s81, 0
	s_add_i32 s80, s86, s33
	global_load_lds_dwordx4 v176, s[100:101]
	s_mov_b32 m0, s80
	s_nop 0
	global_load_lds_dwordx4 v182, s[0:1]
	s_add_i32 m0, s80, 0x2000
	s_nop 0
	global_load_lds_dwordx4 v176, s[0:1]
	s_mov_b32 m0, s50
	s_nop 0
	s_add_u32 s100, s82, 0x80
	s_addc_u32 s101, s83, 0
	global_load_lds_dwordx4 v172, s[100:101]
	s_mov_b32 m0, s51
	s_nop 0
	global_load_lds_dwordx4 v174, s[100:101]
	s_waitcnt vmcnt(8)
	s_waitcnt lgkmcnt(0)
	s_setprio 1
	v_mfma_f32_16x16x32_bf16 v[62:65], v[90:93], v[162:165], v[62:65]
	v_mfma_f32_16x16x32_bf16 v[62:65], v[94:97], v[166:169], v[62:65]
	v_mfma_f32_16x16x32_bf16 v[46:49], v[90:93], v[188:191], v[46:49]
	v_mfma_f32_16x16x32_bf16 v[46:49], v[94:97], v[192:195], v[46:49]
	v_mfma_f32_16x16x32_bf16 v[30:33], v[90:93], v[196:199], v[30:33]
	v_mfma_f32_16x16x32_bf16 v[30:33], v[94:97], v[200:203], v[30:33]
	v_mfma_f32_16x16x32_bf16 v[14:17], v[90:93], v[204:207], v[14:17]
	v_mfma_f32_16x16x32_bf16 v[14:17], v[94:97], v[208:211], v[14:17]
	v_mfma_f32_16x16x32_bf16 v[10:13], v[98:101], v[204:207], v[10:13]
	v_mfma_f32_16x16x32_bf16 v[10:13], v[102:105], v[208:211], v[10:13]
	v_mfma_f32_16x16x32_bf16 v[26:29], v[98:101], v[196:199], v[26:29]
	v_mfma_f32_16x16x32_bf16 v[26:29], v[102:105], v[200:203], v[26:29]
	v_mfma_f32_16x16x32_bf16 v[42:45], v[98:101], v[188:191], v[42:45]
	v_mfma_f32_16x16x32_bf16 v[42:45], v[102:105], v[192:195], v[42:45]
	v_mfma_f32_16x16x32_bf16 v[58:61], v[98:101], v[162:165], v[58:61]
	v_mfma_f32_16x16x32_bf16 v[58:61], v[102:105], v[166:169], v[58:61]
	v_mfma_f32_16x16x32_bf16 v[54:57], v[146:149], v[162:165], v[54:57]
	v_mfma_f32_16x16x32_bf16 v[54:57], v[150:153], v[166:169], v[54:57]
	v_mfma_f32_16x16x32_bf16 v[38:41], v[146:149], v[188:191], v[38:41]
	v_mfma_f32_16x16x32_bf16 v[38:41], v[150:153], v[192:195], v[38:41]
	v_mfma_f32_16x16x32_bf16 v[22:25], v[146:149], v[196:199], v[22:25]
	v_mfma_f32_16x16x32_bf16 v[22:25], v[150:153], v[200:203], v[22:25]
	v_mfma_f32_16x16x32_bf16 v[6:9], v[146:149], v[204:207], v[6:9]
	v_mfma_f32_16x16x32_bf16 v[6:9], v[150:153], v[208:211], v[6:9]
	v_mfma_f32_16x16x32_bf16 v[2:5], v[154:157], v[204:207], v[2:5]
	v_mfma_f32_16x16x32_bf16 v[2:5], v[158:161], v[208:211], v[2:5]
	v_mfma_f32_16x16x32_bf16 v[18:21], v[154:157], v[196:199], v[18:21]
	v_mfma_f32_16x16x32_bf16 v[18:21], v[158:161], v[200:203], v[18:21]
	v_mfma_f32_16x16x32_bf16 v[34:37], v[154:157], v[188:191], v[34:37]
	v_mfma_f32_16x16x32_bf16 v[34:37], v[158:161], v[192:195], v[34:37]
	v_mfma_f32_16x16x32_bf16 v[50:53], v[154:157], v[162:165], v[50:53]
	v_mfma_f32_16x16x32_bf16 v[50:53], v[158:161], v[166:169], v[50:53]
	s_setprio 0
	s_barrier
	s_add_i32 s84, s84, 2
	s_add_u32 s78, s78, 0x100
	s_addc_u32 s79, s79, 0
	s_add_u32 s75, s75, 0x100
	s_addc_u32 s77, s77, 0
	s_cmp_gt_u32 s84, 29
	s_cbranch_scc0 .LBB0_1170
	s_branch .Lhob_wo_exit
.Lhob_wo_Thead:
	s_add_u32 s0, s78, 0xfff80080
	s_addc_u32 s1, s79, -1
	s_add_i32 s85, 0, 0x10000
	s_cmp_eq_u32 s84, 28
	s_cselect_b32 s83, s40, s1
	s_cselect_b32 s82, s41, s0
	s_cselect_b32 s81, s67, s77
	s_cselect_b32 s80, s69, s75
	s_add_i32 s86, 0, 0x14000
	ds_read_b128 v[90:93], v184
	ds_read_b128 v[94:97], v184 offset:1024
	ds_read_b128 v[98:101], v184 offset:2048
	ds_read_b128 v[102:105], v184 offset:3072
	ds_read_b128 v[146:149], v184 offset:16384
	ds_read_b128 v[150:153], v184 offset:17408
	ds_read_b128 v[154:157], v184 offset:18432
	ds_read_b128 v[158:161], v184 offset:19456
	s_add_i32 m0, s45, 0xc000
	ds_read_b128 v[162:165], v227
	ds_read_b128 v[166:169], v227 offset:1024
	ds_read_b128 v[188:191], v227 offset:2048
	ds_read_b128 v[192:195], v227 offset:3072
	ds_read_b128 v[196:199], v227 offset:4096
	ds_read_b128 v[200:203], v227 offset:5120
	ds_read_b128 v[204:207], v227 offset:6144
	ds_read_b128 v[208:211], v227 offset:7168
	global_load_lds_dwordx4 v178, s[78:79]
	s_add_i32 m0, s45, 0xe000
	s_nop 0
	global_load_lds_dwordx4 v180, s[78:79]
	s_waitcnt vmcnt(8)
	s_waitcnt lgkmcnt(0)
	s_barrier
; #define PG8_STAGE(bufoff, gbase, voff) do { _Pragma("unroll") for (int _i = 0; _i < 2; ++_i) \
;         __builtin_amdgcn_global_load_lds((const unsigned*)((const char*)(gbase) + (voff)[_i]), (PG8_LAS unsigned*)(lds + (bufoff) + ldsw + _i * 8192), 16, 0, 0); } while (0)
; #define PG8_LDA(dst, b, h) do { _Pragma("unroll") for (int m = 0; m < 4; ++m) _Pragma("unroll") for (int k = 0; k < 2; ++k) dst[m][k] = *(const PG8_LAS bf16x8*)(lds + PG8_SA(b, h) + aoff + m * 2048 + k * 1024); } while (0)
; #define PG8_LDB(dst, b, h) do { _Pragma("unroll") for (int n = 0; n < 2; ++n) _Pragma("unroll") for (int k = 0; k < 2; ++k) dst[n][k] = *(const PG8_LAS bf16x8*)(lds + PG8_SB(b, h) + boff + n * 2048 + k * 1024); } while (0)
; #define PG8_WAIT_V(n) asm volatile("s_waitcnt vmcnt(" #n ")" ::: "memory")
; #define PG8_WAIT_L(n) asm volatile("s_waitcnt lgkmcnt(" #n ")" ::: "memory")
; #define PG8_WAIT_V_SEL(sel) asm volatile("s_cmp_eq_u32 %0, 0\n\ts_cbranch_scc1 .Lw8_%=\n\ts_waitcnt vmcnt(22)\n\ts_branch .Lwd_%=\n.Lw8_%=:\n\ts_waitcnt vmcnt(8)\n.Lwd_%=:" :: "s"(sel) : "memory", "scc")
; #define PG8_BAR __builtin_amdgcn_s_barrier()
; #define PG8_SCHED __builtin_amdgcn_sched_barrier(0)
;     ...
;             PG8_WAIT_L(0); PG8_BAR; PG8_MMA(0, 0, At, B0); PG8_MMA(0, 1, At, B1); PG8_BAR; PG8_SCHED;
;             PG8_LDA(At, 0, 1); PG8_STAGE(PG8_SB(0, 0), b2, voffB); PG8_STAGE(PG8_SB(0, 1), b2 + hstep, voffB); PG8_STAGE(PG8_SA(0, 0), a2, voffA);
;             PG8_WAIT_V_SEL(relax);
;             PG8_WAIT_L(0); PG8_BAR; PG8_MMA(1, 0, At, B0); PG8_MMA(1, 1, At, B1); PG8_BAR; PG8_SCHED;
;             PG8_LDB(B0, 1, 0); PG8_LDB(B1, 1, 1); PG8_SCHED; PG8_LDA(At, 1, 0); PG8_STAGE(PG8_SA(0, 1), a2 + hstep, voffA);
;             PG8_WAIT_V(8); PG8_WAIT_L(0); PG8_BAR; PG8_MMA(0, 0, At, B0); PG8_MMA(0, 1, At, B1); PG8_BAR; PG8_SCHED;
	s_setprio 2
	v_mfma_f32_16x16x32_bf16 v[142:145], v[90:93], v[162:165], v[142:145]
	v_mfma_f32_16x16x32_bf16 v[142:145], v[94:97], v[166:169], v[142:145]
	v_mfma_f32_16x16x32_bf16 v[126:129], v[90:93], v[188:191], v[126:129]
	v_mfma_f32_16x16x32_bf16 v[126:129], v[94:97], v[192:195], v[126:129]
	v_mfma_f32_16x16x32_bf16 v[110:113], v[90:93], v[196:199], v[110:113]
	v_mfma_f32_16x16x32_bf16 v[110:113], v[94:97], v[200:203], v[110:113]
	v_mfma_f32_16x16x32_bf16 v[78:81], v[90:93], v[204:207], v[78:81]
	v_mfma_f32_16x16x32_bf16 v[78:81], v[94:97], v[208:211], v[78:81]
	v_mfma_f32_16x16x32_bf16 v[74:77], v[98:101], v[204:207], v[74:77]
	v_mfma_f32_16x16x32_bf16 v[74:77], v[102:105], v[208:211], v[74:77]
	v_mfma_f32_16x16x32_bf16 v[106:109], v[98:101], v[196:199], v[106:109]
	v_mfma_f32_16x16x32_bf16 v[106:109], v[102:105], v[200:203], v[106:109]
	v_mfma_f32_16x16x32_bf16 v[122:125], v[98:101], v[188:191], v[122:125]
	v_mfma_f32_16x16x32_bf16 v[122:125], v[102:105], v[192:195], v[122:125]
	v_mfma_f32_16x16x32_bf16 v[138:141], v[98:101], v[162:165], v[138:141]
	v_mfma_f32_16x16x32_bf16 v[138:141], v[102:105], v[166:169], v[138:141]
	v_mfma_f32_16x16x32_bf16 v[134:137], v[146:149], v[162:165], v[134:137]
	v_mfma_f32_16x16x32_bf16 v[134:137], v[150:153], v[166:169], v[134:137]
	v_mfma_f32_16x16x32_bf16 v[118:121], v[146:149], v[188:191], v[118:121]
	v_mfma_f32_16x16x32_bf16 v[118:121], v[150:153], v[192:195], v[118:121]
	v_mfma_f32_16x16x32_bf16 v[86:89], v[146:149], v[196:199], v[86:89]
	v_mfma_f32_16x16x32_bf16 v[86:89], v[150:153], v[200:203], v[86:89]
	v_mfma_f32_16x16x32_bf16 v[70:73], v[146:149], v[204:207], v[70:73]
	v_mfma_f32_16x16x32_bf16 v[70:73], v[150:153], v[208:211], v[70:73]
	v_mfma_f32_16x16x32_bf16 v[66:69], v[154:157], v[204:207], v[66:69]
	v_mfma_f32_16x16x32_bf16 v[66:69], v[158:161], v[208:211], v[66:69]
	v_mfma_f32_16x16x32_bf16 v[82:85], v[154:157], v[196:199], v[82:85]
	v_mfma_f32_16x16x32_bf16 v[82:85], v[158:161], v[200:203], v[82:85]
	v_mfma_f32_16x16x32_bf16 v[114:117], v[154:157], v[188:191], v[114:117]
	v_mfma_f32_16x16x32_bf16 v[114:117], v[158:161], v[192:195], v[114:117]
	v_mfma_f32_16x16x32_bf16 v[130:133], v[154:157], v[162:165], v[130:133]
	v_mfma_f32_16x16x32_bf16 v[130:133], v[158:161], v[166:169], v[130:133]
	s_setprio 0
	s_add_i32 s0, s85, s33
	s_mov_b32 m0, s0
	ds_read_b128 v[162:165], v227 offset:16384
	ds_read_b128 v[166:169], v227 offset:17408
	ds_read_b128 v[188:191], v227 offset:18432
	ds_read_b128 v[192:195], v227 offset:19456
	ds_read_b128 v[196:199], v227 offset:20480
	ds_read_b128 v[200:203], v227 offset:21504
	ds_read_b128 v[204:207], v227 offset:22528
	ds_read_b128 v[208:211], v227 offset:23552
	global_load_lds_dwordx4 v182, s[80:81]
	s_add_i32 m0, s0, 0x2000
	s_add_u32 s0, s80, 0x80000
	s_addc_u32 s1, s81, 0
	s_add_i32 s85, s86, s33
	global_load_lds_dwordx4 v176, s[80:81]
	s_mov_b32 m0, s85
	s_nop 0
	global_load_lds_dwordx4 v182, s[0:1]
	s_add_i32 m0, s85, 0x2000
	s_nop 0
	global_load_lds_dwordx4 v176, s[0:1]
	s_mov_b32 m0, s45
	s_nop 0
	global_load_lds_dwordx4 v172, s[82:83]
	s_mov_b32 m0, s46
	s_nop 0
	global_load_lds_dwordx4 v174, s[82:83]
	s_waitcnt vmcnt(8)
	s_waitcnt lgkmcnt(0)
	s_barrier
	s_setprio 2
	v_mfma_f32_16x16x32_bf16 v[62:65], v[90:93], v[162:165], v[62:65]
	v_mfma_f32_16x16x32_bf16 v[62:65], v[94:97], v[166:169], v[62:65]
	v_mfma_f32_16x16x32_bf16 v[46:49], v[90:93], v[188:191], v[46:49]
	v_mfma_f32_16x16x32_bf16 v[46:49], v[94:97], v[192:195], v[46:49]
	v_mfma_f32_16x16x32_bf16 v[30:33], v[90:93], v[196:199], v[30:33]
	v_mfma_f32_16x16x32_bf16 v[30:33], v[94:97], v[200:203], v[30:33]
	v_mfma_f32_16x16x32_bf16 v[14:17], v[90:93], v[204:207], v[14:17]
	v_mfma_f32_16x16x32_bf16 v[14:17], v[94:97], v[208:211], v[14:17]
	v_mfma_f32_16x16x32_bf16 v[10:13], v[98:101], v[204:207], v[10:13]
	v_mfma_f32_16x16x32_bf16 v[10:13], v[102:105], v[208:211], v[10:13]
	v_mfma_f32_16x16x32_bf16 v[26:29], v[98:101], v[196:199], v[26:29]
	v_mfma_f32_16x16x32_bf16 v[26:29], v[102:105], v[200:203], v[26:29]
	v_mfma_f32_16x16x32_bf16 v[42:45], v[98:101], v[188:191], v[42:45]
	v_mfma_f32_16x16x32_bf16 v[42:45], v[102:105], v[192:195], v[42:45]
	v_mfma_f32_16x16x32_bf16 v[58:61], v[98:101], v[162:165], v[58:61]
	v_mfma_f32_16x16x32_bf16 v[58:61], v[102:105], v[166:169], v[58:61]
	v_mfma_f32_16x16x32_bf16 v[54:57], v[146:149], v[162:165], v[54:57]
	v_mfma_f32_16x16x32_bf16 v[54:57], v[150:153], v[166:169], v[54:57]
	v_mfma_f32_16x16x32_bf16 v[38:41], v[146:149], v[188:191], v[38:41]
	v_mfma_f32_16x16x32_bf16 v[38:41], v[150:153], v[192:195], v[38:41]
	v_mfma_f32_16x16x32_bf16 v[22:25], v[146:149], v[196:199], v[22:25]
	v_mfma_f32_16x16x32_bf16 v[22:25], v[150:153], v[200:203], v[22:25]
	v_mfma_f32_16x16x32_bf16 v[6:9], v[146:149], v[204:207], v[6:9]
	v_mfma_f32_16x16x32_bf16 v[6:9], v[150:153], v[208:211], v[6:9]
	v_mfma_f32_16x16x32_bf16 v[2:5], v[154:157], v[204:207], v[2:5]
	v_mfma_f32_16x16x32_bf16 v[2:5], v[158:161], v[208:211], v[2:5]
	v_mfma_f32_16x16x32_bf16 v[18:21], v[154:157], v[196:199], v[18:21]
	v_mfma_f32_16x16x32_bf16 v[18:21], v[158:161], v[200:203], v[18:21]
	v_mfma_f32_16x16x32_bf16 v[34:37], v[154:157], v[188:191], v[34:37]
	v_mfma_f32_16x16x32_bf16 v[34:37], v[158:161], v[192:195], v[34:37]
	v_mfma_f32_16x16x32_bf16 v[50:53], v[154:157], v[162:165], v[50:53]
	v_mfma_f32_16x16x32_bf16 v[50:53], v[158:161], v[166:169], v[50:53]
	s_setprio 0
	s_add_i32 s85, 0, 0x18000
	s_add_i32 s86, 0, 0x1c000
	ds_read_b128 v[90:93], v184 offset:32768
	ds_read_b128 v[94:97], v184 offset:33792
	ds_read_b128 v[98:101], v184 offset:34816
	ds_read_b128 v[102:105], v184 offset:35840
	ds_read_b128 v[146:149], v184 offset:49152
	ds_read_b128 v[150:153], v184 offset:50176
	ds_read_b128 v[154:157], v184 offset:51200
	ds_read_b128 v[158:161], v184 offset:52224
	s_add_u32 s0, s82, 0x80000
	s_addc_u32 s1, s83, 0
	s_mov_b32 m0, s47
	ds_read_b128 v[162:165], v227 offset:32768
	ds_read_b128 v[166:169], v227 offset:33792
	ds_read_b128 v[188:191], v227 offset:34816
	ds_read_b128 v[192:195], v227 offset:35840
	ds_read_b128 v[196:199], v227 offset:36864
	ds_read_b128 v[200:203], v227 offset:37888
	ds_read_b128 v[204:207], v227 offset:38912
	ds_read_b128 v[208:211], v227 offset:39936
	global_load_lds_dwordx4 v172, s[0:1]
	s_mov_b32 m0, s48
	s_nop 0
	global_load_lds_dwordx4 v174, s[0:1]
	s_waitcnt vmcnt(8)
	s_waitcnt lgkmcnt(0)
	s_barrier
; #define PG8_STAGE(bufoff, gbase, voff) do { _Pragma("unroll") for (int _i = 0; _i < 2; ++_i) \
;         __builtin_amdgcn_global_load_lds((const unsigned*)((const char*)(gbase) + (voff)[_i]), (PG8_LAS unsigned*)(lds + (bufoff) + ldsw + _i * 8192), 16, 0, 0); } while (0)
; #define PG8_LDA(dst, b, h) do { _Pragma("unroll") for (int m = 0; m < 4; ++m) _Pragma("unroll") for (int k = 0; k < 2; ++k) dst[m][k] = *(const PG8_LAS bf16x8*)(lds + PG8_SA(b, h) + aoff + m * 2048 + k * 1024); } while (0)
; #define PG8_WAIT_V(n) asm volatile("s_waitcnt vmcnt(" #n ")" ::: "memory")
; #define PG8_WAIT_L(n) asm volatile("s_waitcnt lgkmcnt(" #n ")" ::: "memory")
; #define PG8_BAR __builtin_amdgcn_s_barrier()
; #define PG8_SCHED __builtin_amdgcn_sched_barrier(0)
;     ...
;             PG8_WAIT_V(8); PG8_WAIT_L(0); PG8_BAR; PG8_MMA(0, 0, At, B0); PG8_MMA(0, 1, At, B1); PG8_BAR; PG8_SCHED;
;             PG8_LDA(At, 1, 1); PG8_STAGE(PG8_SB(1, 0), b3, voffB); PG8_STAGE(PG8_SB(1, 1), b3 + hstep, voffB); PG8_STAGE(PG8_SA(1, 0), a3, voffA);
;             PG8_WAIT_V(8); PG8_WAIT_L(0); PG8_BAR; PG8_MMA(1, 0, At, B0); PG8_MMA(1, 1, At, B1); PG8_BAR; PG8_SCHED;
	s_setprio 2
	v_mfma_f32_16x16x32_bf16 v[142:145], v[90:93], v[162:165], v[142:145]
	v_mfma_f32_16x16x32_bf16 v[142:145], v[94:97], v[166:169], v[142:145]
	v_mfma_f32_16x16x32_bf16 v[126:129], v[90:93], v[188:191], v[126:129]
	v_mfma_f32_16x16x32_bf16 v[126:129], v[94:97], v[192:195], v[126:129]
	v_mfma_f32_16x16x32_bf16 v[110:113], v[90:93], v[196:199], v[110:113]
	v_mfma_f32_16x16x32_bf16 v[110:113], v[94:97], v[200:203], v[110:113]
	v_mfma_f32_16x16x32_bf16 v[78:81], v[90:93], v[204:207], v[78:81]
	v_mfma_f32_16x16x32_bf16 v[78:81], v[94:97], v[208:211], v[78:81]
	v_mfma_f32_16x16x32_bf16 v[74:77], v[98:101], v[204:207], v[74:77]
	v_mfma_f32_16x16x32_bf16 v[74:77], v[102:105], v[208:211], v[74:77]
	v_mfma_f32_16x16x32_bf16 v[106:109], v[98:101], v[196:199], v[106:109]
	v_mfma_f32_16x16x32_bf16 v[106:109], v[102:105], v[200:203], v[106:109]
	v_mfma_f32_16x16x32_bf16 v[122:125], v[98:101], v[188:191], v[122:125]
	v_mfma_f32_16x16x32_bf16 v[122:125], v[102:105], v[192:195], v[122:125]
	v_mfma_f32_16x16x32_bf16 v[138:141], v[98:101], v[162:165], v[138:141]
	v_mfma_f32_16x16x32_bf16 v[138:141], v[102:105], v[166:169], v[138:141]
	v_mfma_f32_16x16x32_bf16 v[134:137], v[146:149], v[162:165], v[134:137]
	v_mfma_f32_16x16x32_bf16 v[134:137], v[150:153], v[166:169], v[134:137]
	v_mfma_f32_16x16x32_bf16 v[118:121], v[146:149], v[188:191], v[118:121]
	v_mfma_f32_16x16x32_bf16 v[118:121], v[150:153], v[192:195], v[118:121]
	v_mfma_f32_16x16x32_bf16 v[86:89], v[146:149], v[196:199], v[86:89]
	v_mfma_f32_16x16x32_bf16 v[86:89], v[150:153], v[200:203], v[86:89]
	v_mfma_f32_16x16x32_bf16 v[70:73], v[146:149], v[204:207], v[70:73]
	v_mfma_f32_16x16x32_bf16 v[70:73], v[150:153], v[208:211], v[70:73]
	v_mfma_f32_16x16x32_bf16 v[66:69], v[154:157], v[204:207], v[66:69]
	v_mfma_f32_16x16x32_bf16 v[66:69], v[158:161], v[208:211], v[66:69]
	v_mfma_f32_16x16x32_bf16 v[82:85], v[154:157], v[196:199], v[82:85]
	v_mfma_f32_16x16x32_bf16 v[82:85], v[158:161], v[200:203], v[82:85]
	v_mfma_f32_16x16x32_bf16 v[114:117], v[154:157], v[188:191], v[114:117]
	v_mfma_f32_16x16x32_bf16 v[114:117], v[158:161], v[192:195], v[114:117]
	v_mfma_f32_16x16x32_bf16 v[130:133], v[154:157], v[162:165], v[130:133]
	v_mfma_f32_16x16x32_bf16 v[130:133], v[158:161], v[166:169], v[130:133]
	s_setprio 0
	s_add_i32 s0, s85, s33
	s_mov_b32 m0, s0
	ds_read_b128 v[162:165], v227 offset:49152
	ds_read_b128 v[166:169], v227 offset:50176
	ds_read_b128 v[188:191], v227 offset:51200
	ds_read_b128 v[192:195], v227 offset:52224
	ds_read_b128 v[196:199], v227 offset:53248
	ds_read_b128 v[200:203], v227 offset:54272
	ds_read_b128 v[204:207], v227 offset:55296
	ds_read_b128 v[208:211], v227 offset:56320
	s_add_u32 s100, s80, 0x80
	s_addc_u32 s101, s81, 0
	global_load_lds_dwordx4 v182, s[100:101]
	s_add_i32 m0, s0, 0x2000
	s_add_u32 s0, s80, 0x80080
	s_addc_u32 s1, s81, 0
	s_add_i32 s80, s86, s33
	global_load_lds_dwordx4 v176, s[100:101]
	s_mov_b32 m0, s80
	s_nop 0
	global_load_lds_dwordx4 v182, s[0:1]
	s_add_i32 m0, s80, 0x2000
	s_nop 0
	global_load_lds_dwordx4 v176, s[0:1]
	s_mov_b32 m0, s50
	s_nop 0
	s_add_u32 s100, s82, 0x80
	s_addc_u32 s101, s83, 0
	global_load_lds_dwordx4 v172, s[100:101]
	s_mov_b32 m0, s51
	s_nop 0
	global_load_lds_dwordx4 v174, s[100:101]
	s_waitcnt vmcnt(8)
	s_waitcnt lgkmcnt(0)
	s_barrier
	s_setprio 2
	v_mfma_f32_16x16x32_bf16 v[62:65], v[90:93], v[162:165], v[62:65]
	v_mfma_f32_16x16x32_bf16 v[62:65], v[94:97], v[166:169], v[62:65]
	v_mfma_f32_16x16x32_bf16 v[46:49], v[90:93], v[188:191], v[46:49]
	v_mfma_f32_16x16x32_bf16 v[46:49], v[94:97], v[192:195], v[46:49]
	v_mfma_f32_16x16x32_bf16 v[30:33], v[90:93], v[196:199], v[30:33]
	v_mfma_f32_16x16x32_bf16 v[30:33], v[94:97], v[200:203], v[30:33]
	v_mfma_f32_16x16x32_bf16 v[14:17], v[90:93], v[204:207], v[14:17]
	v_mfma_f32_16x16x32_bf16 v[14:17], v[94:97], v[208:211], v[14:17]
	v_mfma_f32_16x16x32_bf16 v[10:13], v[98:101], v[204:207], v[10:13]
	v_mfma_f32_16x16x32_bf16 v[10:13], v[102:105], v[208:211], v[10:13]
	v_mfma_f32_16x16x32_bf16 v[26:29], v[98:101], v[196:199], v[26:29]
	v_mfma_f32_16x16x32_bf16 v[26:29], v[102:105], v[200:203], v[26:29]
	v_mfma_f32_16x16x32_bf16 v[42:45], v[98:101], v[188:191], v[42:45]
	v_mfma_f32_16x16x32_bf16 v[42:45], v[102:105], v[192:195], v[42:45]
	v_mfma_f32_16x16x32_bf16 v[58:61], v[98:101], v[162:165], v[58:61]
	v_mfma_f32_16x16x32_bf16 v[58:61], v[102:105], v[166:169], v[58:61]
	v_mfma_f32_16x16x32_bf16 v[54:57], v[146:149], v[162:165], v[54:57]
	v_mfma_f32_16x16x32_bf16 v[54:57], v[150:153], v[166:169], v[54:57]
	v_mfma_f32_16x16x32_bf16 v[38:41], v[146:149], v[188:191], v[38:41]
	v_mfma_f32_16x16x32_bf16 v[38:41], v[150:153], v[192:195], v[38:41]
	v_mfma_f32_16x16x32_bf16 v[22:25], v[146:149], v[196:199], v[22:25]
	v_mfma_f32_16x16x32_bf16 v[22:25], v[150:153], v[200:203], v[22:25]
	v_mfma_f32_16x16x32_bf16 v[6:9], v[146:149], v[204:207], v[6:9]
	v_mfma_f32_16x16x32_bf16 v[6:9], v[150:153], v[208:211], v[6:9]
	v_mfma_f32_16x16x32_bf16 v[2:5], v[154:157], v[204:207], v[2:5]
	v_mfma_f32_16x16x32_bf16 v[2:5], v[158:161], v[208:211], v[2:5]
	v_mfma_f32_16x16x32_bf16 v[18:21], v[154:157], v[196:199], v[18:21]
	v_mfma_f32_16x16x32_bf16 v[18:21], v[158:161], v[200:203], v[18:21]
	v_mfma_f32_16x16x32_bf16 v[34:37], v[154:157], v[188:191], v[34:37]
	v_mfma_f32_16x16x32_bf16 v[34:37], v[158:161], v[192:195], v[34:37]
	v_mfma_f32_16x16x32_bf16 v[50:53], v[154:157], v[162:165], v[50:53]
	v_mfma_f32_16x16x32_bf16 v[50:53], v[158:161], v[166:169], v[50:53]
	s_setprio 0
	s_add_i32 s84, s84, 2
	s_add_u32 s78, s78, 0x100
	s_addc_u32 s79, s79, 0
	s_add_u32 s75, s75, 0x100
	s_addc_u32 s77, s77, 0
	s_cmp_gt_u32 s84, 29
	s_cbranch_scc0 .Lhob_wo_Thead
	s_branch .Lhob_wo_exit

; #define PG8_STAGE(bufoff, gbase, voff) do { _Pragma("unroll") for (int _i = 0; _i < 2; ++_i) \
;         __builtin_amdgcn_global_load_lds((const unsigned*)((const char*)(gbase) + (voff)[_i]), (PG8_LAS unsigned*)(lds + (bufoff) + ldsw + _i * 8192), 16, 0, 0); } while (0)
; #define PG8_BAR __builtin_amdgcn_s_barrier()
;     ...
;     for (int i = 0; i < 2; ++i) { int R, C; stage_rc(tid * 16 + i * 8192, R, C); const int Rb = Epi::PERM ? ((R & ~31) + perm32(R & 31)) : R;
;         const int Ra = Epi::PERMROW ? ((R & ~63) + 4 * (R & 15) + ((R >> 4) & 3)) : R;
;         voffA[i] = (unsigned)(Ra * K + C) * 2u; voffB[i] = (unsigned)(Rb * K + C) * 2u; }
;     ...
;         PG8_STAGE(PG8_SB(0, 0), cB, voffB); PG8_STAGE(PG8_SB(0, 1), cB + hstep, voffB); PG8_STAGE(PG8_SA(0, 0), cA, voffA); PG8_STAGE(PG8_SA(0, 1), cA + hstep, voffA);
;         if (wr == 1) PG8_BAR;
.LBB0_1319:
	v_ashrrev_i32_e32 v5, 31, v3
	v_lshrrev_b32_e32 v5, 26, v5
	v_add_u32_e32 v5, v3, v5
	v_ashrrev_i32_e32 v13, 6, v5
	v_bfe_i32 v5, v3, 27, 1
	v_lshlrev_b32_e32 v4, 4, v3
	v_lshrrev_b32_e32 v5, 22, v5
	v_add_u32_e32 v5, v4, v5
	v_and_b32_e32 v5, 0xfffffc00, v5
	v_sub_u32_e32 v5, v4, v5
	v_lshrrev_b32_e32 v6, 4, v5
	v_bitop3_b32 v6, v6, v5, 32 bitop3:0x6c
	v_ashrrev_i32_e32 v5, 31, v5
	v_lshrrev_b32_e32 v5, 26, v5
	s_add_u32 s23, s62, 0x20000000
	v_add_u32_e32 v5, v6, v5
	s_mul_i32 s3, s46, 0x2b00000
	s_addc_u32 s31, s63, 0
	v_ashrrev_i32_e32 v5, 6, v5
	s_mul_hi_u32 s2, s46, 0x2b00000
	s_add_u32 s3, s62, s3
	v_lshlrev_b32_e32 v7, 3, v13
	v_mul_i32_i24_e32 v9, 64, v5
	s_addc_u32 s2, s63, s2
	v_and_b32_e32 v7, -16, v7
	v_sub_u32_e32 v6, v6, v9
	s_add_u32 s56, s3, 0x7e00000
	v_add_u32_e32 v7, v5, v7
	v_ashrrev_i16_sdwa v6, v235, sext(v6) dst_sel:DWORD dst_unused:UNUSED_PAD src0_sel:DWORD src1_sel:BYTE_0
	s_addc_u32 s57, s2, 0
	v_lshlrev_b32_e32 v8, 5, v13
	v_bfe_i32 v14, v6, 0, 16
	v_lshlrev_b32_e32 v6, 1, v7
	v_lshrrev_b32_e32 v9, 2, v7
	v_and_b32_e32 v5, 3, v5
	s_mov_b32 s2, 0xfffe0
	v_and_b32_e32 v8, 32, v8
	v_and_b32_e32 v6, 24, v6
	v_and_b32_e32 v9, 4, v9
	v_and_or_b32 v5, v7, s2, v5
	v_or3_b32 v5, v5, v9, v6
	v_and_b32_e32 v15, 0xfffc0, v7
	v_lshlrev_b32_e32 v6, 2, v7
	s_waitcnt vmcnt(0)
	v_bfe_u32 v18, v7, 4, 2
	v_add_lshl_u32 v7, v8, v14, 1
	v_add_u32_e32 v4, 0x2000, v4
	v_lshl_add_u32 v182, v5, 12, v7
	v_ashrrev_i32_e32 v5, 31, v4
	v_lshrrev_b32_e32 v5, 22, v5
	v_add_u32_e32 v5, v4, v5
	v_ashrrev_i32_e32 v17, 10, v5
	v_mul_i32_i24_e32 v5, 0x400, v17
	v_sub_u32_e32 v4, v4, v5
	v_and_b32_e32 v16, 60, v6
	v_lshrrev_b32_e32 v5, 4, v4
	v_or3_b32 v6, v15, v16, v18
	v_bitop3_b32 v4, v5, v4, 32 bitop3:0x6c
	v_lshl_add_u32 v188, v6, 12, v7
	v_ashrrev_i32_e32 v6, 31, v4
	v_lshrrev_b32_e32 v6, 26, v6
	v_lshlrev_b32_e32 v5, 3, v17
	v_add_u32_e32 v6, v4, v6
	v_and_b32_e32 v5, -16, v5
	v_ashrrev_i32_e32 v7, 6, v6
	v_and_b32_e32 v6, 0xc0, v6
	v_add_u32_e32 v5, v7, v5
	v_sub_u32_e32 v4, v4, v6
	v_and_b32_e32 v7, 3, v7
	s_ashr_i32 s95, s94, 31
	s_ashr_i32 s11, s10, 31
	s_ashr_i32 s6, s0, 8
	v_ashrrev_i16_sdwa v4, v235, sext(v4) dst_sel:DWORD dst_unused:UNUSED_PAD src0_sel:DWORD src1_sel:BYTE_0
	v_and_or_b32 v7, v5, s2, v7
	s_lshl_b32 s37, s8, 10
	s_lshl_b64 s[2:3], s[94:95], 20
	s_lshl_b64 s[4:5], s[10:11], 20
	v_bfe_i32 v19, v4, 0, 16
	v_lshlrev_b32_e32 v4, 1, v5
	v_lshrrev_b32_e32 v6, 2, v5
	s_add_u32 s96, s56, s4
	v_lshlrev_b32_e32 v8, 5, v17
	v_and_b32_e32 v4, 24, v4
	v_and_b32_e32 v6, 4, v6
	s_addc_u32 s97, s57, s5
	s_add_i32 s95, s37, 0
	v_and_b32_e32 v8, 32, v8
	v_or3_b32 v4, v7, v6, v4
	v_lshlrev_b32_e32 v6, 2, v5
	s_add_i32 m0, s95, 0x10000
	v_and_b32_e32 v21, 60, v6
	v_add_lshl_u32 v6, v8, v19, 1
	global_load_lds_dwordx4 v182, s[96:97]
	s_add_i32 m0, s95, 0x12000
	v_lshl_add_u32 v192, v4, 12, v6
	s_add_u32 s4, s96, 0x80000
	global_load_lds_dwordx4 v192, s[96:97]
	s_addc_u32 s5, s97, 0
	s_add_i32 m0, s95, 0x14000
	v_and_b32_e32 v20, 0xfffc0, v5
	global_load_lds_dwordx4 v182, s[4:5]
	s_add_i32 m0, s95, 0x16000
	s_add_u32 s12, s23, s2
	v_bfe_u32 v22, v5, 4, 2
	s_addc_u32 s13, s31, s3
	s_add_i32 s20, s95, 0x2000
	v_or3_b32 v5, v20, v21, v22
	global_load_lds_dwordx4 v192, s[4:5]
	s_mov_b32 m0, s95
	s_add_u32 s2, s12, 0x80000
	v_lshl_add_u32 v190, v5, 12, v6
	global_load_lds_dwordx4 v188, s[12:13]
	s_mov_b32 m0, s20
	s_addc_u32 s3, s13, 0
	s_add_i32 s44, s95, 0x4000
	global_load_lds_dwordx4 v190, s[12:13]
	s_mov_b32 m0, s44
	s_add_i32 s46, s95, 0x6000
	global_load_lds_dwordx4 v188, s[2:3]
	s_mov_b32 m0, s46
	v_writelane_b32 v255, s76, 43
	global_load_lds_dwordx4 v190, s[2:3]
	s_nop 0
	v_writelane_b32 v255, s77, 44
	v_writelane_b32 v255, s75, 45
	v_writelane_b32 v255, s74, 46
	v_writelane_b32 v255, s51, 47
	v_writelane_b32 v255, s24, 37
	v_mov_b32_e32 v193, v183
	v_mov_b32_e32 v189, v183
	v_mov_b32_e32 v191, v183
	s_cmp_eq_u32 s6, 1
	v_writelane_b32 v255, s35, 36
	v_lshl_add_u64 v[10:11], s[96:97], 0, v[182:183]
	v_lshl_add_u64 v[8:9], s[96:97], 0, v[192:193]
	v_lshl_add_u64 v[4:5], s[12:13], 0, v[188:189]
	s_cselect_b64 s[74:75], -1, 0
	s_cmp_lg_u32 s6, 1
	v_lshl_add_u64 v[6:7], s[12:13], 0, v[190:191]
	s_cbranch_scc1 .LBB0_1321
	s_setprio 0

; #define PG8_STAGE(bufoff, gbase, voff) do { _Pragma("unroll") for (int _i = 0; _i < 2; ++_i) \
;         __builtin_amdgcn_global_load_lds((const unsigned*)((const char*)(gbase) + (voff)[_i]), (PG8_LAS unsigned*)(lds + (bufoff) + ldsw + _i * 8192), 16, 0, 0); } while (0)
; #define PG8_LDA(dst, b, h) do { _Pragma("unroll") for (int m = 0; m < 4; ++m) _Pragma("unroll") for (int k = 0; k < 2; ++k) dst[m][k] = *(const PG8_LAS bf16x8*)(lds + PG8_SA(b, h) + aoff + m * 2048 + k * 1024); } while (0)
; #define PG8_LDB(dst, b, h) do { _Pragma("unroll") for (int n = 0; n < 2; ++n) _Pragma("unroll") for (int k = 0; k < 2; ++k) dst[n][k] = *(const PG8_LAS bf16x8*)(lds + PG8_SB(b, h) + boff + n * 2048 + k * 1024); } while (0)
; #define PG8_WAIT_L(n) asm volatile("s_waitcnt lgkmcnt(" #n ")" ::: "memory")
; #define PG8_WAIT_V_SEL(sel) asm volatile("s_cmp_eq_u32 %0, 0\n\ts_cbranch_scc1 .Lw8_%=\n\ts_waitcnt vmcnt(22)\n\ts_branch .Lwd_%=\n.Lw8_%=:\n\ts_waitcnt vmcnt(8)\n.Lwd_%=:" :: "s"(sel) : "memory", "scc")
; #define PG8_BAR __builtin_amdgcn_s_barrier()
; #define PG8_SCHED __builtin_amdgcn_sched_barrier(0)
;     ...
;         for (int t = 0; t < nt * KREP; t += 2) {
;             const bool last = (t == nt * KREP - 2);
;             const int t1w = KREP > 1 ? ((t + 1) & (nt - 1)) : t + 1, t2w = KREP > 1 ? ((t + 2) & (nt - 1)) : t + 2;
;             const char* a1 = cA + (size_t)t1w * kstep;
;             const char* a2 = last ? nA : cA + (size_t)t2w * kstep; const char* b2 = last ? nB : cB + (size_t)t2w * kstep;
;             const char* a3 = a2 + kstep; const char* b3 = b2 + kstep;
;             if (last && has_next) S.a_ready(nxt);
;             const int relax = __builtin_amdgcn_readfirstlane((MK_RELAXW && t == 0 && ui > 0) ? 1 : 0);
;             if constexpr (SP2) {
;             PG8_LDB(B0, 0, 0); PG8_LDB(B1, 0, 1); PG8_SCHED; PG8_LDA(At, 0, 0); PG8_STAGE(PG8_SA(1, 1), a1 + hstep, voffA);
;             PG8_WAIT_V_SEL(relax);
;             PG8_WAIT_L(0); PG8_BAR; PG8_MMA(0, 0, At, B0); PG8_MMA(0, 1, At, B1); PG8_BAR; PG8_SCHED;
;     ...
; #pragma unroll
;         for (int a = 0; a < 2; ++a)
; #pragma unroll
;             for (int b = 0; b < 2; ++b)
; #pragma unroll
;                 for (int m = 0; m < 4; ++m)
; #pragma unroll
;                     for (int n = 0; n < 2; ++n) acc[a][b][m][n] = (f32x4){0.f, 0.f, 0.f, 0.f};
;         cur = nxt; cA = nA; cB = nB; ++ui;
.LBB0_1326:
	s_ashr_i32 s89, s88, 31
	s_lshl_b64 s[40:41], s[88:89], 20
	s_add_u32 s90, s23, s40
	s_addc_u32 s91, s31, s41
	s_and_b64 s[40:41], s[8:9], exec
	s_cselect_b32 s59, s91, s13
	s_cselect_b32 s64, s90, s12
	s_ashr_i32 s87, s86, 31
	s_lshl_b64 s[40:41], s[86:87], 20
	s_add_u32 s92, s56, s40
	s_addc_u32 s93, s57, s41
	s_and_b64 s[40:41], s[8:9], exec
	s_cselect_b32 s65, s93, s97
	s_cselect_b32 s87, s92, s96
	s_add_u32 s66, s96, 0x100
	v_mov_b64_e32 v[2:3], 0
	v_mov_b64_e32 v[4:5], 0
	v_mov_b64_e32 v[6:7], 0
	v_mov_b64_e32 v[8:9], 0
	v_mov_b64_e32 v[10:11], 0
	v_mov_b64_e32 v[12:13], 0
	v_mov_b64_e32 v[14:15], 0
	v_mov_b64_e32 v[16:17], 0
	v_mov_b64_e32 v[18:19], 0
	v_mov_b64_e32 v[20:21], 0
	v_mov_b64_e32 v[22:23], 0
	v_mov_b64_e32 v[24:25], 0
	v_mov_b64_e32 v[26:27], 0
	v_mov_b64_e32 v[28:29], 0
	v_mov_b64_e32 v[30:31], 0
	v_mov_b64_e32 v[32:33], 0
	v_mov_b64_e32 v[34:35], 0
	v_mov_b64_e32 v[36:37], 0
	v_mov_b64_e32 v[38:39], 0
	v_mov_b64_e32 v[40:41], 0
	v_mov_b64_e32 v[42:43], 0
	v_mov_b64_e32 v[44:45], 0
	v_mov_b64_e32 v[46:47], 0
	v_mov_b64_e32 v[48:49], 0
	v_mov_b64_e32 v[50:51], 0
	v_mov_b64_e32 v[52:53], 0
	v_mov_b64_e32 v[54:55], 0
	v_mov_b64_e32 v[56:57], 0
	v_mov_b64_e32 v[58:59], 0
	v_mov_b64_e32 v[60:61], 0
	v_mov_b64_e32 v[62:63], 0
	v_mov_b64_e32 v[64:65], 0
	v_mov_b64_e32 v[74:75], 0
	v_mov_b64_e32 v[76:77], 0
	v_mov_b64_e32 v[78:79], 0
	v_mov_b64_e32 v[80:81], 0
	v_mov_b64_e32 v[86:87], 0
	v_mov_b64_e32 v[88:89], 0
	v_mov_b64_e32 v[90:91], 0
	v_mov_b64_e32 v[92:93], 0
	v_mov_b64_e32 v[94:95], 0
	v_mov_b64_e32 v[96:97], 0
	v_mov_b64_e32 v[98:99], 0
	v_mov_b64_e32 v[100:101], 0
	v_mov_b64_e32 v[102:103], 0
	v_mov_b64_e32 v[104:105], 0
	v_mov_b64_e32 v[106:107], 0
	v_mov_b64_e32 v[108:109], 0
	v_mov_b64_e32 v[110:111], 0
	v_mov_b64_e32 v[112:113], 0
	v_mov_b64_e32 v[114:115], 0
	v_mov_b64_e32 v[116:117], 0
	v_mov_b64_e32 v[118:119], 0
	v_mov_b64_e32 v[120:121], 0
	v_mov_b64_e32 v[122:123], 0
	v_mov_b64_e32 v[124:125], 0
	v_mov_b64_e32 v[126:127], 0
	v_mov_b64_e32 v[128:129], 0
	v_mov_b64_e32 v[130:131], 0
	v_mov_b64_e32 v[132:133], 0
	v_mov_b64_e32 v[134:135], 0
	v_mov_b64_e32 v[136:137], 0
	v_mov_b64_e32 v[138:139], 0
	v_mov_b64_e32 v[140:141], 0
	s_addc_u32 s67, s97, 0
	s_mov_b32 s0, -2
	v_add_u32_e32 v200, 0x10000, v203
	s_cmp_lg_u32 s78, 0
	s_cbranch_scc0 .Lhob_f1_Thead
.LBB0_1327:
	s_add_u32 s96, s12, 0x100
	s_addc_u32 s97, s13, 0
	s_add_i32 s51, 0, 0x10000
	s_cmp_eq_u32 s0, 28
	s_cselect_b32 s41, s59, s97
	s_cselect_b32 s40, s64, s96
	s_cselect_b32 vcc_hi, s65, s67
	s_cselect_b32 vcc_lo, s87, s66
	s_add_i32 s19, 0, 0x14000
	ds_read_b128 v[66:69], v200
	ds_read_b128 v[70:73], v200 offset:1024
	ds_read_b128 v[82:85], v200 offset:2048
	ds_read_b128 v[142:145], v200 offset:3072
	ds_read_b128 v[146:149], v200 offset:16384
	ds_read_b128 v[150:153], v200 offset:17408
	ds_read_b128 v[154:157], v200 offset:18432
	ds_read_b128 v[158:161], v200 offset:19456
	s_add_i32 m0, s95, 0xc000
	ds_read_b128 v[162:165], v219
	ds_read_b128 v[166:169], v219 offset:1024
	ds_read_b128 v[170:173], v219 offset:2048
	ds_read_b128 v[174:177], v219 offset:3072
	ds_read_b128 v[178:181], v219 offset:4096
	ds_read_b128 v[184:187], v219 offset:5120
	ds_read_b128 v[220:223], v219 offset:6144
	ds_read_b128 v[224:227], v219 offset:7168
	global_load_lds_dwordx4 v196, s[12:13]
	s_add_i32 m0, s95, 0xe000
	s_nop 0
	global_load_lds_dwordx4 v198, s[12:13]
	s_waitcnt vmcnt(8)
	s_waitcnt lgkmcnt(0)
	s_setprio 1
	v_mfma_f32_16x16x32_bf16 v[114:117], v[66:69], v[162:165], v[114:117]
	v_mfma_f32_16x16x32_bf16 v[114:117], v[70:73], v[166:169], v[114:117]
	v_mfma_f32_16x16x32_bf16 v[110:113], v[66:69], v[170:173], v[110:113]
	v_mfma_f32_16x16x32_bf16 v[110:113], v[70:73], v[174:177], v[110:113]
	v_mfma_f32_16x16x32_bf16 v[78:81], v[66:69], v[178:181], v[78:81]
	v_mfma_f32_16x16x32_bf16 v[78:81], v[70:73], v[184:187], v[78:81]
	v_mfma_f32_16x16x32_bf16 v[74:77], v[66:69], v[220:223], v[74:77]
	v_mfma_f32_16x16x32_bf16 v[74:77], v[70:73], v[224:227], v[74:77]
	v_mfma_f32_16x16x32_bf16 v[134:137], v[82:85], v[220:223], v[134:137]
	v_mfma_f32_16x16x32_bf16 v[134:137], v[142:145], v[224:227], v[134:137]
	v_mfma_f32_16x16x32_bf16 v[138:141], v[82:85], v[178:181], v[138:141]
	v_mfma_f32_16x16x32_bf16 v[138:141], v[142:145], v[184:187], v[138:141]
	v_mfma_f32_16x16x32_bf16 v[102:105], v[82:85], v[170:173], v[102:105]
	v_mfma_f32_16x16x32_bf16 v[102:105], v[142:145], v[174:177], v[102:105]
	v_mfma_f32_16x16x32_bf16 v[106:109], v[82:85], v[162:165], v[106:109]
	v_mfma_f32_16x16x32_bf16 v[106:109], v[142:145], v[166:169], v[106:109]
	v_mfma_f32_16x16x32_bf16 v[98:101], v[146:149], v[162:165], v[98:101]
	v_mfma_f32_16x16x32_bf16 v[98:101], v[150:153], v[166:169], v[98:101]
	v_mfma_f32_16x16x32_bf16 v[94:97], v[146:149], v[170:173], v[94:97]
	v_mfma_f32_16x16x32_bf16 v[94:97], v[150:153], v[174:177], v[94:97]
	v_mfma_f32_16x16x32_bf16 v[130:133], v[146:149], v[178:181], v[130:133]
	v_mfma_f32_16x16x32_bf16 v[130:133], v[150:153], v[184:187], v[130:133]
	v_mfma_f32_16x16x32_bf16 v[126:129], v[146:149], v[220:223], v[126:129]
	v_mfma_f32_16x16x32_bf16 v[126:129], v[150:153], v[224:227], v[126:129]
	v_mfma_f32_16x16x32_bf16 v[118:121], v[154:157], v[220:223], v[118:121]
	v_mfma_f32_16x16x32_bf16 v[118:121], v[158:161], v[224:227], v[118:121]
	v_mfma_f32_16x16x32_bf16 v[122:125], v[154:157], v[178:181], v[122:125]
	v_mfma_f32_16x16x32_bf16 v[122:125], v[158:161], v[184:187], v[122:125]
	v_mfma_f32_16x16x32_bf16 v[86:89], v[154:157], v[170:173], v[86:89]
	v_mfma_f32_16x16x32_bf16 v[86:89], v[158:161], v[174:177], v[86:89]
	v_mfma_f32_16x16x32_bf16 v[90:93], v[154:157], v[162:165], v[90:93]
	v_mfma_f32_16x16x32_bf16 v[90:93], v[158:161], v[166:169], v[90:93]
	s_setprio 0
	s_barrier
; #define PG8_STAGE(bufoff, gbase, voff) do { _Pragma("unroll") for (int _i = 0; _i < 2; ++_i) \
;         __builtin_amdgcn_global_load_lds((const unsigned*)((const char*)(gbase) + (voff)[_i]), (PG8_LAS unsigned*)(lds + (bufoff) + ldsw + _i * 8192), 16, 0, 0); } while (0)
; #define PG8_LDA(dst, b, h) do { _Pragma("unroll") for (int m = 0; m < 4; ++m) _Pragma("unroll") for (int k = 0; k < 2; ++k) dst[m][k] = *(const PG8_LAS bf16x8*)(lds + PG8_SA(b, h) + aoff + m * 2048 + k * 1024); } while (0)
; #define PG8_LDB(dst, b, h) do { _Pragma("unroll") for (int n = 0; n < 2; ++n) _Pragma("unroll") for (int k = 0; k < 2; ++k) dst[n][k] = *(const PG8_LAS bf16x8*)(lds + PG8_SB(b, h) + boff + n * 2048 + k * 1024); } while (0)
; #define PG8_WAIT_V(n) asm volatile("s_waitcnt vmcnt(" #n ")" ::: "memory")
; #define PG8_WAIT_L(n) asm volatile("s_waitcnt lgkmcnt(" #n ")" ::: "memory")
; #define PG8_WAIT_V_SEL(sel) asm volatile("s_cmp_eq_u32 %0, 0\n\ts_cbranch_scc1 .Lw8_%=\n\ts_waitcnt vmcnt(22)\n\ts_branch .Lwd_%=\n.Lw8_%=:\n\ts_waitcnt vmcnt(8)\n.Lwd_%=:" :: "s"(sel) : "memory", "scc")
; #define PG8_BAR __builtin_amdgcn_s_barrier()
; #define PG8_SCHED __builtin_amdgcn_sched_barrier(0)
;     ...
;             PG8_LDA(At, 0, 1); PG8_STAGE(PG8_SB(0, 0), b2, voffB); PG8_STAGE(PG8_SB(0, 1), b2 + hstep, voffB); PG8_STAGE(PG8_SA(0, 0), a2, voffA);
;             PG8_WAIT_V_SEL(relax);
;             PG8_WAIT_L(0); PG8_BAR; PG8_MMA(1, 0, At, B0); PG8_MMA(1, 1, At, B1); PG8_BAR; PG8_SCHED;
;             PG8_LDB(B0, 1, 0); PG8_LDB(B1, 1, 1); PG8_SCHED; PG8_LDA(At, 1, 0); PG8_STAGE(PG8_SA(0, 1), a2 + hstep, voffA);
;             PG8_WAIT_V(8); PG8_WAIT_L(0); PG8_BAR; PG8_MMA(0, 0, At, B0); PG8_MMA(0, 1, At, B1); PG8_BAR; PG8_SCHED;
	s_add_i32 s12, s51, s37
	s_mov_b32 m0, s12
	ds_read_b128 v[162:165], v219 offset:16384
	ds_read_b128 v[166:169], v219 offset:17408
	ds_read_b128 v[170:173], v219 offset:18432
	ds_read_b128 v[174:177], v219 offset:19456
	ds_read_b128 v[178:181], v219 offset:20480
	ds_read_b128 v[184:187], v219 offset:21504
	ds_read_b128 v[220:223], v219 offset:22528
	ds_read_b128 v[224:227], v219 offset:23552
	global_load_lds_dwordx4 v182, vcc
	s_add_i32 m0, s12, 0x2000
	s_add_u32 s12, vcc_lo, 0x80000
	s_addc_u32 s13, vcc_hi, 0
	s_add_i32 s19, s19, s37
	global_load_lds_dwordx4 v192, vcc
	s_mov_b32 m0, s19
	s_nop 0
	global_load_lds_dwordx4 v182, s[12:13]
	s_add_i32 m0, s19, 0x2000
	s_nop 0
	global_load_lds_dwordx4 v192, s[12:13]
	s_mov_b32 m0, s95
	s_nop 0
	global_load_lds_dwordx4 v188, s[40:41]
	s_mov_b32 m0, s20
	s_nop 0
	global_load_lds_dwordx4 v190, s[40:41]
	s_waitcnt vmcnt(8)
	s_waitcnt lgkmcnt(0)
	s_setprio 1
	v_mfma_f32_16x16x32_bf16 v[30:33], v[66:69], v[162:165], v[30:33]
	v_mfma_f32_16x16x32_bf16 v[30:33], v[70:73], v[166:169], v[30:33]
	v_mfma_f32_16x16x32_bf16 v[26:29], v[66:69], v[170:173], v[26:29]
	v_mfma_f32_16x16x32_bf16 v[26:29], v[70:73], v[174:177], v[26:29]
	v_mfma_f32_16x16x32_bf16 v[62:65], v[66:69], v[178:181], v[62:65]
	v_mfma_f32_16x16x32_bf16 v[62:65], v[70:73], v[184:187], v[62:65]
	v_mfma_f32_16x16x32_bf16 v[58:61], v[66:69], v[220:223], v[58:61]
	v_mfma_f32_16x16x32_bf16 v[58:61], v[70:73], v[224:227], v[58:61]
	v_mfma_f32_16x16x32_bf16 v[50:53], v[82:85], v[220:223], v[50:53]
	v_mfma_f32_16x16x32_bf16 v[50:53], v[142:145], v[224:227], v[50:53]
	v_mfma_f32_16x16x32_bf16 v[54:57], v[82:85], v[178:181], v[54:57]
	v_mfma_f32_16x16x32_bf16 v[54:57], v[142:145], v[184:187], v[54:57]
	v_mfma_f32_16x16x32_bf16 v[18:21], v[82:85], v[170:173], v[18:21]
	v_mfma_f32_16x16x32_bf16 v[18:21], v[142:145], v[174:177], v[18:21]
	v_mfma_f32_16x16x32_bf16 v[22:25], v[82:85], v[162:165], v[22:25]
	v_mfma_f32_16x16x32_bf16 v[22:25], v[142:145], v[166:169], v[22:25]
	v_mfma_f32_16x16x32_bf16 v[14:17], v[146:149], v[162:165], v[14:17]
	v_mfma_f32_16x16x32_bf16 v[14:17], v[150:153], v[166:169], v[14:17]
	v_mfma_f32_16x16x32_bf16 v[10:13], v[146:149], v[170:173], v[10:13]
	v_mfma_f32_16x16x32_bf16 v[10:13], v[150:153], v[174:177], v[10:13]
	v_mfma_f32_16x16x32_bf16 v[46:49], v[146:149], v[178:181], v[46:49]
	v_mfma_f32_16x16x32_bf16 v[46:49], v[150:153], v[184:187], v[46:49]
	v_mfma_f32_16x16x32_bf16 v[38:41], v[146:149], v[220:223], v[38:41]
	v_mfma_f32_16x16x32_bf16 v[38:41], v[150:153], v[224:227], v[38:41]
	v_mfma_f32_16x16x32_bf16 v[42:45], v[154:157], v[220:223], v[42:45]
	v_mfma_f32_16x16x32_bf16 v[42:45], v[158:161], v[224:227], v[42:45]
	v_mfma_f32_16x16x32_bf16 v[34:37], v[154:157], v[178:181], v[34:37]
	v_mfma_f32_16x16x32_bf16 v[34:37], v[158:161], v[184:187], v[34:37]
	v_mfma_f32_16x16x32_bf16 v[2:5], v[154:157], v[170:173], v[2:5]
	v_mfma_f32_16x16x32_bf16 v[2:5], v[158:161], v[174:177], v[2:5]
	v_mfma_f32_16x16x32_bf16 v[6:9], v[154:157], v[162:165], v[6:9]
	v_mfma_f32_16x16x32_bf16 v[6:9], v[158:161], v[166:169], v[6:9]
	s_setprio 0
	s_barrier
	s_add_i32 s19, 0, 0x18000
	s_add_i32 s51, 0, 0x1c000
	ds_read_b128 v[66:69], v200 offset:32768
	ds_read_b128 v[70:73], v200 offset:33792
	ds_read_b128 v[82:85], v200 offset:34816
	ds_read_b128 v[142:145], v200 offset:35840
	ds_read_b128 v[146:149], v200 offset:49152
	ds_read_b128 v[150:153], v200 offset:50176
	ds_read_b128 v[154:157], v200 offset:51200
	ds_read_b128 v[158:161], v200 offset:52224
	s_add_u32 s12, s40, 0x80000
	s_addc_u32 s13, s41, 0
	s_mov_b32 m0, s44
	ds_read_b128 v[162:165], v219 offset:32768
	ds_read_b128 v[166:169], v219 offset:33792
	ds_read_b128 v[170:173], v219 offset:34816
	ds_read_b128 v[174:177], v219 offset:35840
	ds_read_b128 v[178:181], v219 offset:36864
	ds_read_b128 v[184:187], v219 offset:37888
	ds_read_b128 v[220:223], v219 offset:38912
	ds_read_b128 v[224:227], v219 offset:39936
	global_load_lds_dwordx4 v188, s[12:13]
	s_mov_b32 m0, s46
	s_nop 0
	global_load_lds_dwordx4 v190, s[12:13]
	s_waitcnt vmcnt(8)
	s_waitcnt lgkmcnt(0)
	s_setprio 1
	v_mfma_f32_16x16x32_bf16 v[114:117], v[66:69], v[162:165], v[114:117]
	v_mfma_f32_16x16x32_bf16 v[114:117], v[70:73], v[166:169], v[114:117]
	v_mfma_f32_16x16x32_bf16 v[110:113], v[66:69], v[170:173], v[110:113]
	v_mfma_f32_16x16x32_bf16 v[110:113], v[70:73], v[174:177], v[110:113]
	v_mfma_f32_16x16x32_bf16 v[78:81], v[66:69], v[178:181], v[78:81]
	v_mfma_f32_16x16x32_bf16 v[78:81], v[70:73], v[184:187], v[78:81]
	v_mfma_f32_16x16x32_bf16 v[74:77], v[66:69], v[220:223], v[74:77]
	v_mfma_f32_16x16x32_bf16 v[74:77], v[70:73], v[224:227], v[74:77]
	v_mfma_f32_16x16x32_bf16 v[134:137], v[82:85], v[220:223], v[134:137]
	v_mfma_f32_16x16x32_bf16 v[134:137], v[142:145], v[224:227], v[134:137]
	v_mfma_f32_16x16x32_bf16 v[138:141], v[82:85], v[178:181], v[138:141]
	v_mfma_f32_16x16x32_bf16 v[138:141], v[142:145], v[184:187], v[138:141]
	v_mfma_f32_16x16x32_bf16 v[102:105], v[82:85], v[170:173], v[102:105]
	v_mfma_f32_16x16x32_bf16 v[102:105], v[142:145], v[174:177], v[102:105]
	v_mfma_f32_16x16x32_bf16 v[106:109], v[82:85], v[162:165], v[106:109]
	v_mfma_f32_16x16x32_bf16 v[106:109], v[142:145], v[166:169], v[106:109]
	v_mfma_f32_16x16x32_bf16 v[98:101], v[146:149], v[162:165], v[98:101]
	v_mfma_f32_16x16x32_bf16 v[98:101], v[150:153], v[166:169], v[98:101]
	v_mfma_f32_16x16x32_bf16 v[94:97], v[146:149], v[170:173], v[94:97]
	v_mfma_f32_16x16x32_bf16 v[94:97], v[150:153], v[174:177], v[94:97]
	v_mfma_f32_16x16x32_bf16 v[130:133], v[146:149], v[178:181], v[130:133]
	v_mfma_f32_16x16x32_bf16 v[130:133], v[150:153], v[184:187], v[130:133]
	v_mfma_f32_16x16x32_bf16 v[126:129], v[146:149], v[220:223], v[126:129]
	v_mfma_f32_16x16x32_bf16 v[126:129], v[150:153], v[224:227], v[126:129]
	v_mfma_f32_16x16x32_bf16 v[118:121], v[154:157], v[220:223], v[118:121]
	v_mfma_f32_16x16x32_bf16 v[118:121], v[158:161], v[224:227], v[118:121]
	v_mfma_f32_16x16x32_bf16 v[122:125], v[154:157], v[178:181], v[122:125]
	v_mfma_f32_16x16x32_bf16 v[122:125], v[158:161], v[184:187], v[122:125]
	v_mfma_f32_16x16x32_bf16 v[86:89], v[154:157], v[170:173], v[86:89]
	v_mfma_f32_16x16x32_bf16 v[86:89], v[158:161], v[174:177], v[86:89]
	v_mfma_f32_16x16x32_bf16 v[90:93], v[154:157], v[162:165], v[90:93]
	v_mfma_f32_16x16x32_bf16 v[90:93], v[158:161], v[166:169], v[90:93]
	s_setprio 0
	s_barrier
; #define PG8_STAGE(bufoff, gbase, voff) do { _Pragma("unroll") for (int _i = 0; _i < 2; ++_i) \
;         __builtin_amdgcn_global_load_lds((const unsigned*)((const char*)(gbase) + (voff)[_i]), (PG8_LAS unsigned*)(lds + (bufoff) + ldsw + _i * 8192), 16, 0, 0); } while (0)
; #define PG8_LDA(dst, b, h) do { _Pragma("unroll") for (int m = 0; m < 4; ++m) _Pragma("unroll") for (int k = 0; k < 2; ++k) dst[m][k] = *(const PG8_LAS bf16x8*)(lds + PG8_SA(b, h) + aoff + m * 2048 + k * 1024); } while (0)
; #define PG8_LDB(dst, b, h) do { _Pragma("unroll") for (int n = 0; n < 2; ++n) _Pragma("unroll") for (int k = 0; k < 2; ++k) dst[n][k] = *(const PG8_LAS bf16x8*)(lds + PG8_SB(b, h) + boff + n * 2048 + k * 1024); } while (0)
; #define PG8_WAIT_V(n) asm volatile("s_waitcnt vmcnt(" #n ")" ::: "memory")
; #define PG8_WAIT_L(n) asm volatile("s_waitcnt lgkmcnt(" #n ")" ::: "memory")
; #define PG8_WAIT_V_SEL(sel) asm volatile("s_cmp_eq_u32 %0, 0\n\ts_cbranch_scc1 .Lw8_%=\n\ts_waitcnt vmcnt(22)\n\ts_branch .Lwd_%=\n.Lw8_%=:\n\ts_waitcnt vmcnt(8)\n.Lwd_%=:" :: "s"(sel) : "memory", "scc")
; #define PG8_BAR __builtin_amdgcn_s_barrier()
; #define PG8_SCHED __builtin_amdgcn_sched_barrier(0)
;     ...
;             PG8_LDB(B0, 0, 0); PG8_LDB(B1, 0, 1); PG8_SCHED; PG8_LDA(At, 0, 0); PG8_STAGE(PG8_SA(1, 1), a1 + hstep, voffA);
;             PG8_WAIT_V_SEL(relax);
;             PG8_WAIT_L(0); PG8_BAR; PG8_MMA(0, 0, At, B0); PG8_MMA(0, 1, At, B1); PG8_BAR; PG8_SCHED;
;             PG8_LDA(At, 0, 1); PG8_STAGE(PG8_SB(0, 0), b2, voffB); PG8_STAGE(PG8_SB(0, 1), b2 + hstep, voffB); PG8_STAGE(PG8_SA(0, 0), a2, voffA);
;             PG8_WAIT_V_SEL(relax);
;             PG8_WAIT_L(0); PG8_BAR; PG8_MMA(1, 0, At, B0); PG8_MMA(1, 1, At, B1); PG8_BAR; PG8_SCHED;
;             PG8_LDB(B0, 1, 0); PG8_LDB(B1, 1, 1); PG8_SCHED; PG8_LDA(At, 1, 0); PG8_STAGE(PG8_SA(0, 1), a2 + hstep, voffA);
;             PG8_WAIT_V(8); PG8_WAIT_L(0); PG8_BAR; PG8_MMA(0, 0, At, B0); PG8_MMA(0, 1, At, B1); PG8_BAR; PG8_SCHED;
;             PG8_LDA(At, 1, 1); PG8_STAGE(PG8_SB(1, 0), b3, voffB); PG8_STAGE(PG8_SB(1, 1), b3 + hstep, voffB); PG8_STAGE(PG8_SA(1, 0), a3, voffA);
;             PG8_WAIT_V(8); PG8_WAIT_L(0); PG8_BAR; PG8_MMA(1, 0, At, B0); PG8_MMA(1, 1, At, B1); PG8_BAR; PG8_SCHED;
	s_add_i32 s12, s19, s37
	s_mov_b32 m0, s12
	ds_read_b128 v[162:165], v219 offset:49152
	ds_read_b128 v[166:169], v219 offset:50176
	ds_read_b128 v[170:173], v219 offset:51200
	ds_read_b128 v[174:177], v219 offset:52224
	ds_read_b128 v[178:181], v219 offset:53248
	ds_read_b128 v[184:187], v219 offset:54272
	ds_read_b128 v[220:223], v219 offset:55296
	ds_read_b128 v[224:227], v219 offset:56320
	s_add_u32 s100, vcc_lo, 0x80
	s_addc_u32 s101, vcc_hi, 0
	global_load_lds_dwordx4 v182, s[100:101]
	s_add_i32 m0, s12, 0x2000
	s_add_u32 s12, vcc_lo, 0x80080
	s_addc_u32 s13, vcc_hi, 0
	s_add_i32 s19, s51, s37
	global_load_lds_dwordx4 v192, s[100:101]
	s_mov_b32 m0, s19
	s_nop 0
	global_load_lds_dwordx4 v182, s[12:13]
	s_add_i32 m0, s19, 0x2000
	s_nop 0
	global_load_lds_dwordx4 v192, s[12:13]
	s_mov_b32 m0, s45
	s_nop 0
	s_add_u32 s100, s40, 0x80
	s_addc_u32 s101, s41, 0
	global_load_lds_dwordx4 v188, s[100:101]
	s_mov_b32 m0, s24
	s_nop 0
	global_load_lds_dwordx4 v190, s[100:101]
	s_waitcnt vmcnt(8)
	s_waitcnt lgkmcnt(0)
	s_setprio 1
	v_mfma_f32_16x16x32_bf16 v[30:33], v[66:69], v[162:165], v[30:33]
	v_mfma_f32_16x16x32_bf16 v[30:33], v[70:73], v[166:169], v[30:33]
	v_mfma_f32_16x16x32_bf16 v[26:29], v[66:69], v[170:173], v[26:29]
	v_mfma_f32_16x16x32_bf16 v[26:29], v[70:73], v[174:177], v[26:29]
	v_mfma_f32_16x16x32_bf16 v[62:65], v[66:69], v[178:181], v[62:65]
	v_mfma_f32_16x16x32_bf16 v[62:65], v[70:73], v[184:187], v[62:65]
	v_mfma_f32_16x16x32_bf16 v[58:61], v[66:69], v[220:223], v[58:61]
	v_mfma_f32_16x16x32_bf16 v[58:61], v[70:73], v[224:227], v[58:61]
	v_mfma_f32_16x16x32_bf16 v[50:53], v[82:85], v[220:223], v[50:53]
	v_mfma_f32_16x16x32_bf16 v[50:53], v[142:145], v[224:227], v[50:53]
	v_mfma_f32_16x16x32_bf16 v[54:57], v[82:85], v[178:181], v[54:57]
	v_mfma_f32_16x16x32_bf16 v[54:57], v[142:145], v[184:187], v[54:57]
	v_mfma_f32_16x16x32_bf16 v[18:21], v[82:85], v[170:173], v[18:21]
	v_mfma_f32_16x16x32_bf16 v[18:21], v[142:145], v[174:177], v[18:21]
	v_mfma_f32_16x16x32_bf16 v[22:25], v[82:85], v[162:165], v[22:25]
	v_mfma_f32_16x16x32_bf16 v[22:25], v[142:145], v[166:169], v[22:25]
	v_mfma_f32_16x16x32_bf16 v[14:17], v[146:149], v[162:165], v[14:17]
	v_mfma_f32_16x16x32_bf16 v[14:17], v[150:153], v[166:169], v[14:17]
	v_mfma_f32_16x16x32_bf16 v[10:13], v[146:149], v[170:173], v[10:13]
	v_mfma_f32_16x16x32_bf16 v[10:13], v[150:153], v[174:177], v[10:13]
	v_mfma_f32_16x16x32_bf16 v[46:49], v[146:149], v[178:181], v[46:49]
	v_mfma_f32_16x16x32_bf16 v[46:49], v[150:153], v[184:187], v[46:49]
	v_mfma_f32_16x16x32_bf16 v[38:41], v[146:149], v[220:223], v[38:41]
	v_mfma_f32_16x16x32_bf16 v[38:41], v[150:153], v[224:227], v[38:41]
	v_mfma_f32_16x16x32_bf16 v[42:45], v[154:157], v[220:223], v[42:45]
	v_mfma_f32_16x16x32_bf16 v[42:45], v[158:161], v[224:227], v[42:45]
	v_mfma_f32_16x16x32_bf16 v[34:37], v[154:157], v[178:181], v[34:37]
	v_mfma_f32_16x16x32_bf16 v[34:37], v[158:161], v[184:187], v[34:37]
	v_mfma_f32_16x16x32_bf16 v[2:5], v[154:157], v[170:173], v[2:5]
	v_mfma_f32_16x16x32_bf16 v[2:5], v[158:161], v[174:177], v[2:5]
	v_mfma_f32_16x16x32_bf16 v[6:9], v[154:157], v[162:165], v[6:9]
	v_mfma_f32_16x16x32_bf16 v[6:9], v[158:161], v[166:169], v[6:9]
	s_setprio 0
	s_barrier
	s_add_i32 s0, s0, 2
	s_add_u32 s66, s66, 0x100
	s_addc_u32 s67, s67, 0
	s_cmp_gt_u32 s0, 29
	s_mov_b64 s[12:13], s[96:97]
	s_cbranch_scc0 .LBB0_1327
	s_branch .Lhob_f1_exit
.Lhob_f1_Thead:
	s_add_u32 s96, s12, 0x100
	s_addc_u32 s97, s13, 0
	s_add_i32 s51, 0, 0x10000
	s_cmp_eq_u32 s0, 28
	s_cselect_b32 s41, s59, s97
	s_cselect_b32 s40, s64, s96
	s_cselect_b32 vcc_hi, s65, s67
	s_cselect_b32 vcc_lo, s87, s66
	s_add_i32 s19, 0, 0x14000
	ds_read_b128 v[66:69], v200
	ds_read_b128 v[70:73], v200 offset:1024
	ds_read_b128 v[82:85], v200 offset:2048
	ds_read_b128 v[142:145], v200 offset:3072
	ds_read_b128 v[146:149], v200 offset:16384
	ds_read_b128 v[150:153], v200 offset:17408
	ds_read_b128 v[154:157], v200 offset:18432
	ds_read_b128 v[158:161], v200 offset:19456
	s_add_i32 m0, s95, 0xc000
	ds_read_b128 v[162:165], v219
	ds_read_b128 v[166:169], v219 offset:1024
	ds_read_b128 v[170:173], v219 offset:2048
	ds_read_b128 v[174:177], v219 offset:3072
	ds_read_b128 v[178:181], v219 offset:4096
	ds_read_b128 v[184:187], v219 offset:5120
	ds_read_b128 v[220:223], v219 offset:6144
	ds_read_b128 v[224:227], v219 offset:7168
	global_load_lds_dwordx4 v196, s[12:13]
	s_add_i32 m0, s95, 0xe000
	s_nop 0
	global_load_lds_dwordx4 v198, s[12:13]
	s_waitcnt vmcnt(8)
	s_waitcnt lgkmcnt(0)
	s_barrier
; #define PG8_STAGE(bufoff, gbase, voff) do { _Pragma("unroll") for (int _i = 0; _i < 2; ++_i) \
;         __builtin_amdgcn_global_load_lds((const unsigned*)((const char*)(gbase) + (voff)[_i]), (PG8_LAS unsigned*)(lds + (bufoff) + ldsw + _i * 8192), 16, 0, 0); } while (0)
; #define PG8_LDA(dst, b, h) do { _Pragma("unroll") for (int m = 0; m < 4; ++m) _Pragma("unroll") for (int k = 0; k < 2; ++k) dst[m][k] = *(const PG8_LAS bf16x8*)(lds + PG8_SA(b, h) + aoff + m * 2048 + k * 1024); } while (0)
; #define PG8_LDB(dst, b, h) do { _Pragma("unroll") for (int n = 0; n < 2; ++n) _Pragma("unroll") for (int k = 0; k < 2; ++k) dst[n][k] = *(const PG8_LAS bf16x8*)(lds + PG8_SB(b, h) + boff + n * 2048 + k * 1024); } while (0)
; #define PG8_WAIT_V(n) asm volatile("s_waitcnt vmcnt(" #n ")" ::: "memory")
; #define PG8_WAIT_L(n) asm volatile("s_waitcnt lgkmcnt(" #n ")" ::: "memory")
; #define PG8_WAIT_V_SEL(sel) asm volatile("s_cmp_eq_u32 %0, 0\n\ts_cbranch_scc1 .Lw8_%=\n\ts_waitcnt vmcnt(22)\n\ts_branch .Lwd_%=\n.Lw8_%=:\n\ts_waitcnt vmcnt(8)\n.Lwd_%=:" :: "s"(sel) : "memory", "scc")
; #define PG8_BAR __builtin_amdgcn_s_barrier()
; #define PG8_SCHED __builtin_amdgcn_sched_barrier(0)
;     ...
;             PG8_LDB(B0, 0, 0); PG8_LDB(B1, 0, 1); PG8_SCHED; PG8_LDA(At, 0, 0); PG8_STAGE(PG8_SA(1, 1), a1 + hstep, voffA);
;             PG8_WAIT_V_SEL(relax);
;             PG8_WAIT_L(0); PG8_BAR; PG8_MMA(0, 0, At, B0); PG8_MMA(0, 1, At, B1); PG8_BAR; PG8_SCHED;
;             PG8_LDA(At, 0, 1); PG8_STAGE(PG8_SB(0, 0), b2, voffB); PG8_STAGE(PG8_SB(0, 1), b2 + hstep, voffB); PG8_STAGE(PG8_SA(0, 0), a2, voffA);
;             PG8_WAIT_V_SEL(relax);
;             PG8_WAIT_L(0); PG8_BAR; PG8_MMA(1, 0, At, B0); PG8_MMA(1, 1, At, B1); PG8_BAR; PG8_SCHED;
;             PG8_LDB(B0, 1, 0); PG8_LDB(B1, 1, 1); PG8_SCHED; PG8_LDA(At, 1, 0); PG8_STAGE(PG8_SA(0, 1), a2 + hstep, voffA);
;             PG8_WAIT_V(8); PG8_WAIT_L(0); PG8_BAR; PG8_MMA(0, 0, At, B0); PG8_MMA(0, 1, At, B1); PG8_BAR; PG8_SCHED;
	s_setprio 2
	v_mfma_f32_16x16x32_bf16 v[114:117], v[66:69], v[162:165], v[114:117]
	v_mfma_f32_16x16x32_bf16 v[114:117], v[70:73], v[166:169], v[114:117]
	v_mfma_f32_16x16x32_bf16 v[110:113], v[66:69], v[170:173], v[110:113]
	v_mfma_f32_16x16x32_bf16 v[110:113], v[70:73], v[174:177], v[110:113]
	v_mfma_f32_16x16x32_bf16 v[78:81], v[66:69], v[178:181], v[78:81]
	v_mfma_f32_16x16x32_bf16 v[78:81], v[70:73], v[184:187], v[78:81]
	v_mfma_f32_16x16x32_bf16 v[74:77], v[66:69], v[220:223], v[74:77]
	v_mfma_f32_16x16x32_bf16 v[74:77], v[70:73], v[224:227], v[74:77]
	v_mfma_f32_16x16x32_bf16 v[134:137], v[82:85], v[220:223], v[134:137]
	v_mfma_f32_16x16x32_bf16 v[134:137], v[142:145], v[224:227], v[134:137]
	v_mfma_f32_16x16x32_bf16 v[138:141], v[82:85], v[178:181], v[138:141]
	v_mfma_f32_16x16x32_bf16 v[138:141], v[142:145], v[184:187], v[138:141]
	v_mfma_f32_16x16x32_bf16 v[102:105], v[82:85], v[170:173], v[102:105]
	v_mfma_f32_16x16x32_bf16 v[102:105], v[142:145], v[174:177], v[102:105]
	v_mfma_f32_16x16x32_bf16 v[106:109], v[82:85], v[162:165], v[106:109]
	v_mfma_f32_16x16x32_bf16 v[106:109], v[142:145], v[166:169], v[106:109]
	v_mfma_f32_16x16x32_bf16 v[98:101], v[146:149], v[162:165], v[98:101]
	v_mfma_f32_16x16x32_bf16 v[98:101], v[150:153], v[166:169], v[98:101]
	v_mfma_f32_16x16x32_bf16 v[94:97], v[146:149], v[170:173], v[94:97]
	v_mfma_f32_16x16x32_bf16 v[94:97], v[150:153], v[174:177], v[94:97]
	v_mfma_f32_16x16x32_bf16 v[130:133], v[146:149], v[178:181], v[130:133]
	v_mfma_f32_16x16x32_bf16 v[130:133], v[150:153], v[184:187], v[130:133]
	v_mfma_f32_16x16x32_bf16 v[126:129], v[146:149], v[220:223], v[126:129]
	v_mfma_f32_16x16x32_bf16 v[126:129], v[150:153], v[224:227], v[126:129]
	v_mfma_f32_16x16x32_bf16 v[118:121], v[154:157], v[220:223], v[118:121]
	v_mfma_f32_16x16x32_bf16 v[118:121], v[158:161], v[224:227], v[118:121]
	v_mfma_f32_16x16x32_bf16 v[122:125], v[154:157], v[178:181], v[122:125]
	v_mfma_f32_16x16x32_bf16 v[122:125], v[158:161], v[184:187], v[122:125]
	v_mfma_f32_16x16x32_bf16 v[86:89], v[154:157], v[170:173], v[86:89]
	v_mfma_f32_16x16x32_bf16 v[86:89], v[158:161], v[174:177], v[86:89]
	v_mfma_f32_16x16x32_bf16 v[90:93], v[154:157], v[162:165], v[90:93]
	v_mfma_f32_16x16x32_bf16 v[90:93], v[158:161], v[166:169], v[90:93]
	s_setprio 0
	s_add_i32 s12, s51, s37
	s_mov_b32 m0, s12
	ds_read_b128 v[162:165], v219 offset:16384
	ds_read_b128 v[166:169], v219 offset:17408
	ds_read_b128 v[170:173], v219 offset:18432
	ds_read_b128 v[174:177], v219 offset:19456
	ds_read_b128 v[178:181], v219 offset:20480
	ds_read_b128 v[184:187], v219 offset:21504
	ds_read_b128 v[220:223], v219 offset:22528
	ds_read_b128 v[224:227], v219 offset:23552
	global_load_lds_dwordx4 v182, vcc
	s_add_i32 m0, s12, 0x2000
	s_add_u32 s12, vcc_lo, 0x80000
	s_addc_u32 s13, vcc_hi, 0
	s_add_i32 s19, s19, s37
	global_load_lds_dwordx4 v192, vcc
	s_mov_b32 m0, s19
	s_nop 0
	global_load_lds_dwordx4 v182, s[12:13]
	s_add_i32 m0, s19, 0x2000
	s_nop 0
	global_load_lds_dwordx4 v192, s[12:13]
	s_mov_b32 m0, s95
	s_nop 0
	global_load_lds_dwordx4 v188, s[40:41]
	s_mov_b32 m0, s20
	s_nop 0
	global_load_lds_dwordx4 v190, s[40:41]
	s_waitcnt vmcnt(8)
	s_waitcnt lgkmcnt(0)
	s_barrier
	s_setprio 2
	v_mfma_f32_16x16x32_bf16 v[30:33], v[66:69], v[162:165], v[30:33]
	v_mfma_f32_16x16x32_bf16 v[30:33], v[70:73], v[166:169], v[30:33]
	v_mfma_f32_16x16x32_bf16 v[26:29], v[66:69], v[170:173], v[26:29]
	v_mfma_f32_16x16x32_bf16 v[26:29], v[70:73], v[174:177], v[26:29]
	v_mfma_f32_16x16x32_bf16 v[62:65], v[66:69], v[178:181], v[62:65]
	v_mfma_f32_16x16x32_bf16 v[62:65], v[70:73], v[184:187], v[62:65]
	v_mfma_f32_16x16x32_bf16 v[58:61], v[66:69], v[220:223], v[58:61]
	v_mfma_f32_16x16x32_bf16 v[58:61], v[70:73], v[224:227], v[58:61]
	v_mfma_f32_16x16x32_bf16 v[50:53], v[82:85], v[220:223], v[50:53]
	v_mfma_f32_16x16x32_bf16 v[50:53], v[142:145], v[224:227], v[50:53]
	v_mfma_f32_16x16x32_bf16 v[54:57], v[82:85], v[178:181], v[54:57]
	v_mfma_f32_16x16x32_bf16 v[54:57], v[142:145], v[184:187], v[54:57]
	v_mfma_f32_16x16x32_bf16 v[18:21], v[82:85], v[170:173], v[18:21]
	v_mfma_f32_16x16x32_bf16 v[18:21], v[142:145], v[174:177], v[18:21]
	v_mfma_f32_16x16x32_bf16 v[22:25], v[82:85], v[162:165], v[22:25]
	v_mfma_f32_16x16x32_bf16 v[22:25], v[142:145], v[166:169], v[22:25]
	v_mfma_f32_16x16x32_bf16 v[14:17], v[146:149], v[162:165], v[14:17]
	v_mfma_f32_16x16x32_bf16 v[14:17], v[150:153], v[166:169], v[14:17]
	v_mfma_f32_16x16x32_bf16 v[10:13], v[146:149], v[170:173], v[10:13]
	v_mfma_f32_16x16x32_bf16 v[10:13], v[150:153], v[174:177], v[10:13]
	v_mfma_f32_16x16x32_bf16 v[46:49], v[146:149], v[178:181], v[46:49]
	v_mfma_f32_16x16x32_bf16 v[46:49], v[150:153], v[184:187], v[46:49]
	v_mfma_f32_16x16x32_bf16 v[38:41], v[146:149], v[220:223], v[38:41]
	v_mfma_f32_16x16x32_bf16 v[38:41], v[150:153], v[224:227], v[38:41]
	v_mfma_f32_16x16x32_bf16 v[42:45], v[154:157], v[220:223], v[42:45]
	v_mfma_f32_16x16x32_bf16 v[42:45], v[158:161], v[224:227], v[42:45]
	v_mfma_f32_16x16x32_bf16 v[34:37], v[154:157], v[178:181], v[34:37]
	v_mfma_f32_16x16x32_bf16 v[34:37], v[158:161], v[184:187], v[34:37]
	v_mfma_f32_16x16x32_bf16 v[2:5], v[154:157], v[170:173], v[2:5]
	v_mfma_f32_16x16x32_bf16 v[2:5], v[158:161], v[174:177], v[2:5]
	v_mfma_f32_16x16x32_bf16 v[6:9], v[154:157], v[162:165], v[6:9]
	v_mfma_f32_16x16x32_bf16 v[6:9], v[158:161], v[166:169], v[6:9]
	s_setprio 0
	s_add_i32 s19, 0, 0x18000
	s_add_i32 s51, 0, 0x1c000
	ds_read_b128 v[66:69], v200 offset:32768
	ds_read_b128 v[70:73], v200 offset:33792
	ds_read_b128 v[82:85], v200 offset:34816
	ds_read_b128 v[142:145], v200 offset:35840
	ds_read_b128 v[146:149], v200 offset:49152
	ds_read_b128 v[150:153], v200 offset:50176
	ds_read_b128 v[154:157], v200 offset:51200
	ds_read_b128 v[158:161], v200 offset:52224
	s_add_u32 s12, s40, 0x80000
	s_addc_u32 s13, s41, 0
	s_mov_b32 m0, s44
	ds_read_b128 v[162:165], v219 offset:32768
	ds_read_b128 v[166:169], v219 offset:33792
	ds_read_b128 v[170:173], v219 offset:34816
	ds_read_b128 v[174:177], v219 offset:35840
	ds_read_b128 v[178:181], v219 offset:36864
	ds_read_b128 v[184:187], v219 offset:37888
	ds_read_b128 v[220:223], v219 offset:38912
	ds_read_b128 v[224:227], v219 offset:39936
	global_load_lds_dwordx4 v188, s[12:13]
	s_mov_b32 m0, s46
	s_nop 0
	global_load_lds_dwordx4 v190, s[12:13]
	s_waitcnt vmcnt(8)
	s_waitcnt lgkmcnt(0)
	s_barrier
; #define PG8_STAGE(bufoff, gbase, voff) do { _Pragma("unroll") for (int _i = 0; _i < 2; ++_i) \
;         __builtin_amdgcn_global_load_lds((const unsigned*)((const char*)(gbase) + (voff)[_i]), (PG8_LAS unsigned*)(lds + (bufoff) + ldsw + _i * 8192), 16, 0, 0); } while (0)
; #define PG8_LDA(dst, b, h) do { _Pragma("unroll") for (int m = 0; m < 4; ++m) _Pragma("unroll") for (int k = 0; k < 2; ++k) dst[m][k] = *(const PG8_LAS bf16x8*)(lds + PG8_SA(b, h) + aoff + m * 2048 + k * 1024); } while (0)
; #define PG8_LDB(dst, b, h) do { _Pragma("unroll") for (int n = 0; n < 2; ++n) _Pragma("unroll") for (int k = 0; k < 2; ++k) dst[n][k] = *(const PG8_LAS bf16x8*)(lds + PG8_SB(b, h) + boff + n * 2048 + k * 1024); } while (0)
; #define PG8_WAIT_V(n) asm volatile("s_waitcnt vmcnt(" #n ")" ::: "memory")
; #define PG8_WAIT_L(n) asm volatile("s_waitcnt lgkmcnt(" #n ")" ::: "memory")
; #define PG8_BAR __builtin_amdgcn_s_barrier()
; #define PG8_SCHED __builtin_amdgcn_sched_barrier(0)
;     ...
;             PG8_LDB(B0, 1, 0); PG8_LDB(B1, 1, 1); PG8_SCHED; PG8_LDA(At, 1, 0); PG8_STAGE(PG8_SA(0, 1), a2 + hstep, voffA);
;             PG8_WAIT_V(8); PG8_WAIT_L(0); PG8_BAR; PG8_MMA(0, 0, At, B0); PG8_MMA(0, 1, At, B1); PG8_BAR; PG8_SCHED;
;             PG8_LDA(At, 1, 1); PG8_STAGE(PG8_SB(1, 0), b3, voffB); PG8_STAGE(PG8_SB(1, 1), b3 + hstep, voffB); PG8_STAGE(PG8_SA(1, 0), a3, voffA);
;             PG8_WAIT_V(8); PG8_WAIT_L(0); PG8_BAR; PG8_MMA(1, 0, At, B0); PG8_MMA(1, 1, At, B1); PG8_BAR; PG8_SCHED;
	s_setprio 2
	v_mfma_f32_16x16x32_bf16 v[114:117], v[66:69], v[162:165], v[114:117]
	v_mfma_f32_16x16x32_bf16 v[114:117], v[70:73], v[166:169], v[114:117]
	v_mfma_f32_16x16x32_bf16 v[110:113], v[66:69], v[170:173], v[110:113]
	v_mfma_f32_16x16x32_bf16 v[110:113], v[70:73], v[174:177], v[110:113]
	v_mfma_f32_16x16x32_bf16 v[78:81], v[66:69], v[178:181], v[78:81]
	v_mfma_f32_16x16x32_bf16 v[78:81], v[70:73], v[184:187], v[78:81]
	v_mfma_f32_16x16x32_bf16 v[74:77], v[66:69], v[220:223], v[74:77]
	v_mfma_f32_16x16x32_bf16 v[74:77], v[70:73], v[224:227], v[74:77]
	v_mfma_f32_16x16x32_bf16 v[134:137], v[82:85], v[220:223], v[134:137]
	v_mfma_f32_16x16x32_bf16 v[134:137], v[142:145], v[224:227], v[134:137]
	v_mfma_f32_16x16x32_bf16 v[138:141], v[82:85], v[178:181], v[138:141]
	v_mfma_f32_16x16x32_bf16 v[138:141], v[142:145], v[184:187], v[138:141]
	v_mfma_f32_16x16x32_bf16 v[102:105], v[82:85], v[170:173], v[102:105]
	v_mfma_f32_16x16x32_bf16 v[102:105], v[142:145], v[174:177], v[102:105]
	v_mfma_f32_16x16x32_bf16 v[106:109], v[82:85], v[162:165], v[106:109]
	v_mfma_f32_16x16x32_bf16 v[106:109], v[142:145], v[166:169], v[106:109]
	v_mfma_f32_16x16x32_bf16 v[98:101], v[146:149], v[162:165], v[98:101]
	v_mfma_f32_16x16x32_bf16 v[98:101], v[150:153], v[166:169], v[98:101]
	v_mfma_f32_16x16x32_bf16 v[94:97], v[146:149], v[170:173], v[94:97]
	v_mfma_f32_16x16x32_bf16 v[94:97], v[150:153], v[174:177], v[94:97]
	v_mfma_f32_16x16x32_bf16 v[130:133], v[146:149], v[178:181], v[130:133]
	v_mfma_f32_16x16x32_bf16 v[130:133], v[150:153], v[184:187], v[130:133]
	v_mfma_f32_16x16x32_bf16 v[126:129], v[146:149], v[220:223], v[126:129]
	v_mfma_f32_16x16x32_bf16 v[126:129], v[150:153], v[224:227], v[126:129]
	v_mfma_f32_16x16x32_bf16 v[118:121], v[154:157], v[220:223], v[118:121]
	v_mfma_f32_16x16x32_bf16 v[118:121], v[158:161], v[224:227], v[118:121]
	v_mfma_f32_16x16x32_bf16 v[122:125], v[154:157], v[178:181], v[122:125]
	v_mfma_f32_16x16x32_bf16 v[122:125], v[158:161], v[184:187], v[122:125]
	v_mfma_f32_16x16x32_bf16 v[86:89], v[154:157], v[170:173], v[86:89]
	v_mfma_f32_16x16x32_bf16 v[86:89], v[158:161], v[174:177], v[86:89]
	v_mfma_f32_16x16x32_bf16 v[90:93], v[154:157], v[162:165], v[90:93]
	v_mfma_f32_16x16x32_bf16 v[90:93], v[158:161], v[166:169], v[90:93]
	s_setprio 0
	s_add_i32 s12, s19, s37
	s_mov_b32 m0, s12
	ds_read_b128 v[162:165], v219 offset:49152
	ds_read_b128 v[166:169], v219 offset:50176
	ds_read_b128 v[170:173], v219 offset:51200
	ds_read_b128 v[174:177], v219 offset:52224
	ds_read_b128 v[178:181], v219 offset:53248
	ds_read_b128 v[184:187], v219 offset:54272
	ds_read_b128 v[220:223], v219 offset:55296
	ds_read_b128 v[224:227], v219 offset:56320
	s_add_u32 s100, vcc_lo, 0x80
	s_addc_u32 s101, vcc_hi, 0
	global_load_lds_dwordx4 v182, s[100:101]
	s_add_i32 m0, s12, 0x2000
	s_add_u32 s12, vcc_lo, 0x80080
	s_addc_u32 s13, vcc_hi, 0
	s_add_i32 s19, s51, s37
	global_load_lds_dwordx4 v192, s[100:101]
	s_mov_b32 m0, s19
	s_nop 0
	global_load_lds_dwordx4 v182, s[12:13]
	s_add_i32 m0, s19, 0x2000
	s_nop 0
	global_load_lds_dwordx4 v192, s[12:13]
	s_mov_b32 m0, s45
	s_nop 0
	s_add_u32 s100, s40, 0x80
	s_addc_u32 s101, s41, 0
	global_load_lds_dwordx4 v188, s[100:101]
	s_mov_b32 m0, s24
	s_nop 0
	global_load_lds_dwordx4 v190, s[100:101]
	s_waitcnt vmcnt(8)
	s_waitcnt lgkmcnt(0)
	s_barrier
	s_setprio 2
	v_mfma_f32_16x16x32_bf16 v[30:33], v[66:69], v[162:165], v[30:33]
	v_mfma_f32_16x16x32_bf16 v[30:33], v[70:73], v[166:169], v[30:33]
	v_mfma_f32_16x16x32_bf16 v[26:29], v[66:69], v[170:173], v[26:29]
	v_mfma_f32_16x16x32_bf16 v[26:29], v[70:73], v[174:177], v[26:29]
	v_mfma_f32_16x16x32_bf16 v[62:65], v[66:69], v[178:181], v[62:65]
	v_mfma_f32_16x16x32_bf16 v[62:65], v[70:73], v[184:187], v[62:65]
	v_mfma_f32_16x16x32_bf16 v[58:61], v[66:69], v[220:223], v[58:61]
	v_mfma_f32_16x16x32_bf16 v[58:61], v[70:73], v[224:227], v[58:61]
	v_mfma_f32_16x16x32_bf16 v[50:53], v[82:85], v[220:223], v[50:53]
	v_mfma_f32_16x16x32_bf16 v[50:53], v[142:145], v[224:227], v[50:53]
	v_mfma_f32_16x16x32_bf16 v[54:57], v[82:85], v[178:181], v[54:57]
	v_mfma_f32_16x16x32_bf16 v[54:57], v[142:145], v[184:187], v[54:57]
	v_mfma_f32_16x16x32_bf16 v[18:21], v[82:85], v[170:173], v[18:21]
	v_mfma_f32_16x16x32_bf16 v[18:21], v[142:145], v[174:177], v[18:21]
	v_mfma_f32_16x16x32_bf16 v[22:25], v[82:85], v[162:165], v[22:25]
	v_mfma_f32_16x16x32_bf16 v[22:25], v[142:145], v[166:169], v[22:25]
	v_mfma_f32_16x16x32_bf16 v[14:17], v[146:149], v[162:165], v[14:17]
	v_mfma_f32_16x16x32_bf16 v[14:17], v[150:153], v[166:169], v[14:17]
	v_mfma_f32_16x16x32_bf16 v[10:13], v[146:149], v[170:173], v[10:13]
	v_mfma_f32_16x16x32_bf16 v[10:13], v[150:153], v[174:177], v[10:13]
	v_mfma_f32_16x16x32_bf16 v[46:49], v[146:149], v[178:181], v[46:49]
	v_mfma_f32_16x16x32_bf16 v[46:49], v[150:153], v[184:187], v[46:49]
	v_mfma_f32_16x16x32_bf16 v[38:41], v[146:149], v[220:223], v[38:41]
	v_mfma_f32_16x16x32_bf16 v[38:41], v[150:153], v[224:227], v[38:41]
	v_mfma_f32_16x16x32_bf16 v[42:45], v[154:157], v[220:223], v[42:45]
	v_mfma_f32_16x16x32_bf16 v[42:45], v[158:161], v[224:227], v[42:45]
	v_mfma_f32_16x16x32_bf16 v[34:37], v[154:157], v[178:181], v[34:37]
	v_mfma_f32_16x16x32_bf16 v[34:37], v[158:161], v[184:187], v[34:37]
	v_mfma_f32_16x16x32_bf16 v[2:5], v[154:157], v[170:173], v[2:5]
	v_mfma_f32_16x16x32_bf16 v[2:5], v[158:161], v[174:177], v[2:5]
	v_mfma_f32_16x16x32_bf16 v[6:9], v[154:157], v[162:165], v[6:9]
	v_mfma_f32_16x16x32_bf16 v[6:9], v[158:161], v[166:169], v[6:9]
	s_setprio 0
	s_add_i32 s0, s0, 2
	s_add_u32 s66, s66, 0x100
	s_addc_u32 s67, s67, 0
	s_cmp_gt_u32 s0, 29
	s_mov_b64 s[12:13], s[96:97]
	s_cbranch_scc0 .Lhob_f1_Thead
	s_branch .Lhob_f1_exit
.Lhob_f1_exit:
	s_and_b64 vcc, exec, s[78:79]
	s_cbranch_vccz .LBB0_1330
	s_setprio 0

;     __host__ __device__ bool next(int i, Unit& u) const { const long L = (long)i * G + c; if (L >= lim) return false; unit_of((int)L, u); return true; }
;     __device__ __forceinline__ bool next(int i, Unit& v) const { if (i != 0) return false; v = u; return true; }
;     __device__ __forceinline__ void stage(const Unit& u, int p, int wid, int lane) const { ra.stage<false>(u, p, wid, lane); }
;     __device__ __forceinline__ void stage(const Unit& u, int p, int wid, int lane) const { ra.stage<false>(u, p, wid, lane); }
; #define PG8_STAGE(bufoff, gbase, voff) do { _Pragma("unroll") for (int _i = 0; _i < 2; ++_i) \
;         __builtin_amdgcn_global_load_lds((const unsigned*)((const char*)(gbase) + (voff)[_i]), (PG8_LAS unsigned*)(lds + (bufoff) + ldsw + _i * 8192), 16, 0, 0); } while (0)
; #define PG8_BAR __builtin_amdgcn_s_barrier()
;     ...
;     for (int i = 0; i < 2; ++i) { int R, C; stage_rc(tid * 16 + i * 8192, R, C); const int Rb = Epi::PERM ? ((R & ~31) + perm32(R & 31)) : R;
;         const int Ra = Epi::PERMROW ? ((R & ~63) + 4 * (R & 15) + ((R >> 4) & 3)) : R;
;         voffA[i] = (unsigned)(Ra * K + C) * 2u; voffB[i] = (unsigned)(Rb * K + C) * 2u; }
;     const size_t kstep = (size_t)(BK * 2);
;     const size_t hstep = (size_t)HALF * K * 2;
;     const size_t tstep = 2 * hstep;
;     const unsigned ldsw = (unsigned)wid * 1024u;
;     const int aoff = lds_byte(wr * 64 + fr, fq * 8), boff = lds_byte(wc * 32 + fr, fq * 8);
;     ...
;     Unit cur, nxt; int ui = 0;
;     if (!S.next(0, cur)) return;
;     E.stage(cur, 0, wid, lane);
;     f32x4 acc[2][2][4][2];
; #pragma unroll
;     for (int a = 0; a < 2; ++a)
; #pragma unroll
;         for (int b = 0; b < 2; ++b)
; #pragma unroll
;             for (int m = 0; m < 4; ++m)
; #pragma unroll
;                 for (int n = 0; n < 2; ++n) acc[a][b][m][n] = (f32x4){0.f, 0.f, 0.f, 0.f};
;     bf16x8 At[4][2], B0[2][2], B1[2][2];
;     const char* cA = (const char*)g.A + (size_t)cur.pm * tstep; const char* cB = (const char*)g.Bt + (size_t)cur.pn * tstep;
;     S.a_ready(cur);
;     if constexpr (SP2) {
;         PG8_STAGE(PG8_SB(0, 0), cB, voffB); PG8_STAGE(PG8_SB(0, 1), cB + hstep, voffB); PG8_STAGE(PG8_SA(0, 0), cA, voffA); PG8_STAGE(PG8_SA(0, 1), cA + hstep, voffA);
;         if (wr == 1) PG8_BAR;
.LBB0_1632:
	v_ashrrev_i32_e32 v3, 31, v11
	v_lshrrev_b32_e32 v3, 26, v3
	v_add_u32_e32 v3, v11, v3
	v_ashrrev_i32_e32 v12, 6, v3
	v_bfe_i32 v3, v11, 27, 1
	v_lshlrev_b32_e32 v2, 4, v11
	v_lshrrev_b32_e32 v3, 22, v3
	v_add_u32_e32 v3, v2, v3
	v_and_b32_e32 v3, 0xfffffc00, v3
	v_sub_u32_e32 v3, v2, v3
	v_lshrrev_b32_e32 v4, 4, v3
	v_bitop3_b32 v4, v4, v3, 32 bitop3:0x6c
	v_ashrrev_i32_e32 v3, 31, v3
	v_lshrrev_b32_e32 v3, 26, v3
	v_lshlrev_b32_e32 v5, 3, v12
	v_add_u32_e32 v3, v4, v3
	s_add_u32 s86, s58, 0x48000000
	v_and_b32_e32 v5, -16, v5
	v_ashrrev_i32_e32 v14, 6, v3
	s_mul_i32 s7, s46, 0x1580000
	s_addc_u32 s87, s59, 0
	v_add_u32_e32 v3, v14, v5
	v_lshlrev_b32_e32 v5, 5, v12
	s_mul_hi_u32 s6, s46, 0x1580000
	s_add_u32 s7, s58, s7
	v_and_b32_e32 v13, 32, v5
	v_mul_i32_i24_e32 v5, 64, v14
	s_addc_u32 s6, s59, s6
	v_sub_u32_e32 v4, v4, v5
	s_add_u32 s88, s7, 0x12a00000
	v_ashrrev_i16_sdwa v4, v235, sext(v4) dst_sel:DWORD dst_unused:UNUSED_PAD src0_sel:DWORD src1_sel:BYTE_0
	v_lshlrev_b32_e32 v5, 1, v3
	v_lshrrev_b32_e32 v6, 2, v3
	v_and_b32_e32 v7, 3, v14
	s_mov_b32 s7, 0x1ffffe0
	s_addc_u32 s89, s6, 0
	v_bfe_i32 v15, v4, 0, 16
	v_and_b32_e32 v5, 24, v5
	v_and_b32_e32 v6, 4, v6
	v_and_or_b32 v7, v3, s7, v7
	s_movk_i32 s6, 0x1580
	v_add_u32_e32 v4, v13, v15
	v_or3_b32 v5, v7, v6, v5
	v_mul_lo_u32 v3, v3, s6
	v_add_lshl_u32 v178, v4, v3, 1
	v_mul_lo_u32 v3, v5, s6
	v_add_u32_e32 v2, 0x2000, v2
	v_add_lshl_u32 v182, v3, v4, 1
	v_ashrrev_i32_e32 v3, 31, v2
	v_lshrrev_b32_e32 v3, 22, v3
	v_add_u32_e32 v3, v2, v3
	v_ashrrev_i32_e32 v16, 10, v3
	v_mul_i32_i24_e32 v3, 0x400, v16
	v_sub_u32_e32 v2, v2, v3
	v_lshrrev_b32_e32 v3, 4, v2
	v_bitop3_b32 v2, v3, v2, 32 bitop3:0x6c
	v_ashrrev_i32_e32 v4, 31, v2
	v_lshrrev_b32_e32 v4, 26, v4
	v_lshlrev_b32_e32 v3, 3, v16
	v_add_u32_e32 v4, v2, v4
	v_and_b32_e32 v3, -16, v3
	s_waitcnt vmcnt(0)
	v_ashrrev_i32_e32 v18, 6, v4
	v_and_b32_e32 v4, 0xc0, v4
	v_add_u32_e32 v3, v18, v3
	v_lshlrev_b32_e32 v5, 5, v16
	v_sub_u32_e32 v2, v2, v4
	v_and_b32_e32 v17, 32, v5
	v_ashrrev_i16_sdwa v2, v235, sext(v2) dst_sel:DWORD dst_unused:UNUSED_PAD src0_sel:DWORD src1_sel:BYTE_0
	v_lshlrev_b32_e32 v4, 1, v3
	v_lshrrev_b32_e32 v5, 2, v3
	v_and_b32_e32 v6, 3, v18
	v_bfe_i32 v19, v2, 0, 16
	v_and_b32_e32 v4, 24, v4
	v_and_b32_e32 v5, 4, v5
	v_and_or_b32 v6, v3, s7, v6
	v_add_u32_e32 v2, v17, v19
	v_or3_b32 v4, v6, v5, v4
	v_mul_lo_u32 v3, v3, s6
	v_add_lshl_u32 v180, v2, v3, 1
	v_mul_lo_u32 v3, v4, s6
	s_ashr_i32 s6, s0, 8
	s_lshl_b32 s90, s85, 10
	s_mul_i32 s9, s18, 0x2b0000
	s_mul_hi_i32 s8, s18, 0x2b0000
	s_add_u32 s10, s88, s9
	s_addc_u32 s11, s89, s8
	s_add_i32 s91, s90, 0
	s_add_i32 m0, s91, 0x10000
	v_add_lshl_u32 v188, v3, v2, 1
	global_load_lds_dwordx4 v182, s[10:11]
	s_add_i32 m0, s91, 0x12000
	s_add_u32 s8, s10, 0x158000
	global_load_lds_dwordx4 v188, s[10:11]
	s_addc_u32 s9, s11, 0
	s_add_i32 m0, s91, 0x14000
	s_mul_i32 s26, s19, 0x2b0000
	global_load_lds_dwordx4 v182, s[8:9]
	s_add_i32 m0, s91, 0x16000
	s_mul_hi_i32 s7, s19, 0x2b0000
	global_load_lds_dwordx4 v188, s[8:9]
	s_add_u32 s8, s86, s26
	s_addc_u32 s9, s87, s7
	s_add_i32 s92, s91, 0x2000
	s_mov_b32 m0, s91
	s_add_u32 s40, s8, 0x158000
	global_load_lds_dwordx4 v178, s[8:9]
	s_mov_b32 m0, s92
	s_addc_u32 s41, s9, 0
	s_add_i32 s93, s91, 0x4000
	global_load_lds_dwordx4 v180, s[8:9]
	s_mov_b32 m0, s93
	s_add_i32 s94, s91, 0x6000
	global_load_lds_dwordx4 v178, s[40:41]
	s_mov_b32 m0, s94
	v_mov_b32_e32 v189, v183
	global_load_lds_dwordx4 v180, s[40:41]
	v_mov_b32_e32 v179, v183
	v_mov_b32_e32 v181, v183
	s_cmp_eq_u32 s6, 1
	s_mov_b32 s96, s37
	s_mov_b32 s51, s35
	v_lshl_add_u64 v[8:9], s[10:11], 0, v[182:183]
	v_lshl_add_u64 v[6:7], s[10:11], 0, v[188:189]
	v_lshl_add_u64 v[2:3], s[8:9], 0, v[178:179]
	s_cselect_b64 s[64:65], -1, 0
	s_cmp_lg_u32 s6, 1
	v_lshl_add_u64 v[4:5], s[8:9], 0, v[180:181]
	s_cbranch_scc1 .LBB0_1634
	s_setprio 0

; #define PG8_STAGE(bufoff, gbase, voff) do { _Pragma("unroll") for (int _i = 0; _i < 2; ++_i) \
;         __builtin_amdgcn_global_load_lds((const unsigned*)((const char*)(gbase) + (voff)[_i]), (PG8_LAS unsigned*)(lds + (bufoff) + ldsw + _i * 8192), 16, 0, 0); } while (0)
; #define PG8_LDA(dst, b, h) do { _Pragma("unroll") for (int m = 0; m < 4; ++m) _Pragma("unroll") for (int k = 0; k < 2; ++k) dst[m][k] = *(const PG8_LAS bf16x8*)(lds + PG8_SA(b, h) + aoff + m * 2048 + k * 1024); } while (0)
; #define PG8_LDB(dst, b, h) do { _Pragma("unroll") for (int n = 0; n < 2; ++n) _Pragma("unroll") for (int k = 0; k < 2; ++k) dst[n][k] = *(const PG8_LAS bf16x8*)(lds + PG8_SB(b, h) + boff + n * 2048 + k * 1024); } while (0)
; #define PG8_WAIT_L(n) asm volatile("s_waitcnt lgkmcnt(" #n ")" ::: "memory")
; #define PG8_WAIT_V_SEL(sel) asm volatile("s_cmp_eq_u32 %0, 0\n\ts_cbranch_scc1 .Lw8_%=\n\ts_waitcnt vmcnt(22)\n\ts_branch .Lwd_%=\n.Lw8_%=:\n\ts_waitcnt vmcnt(8)\n.Lwd_%=:" :: "s"(sel) : "memory", "scc")
; #define PG8_BAR __builtin_amdgcn_s_barrier()
; #define PG8_SCHED __builtin_amdgcn_sched_barrier(0)
;     ...
;             PG8_LDB(B0, 0, 0); PG8_LDB(B1, 0, 1); PG8_SCHED; PG8_LDA(At, 0, 0); PG8_STAGE(PG8_SA(1, 1), a1 + hstep, voffA);
;             PG8_WAIT_V_SEL(relax);
;             PG8_WAIT_L(0); PG8_BAR; PG8_MMA(0, 0, At, B0); PG8_MMA(0, 1, At, B1); PG8_BAR; PG8_SCHED;
;     ...
; #pragma unroll
;         for (int a = 0; a < 2; ++a)
; #pragma unroll
;             for (int b = 0; b < 2; ++b)
; #pragma unroll
;                 for (int m = 0; m < 4; ++m)
; #pragma unroll
;                     for (int n = 0; n < 2; ++n) acc[a][b][m][n] = (f32x4){0.f, 0.f, 0.f, 0.f};
;         cur = nxt; cA = nA; cB = nB; ++ui;
.LBB0_1647:
	s_add_u32 s37, s10, 0x100
	v_mov_b64_e32 v[2:3], 0
	v_mov_b64_e32 v[4:5], 0
	v_mov_b64_e32 v[6:7], 0
	v_mov_b64_e32 v[8:9], 0
	v_mov_b64_e32 v[10:11], 0
	v_mov_b64_e32 v[12:13], 0
	v_mov_b64_e32 v[14:15], 0
	v_mov_b64_e32 v[16:17], 0
	v_mov_b64_e32 v[18:19], 0
	v_mov_b64_e32 v[20:21], 0
	v_mov_b64_e32 v[22:23], 0
	v_mov_b64_e32 v[24:25], 0
	v_mov_b64_e32 v[26:27], 0
	v_mov_b64_e32 v[28:29], 0
	v_mov_b64_e32 v[30:31], 0
	v_mov_b64_e32 v[32:33], 0
	v_mov_b64_e32 v[34:35], 0
	v_mov_b64_e32 v[36:37], 0
	v_mov_b64_e32 v[38:39], 0
	v_mov_b64_e32 v[40:41], 0
	v_mov_b64_e32 v[42:43], 0
	v_mov_b64_e32 v[44:45], 0
	v_mov_b64_e32 v[46:47], 0
	v_mov_b64_e32 v[48:49], 0
	v_mov_b64_e32 v[50:51], 0
	v_mov_b64_e32 v[52:53], 0
	v_mov_b64_e32 v[54:55], 0
	v_mov_b64_e32 v[56:57], 0
	v_mov_b64_e32 v[66:67], 0
	v_mov_b64_e32 v[68:69], 0
	v_mov_b64_e32 v[70:71], 0
	v_mov_b64_e32 v[72:73], 0
	v_mov_b64_e32 v[82:83], 0
	v_mov_b64_e32 v[84:85], 0
	v_mov_b64_e32 v[86:87], 0
	v_mov_b64_e32 v[88:89], 0
	v_mov_b64_e32 v[90:91], 0
	v_mov_b64_e32 v[92:93], 0
	v_mov_b64_e32 v[94:95], 0
	v_mov_b64_e32 v[96:97], 0
	v_mov_b64_e32 v[98:99], 0
	v_mov_b64_e32 v[100:101], 0
	v_mov_b64_e32 v[102:103], 0
	v_mov_b64_e32 v[104:105], 0
	v_mov_b64_e32 v[106:107], 0
	v_mov_b64_e32 v[108:109], 0
	v_mov_b64_e32 v[110:111], 0
	v_mov_b64_e32 v[112:113], 0
	v_mov_b64_e32 v[114:115], 0
	v_mov_b64_e32 v[116:117], 0
	v_mov_b64_e32 v[118:119], 0
	v_mov_b64_e32 v[120:121], 0
	v_mov_b64_e32 v[122:123], 0
	v_mov_b64_e32 v[124:125], 0
	v_mov_b64_e32 v[126:127], 0
	v_mov_b64_e32 v[128:129], 0
	v_mov_b64_e32 v[134:135], 0
	v_mov_b64_e32 v[136:137], 0
	v_mov_b64_e32 v[138:139], 0
	v_mov_b64_e32 v[140:141], 0
	v_mov_b64_e32 v[146:147], 0
	v_mov_b64_e32 v[148:149], 0
	v_mov_b64_e32 v[150:151], 0
	v_mov_b64_e32 v[152:153], 0
	s_addc_u32 s44, s11, 0
	s_mov_b32 s45, -2
	s_waitcnt lgkmcnt(0)
	v_add_u32_e32 v206, 0x10000, v243
	s_cmp_lg_u32 s76, 0
	s_cbranch_scc0 .Lhob_f2_Thead
.LBB0_1648:
	s_add_u32 s10, s8, 0x100
	s_addc_u32 s11, s9, 0
	s_add_i32 s46, 0, 0x10000
	s_cmpk_eq_i32 s45, 0x52
	s_cselect_b32 s41, s1, s11
	s_cselect_b32 s40, s0, s10
	s_cselect_b32 s81, s79, s44
	s_cselect_b32 s80, s78, s37
	s_add_i32 s47, 0, 0x14000
	ds_read_b128 v[58:61], v206
	ds_read_b128 v[62:65], v206 offset:1024
	ds_read_b128 v[74:77], v206 offset:2048
	ds_read_b128 v[78:81], v206 offset:3072
	ds_read_b128 v[130:133], v206 offset:16384
	ds_read_b128 v[142:145], v206 offset:17408
	ds_read_b128 v[154:157], v206 offset:18432
	ds_read_b128 v[158:161], v206 offset:19456
	s_add_i32 m0, s91, 0xc000
	ds_read_b128 v[162:165], v246
	ds_read_b128 v[166:169], v246 offset:1024
	ds_read_b128 v[170:173], v246 offset:2048
	ds_read_b128 v[174:177], v246 offset:3072
	ds_read_b128 v[184:187], v246 offset:4096
	ds_read_b128 v[194:197], v246 offset:5120
	ds_read_b128 v[198:201], v246 offset:6144
	ds_read_b128 v[202:205], v246 offset:7168
	global_load_lds_dwordx4 v190, s[8:9]
	s_add_i32 m0, s91, 0xe000
	s_nop 0
	global_load_lds_dwordx4 v192, s[8:9]
	s_waitcnt vmcnt(8)
	s_waitcnt lgkmcnt(0)
	s_setprio 1
	v_mfma_f32_16x16x32_bf16 v[150:153], v[58:61], v[162:165], v[150:153]
	v_mfma_f32_16x16x32_bf16 v[150:153], v[62:65], v[166:169], v[150:153]
	v_mfma_f32_16x16x32_bf16 v[126:129], v[58:61], v[170:173], v[126:129]
	v_mfma_f32_16x16x32_bf16 v[126:129], v[62:65], v[174:177], v[126:129]
	v_mfma_f32_16x16x32_bf16 v[110:113], v[58:61], v[184:187], v[110:113]
	v_mfma_f32_16x16x32_bf16 v[110:113], v[62:65], v[194:197], v[110:113]
	v_mfma_f32_16x16x32_bf16 v[94:97], v[58:61], v[198:201], v[94:97]
	v_mfma_f32_16x16x32_bf16 v[94:97], v[62:65], v[202:205], v[94:97]
	v_mfma_f32_16x16x32_bf16 v[90:93], v[74:77], v[198:201], v[90:93]
	v_mfma_f32_16x16x32_bf16 v[90:93], v[78:81], v[202:205], v[90:93]
	v_mfma_f32_16x16x32_bf16 v[106:109], v[74:77], v[184:187], v[106:109]
	v_mfma_f32_16x16x32_bf16 v[106:109], v[78:81], v[194:197], v[106:109]
	v_mfma_f32_16x16x32_bf16 v[122:125], v[74:77], v[170:173], v[122:125]
	v_mfma_f32_16x16x32_bf16 v[122:125], v[78:81], v[174:177], v[122:125]
	v_mfma_f32_16x16x32_bf16 v[146:149], v[74:77], v[162:165], v[146:149]
	v_mfma_f32_16x16x32_bf16 v[146:149], v[78:81], v[166:169], v[146:149]
	v_mfma_f32_16x16x32_bf16 v[138:141], v[130:133], v[162:165], v[138:141]
	v_mfma_f32_16x16x32_bf16 v[138:141], v[142:145], v[166:169], v[138:141]
	v_mfma_f32_16x16x32_bf16 v[118:121], v[130:133], v[170:173], v[118:121]
	v_mfma_f32_16x16x32_bf16 v[118:121], v[142:145], v[174:177], v[118:121]
	v_mfma_f32_16x16x32_bf16 v[102:105], v[130:133], v[184:187], v[102:105]
	v_mfma_f32_16x16x32_bf16 v[102:105], v[142:145], v[194:197], v[102:105]
	v_mfma_f32_16x16x32_bf16 v[86:89], v[130:133], v[198:201], v[86:89]
	v_mfma_f32_16x16x32_bf16 v[86:89], v[142:145], v[202:205], v[86:89]
	v_mfma_f32_16x16x32_bf16 v[82:85], v[154:157], v[198:201], v[82:85]
	v_mfma_f32_16x16x32_bf16 v[82:85], v[158:161], v[202:205], v[82:85]
	v_mfma_f32_16x16x32_bf16 v[98:101], v[154:157], v[184:187], v[98:101]
	v_mfma_f32_16x16x32_bf16 v[98:101], v[158:161], v[194:197], v[98:101]
	v_mfma_f32_16x16x32_bf16 v[114:117], v[154:157], v[170:173], v[114:117]
	v_mfma_f32_16x16x32_bf16 v[114:117], v[158:161], v[174:177], v[114:117]
	v_mfma_f32_16x16x32_bf16 v[134:137], v[154:157], v[162:165], v[134:137]
	v_mfma_f32_16x16x32_bf16 v[134:137], v[158:161], v[166:169], v[134:137]
	s_setprio 0
	s_barrier
; #define PG8_STAGE(bufoff, gbase, voff) do { _Pragma("unroll") for (int _i = 0; _i < 2; ++_i) \
;         __builtin_amdgcn_global_load_lds((const unsigned*)((const char*)(gbase) + (voff)[_i]), (PG8_LAS unsigned*)(lds + (bufoff) + ldsw + _i * 8192), 16, 0, 0); } while (0)
; #define PG8_LDA(dst, b, h) do { _Pragma("unroll") for (int m = 0; m < 4; ++m) _Pragma("unroll") for (int k = 0; k < 2; ++k) dst[m][k] = *(const PG8_LAS bf16x8*)(lds + PG8_SA(b, h) + aoff + m * 2048 + k * 1024); } while (0)
; #define PG8_LDB(dst, b, h) do { _Pragma("unroll") for (int n = 0; n < 2; ++n) _Pragma("unroll") for (int k = 0; k < 2; ++k) dst[n][k] = *(const PG8_LAS bf16x8*)(lds + PG8_SB(b, h) + boff + n * 2048 + k * 1024); } while (0)
; #define PG8_WAIT_V(n) asm volatile("s_waitcnt vmcnt(" #n ")" ::: "memory")
; #define PG8_WAIT_L(n) asm volatile("s_waitcnt lgkmcnt(" #n ")" ::: "memory")
; #define PG8_WAIT_V_SEL(sel) asm volatile("s_cmp_eq_u32 %0, 0\n\ts_cbranch_scc1 .Lw8_%=\n\ts_waitcnt vmcnt(22)\n\ts_branch .Lwd_%=\n.Lw8_%=:\n\ts_waitcnt vmcnt(8)\n.Lwd_%=:" :: "s"(sel) : "memory", "scc")
; #define PG8_BAR __builtin_amdgcn_s_barrier()
; #define PG8_SCHED __builtin_amdgcn_sched_barrier(0)
;     ...
;             PG8_WAIT_L(0); PG8_BAR; PG8_MMA(0, 0, At, B0); PG8_MMA(0, 1, At, B1); PG8_BAR; PG8_SCHED;
;             PG8_LDA(At, 0, 1); PG8_STAGE(PG8_SB(0, 0), b2, voffB); PG8_STAGE(PG8_SB(0, 1), b2 + hstep, voffB); PG8_STAGE(PG8_SA(0, 0), a2, voffA);
;             PG8_WAIT_V_SEL(relax);
;             PG8_WAIT_L(0); PG8_BAR; PG8_MMA(1, 0, At, B0); PG8_MMA(1, 1, At, B1); PG8_BAR; PG8_SCHED;
;             PG8_LDB(B0, 1, 0); PG8_LDB(B1, 1, 1); PG8_SCHED; PG8_LDA(At, 1, 0); PG8_STAGE(PG8_SA(0, 1), a2 + hstep, voffA);
;             PG8_WAIT_V(8); PG8_WAIT_L(0); PG8_BAR; PG8_MMA(0, 0, At, B0); PG8_MMA(0, 1, At, B1); PG8_BAR; PG8_SCHED;
;             PG8_LDA(At, 1, 1); PG8_STAGE(PG8_SB(1, 0), b3, voffB); PG8_STAGE(PG8_SB(1, 1), b3 + hstep, voffB); PG8_STAGE(PG8_SA(1, 0), a3, voffA);
	s_add_i32 s8, s46, s90
	s_mov_b32 m0, s8
	ds_read_b128 v[162:165], v246 offset:16384
	ds_read_b128 v[166:169], v246 offset:17408
	ds_read_b128 v[170:173], v246 offset:18432
	ds_read_b128 v[174:177], v246 offset:19456
	ds_read_b128 v[184:187], v246 offset:20480
	ds_read_b128 v[194:197], v246 offset:21504
	ds_read_b128 v[198:201], v246 offset:22528
	ds_read_b128 v[202:205], v246 offset:23552
	global_load_lds_dwordx4 v182, s[80:81]
	s_add_i32 m0, s8, 0x2000
	s_add_u32 s8, s80, 0x158000
	s_addc_u32 s9, s81, 0
	s_add_i32 s46, s47, s90
	global_load_lds_dwordx4 v188, s[80:81]
	s_mov_b32 m0, s46
	s_nop 0
	global_load_lds_dwordx4 v182, s[8:9]
	s_add_i32 m0, s46, 0x2000
	s_nop 0
	global_load_lds_dwordx4 v188, s[8:9]
	s_mov_b32 m0, s91
	s_nop 0
	global_load_lds_dwordx4 v178, s[40:41]
	s_mov_b32 m0, s92
	s_nop 0
	global_load_lds_dwordx4 v180, s[40:41]
	s_waitcnt vmcnt(8)
	s_waitcnt lgkmcnt(0)
	s_setprio 1
	v_mfma_f32_16x16x32_bf16 v[70:73], v[58:61], v[162:165], v[70:73]
	v_mfma_f32_16x16x32_bf16 v[70:73], v[62:65], v[166:169], v[70:73]
	v_mfma_f32_16x16x32_bf16 v[46:49], v[58:61], v[170:173], v[46:49]
	v_mfma_f32_16x16x32_bf16 v[46:49], v[62:65], v[174:177], v[46:49]
	v_mfma_f32_16x16x32_bf16 v[30:33], v[58:61], v[184:187], v[30:33]
	v_mfma_f32_16x16x32_bf16 v[30:33], v[62:65], v[194:197], v[30:33]
	v_mfma_f32_16x16x32_bf16 v[14:17], v[58:61], v[198:201], v[14:17]
	v_mfma_f32_16x16x32_bf16 v[14:17], v[62:65], v[202:205], v[14:17]
	v_mfma_f32_16x16x32_bf16 v[10:13], v[74:77], v[198:201], v[10:13]
	v_mfma_f32_16x16x32_bf16 v[10:13], v[78:81], v[202:205], v[10:13]
	v_mfma_f32_16x16x32_bf16 v[26:29], v[74:77], v[184:187], v[26:29]
	v_mfma_f32_16x16x32_bf16 v[26:29], v[78:81], v[194:197], v[26:29]
	v_mfma_f32_16x16x32_bf16 v[42:45], v[74:77], v[170:173], v[42:45]
	v_mfma_f32_16x16x32_bf16 v[42:45], v[78:81], v[174:177], v[42:45]
	v_mfma_f32_16x16x32_bf16 v[66:69], v[74:77], v[162:165], v[66:69]
	v_mfma_f32_16x16x32_bf16 v[66:69], v[78:81], v[166:169], v[66:69]
	v_mfma_f32_16x16x32_bf16 v[54:57], v[130:133], v[162:165], v[54:57]
	v_mfma_f32_16x16x32_bf16 v[54:57], v[142:145], v[166:169], v[54:57]
	v_mfma_f32_16x16x32_bf16 v[38:41], v[130:133], v[170:173], v[38:41]
	v_mfma_f32_16x16x32_bf16 v[38:41], v[142:145], v[174:177], v[38:41]
	v_mfma_f32_16x16x32_bf16 v[22:25], v[130:133], v[184:187], v[22:25]
	v_mfma_f32_16x16x32_bf16 v[22:25], v[142:145], v[194:197], v[22:25]
	v_mfma_f32_16x16x32_bf16 v[6:9], v[130:133], v[198:201], v[6:9]
	v_mfma_f32_16x16x32_bf16 v[6:9], v[142:145], v[202:205], v[6:9]
	v_mfma_f32_16x16x32_bf16 v[2:5], v[154:157], v[198:201], v[2:5]
	v_mfma_f32_16x16x32_bf16 v[2:5], v[158:161], v[202:205], v[2:5]
	v_mfma_f32_16x16x32_bf16 v[18:21], v[154:157], v[184:187], v[18:21]
	v_mfma_f32_16x16x32_bf16 v[18:21], v[158:161], v[194:197], v[18:21]
	v_mfma_f32_16x16x32_bf16 v[34:37], v[154:157], v[170:173], v[34:37]
	v_mfma_f32_16x16x32_bf16 v[34:37], v[158:161], v[174:177], v[34:37]
	v_mfma_f32_16x16x32_bf16 v[50:53], v[154:157], v[162:165], v[50:53]
	v_mfma_f32_16x16x32_bf16 v[50:53], v[158:161], v[166:169], v[50:53]
	s_setprio 0
	s_barrier
	s_add_i32 s46, 0, 0x18000
	s_add_i32 s47, 0, 0x1c000
	ds_read_b128 v[58:61], v206 offset:32768
	ds_read_b128 v[62:65], v206 offset:33792
	ds_read_b128 v[74:77], v206 offset:34816
	ds_read_b128 v[78:81], v206 offset:35840
	ds_read_b128 v[130:133], v206 offset:49152
	ds_read_b128 v[142:145], v206 offset:50176
	ds_read_b128 v[154:157], v206 offset:51200
	ds_read_b128 v[158:161], v206 offset:52224
	s_add_u32 s8, s40, 0x158000
	s_addc_u32 s9, s41, 0
	s_mov_b32 m0, s93
	ds_read_b128 v[162:165], v246 offset:32768
	ds_read_b128 v[166:169], v246 offset:33792
	ds_read_b128 v[170:173], v246 offset:34816
	ds_read_b128 v[174:177], v246 offset:35840
	ds_read_b128 v[184:187], v246 offset:36864
	ds_read_b128 v[194:197], v246 offset:37888
	ds_read_b128 v[198:201], v246 offset:38912
	ds_read_b128 v[202:205], v246 offset:39936
	global_load_lds_dwordx4 v178, s[8:9]
	s_mov_b32 m0, s94
	s_nop 0
	global_load_lds_dwordx4 v180, s[8:9]
	s_waitcnt vmcnt(8)
	s_waitcnt lgkmcnt(0)
	s_setprio 1
	v_mfma_f32_16x16x32_bf16 v[150:153], v[58:61], v[162:165], v[150:153]
	v_mfma_f32_16x16x32_bf16 v[150:153], v[62:65], v[166:169], v[150:153]
	v_mfma_f32_16x16x32_bf16 v[126:129], v[58:61], v[170:173], v[126:129]
	v_mfma_f32_16x16x32_bf16 v[126:129], v[62:65], v[174:177], v[126:129]
	v_mfma_f32_16x16x32_bf16 v[110:113], v[58:61], v[184:187], v[110:113]
	v_mfma_f32_16x16x32_bf16 v[110:113], v[62:65], v[194:197], v[110:113]
	v_mfma_f32_16x16x32_bf16 v[94:97], v[58:61], v[198:201], v[94:97]
	v_mfma_f32_16x16x32_bf16 v[94:97], v[62:65], v[202:205], v[94:97]
	v_mfma_f32_16x16x32_bf16 v[90:93], v[74:77], v[198:201], v[90:93]
	v_mfma_f32_16x16x32_bf16 v[90:93], v[78:81], v[202:205], v[90:93]
	v_mfma_f32_16x16x32_bf16 v[106:109], v[74:77], v[184:187], v[106:109]
	v_mfma_f32_16x16x32_bf16 v[106:109], v[78:81], v[194:197], v[106:109]
	v_mfma_f32_16x16x32_bf16 v[122:125], v[74:77], v[170:173], v[122:125]
	v_mfma_f32_16x16x32_bf16 v[122:125], v[78:81], v[174:177], v[122:125]
	v_mfma_f32_16x16x32_bf16 v[146:149], v[74:77], v[162:165], v[146:149]
	v_mfma_f32_16x16x32_bf16 v[146:149], v[78:81], v[166:169], v[146:149]
	v_mfma_f32_16x16x32_bf16 v[138:141], v[130:133], v[162:165], v[138:141]
	v_mfma_f32_16x16x32_bf16 v[138:141], v[142:145], v[166:169], v[138:141]
	v_mfma_f32_16x16x32_bf16 v[118:121], v[130:133], v[170:173], v[118:121]
	v_mfma_f32_16x16x32_bf16 v[118:121], v[142:145], v[174:177], v[118:121]
	v_mfma_f32_16x16x32_bf16 v[102:105], v[130:133], v[184:187], v[102:105]
	v_mfma_f32_16x16x32_bf16 v[102:105], v[142:145], v[194:197], v[102:105]
	v_mfma_f32_16x16x32_bf16 v[86:89], v[130:133], v[198:201], v[86:89]
	v_mfma_f32_16x16x32_bf16 v[86:89], v[142:145], v[202:205], v[86:89]
	v_mfma_f32_16x16x32_bf16 v[82:85], v[154:157], v[198:201], v[82:85]
	v_mfma_f32_16x16x32_bf16 v[82:85], v[158:161], v[202:205], v[82:85]
	v_mfma_f32_16x16x32_bf16 v[98:101], v[154:157], v[184:187], v[98:101]
	v_mfma_f32_16x16x32_bf16 v[98:101], v[158:161], v[194:197], v[98:101]
	v_mfma_f32_16x16x32_bf16 v[114:117], v[154:157], v[170:173], v[114:117]
	v_mfma_f32_16x16x32_bf16 v[114:117], v[158:161], v[174:177], v[114:117]
	v_mfma_f32_16x16x32_bf16 v[134:137], v[154:157], v[162:165], v[134:137]
	v_mfma_f32_16x16x32_bf16 v[134:137], v[158:161], v[166:169], v[134:137]
	s_setprio 0
	s_barrier
; #define PG8_STAGE(bufoff, gbase, voff) do { _Pragma("unroll") for (int _i = 0; _i < 2; ++_i) \
;         __builtin_amdgcn_global_load_lds((const unsigned*)((const char*)(gbase) + (voff)[_i]), (PG8_LAS unsigned*)(lds + (bufoff) + ldsw + _i * 8192), 16, 0, 0); } while (0)
; #define PG8_LDA(dst, b, h) do { _Pragma("unroll") for (int m = 0; m < 4; ++m) _Pragma("unroll") for (int k = 0; k < 2; ++k) dst[m][k] = *(const PG8_LAS bf16x8*)(lds + PG8_SA(b, h) + aoff + m * 2048 + k * 1024); } while (0)
; #define PG8_LDB(dst, b, h) do { _Pragma("unroll") for (int n = 0; n < 2; ++n) _Pragma("unroll") for (int k = 0; k < 2; ++k) dst[n][k] = *(const PG8_LAS bf16x8*)(lds + PG8_SB(b, h) + boff + n * 2048 + k * 1024); } while (0)
; #define PG8_WAIT_V(n) asm volatile("s_waitcnt vmcnt(" #n ")" ::: "memory")
; #define PG8_WAIT_L(n) asm volatile("s_waitcnt lgkmcnt(" #n ")" ::: "memory")
; #define PG8_BAR __builtin_amdgcn_s_barrier()
;     ...
;         for (int t = 0; t < nt * KREP; t += 2) {
;             const bool last = (t == nt * KREP - 2);
;             const int t1w = KREP > 1 ? ((t + 1) & (nt - 1)) : t + 1, t2w = KREP > 1 ? ((t + 2) & (nt - 1)) : t + 2;
;             const char* a1 = cA + (size_t)t1w * kstep;
;             const char* a2 = last ? nA : cA + (size_t)t2w * kstep; const char* b2 = last ? nB : cB + (size_t)t2w * kstep;
;             const char* a3 = a2 + kstep; const char* b3 = b2 + kstep;
;             if (last && has_next) S.a_ready(nxt);
;             const int relax = __builtin_amdgcn_readfirstlane((MK_RELAXW && t == 0 && ui > 0) ? 1 : 0);
;             if constexpr (SP2) {
;             PG8_LDB(B0, 0, 0); PG8_LDB(B1, 0, 1); PG8_SCHED; PG8_LDA(At, 0, 0); PG8_STAGE(PG8_SA(1, 1), a1 + hstep, voffA);
;             PG8_WAIT_V_SEL(relax);
;             PG8_WAIT_L(0); PG8_BAR; PG8_MMA(0, 0, At, B0); PG8_MMA(0, 1, At, B1); PG8_BAR; PG8_SCHED;
;     ...
;             PG8_LDB(B0, 1, 0); PG8_LDB(B1, 1, 1); PG8_SCHED; PG8_LDA(At, 1, 0); PG8_STAGE(PG8_SA(0, 1), a2 + hstep, voffA);
;             PG8_WAIT_V(8); PG8_WAIT_L(0); PG8_BAR; PG8_MMA(0, 0, At, B0); PG8_MMA(0, 1, At, B1); PG8_BAR; PG8_SCHED;
;             PG8_LDA(At, 1, 1); PG8_STAGE(PG8_SB(1, 0), b3, voffB); PG8_STAGE(PG8_SB(1, 1), b3 + hstep, voffB); PG8_STAGE(PG8_SA(1, 0), a3, voffA);
;             PG8_WAIT_V(8); PG8_WAIT_L(0); PG8_BAR; PG8_MMA(1, 0, At, B0); PG8_MMA(1, 1, At, B1); PG8_BAR; PG8_SCHED;
	s_add_i32 s8, s46, s90
	s_mov_b32 m0, s8
	ds_read_b128 v[162:165], v246 offset:49152
	ds_read_b128 v[166:169], v246 offset:50176
	ds_read_b128 v[170:173], v246 offset:51200
	ds_read_b128 v[174:177], v246 offset:52224
	ds_read_b128 v[184:187], v246 offset:53248
	ds_read_b128 v[194:197], v246 offset:54272
	ds_read_b128 v[198:201], v246 offset:55296
	ds_read_b128 v[202:205], v246 offset:56320
	s_add_u32 s100, s80, 0x80
	s_addc_u32 s101, s81, 0
	global_load_lds_dwordx4 v182, s[100:101]
	s_add_i32 m0, s8, 0x2000
	s_add_u32 s8, s80, 0x158080
	s_addc_u32 s9, s81, 0
	s_add_i32 vcc_lo, s47, s90
	global_load_lds_dwordx4 v188, s[100:101]
	s_mov_b32 m0, vcc_lo
	s_nop 0
	global_load_lds_dwordx4 v182, s[8:9]
	s_add_i32 m0, vcc_lo, 0x2000
	s_nop 0
	global_load_lds_dwordx4 v188, s[8:9]
	s_mov_b32 m0, s31
	s_nop 0
	s_add_u32 s100, s40, 0x80
	s_addc_u32 s101, s41, 0
	global_load_lds_dwordx4 v178, s[100:101]
	s_mov_b32 m0, s56
	s_nop 0
	global_load_lds_dwordx4 v180, s[100:101]
	s_waitcnt vmcnt(8)
	s_waitcnt lgkmcnt(0)
	s_setprio 1
	v_mfma_f32_16x16x32_bf16 v[70:73], v[58:61], v[162:165], v[70:73]
	v_mfma_f32_16x16x32_bf16 v[70:73], v[62:65], v[166:169], v[70:73]
	v_mfma_f32_16x16x32_bf16 v[46:49], v[58:61], v[170:173], v[46:49]
	v_mfma_f32_16x16x32_bf16 v[46:49], v[62:65], v[174:177], v[46:49]
	v_mfma_f32_16x16x32_bf16 v[30:33], v[58:61], v[184:187], v[30:33]
	v_mfma_f32_16x16x32_bf16 v[30:33], v[62:65], v[194:197], v[30:33]
	v_mfma_f32_16x16x32_bf16 v[14:17], v[58:61], v[198:201], v[14:17]
	v_mfma_f32_16x16x32_bf16 v[14:17], v[62:65], v[202:205], v[14:17]
	v_mfma_f32_16x16x32_bf16 v[10:13], v[74:77], v[198:201], v[10:13]
	v_mfma_f32_16x16x32_bf16 v[10:13], v[78:81], v[202:205], v[10:13]
	v_mfma_f32_16x16x32_bf16 v[26:29], v[74:77], v[184:187], v[26:29]
	v_mfma_f32_16x16x32_bf16 v[26:29], v[78:81], v[194:197], v[26:29]
	v_mfma_f32_16x16x32_bf16 v[42:45], v[74:77], v[170:173], v[42:45]
	v_mfma_f32_16x16x32_bf16 v[42:45], v[78:81], v[174:177], v[42:45]
	v_mfma_f32_16x16x32_bf16 v[66:69], v[74:77], v[162:165], v[66:69]
	v_mfma_f32_16x16x32_bf16 v[66:69], v[78:81], v[166:169], v[66:69]
	v_mfma_f32_16x16x32_bf16 v[54:57], v[130:133], v[162:165], v[54:57]
	v_mfma_f32_16x16x32_bf16 v[54:57], v[142:145], v[166:169], v[54:57]
	v_mfma_f32_16x16x32_bf16 v[38:41], v[130:133], v[170:173], v[38:41]
	v_mfma_f32_16x16x32_bf16 v[38:41], v[142:145], v[174:177], v[38:41]
	v_mfma_f32_16x16x32_bf16 v[22:25], v[130:133], v[184:187], v[22:25]
	v_mfma_f32_16x16x32_bf16 v[22:25], v[142:145], v[194:197], v[22:25]
	v_mfma_f32_16x16x32_bf16 v[6:9], v[130:133], v[198:201], v[6:9]
	v_mfma_f32_16x16x32_bf16 v[6:9], v[142:145], v[202:205], v[6:9]
	v_mfma_f32_16x16x32_bf16 v[2:5], v[154:157], v[198:201], v[2:5]
	v_mfma_f32_16x16x32_bf16 v[2:5], v[158:161], v[202:205], v[2:5]
	v_mfma_f32_16x16x32_bf16 v[18:21], v[154:157], v[184:187], v[18:21]
	v_mfma_f32_16x16x32_bf16 v[18:21], v[158:161], v[194:197], v[18:21]
	v_mfma_f32_16x16x32_bf16 v[34:37], v[154:157], v[170:173], v[34:37]
	v_mfma_f32_16x16x32_bf16 v[34:37], v[158:161], v[174:177], v[34:37]
	v_mfma_f32_16x16x32_bf16 v[50:53], v[154:157], v[162:165], v[50:53]
	v_mfma_f32_16x16x32_bf16 v[50:53], v[158:161], v[166:169], v[50:53]
	s_setprio 0
	s_barrier
	s_add_i32 s45, s45, 2
	s_add_u32 s37, s37, 0x100
	s_addc_u32 s44, s44, 0
	s_cmpk_gt_u32 s45, 0x53
	s_mov_b64 s[8:9], s[10:11]
	s_cbranch_scc0 .LBB0_1648
	s_branch .Lhob_f2_exit
.Lhob_f2_Thead:
	s_add_u32 s10, s8, 0x100
	s_addc_u32 s11, s9, 0
	s_add_i32 s46, 0, 0x10000
	s_cmpk_eq_i32 s45, 0x52
	s_cselect_b32 s41, s1, s11
	s_cselect_b32 s40, s0, s10
	s_cselect_b32 s81, s79, s44
	s_cselect_b32 s80, s78, s37
	s_add_i32 s47, 0, 0x14000
	ds_read_b128 v[58:61], v206
	ds_read_b128 v[62:65], v206 offset:1024
	ds_read_b128 v[74:77], v206 offset:2048
	ds_read_b128 v[78:81], v206 offset:3072
	ds_read_b128 v[130:133], v206 offset:16384
	ds_read_b128 v[142:145], v206 offset:17408
	ds_read_b128 v[154:157], v206 offset:18432
	ds_read_b128 v[158:161], v206 offset:19456
	s_add_i32 m0, s91, 0xc000
	ds_read_b128 v[162:165], v246
	ds_read_b128 v[166:169], v246 offset:1024
	ds_read_b128 v[170:173], v246 offset:2048
	ds_read_b128 v[174:177], v246 offset:3072
	ds_read_b128 v[184:187], v246 offset:4096
	ds_read_b128 v[194:197], v246 offset:5120
	ds_read_b128 v[198:201], v246 offset:6144
	ds_read_b128 v[202:205], v246 offset:7168
	global_load_lds_dwordx4 v190, s[8:9]
	s_add_i32 m0, s91, 0xe000
	s_nop 0
	global_load_lds_dwordx4 v192, s[8:9]
	s_waitcnt vmcnt(8)
	s_waitcnt lgkmcnt(0)
	s_barrier
; #define PG8_STAGE(bufoff, gbase, voff) do { _Pragma("unroll") for (int _i = 0; _i < 2; ++_i) \
;         __builtin_amdgcn_global_load_lds((const unsigned*)((const char*)(gbase) + (voff)[_i]), (PG8_LAS unsigned*)(lds + (bufoff) + ldsw + _i * 8192), 16, 0, 0); } while (0)
; #define PG8_LDA(dst, b, h) do { _Pragma("unroll") for (int m = 0; m < 4; ++m) _Pragma("unroll") for (int k = 0; k < 2; ++k) dst[m][k] = *(const PG8_LAS bf16x8*)(lds + PG8_SA(b, h) + aoff + m * 2048 + k * 1024); } while (0)
; #define PG8_LDB(dst, b, h) do { _Pragma("unroll") for (int n = 0; n < 2; ++n) _Pragma("unroll") for (int k = 0; k < 2; ++k) dst[n][k] = *(const PG8_LAS bf16x8*)(lds + PG8_SB(b, h) + boff + n * 2048 + k * 1024); } while (0)
; #define PG8_WAIT_V(n) asm volatile("s_waitcnt vmcnt(" #n ")" ::: "memory")
; #define PG8_WAIT_L(n) asm volatile("s_waitcnt lgkmcnt(" #n ")" ::: "memory")
; #define PG8_WAIT_V_SEL(sel) asm volatile("s_cmp_eq_u32 %0, 0\n\ts_cbranch_scc1 .Lw8_%=\n\ts_waitcnt vmcnt(22)\n\ts_branch .Lwd_%=\n.Lw8_%=:\n\ts_waitcnt vmcnt(8)\n.Lwd_%=:" :: "s"(sel) : "memory", "scc")
; #define PG8_BAR __builtin_amdgcn_s_barrier()
; #define PG8_SCHED __builtin_amdgcn_sched_barrier(0)
;     ...
;             PG8_WAIT_L(0); PG8_BAR; PG8_MMA(0, 0, At, B0); PG8_MMA(0, 1, At, B1); PG8_BAR; PG8_SCHED;
;             PG8_LDA(At, 0, 1); PG8_STAGE(PG8_SB(0, 0), b2, voffB); PG8_STAGE(PG8_SB(0, 1), b2 + hstep, voffB); PG8_STAGE(PG8_SA(0, 0), a2, voffA);
;             PG8_WAIT_V_SEL(relax);
;             PG8_WAIT_L(0); PG8_BAR; PG8_MMA(1, 0, At, B0); PG8_MMA(1, 1, At, B1); PG8_BAR; PG8_SCHED;
;             PG8_LDB(B0, 1, 0); PG8_LDB(B1, 1, 1); PG8_SCHED; PG8_LDA(At, 1, 0); PG8_STAGE(PG8_SA(0, 1), a2 + hstep, voffA);
;             PG8_WAIT_V(8); PG8_WAIT_L(0); PG8_BAR; PG8_MMA(0, 0, At, B0); PG8_MMA(0, 1, At, B1); PG8_BAR; PG8_SCHED;
;             PG8_LDA(At, 1, 1); PG8_STAGE(PG8_SB(1, 0), b3, voffB); PG8_STAGE(PG8_SB(1, 1), b3 + hstep, voffB); PG8_STAGE(PG8_SA(1, 0), a3, voffA);
	s_setprio 2
	v_mfma_f32_16x16x32_bf16 v[150:153], v[58:61], v[162:165], v[150:153]
	v_mfma_f32_16x16x32_bf16 v[150:153], v[62:65], v[166:169], v[150:153]
	v_mfma_f32_16x16x32_bf16 v[126:129], v[58:61], v[170:173], v[126:129]
	v_mfma_f32_16x16x32_bf16 v[126:129], v[62:65], v[174:177], v[126:129]
	v_mfma_f32_16x16x32_bf16 v[110:113], v[58:61], v[184:187], v[110:113]
	v_mfma_f32_16x16x32_bf16 v[110:113], v[62:65], v[194:197], v[110:113]
	v_mfma_f32_16x16x32_bf16 v[94:97], v[58:61], v[198:201], v[94:97]
	v_mfma_f32_16x16x32_bf16 v[94:97], v[62:65], v[202:205], v[94:97]
	v_mfma_f32_16x16x32_bf16 v[90:93], v[74:77], v[198:201], v[90:93]
	v_mfma_f32_16x16x32_bf16 v[90:93], v[78:81], v[202:205], v[90:93]
	v_mfma_f32_16x16x32_bf16 v[106:109], v[74:77], v[184:187], v[106:109]
	v_mfma_f32_16x16x32_bf16 v[106:109], v[78:81], v[194:197], v[106:109]
	v_mfma_f32_16x16x32_bf16 v[122:125], v[74:77], v[170:173], v[122:125]
	v_mfma_f32_16x16x32_bf16 v[122:125], v[78:81], v[174:177], v[122:125]
	v_mfma_f32_16x16x32_bf16 v[146:149], v[74:77], v[162:165], v[146:149]
	v_mfma_f32_16x16x32_bf16 v[146:149], v[78:81], v[166:169], v[146:149]
	v_mfma_f32_16x16x32_bf16 v[138:141], v[130:133], v[162:165], v[138:141]
	v_mfma_f32_16x16x32_bf16 v[138:141], v[142:145], v[166:169], v[138:141]
	v_mfma_f32_16x16x32_bf16 v[118:121], v[130:133], v[170:173], v[118:121]
	v_mfma_f32_16x16x32_bf16 v[118:121], v[142:145], v[174:177], v[118:121]
	v_mfma_f32_16x16x32_bf16 v[102:105], v[130:133], v[184:187], v[102:105]
	v_mfma_f32_16x16x32_bf16 v[102:105], v[142:145], v[194:197], v[102:105]
	v_mfma_f32_16x16x32_bf16 v[86:89], v[130:133], v[198:201], v[86:89]
	v_mfma_f32_16x16x32_bf16 v[86:89], v[142:145], v[202:205], v[86:89]
	v_mfma_f32_16x16x32_bf16 v[82:85], v[154:157], v[198:201], v[82:85]
	v_mfma_f32_16x16x32_bf16 v[82:85], v[158:161], v[202:205], v[82:85]
	v_mfma_f32_16x16x32_bf16 v[98:101], v[154:157], v[184:187], v[98:101]
	v_mfma_f32_16x16x32_bf16 v[98:101], v[158:161], v[194:197], v[98:101]
	v_mfma_f32_16x16x32_bf16 v[114:117], v[154:157], v[170:173], v[114:117]
	v_mfma_f32_16x16x32_bf16 v[114:117], v[158:161], v[174:177], v[114:117]
	v_mfma_f32_16x16x32_bf16 v[134:137], v[154:157], v[162:165], v[134:137]
	v_mfma_f32_16x16x32_bf16 v[134:137], v[158:161], v[166:169], v[134:137]
	s_setprio 0
	s_add_i32 s8, s46, s90
	s_mov_b32 m0, s8
	ds_read_b128 v[162:165], v246 offset:16384
	ds_read_b128 v[166:169], v246 offset:17408
	ds_read_b128 v[170:173], v246 offset:18432
	ds_read_b128 v[174:177], v246 offset:19456
	ds_read_b128 v[184:187], v246 offset:20480
	ds_read_b128 v[194:197], v246 offset:21504
	ds_read_b128 v[198:201], v246 offset:22528
	ds_read_b128 v[202:205], v246 offset:23552
	global_load_lds_dwordx4 v182, s[80:81]
	s_add_i32 m0, s8, 0x2000
	s_add_u32 s8, s80, 0x158000
	s_addc_u32 s9, s81, 0
	s_add_i32 s46, s47, s90
	global_load_lds_dwordx4 v188, s[80:81]
	s_mov_b32 m0, s46
	s_nop 0
	global_load_lds_dwordx4 v182, s[8:9]
	s_add_i32 m0, s46, 0x2000
	s_nop 0
	global_load_lds_dwordx4 v188, s[8:9]
	s_mov_b32 m0, s91
	s_nop 0
	global_load_lds_dwordx4 v178, s[40:41]
	s_mov_b32 m0, s92
	s_nop 0
	global_load_lds_dwordx4 v180, s[40:41]
	s_waitcnt vmcnt(8)
	s_waitcnt lgkmcnt(0)
	s_barrier
	s_setprio 2
	v_mfma_f32_16x16x32_bf16 v[70:73], v[58:61], v[162:165], v[70:73]
	v_mfma_f32_16x16x32_bf16 v[70:73], v[62:65], v[166:169], v[70:73]
	v_mfma_f32_16x16x32_bf16 v[46:49], v[58:61], v[170:173], v[46:49]
	v_mfma_f32_16x16x32_bf16 v[46:49], v[62:65], v[174:177], v[46:49]
	v_mfma_f32_16x16x32_bf16 v[30:33], v[58:61], v[184:187], v[30:33]
	v_mfma_f32_16x16x32_bf16 v[30:33], v[62:65], v[194:197], v[30:33]
	v_mfma_f32_16x16x32_bf16 v[14:17], v[58:61], v[198:201], v[14:17]
	v_mfma_f32_16x16x32_bf16 v[14:17], v[62:65], v[202:205], v[14:17]
	v_mfma_f32_16x16x32_bf16 v[10:13], v[74:77], v[198:201], v[10:13]
	v_mfma_f32_16x16x32_bf16 v[10:13], v[78:81], v[202:205], v[10:13]
	v_mfma_f32_16x16x32_bf16 v[26:29], v[74:77], v[184:187], v[26:29]
	v_mfma_f32_16x16x32_bf16 v[26:29], v[78:81], v[194:197], v[26:29]
	v_mfma_f32_16x16x32_bf16 v[42:45], v[74:77], v[170:173], v[42:45]
	v_mfma_f32_16x16x32_bf16 v[42:45], v[78:81], v[174:177], v[42:45]
	v_mfma_f32_16x16x32_bf16 v[66:69], v[74:77], v[162:165], v[66:69]
	v_mfma_f32_16x16x32_bf16 v[66:69], v[78:81], v[166:169], v[66:69]
	v_mfma_f32_16x16x32_bf16 v[54:57], v[130:133], v[162:165], v[54:57]
	v_mfma_f32_16x16x32_bf16 v[54:57], v[142:145], v[166:169], v[54:57]
	v_mfma_f32_16x16x32_bf16 v[38:41], v[130:133], v[170:173], v[38:41]
	v_mfma_f32_16x16x32_bf16 v[38:41], v[142:145], v[174:177], v[38:41]
	v_mfma_f32_16x16x32_bf16 v[22:25], v[130:133], v[184:187], v[22:25]
	v_mfma_f32_16x16x32_bf16 v[22:25], v[142:145], v[194:197], v[22:25]
	v_mfma_f32_16x16x32_bf16 v[6:9], v[130:133], v[198:201], v[6:9]
	v_mfma_f32_16x16x32_bf16 v[6:9], v[142:145], v[202:205], v[6:9]
	v_mfma_f32_16x16x32_bf16 v[2:5], v[154:157], v[198:201], v[2:5]
	v_mfma_f32_16x16x32_bf16 v[2:5], v[158:161], v[202:205], v[2:5]
	v_mfma_f32_16x16x32_bf16 v[18:21], v[154:157], v[184:187], v[18:21]
	v_mfma_f32_16x16x32_bf16 v[18:21], v[158:161], v[194:197], v[18:21]
	v_mfma_f32_16x16x32_bf16 v[34:37], v[154:157], v[170:173], v[34:37]
	v_mfma_f32_16x16x32_bf16 v[34:37], v[158:161], v[174:177], v[34:37]
	v_mfma_f32_16x16x32_bf16 v[50:53], v[154:157], v[162:165], v[50:53]
	v_mfma_f32_16x16x32_bf16 v[50:53], v[158:161], v[166:169], v[50:53]
	s_setprio 0
	s_add_i32 s46, 0, 0x18000
	s_add_i32 s47, 0, 0x1c000
	ds_read_b128 v[58:61], v206 offset:32768
	ds_read_b128 v[62:65], v206 offset:33792
	ds_read_b128 v[74:77], v206 offset:34816
	ds_read_b128 v[78:81], v206 offset:35840
	ds_read_b128 v[130:133], v206 offset:49152
	ds_read_b128 v[142:145], v206 offset:50176
	ds_read_b128 v[154:157], v206 offset:51200
	ds_read_b128 v[158:161], v206 offset:52224
	s_add_u32 s8, s40, 0x158000
	s_addc_u32 s9, s41, 0
	s_mov_b32 m0, s93
	ds_read_b128 v[162:165], v246 offset:32768
	ds_read_b128 v[166:169], v246 offset:33792
	ds_read_b128 v[170:173], v246 offset:34816
	ds_read_b128 v[174:177], v246 offset:35840
	ds_read_b128 v[184:187], v246 offset:36864
	ds_read_b128 v[194:197], v246 offset:37888
	ds_read_b128 v[198:201], v246 offset:38912
	ds_read_b128 v[202:205], v246 offset:39936
	global_load_lds_dwordx4 v178, s[8:9]
	s_mov_b32 m0, s94
	s_nop 0
	global_load_lds_dwordx4 v180, s[8:9]
	s_waitcnt vmcnt(8)
	s_waitcnt lgkmcnt(0)
	s_barrier
; #define PG8_STAGE(bufoff, gbase, voff) do { _Pragma("unroll") for (int _i = 0; _i < 2; ++_i) \
;         __builtin_amdgcn_global_load_lds((const unsigned*)((const char*)(gbase) + (voff)[_i]), (PG8_LAS unsigned*)(lds + (bufoff) + ldsw + _i * 8192), 16, 0, 0); } while (0)
; #define PG8_LDA(dst, b, h) do { _Pragma("unroll") for (int m = 0; m < 4; ++m) _Pragma("unroll") for (int k = 0; k < 2; ++k) dst[m][k] = *(const PG8_LAS bf16x8*)(lds + PG8_SA(b, h) + aoff + m * 2048 + k * 1024); } while (0)
; #define PG8_LDB(dst, b, h) do { _Pragma("unroll") for (int n = 0; n < 2; ++n) _Pragma("unroll") for (int k = 0; k < 2; ++k) dst[n][k] = *(const PG8_LAS bf16x8*)(lds + PG8_SB(b, h) + boff + n * 2048 + k * 1024); } while (0)
; #define PG8_WAIT_V(n) asm volatile("s_waitcnt vmcnt(" #n ")" ::: "memory")
; #define PG8_WAIT_L(n) asm volatile("s_waitcnt lgkmcnt(" #n ")" ::: "memory")
; #define PG8_BAR __builtin_amdgcn_s_barrier()
; #define PG8_SCHED __builtin_amdgcn_sched_barrier(0)
;     ...
;             PG8_LDB(B0, 1, 0); PG8_LDB(B1, 1, 1); PG8_SCHED; PG8_LDA(At, 1, 0); PG8_STAGE(PG8_SA(0, 1), a2 + hstep, voffA);
;             PG8_WAIT_V(8); PG8_WAIT_L(0); PG8_BAR; PG8_MMA(0, 0, At, B0); PG8_MMA(0, 1, At, B1); PG8_BAR; PG8_SCHED;
;             PG8_LDA(At, 1, 1); PG8_STAGE(PG8_SB(1, 0), b3, voffB); PG8_STAGE(PG8_SB(1, 1), b3 + hstep, voffB); PG8_STAGE(PG8_SA(1, 0), a3, voffA);
;             PG8_WAIT_V(8); PG8_WAIT_L(0); PG8_BAR; PG8_MMA(1, 0, At, B0); PG8_MMA(1, 1, At, B1); PG8_BAR; PG8_SCHED;
	s_setprio 2
	v_mfma_f32_16x16x32_bf16 v[150:153], v[58:61], v[162:165], v[150:153]
	v_mfma_f32_16x16x32_bf16 v[150:153], v[62:65], v[166:169], v[150:153]
	v_mfma_f32_16x16x32_bf16 v[126:129], v[58:61], v[170:173], v[126:129]
	v_mfma_f32_16x16x32_bf16 v[126:129], v[62:65], v[174:177], v[126:129]
	v_mfma_f32_16x16x32_bf16 v[110:113], v[58:61], v[184:187], v[110:113]
	v_mfma_f32_16x16x32_bf16 v[110:113], v[62:65], v[194:197], v[110:113]
	v_mfma_f32_16x16x32_bf16 v[94:97], v[58:61], v[198:201], v[94:97]
	v_mfma_f32_16x16x32_bf16 v[94:97], v[62:65], v[202:205], v[94:97]
	v_mfma_f32_16x16x32_bf16 v[90:93], v[74:77], v[198:201], v[90:93]
	v_mfma_f32_16x16x32_bf16 v[90:93], v[78:81], v[202:205], v[90:93]
	v_mfma_f32_16x16x32_bf16 v[106:109], v[74:77], v[184:187], v[106:109]
	v_mfma_f32_16x16x32_bf16 v[106:109], v[78:81], v[194:197], v[106:109]
	v_mfma_f32_16x16x32_bf16 v[122:125], v[74:77], v[170:173], v[122:125]
	v_mfma_f32_16x16x32_bf16 v[122:125], v[78:81], v[174:177], v[122:125]
	v_mfma_f32_16x16x32_bf16 v[146:149], v[74:77], v[162:165], v[146:149]
	v_mfma_f32_16x16x32_bf16 v[146:149], v[78:81], v[166:169], v[146:149]
	v_mfma_f32_16x16x32_bf16 v[138:141], v[130:133], v[162:165], v[138:141]
	v_mfma_f32_16x16x32_bf16 v[138:141], v[142:145], v[166:169], v[138:141]
	v_mfma_f32_16x16x32_bf16 v[118:121], v[130:133], v[170:173], v[118:121]
	v_mfma_f32_16x16x32_bf16 v[118:121], v[142:145], v[174:177], v[118:121]
	v_mfma_f32_16x16x32_bf16 v[102:105], v[130:133], v[184:187], v[102:105]
	v_mfma_f32_16x16x32_bf16 v[102:105], v[142:145], v[194:197], v[102:105]
	v_mfma_f32_16x16x32_bf16 v[86:89], v[130:133], v[198:201], v[86:89]
	v_mfma_f32_16x16x32_bf16 v[86:89], v[142:145], v[202:205], v[86:89]
	v_mfma_f32_16x16x32_bf16 v[82:85], v[154:157], v[198:201], v[82:85]
	v_mfma_f32_16x16x32_bf16 v[82:85], v[158:161], v[202:205], v[82:85]
	v_mfma_f32_16x16x32_bf16 v[98:101], v[154:157], v[184:187], v[98:101]
	v_mfma_f32_16x16x32_bf16 v[98:101], v[158:161], v[194:197], v[98:101]
	v_mfma_f32_16x16x32_bf16 v[114:117], v[154:157], v[170:173], v[114:117]
	v_mfma_f32_16x16x32_bf16 v[114:117], v[158:161], v[174:177], v[114:117]
	v_mfma_f32_16x16x32_bf16 v[134:137], v[154:157], v[162:165], v[134:137]
	v_mfma_f32_16x16x32_bf16 v[134:137], v[158:161], v[166:169], v[134:137]
	s_setprio 0
	s_add_i32 s8, s46, s90
	s_mov_b32 m0, s8
	ds_read_b128 v[162:165], v246 offset:49152
	ds_read_b128 v[166:169], v246 offset:50176
	ds_read_b128 v[170:173], v246 offset:51200
	ds_read_b128 v[174:177], v246 offset:52224
	ds_read_b128 v[184:187], v246 offset:53248
	ds_read_b128 v[194:197], v246 offset:54272
	ds_read_b128 v[198:201], v246 offset:55296
	ds_read_b128 v[202:205], v246 offset:56320
	s_add_u32 s100, s80, 0x80
	s_addc_u32 s101, s81, 0
	global_load_lds_dwordx4 v182, s[100:101]
	s_add_i32 m0, s8, 0x2000
	s_add_u32 s8, s80, 0x158080
	s_addc_u32 s9, s81, 0
	s_add_i32 vcc_lo, s47, s90
	global_load_lds_dwordx4 v188, s[100:101]
	s_mov_b32 m0, vcc_lo
	s_nop 0
	global_load_lds_dwordx4 v182, s[8:9]
	s_add_i32 m0, vcc_lo, 0x2000
	s_nop 0
	global_load_lds_dwordx4 v188, s[8:9]
	s_mov_b32 m0, s31
	s_nop 0
	s_add_u32 s100, s40, 0x80
	s_addc_u32 s101, s41, 0
	global_load_lds_dwordx4 v178, s[100:101]
	s_mov_b32 m0, s56
	s_nop 0
	global_load_lds_dwordx4 v180, s[100:101]
	s_waitcnt vmcnt(8)
	s_waitcnt lgkmcnt(0)
	s_barrier
	s_setprio 2
	v_mfma_f32_16x16x32_bf16 v[70:73], v[58:61], v[162:165], v[70:73]
	v_mfma_f32_16x16x32_bf16 v[70:73], v[62:65], v[166:169], v[70:73]
	v_mfma_f32_16x16x32_bf16 v[46:49], v[58:61], v[170:173], v[46:49]
	v_mfma_f32_16x16x32_bf16 v[46:49], v[62:65], v[174:177], v[46:49]
	v_mfma_f32_16x16x32_bf16 v[30:33], v[58:61], v[184:187], v[30:33]
	v_mfma_f32_16x16x32_bf16 v[30:33], v[62:65], v[194:197], v[30:33]
	v_mfma_f32_16x16x32_bf16 v[14:17], v[58:61], v[198:201], v[14:17]
	v_mfma_f32_16x16x32_bf16 v[14:17], v[62:65], v[202:205], v[14:17]
	v_mfma_f32_16x16x32_bf16 v[10:13], v[74:77], v[198:201], v[10:13]
	v_mfma_f32_16x16x32_bf16 v[10:13], v[78:81], v[202:205], v[10:13]
	v_mfma_f32_16x16x32_bf16 v[26:29], v[74:77], v[184:187], v[26:29]
	v_mfma_f32_16x16x32_bf16 v[26:29], v[78:81], v[194:197], v[26:29]
	v_mfma_f32_16x16x32_bf16 v[42:45], v[74:77], v[170:173], v[42:45]
	v_mfma_f32_16x16x32_bf16 v[42:45], v[78:81], v[174:177], v[42:45]
	v_mfma_f32_16x16x32_bf16 v[66:69], v[74:77], v[162:165], v[66:69]
	v_mfma_f32_16x16x32_bf16 v[66:69], v[78:81], v[166:169], v[66:69]
	v_mfma_f32_16x16x32_bf16 v[54:57], v[130:133], v[162:165], v[54:57]
	v_mfma_f32_16x16x32_bf16 v[54:57], v[142:145], v[166:169], v[54:57]
	v_mfma_f32_16x16x32_bf16 v[38:41], v[130:133], v[170:173], v[38:41]
	v_mfma_f32_16x16x32_bf16 v[38:41], v[142:145], v[174:177], v[38:41]
	v_mfma_f32_16x16x32_bf16 v[22:25], v[130:133], v[184:187], v[22:25]
	v_mfma_f32_16x16x32_bf16 v[22:25], v[142:145], v[194:197], v[22:25]
	v_mfma_f32_16x16x32_bf16 v[6:9], v[130:133], v[198:201], v[6:9]
	v_mfma_f32_16x16x32_bf16 v[6:9], v[142:145], v[202:205], v[6:9]
	v_mfma_f32_16x16x32_bf16 v[2:5], v[154:157], v[198:201], v[2:5]
	v_mfma_f32_16x16x32_bf16 v[2:5], v[158:161], v[202:205], v[2:5]
	v_mfma_f32_16x16x32_bf16 v[18:21], v[154:157], v[184:187], v[18:21]
	v_mfma_f32_16x16x32_bf16 v[18:21], v[158:161], v[194:197], v[18:21]
	v_mfma_f32_16x16x32_bf16 v[34:37], v[154:157], v[170:173], v[34:37]
	v_mfma_f32_16x16x32_bf16 v[34:37], v[158:161], v[174:177], v[34:37]
	v_mfma_f32_16x16x32_bf16 v[50:53], v[154:157], v[162:165], v[50:53]
	v_mfma_f32_16x16x32_bf16 v[50:53], v[158:161], v[166:169], v[50:53]
	s_setprio 0
	s_add_i32 s45, s45, 2
	s_add_u32 s37, s37, 0x100
	s_addc_u32 s44, s44, 0
	s_cmpk_gt_u32 s45, 0x53
	s_mov_b64 s[8:9], s[10:11]
	s_cbranch_scc0 .Lhob_f2_Thead
	s_branch .Lhob_f2_exit
.Lhob_f2_exit:
	s_and_b64 vcc, exec, s[76:77]
	s_cbranch_vccz .LBB0_1651
	s_setprio 0
